# residual epilogues: 16-lane sum-of-squares butterflies via v_mov_b32_dpp instead of index math + ds_bpermute (400 of 512 sites)
# baseline (speedup 1.0000x reference)
; #define MFMA16(a, b, c) __builtin_amdgcn_mfma_f32_16x16x32_bf16((a), (b), (c), 0, 0, 0)
; template <class Epi>
; DI void gemm8_tile(const bf16_t* __restrict__ Ab, int lda, const bf16_t* __restrict__ Bb, int ldb, int K, int brow, int bcol, const Epi epi,
;                    bool staged, bool has_next, const bf16_t* __restrict__ Abn, const bf16_t* __restrict__ Bbn) {
;     ...
;       for (int m = 0; m < 8; ++m)
; #pragma unroll
;         for (int n = 0; n < 4; ++n) acc[m][n] = MFMA16(At[m], Bf[n], acc[m][n]);
;       __builtin_amdgcn_sched_barrier(0);
;     }
;     asm volatile("s_waitcnt vmcnt(0)" ::: "memory");
;     __syncthreads();
;   DI void run8(f32x4 (&acc)[8][4], int rb, int cb, int fr, int fq) const {
;     const int lane = fq * 16 + fr, wid = (int)(threadIdx.x >> 6);
;     const float sc = scale; bf16_t* const xbp = xb; float* const ssqp = ssq;
;     float* scr = (float*)(smem + G8_STAGE_B + wid * 4352);
;     const int prow = lane >> 4, c4 = lane & 15;
;     const float* xp = xin + (size_t)(rb + prow) * D + cb + c4 * 4;
;     float* op = xout + (size_t)(rb + prow) * D + cb + c4 * 4;
.LBB0_488:
	v_lshrrev_b32_e32 v194, 4, v206
	s_waitcnt lgkmcnt(0)
	v_mfma_f32_16x16x32_bf16 v[200:203], v[58:61], v[2:5], v[126:129]
	v_mfma_f32_16x16x32_bf16 v[206:209], v[58:61], v[138:141], v[122:125]
	v_mfma_f32_16x16x32_bf16 v[212:215], v[58:61], v[182:185], v[118:121]
	v_mfma_f32_16x16x32_bf16 v[222:225], v[58:61], v[186:189], v[114:117]
	v_mfma_f32_16x16x32_bf16 v[150:153], v[50:53], v[2:5], v[110:113]
	v_mfma_f32_16x16x32_bf16 v[154:157], v[50:53], v[138:141], v[106:109]
	v_mfma_f32_16x16x32_bf16 v[142:145], v[50:53], v[182:185], v[102:105]
	v_mfma_f32_16x16x32_bf16 v[146:149], v[50:53], v[186:189], v[98:101]
	v_mfma_f32_16x16x32_bf16 v[114:117], v[42:45], v[2:5], v[94:97]
	v_mfma_f32_16x16x32_bf16 v[118:121], v[42:45], v[138:141], v[90:93]
	v_mfma_f32_16x16x32_bf16 v[106:109], v[42:45], v[182:185], v[86:89]
	v_mfma_f32_16x16x32_bf16 v[110:113], v[42:45], v[186:189], v[82:85]
	v_mfma_f32_16x16x32_bf16 v[82:85], v[34:37], v[2:5], v[78:81]
	v_mfma_f32_16x16x32_bf16 v[86:89], v[34:37], v[138:141], v[74:77]
	v_mfma_f32_16x16x32_bf16 v[74:77], v[34:37], v[182:185], v[70:73]
	v_mfma_f32_16x16x32_bf16 v[78:81], v[34:37], v[186:189], v[66:69]
	v_mfma_f32_16x16x32_bf16 v[58:61], v[26:29], v[2:5], v[62:65]
	v_mfma_f32_16x16x32_bf16 v[62:65], v[26:29], v[138:141], v[158:161]
	v_mfma_f32_16x16x32_bf16 v[50:53], v[26:29], v[182:185], v[54:57]
	v_mfma_f32_16x16x32_bf16 v[54:57], v[26:29], v[186:189], v[162:165]
	v_mfma_f32_16x16x32_bf16 v[42:45], v[18:21], v[2:5], v[46:49]
	v_mfma_f32_16x16x32_bf16 v[46:49], v[18:21], v[138:141], v[166:169]
	v_mfma_f32_16x16x32_bf16 v[34:37], v[18:21], v[182:185], v[38:41]
	v_mfma_f32_16x16x32_bf16 v[38:41], v[18:21], v[186:189], v[170:173]
	v_mfma_f32_16x16x32_bf16 v[26:29], v[10:13], v[2:5], v[30:33]
	v_mfma_f32_16x16x32_bf16 v[30:33], v[10:13], v[138:141], v[174:177]
	v_mfma_f32_16x16x32_bf16 v[18:21], v[10:13], v[182:185], v[22:25]
	v_mfma_f32_16x16x32_bf16 v[22:25], v[10:13], v[186:189], v[178:181]
	v_mfma_f32_16x16x32_bf16 v[10:13], v[190:193], v[2:5], v[14:17]
	v_mfma_f32_16x16x32_bf16 v[14:17], v[190:193], v[138:141], v[130:133]
	v_mfma_f32_16x16x32_bf16 v[2:5], v[190:193], v[182:185], v[6:9]
	v_mfma_f32_16x16x32_bf16 v[6:9], v[190:193], v[186:189], v[134:137]
	v_add_u32_e32 v0, s3, v205
	v_or_b32_e32 v178, v0, v194
	v_lshl_or_b32 v180, v204, 6, s31
	v_ashrrev_i32_e32 v179, 31, v178
	v_lshlrev_b64 v[182:183], 12, v[178:179]
	v_ashrrev_i32_e32 v181, 31, v180
	v_lshl_add_u64 v[66:67], s[38:39], 0, v[182:183]
	v_lshlrev_b64 v[186:187], 2, v[180:181]
	v_lshl_add_u64 v[66:67], v[66:67], 0, v[186:187]
	v_lshlrev_b32_e32 v0, 2, v199
	v_lshl_add_u64 v[184:185], v[66:67], 0, v[0:1]
	s_movk_i32 s0, 0x4000
	v_add_co_u32_e32 v66, vcc, s0, v184
	s_mov_b32 s0, 0x8000
	s_nop 0
	v_addc_co_u32_e32 v67, vcc, 0, v185, vcc
	s_waitcnt vmcnt(0)
	s_waitcnt vmcnt(0)
	s_barrier
; DI unsigned pack_bf16(float lo, float hi) { f32x2 v = {lo, hi}; bf16v2 b = __builtin_convertvector(v, bf16v2); return __builtin_bit_cast(unsigned, b); }
; DI float red16(float v) { v += __shfl_xor(v, 1); v += __shfl_xor(v, 2); v += __shfl_xor(v, 4); v += __shfl_xor(v, 8); return v; }
;   DI void run8(f32x4 (&acc)[8][4], int rb, int cb, int fr, int fq) const {
;     ...
;     for (int mh = 0; mh < 2; ++mh) {
;       f32x4 xv[4][4];
; #pragma unroll
;       for (int mm = 0; mm < 4; ++mm)
; #pragma unroll
;         for (int ps = 0; ps < 4; ++ps) xv[mm][ps] = __builtin_nontemporal_load((const f32x4*)(xp + (size_t)((mh * 4 + mm) * 16 + ps * 4) * D));
;       __builtin_amdgcn_sched_barrier(0);
; #pragma unroll
;       for (int mm = 0; mm < 4; ++mm) {
;         const int m = mh * 4 + mm;
; #pragma unroll
;         for (int n = 0; n < 4; ++n)
; #pragma unroll
;           for (int j = 0; j < 4; ++j) scr[(fq * 4 + j) * 68 + n * 16 + fr] = acc[m][n][j];
;         __builtin_amdgcn_sched_barrier(0);
; #pragma unroll
;         for (int ps = 0; ps < 4; ++ps) {
;           const f32x4 a = *(const f32x4*)(scr + (ps * 4 + prow) * 68 + c4 * 4);
;           f32x4 v;
;           v.x = xv[mm][ps].x + a.x * sc; v.y = xv[mm][ps].y + a.y * sc; v.z = xv[mm][ps].z + a.z * sc; v.w = xv[mm][ps].w + a.w * sc;
;           const int grow = rb + m * 16 + ps * 4 + prow;
;           __builtin_nontemporal_store(v, (f32x4*)(op + (size_t)(m * 16 + ps * 4) * D));
;           if (xbp) {
;             u32x2 o; o.x = pack_bf16(v.x, v.y); o.y = pack_bf16(v.z, v.w);
;             *(u32x2*)(xbp + (size_t)grow * LDH + cb + c4 * 4) = o;
;             const float t = red16(v.x * v.x + v.y * v.y + v.z * v.z + v.w * v.w);
;             if (c4 == 0) atomicAdd(ssqp + grow, t);
;           }
	global_load_dwordx4 v[174:177], v[184:185], off nt
	global_load_dwordx4 v[170:173], v[66:67], off nt
	v_add_co_u32_e32 v66, vcc, s0, v184
	s_mov_b32 s0, 0xc000
	s_nop 0
	v_addc_co_u32_e32 v67, vcc, 0, v185, vcc
	v_add_co_u32_e32 v68, vcc, s0, v184
	s_mov_b32 s0, 0x14000
	s_nop 0
	v_addc_co_u32_e32 v69, vcc, 0, v185, vcc
	global_load_dwordx4 v[166:169], v[66:67], off nt
	global_load_dwordx4 v[162:165], v[68:69], off nt
	v_add_co_u32_e32 v66, vcc, s92, v184
	v_readlane_b32 s8, v254, 0
	s_nop 0
	v_addc_co_u32_e32 v67, vcc, 0, v185, vcc
	v_add_co_u32_e32 v68, vcc, s0, v184
	s_mov_b32 s0, 0x18000
	s_nop 0
	v_addc_co_u32_e32 v69, vcc, 0, v185, vcc
	global_load_dwordx4 v[158:161], v[66:67], off nt
	global_load_dwordx4 v[138:141], v[68:69], off nt
	v_add_co_u32_e32 v66, vcc, s0, v184
	s_mov_b32 s0, 0x1c000
	s_nop 0
	v_addc_co_u32_e32 v67, vcc, 0, v185, vcc
	v_add_co_u32_e32 v68, vcc, s0, v184
	s_mov_b32 s0, 0x20000
	s_nop 0
	v_addc_co_u32_e32 v69, vcc, 0, v185, vcc
	global_load_dwordx4 v[134:137], v[66:67], off nt
	global_load_dwordx4 v[130:133], v[68:69], off nt
	v_add_co_u32_e32 v66, vcc, s0, v184
	s_mov_b32 s0, 0x24000
	s_nop 0
	v_addc_co_u32_e32 v67, vcc, 0, v185, vcc
	v_add_co_u32_e32 v68, vcc, s0, v184
	s_mov_b32 s0, 0x28000
	s_nop 0
	v_addc_co_u32_e32 v69, vcc, 0, v185, vcc
	global_load_dwordx4 v[126:129], v[66:67], off nt
	global_load_dwordx4 v[122:125], v[68:69], off nt
	v_add_co_u32_e32 v66, vcc, s0, v184
	s_mov_b32 s0, 0x2c000
	s_nop 0
	v_addc_co_u32_e32 v67, vcc, 0, v185, vcc
	v_add_co_u32_e32 v68, vcc, s0, v184
	s_mov_b32 s0, 0x30000
	s_nop 0
	v_addc_co_u32_e32 v69, vcc, 0, v185, vcc
	global_load_dwordx4 v[102:105], v[66:67], off nt
	global_load_dwordx4 v[98:101], v[68:69], off nt
	v_add_co_u32_e32 v66, vcc, s0, v184
	s_mov_b32 s0, 0x34000
	s_nop 0
	v_addc_co_u32_e32 v67, vcc, 0, v185, vcc
	v_add_co_u32_e32 v68, vcc, s0, v184
	s_mov_b32 s0, 0x38000
	s_nop 0
	v_addc_co_u32_e32 v69, vcc, 0, v185, vcc
	global_load_dwordx4 v[94:97], v[66:67], off nt
	global_load_dwordx4 v[90:93], v[68:69], off nt
	v_add_co_u32_e32 v66, vcc, s0, v184
	s_mov_b32 s0, 0x3c000
	s_nop 0
	v_addc_co_u32_e32 v67, vcc, 0, v185, vcc
	v_add_co_u32_e32 v68, vcc, s0, v184
	v_readlane_b32 s10, v254, 2
	s_nop 0
	v_addc_co_u32_e32 v69, vcc, 0, v185, vcc
	global_load_dwordx4 v[70:73], v[66:67], off nt
	s_nop 0
	global_load_dwordx4 v[66:69], v[68:69], off nt
	v_readlane_b32 s11, v254, 3
	v_readlane_b32 s9, v254, 1
	v_lshl_add_u64 v[180:181], v[180:181], 1, s[50:51]
	v_lshl_add_u64 v[182:183], s[10:11], 0, v[182:183]
	v_lshl_add_u64 v[182:183], v[182:183], 0, v[186:187]
	v_lshl_add_u64 v[182:183], v[182:183], 0, v[0:1]
	v_lshl_add_u32 v186, v198, 2, v218
	v_lshlrev_b32_e32 v0, 1, v199
	v_mad_u32_u24 v187, v198, 12, v186
	v_lshl_add_u64 v[180:181], v[180:181], 0, v[0:1]
	v_cmp_eq_u32_e64 s[8:9], 0, v198
	v_mad_u32_u24 v186, v194, s88, v186
	ds_write2_b32 v186, v200, v206 offset1:16
	ds_write2_b32 v186, v201, v207 offset0:68 offset1:84
	ds_write2_b32 v186, v202, v208 offset0:136 offset1:152
	ds_write2_b32 v186, v203, v209 offset0:204 offset1:220
	ds_write2_b32 v186, v212, v222 offset0:32 offset1:48
	ds_write2_b32 v186, v213, v223 offset0:100 offset1:116
	ds_write2_b32 v186, v214, v224 offset0:168 offset1:184
	ds_write2_b32 v186, v215, v225 offset0:236 offset1:252
	s_movk_i32 s0, 0x110
	v_mad_u32_u24 v0, v194, s0, v187
	ds_read_b128 v[188:191], v0
	v_cndmask_b32_e64 v0, 0, 1, s[76:77]
	v_cmp_ne_u32_e64 s[10:11], 1, v0
	s_andn2_b64 vcc, exec, s[76:77]
	s_waitcnt vmcnt(15) lgkmcnt(0)
	v_pk_fma_f32 v[174:175], v[188:189], 0.5, v[174:175] op_sel_hi:[1,0,1]
	v_pk_fma_f32 v[176:177], v[190:191], 0.5, v[176:177] op_sel_hi:[1,0,1]
	global_store_dwordx4 v[182:183], v[174:177], off nt
	s_cbranch_vccnz .LBB0_492
	v_cvt_pk_bf16_f32 v188, v174, v175
	v_pk_mul_f32 v[174:175], v[174:175], v[174:175]
	v_cvt_pk_bf16_f32 v189, v176, v177
	v_add_f32_e32 v0, v174, v175
	v_and_b32_e32 v175, 64, v219
	s_nop 0
	v_add_u32_e32 v175, 64, v175
	v_pk_mul_f32 v[176:177], v[176:177], v[176:177]
	s_nop 0
	v_add_f32_e32 v0, v176, v0
	v_add_f32_e32 v0, v177, v0
	s_nop 1
	v_mov_b32_dpp v174, v0 quad_perm:[1,0,3,2] row_mask:0xf bank_mask:0xf
	v_mad_i64_i32 v[190:191], s[0:1], v178, s66, v[180:181]
	global_store_dwordx2 v[190:191], v[188:189], off
	s_waitcnt lgkmcnt(0)
	v_add_f32_e32 v0, v0, v174
	s_nop 5
	v_mov_b32_dpp v174, v0 quad_perm:[2,3,0,1] row_mask:0xf bank_mask:0xf
	s_waitcnt lgkmcnt(0)
	v_add_f32_e32 v0, v0, v174
	s_nop 5
	v_mov_b32_dpp v174, v0 row_half_mirror row_mask:0xf bank_mask:0xf
	s_waitcnt lgkmcnt(0)
	v_add_f32_e32 v0, v0, v174
	v_xor_b32_e32 v174, 8, v219
	v_cmp_lt_i32_e32 vcc, v174, v175
	s_nop 3
	v_mov_b32_dpp v174, v0 row_mirror row_mask:0xf bank_mask:0xf
	s_and_saveexec_b64 s[0:1], s[8:9]
	s_cbranch_execz .LBB0_491
	s_waitcnt lgkmcnt(0)
	v_add_f32_e32 v0, v0, v174
	v_lshl_add_u64 v[174:175], v[178:179], 2, s[62:63]
	global_atomic_add_f32 v[174:175], v0, off

; DI unsigned pack_bf16(float lo, float hi) { f32x2 v = {lo, hi}; bf16v2 b = __builtin_convertvector(v, bf16v2); return __builtin_bit_cast(unsigned, b); }
; DI float red16(float v) { v += __shfl_xor(v, 1); v += __shfl_xor(v, 2); v += __shfl_xor(v, 4); v += __shfl_xor(v, 8); return v; }
;   DI void run8(f32x4 (&acc)[8][4], int rb, int cb, int fr, int fq) const {
;     ...
;         for (int ps = 0; ps < 4; ++ps) {
;           const f32x4 a = *(const f32x4*)(scr + (ps * 4 + prow) * 68 + c4 * 4);
;           f32x4 v;
;           v.x = xv[mm][ps].x + a.x * sc; v.y = xv[mm][ps].y + a.y * sc; v.z = xv[mm][ps].z + a.z * sc; v.w = xv[mm][ps].w + a.w * sc;
;           const int grow = rb + m * 16 + ps * 4 + prow;
;           __builtin_nontemporal_store(v, (f32x4*)(op + (size_t)(m * 16 + ps * 4) * D));
;           if (xbp) {
;             u32x2 o; o.x = pack_bf16(v.x, v.y); o.y = pack_bf16(v.z, v.w);
;             *(u32x2*)(xbp + (size_t)grow * LDH + cb + c4 * 4) = o;
;             const float t = red16(v.x * v.x + v.y * v.y + v.z * v.z + v.w * v.w);
;             if (c4 == 0) atomicAdd(ssqp + grow, t);
;           }
.LBB0_492:
	v_mul_u32_u24_e32 v0, 0x110, v194
	v_add_u32_e32 v0, v187, v0
	s_waitcnt lgkmcnt(0)
	ds_read_b128 v[174:177], v0 offset:1088
	s_waitcnt vmcnt(15) lgkmcnt(0)
	v_pk_fma_f32 v[170:171], v[174:175], 0.5, v[170:171] op_sel_hi:[1,0,1]
	v_add_co_u32_e32 v174, vcc, 0x4000, v182
	v_pk_fma_f32 v[172:173], v[176:177], 0.5, v[172:173] op_sel_hi:[1,0,1]
	s_nop 0
	v_addc_co_u32_e32 v175, vcc, 0, v183, vcc
	s_and_b64 vcc, exec, s[10:11]
	global_store_dwordx4 v[174:175], v[170:173], off nt
	s_cbranch_vccnz .LBB0_496
	v_pk_mul_f32 v[174:175], v[170:171], v[170:171]
	v_pk_mul_f32 v[176:177], v[172:173], v[172:173]
	v_add_f32_e32 v174, v174, v175
	v_add_f32_e32 v174, v176, v174
	v_and_b32_e32 v176, 64, v219
	v_add_f32_e32 v174, v177, v174
	s_nop 0
	v_add_u32_e32 v177, 64, v176
	s_nop 0
	v_cvt_pk_bf16_f32 v176, v170, v171
	v_xor_b32_e32 v171, 8, v219
	s_nop 1
	v_mov_b32_dpp v175, v174 quad_perm:[1,0,3,2] row_mask:0xf bank_mask:0xf
	s_waitcnt lgkmcnt(0)
	v_add_f32_e32 v174, v174, v175
	s_nop 5
	v_mov_b32_dpp v175, v174 quad_perm:[2,3,0,1] row_mask:0xf bank_mask:0xf
	s_waitcnt lgkmcnt(0)
	v_add_f32_e32 v175, v174, v175
	s_nop 5
	v_mov_b32_dpp v179, v175 row_half_mirror row_mask:0xf bank_mask:0xf
	v_cmp_lt_i32_e32 vcc, v171, v177
	v_or_b32_e32 v174, 4, v178
	v_cvt_pk_bf16_f32 v177, v172, v173
	s_nop 0
	s_waitcnt lgkmcnt(0)
	v_add_f32_e32 v170, v175, v179
	s_nop 1
	v_mov_b32_dpp v171, v170 row_mirror row_mask:0xf bank_mask:0xf
	v_mad_i64_i32 v[172:173], s[0:1], v174, s66, v[180:181]
	global_store_dwordx2 v[172:173], v[176:177], off
	s_and_saveexec_b64 s[0:1], s[8:9]
	s_cbranch_execz .LBB0_495
	v_ashrrev_i32_e32 v175, 31, v174
	s_waitcnt lgkmcnt(0)
	v_add_f32_e32 v172, v170, v171
	v_lshl_add_u64 v[170:171], v[174:175], 2, s[62:63]
	global_atomic_add_f32 v[170:171], v172, off

; DI unsigned pack_bf16(float lo, float hi) { f32x2 v = {lo, hi}; bf16v2 b = __builtin_convertvector(v, bf16v2); return __builtin_bit_cast(unsigned, b); }
; DI float red16(float v) { v += __shfl_xor(v, 1); v += __shfl_xor(v, 2); v += __shfl_xor(v, 4); v += __shfl_xor(v, 8); return v; }
;   DI void run8(f32x4 (&acc)[8][4], int rb, int cb, int fr, int fq) const {
;     ...
;         for (int ps = 0; ps < 4; ++ps) {
;           const f32x4 a = *(const f32x4*)(scr + (ps * 4 + prow) * 68 + c4 * 4);
;           f32x4 v;
;           v.x = xv[mm][ps].x + a.x * sc; v.y = xv[mm][ps].y + a.y * sc; v.z = xv[mm][ps].z + a.z * sc; v.w = xv[mm][ps].w + a.w * sc;
;           const int grow = rb + m * 16 + ps * 4 + prow;
;           __builtin_nontemporal_store(v, (f32x4*)(op + (size_t)(m * 16 + ps * 4) * D));
;           if (xbp) {
;             u32x2 o; o.x = pack_bf16(v.x, v.y); o.y = pack_bf16(v.z, v.w);
;             *(u32x2*)(xbp + (size_t)grow * LDH + cb + c4 * 4) = o;
;             const float t = red16(v.x * v.x + v.y * v.y + v.z * v.z + v.w * v.w);
;             if (c4 == 0) atomicAdd(ssqp + grow, t);
;           }
.LBB0_496:
	s_waitcnt lgkmcnt(0)
	ds_read_b128 v[170:173], v0 offset:2176
	s_waitcnt vmcnt(15) lgkmcnt(0)
	v_pk_fma_f32 v[166:167], v[170:171], 0.5, v[166:167] op_sel_hi:[1,0,1]
	v_add_co_u32_e32 v170, vcc, 0x8000, v182
	v_pk_fma_f32 v[168:169], v[172:173], 0.5, v[168:169] op_sel_hi:[1,0,1]
	s_nop 0
	v_addc_co_u32_e32 v171, vcc, 0, v183, vcc
	s_and_b64 vcc, exec, s[10:11]
	global_store_dwordx4 v[170:171], v[166:169], off nt
	s_cbranch_vccnz .LBB0_500
	v_pk_mul_f32 v[170:171], v[166:167], v[166:167]
	v_pk_mul_f32 v[172:173], v[168:169], v[168:169]
	v_add_f32_e32 v170, v170, v171
	v_add_f32_e32 v170, v172, v170
	v_and_b32_e32 v172, 64, v219
	v_add_f32_e32 v170, v173, v170
	s_nop 0
	v_add_u32_e32 v173, 64, v172
	s_nop 0
	v_cvt_pk_bf16_f32 v172, v166, v167
	v_xor_b32_e32 v167, 8, v219
	s_nop 1
	v_mov_b32_dpp v171, v170 quad_perm:[1,0,3,2] row_mask:0xf bank_mask:0xf
	s_waitcnt lgkmcnt(0)
	v_add_f32_e32 v170, v170, v171
	s_nop 5
	v_mov_b32_dpp v171, v170 quad_perm:[2,3,0,1] row_mask:0xf bank_mask:0xf
	s_waitcnt lgkmcnt(0)
	v_add_f32_e32 v171, v170, v171
	s_nop 5
	v_mov_b32_dpp v174, v171 row_half_mirror row_mask:0xf bank_mask:0xf
	v_cmp_lt_i32_e32 vcc, v167, v173
	v_or_b32_e32 v170, 8, v178
	v_cvt_pk_bf16_f32 v173, v168, v169
	s_nop 0
	s_waitcnt lgkmcnt(0)
	v_add_f32_e32 v166, v171, v174
	s_nop 1
	v_mov_b32_dpp v167, v166 row_mirror row_mask:0xf bank_mask:0xf
	v_mad_i64_i32 v[168:169], s[0:1], v170, s66, v[180:181]
	global_store_dwordx2 v[168:169], v[172:173], off
	s_and_saveexec_b64 s[0:1], s[8:9]
	s_cbranch_execz .LBB0_499
	v_ashrrev_i32_e32 v171, 31, v170
	s_waitcnt lgkmcnt(0)
	v_add_f32_e32 v168, v166, v167
	v_lshl_add_u64 v[166:167], v[170:171], 2, s[62:63]
	global_atomic_add_f32 v[166:167], v168, off

; DI unsigned pack_bf16(float lo, float hi) { f32x2 v = {lo, hi}; bf16v2 b = __builtin_convertvector(v, bf16v2); return __builtin_bit_cast(unsigned, b); }
; DI float red16(float v) { v += __shfl_xor(v, 1); v += __shfl_xor(v, 2); v += __shfl_xor(v, 4); v += __shfl_xor(v, 8); return v; }
;   DI void run8(f32x4 (&acc)[8][4], int rb, int cb, int fr, int fq) const {
;     ...
;         for (int ps = 0; ps < 4; ++ps) {
;           const f32x4 a = *(const f32x4*)(scr + (ps * 4 + prow) * 68 + c4 * 4);
;           f32x4 v;
;           v.x = xv[mm][ps].x + a.x * sc; v.y = xv[mm][ps].y + a.y * sc; v.z = xv[mm][ps].z + a.z * sc; v.w = xv[mm][ps].w + a.w * sc;
;           const int grow = rb + m * 16 + ps * 4 + prow;
;           __builtin_nontemporal_store(v, (f32x4*)(op + (size_t)(m * 16 + ps * 4) * D));
;           if (xbp) {
;             u32x2 o; o.x = pack_bf16(v.x, v.y); o.y = pack_bf16(v.z, v.w);
;             *(u32x2*)(xbp + (size_t)grow * LDH + cb + c4 * 4) = o;
;             const float t = red16(v.x * v.x + v.y * v.y + v.z * v.z + v.w * v.w);
;             if (c4 == 0) atomicAdd(ssqp + grow, t);
;           }
.LBB0_500:
	s_waitcnt lgkmcnt(0)
	ds_read_b128 v[166:169], v0 offset:3264
	s_waitcnt vmcnt(15) lgkmcnt(0)
	v_pk_fma_f32 v[162:163], v[166:167], 0.5, v[162:163] op_sel_hi:[1,0,1]
	v_add_co_u32_e32 v166, vcc, 0xc000, v182
	v_pk_fma_f32 v[164:165], v[168:169], 0.5, v[164:165] op_sel_hi:[1,0,1]
	s_nop 0
	v_addc_co_u32_e32 v167, vcc, 0, v183, vcc
	s_and_b64 vcc, exec, s[10:11]
	global_store_dwordx4 v[166:167], v[162:165], off nt
	s_cbranch_vccnz .LBB0_504
	v_pk_mul_f32 v[166:167], v[162:163], v[162:163]
	v_pk_mul_f32 v[168:169], v[164:165], v[164:165]
	v_add_f32_e32 v166, v166, v167
	v_add_f32_e32 v166, v168, v166
	v_and_b32_e32 v168, 64, v219
	v_add_f32_e32 v166, v169, v166
	s_nop 0
	v_add_u32_e32 v169, 64, v168
	s_nop 0
	v_cvt_pk_bf16_f32 v168, v162, v163
	v_xor_b32_e32 v163, 8, v219
	s_nop 1
	v_mov_b32_dpp v167, v166 quad_perm:[1,0,3,2] row_mask:0xf bank_mask:0xf
	s_waitcnt lgkmcnt(0)
	v_add_f32_e32 v166, v166, v167
	s_nop 5
	v_mov_b32_dpp v167, v166 quad_perm:[2,3,0,1] row_mask:0xf bank_mask:0xf
	s_waitcnt lgkmcnt(0)
	v_add_f32_e32 v167, v166, v167
	s_nop 5
	v_mov_b32_dpp v170, v167 row_half_mirror row_mask:0xf bank_mask:0xf
	v_cmp_lt_i32_e32 vcc, v163, v169
	v_or_b32_e32 v166, 12, v178
	v_cvt_pk_bf16_f32 v169, v164, v165
	s_nop 0
	s_waitcnt lgkmcnt(0)
	v_add_f32_e32 v162, v167, v170
	s_nop 1
	v_mov_b32_dpp v163, v162 row_mirror row_mask:0xf bank_mask:0xf
	v_mad_i64_i32 v[164:165], s[0:1], v166, s66, v[180:181]
	global_store_dwordx2 v[164:165], v[168:169], off
	s_and_saveexec_b64 s[0:1], s[8:9]
	s_cbranch_execz .LBB0_503
	v_ashrrev_i32_e32 v167, 31, v166
	s_waitcnt lgkmcnt(0)
	v_add_f32_e32 v164, v162, v163
	v_lshl_add_u64 v[162:163], v[166:167], 2, s[62:63]
	global_atomic_add_f32 v[162:163], v164, off

; DI unsigned pack_bf16(float lo, float hi) { f32x2 v = {lo, hi}; bf16v2 b = __builtin_convertvector(v, bf16v2); return __builtin_bit_cast(unsigned, b); }
; DI float red16(float v) { v += __shfl_xor(v, 1); v += __shfl_xor(v, 2); v += __shfl_xor(v, 4); v += __shfl_xor(v, 8); return v; }
;   DI void run8(f32x4 (&acc)[8][4], int rb, int cb, int fr, int fq) const {
;     ...
;       for (int mm = 0; mm < 4; ++mm) {
;         const int m = mh * 4 + mm;
; #pragma unroll
;         for (int n = 0; n < 4; ++n)
; #pragma unroll
;           for (int j = 0; j < 4; ++j) scr[(fq * 4 + j) * 68 + n * 16 + fr] = acc[m][n][j];
;         __builtin_amdgcn_sched_barrier(0);
; #pragma unroll
;         for (int ps = 0; ps < 4; ++ps) {
;           const f32x4 a = *(const f32x4*)(scr + (ps * 4 + prow) * 68 + c4 * 4);
;           f32x4 v;
;           v.x = xv[mm][ps].x + a.x * sc; v.y = xv[mm][ps].y + a.y * sc; v.z = xv[mm][ps].z + a.z * sc; v.w = xv[mm][ps].w + a.w * sc;
;           const int grow = rb + m * 16 + ps * 4 + prow;
;           __builtin_nontemporal_store(v, (f32x4*)(op + (size_t)(m * 16 + ps * 4) * D));
;           if (xbp) {
;             u32x2 o; o.x = pack_bf16(v.x, v.y); o.y = pack_bf16(v.z, v.w);
;             *(u32x2*)(xbp + (size_t)grow * LDH + cb + c4 * 4) = o;
;             const float t = red16(v.x * v.x + v.y * v.y + v.z * v.z + v.w * v.w);
;             if (c4 == 0) atomicAdd(ssqp + grow, t);
;           }
.LBB0_504:
	ds_write2_b32 v186, v150, v154 offset1:16
	ds_write2_b32 v186, v151, v155 offset0:68 offset1:84
	ds_write2_b32 v186, v152, v156 offset0:136 offset1:152
	ds_write2_b32 v186, v153, v157 offset0:204 offset1:220
	ds_write2_b32 v186, v142, v146 offset0:32 offset1:48
	ds_write2_b32 v186, v143, v147 offset0:100 offset1:116
	ds_write2_b32 v186, v144, v148 offset0:168 offset1:184
	ds_write2_b32 v186, v145, v149 offset0:236 offset1:252
	ds_read_b128 v[142:145], v0
	v_add_co_u32_e32 v146, vcc, 0x10000, v182
	s_waitcnt vmcnt(15) lgkmcnt(0)
	v_pk_fma_f32 v[142:143], v[142:143], 0.5, v[158:159] op_sel_hi:[1,0,1]
	v_addc_co_u32_e32 v147, vcc, 0, v183, vcc
	v_pk_fma_f32 v[144:145], v[144:145], 0.5, v[160:161] op_sel_hi:[1,0,1]
	s_and_b64 vcc, exec, s[10:11]
	global_store_dwordx4 v[146:147], v[142:145], off nt
	s_cbranch_vccnz .LBB0_508
	v_pk_mul_f32 v[146:147], v[142:143], v[142:143]
	v_pk_mul_f32 v[148:149], v[144:145], v[144:145]
	v_add_f32_e32 v146, v146, v147
	v_add_f32_e32 v146, v148, v146
	v_and_b32_e32 v148, 64, v219
	v_add_f32_e32 v146, v149, v146
	s_nop 0
	v_add_u32_e32 v149, 64, v148
	s_nop 0
	v_cvt_pk_bf16_f32 v148, v142, v143
	v_xor_b32_e32 v143, 8, v219
	s_nop 1
	v_mov_b32_dpp v147, v146 quad_perm:[1,0,3,2] row_mask:0xf bank_mask:0xf
	s_waitcnt lgkmcnt(0)
	v_add_f32_e32 v146, v146, v147
	s_nop 5
	v_mov_b32_dpp v147, v146 quad_perm:[2,3,0,1] row_mask:0xf bank_mask:0xf
	s_waitcnt lgkmcnt(0)
	v_add_f32_e32 v147, v146, v147
	s_nop 5
	v_mov_b32_dpp v150, v147 row_half_mirror row_mask:0xf bank_mask:0xf
	v_cmp_lt_i32_e32 vcc, v143, v149
	v_or_b32_e32 v146, 16, v178
	v_cvt_pk_bf16_f32 v149, v144, v145
	s_nop 0
	s_waitcnt lgkmcnt(0)
	v_add_f32_e32 v142, v147, v150
	s_nop 1
	v_mov_b32_dpp v143, v142 row_mirror row_mask:0xf bank_mask:0xf
	v_mad_i64_i32 v[144:145], s[0:1], v146, s66, v[180:181]
	global_store_dwordx2 v[144:145], v[148:149], off
	s_and_saveexec_b64 s[0:1], s[8:9]
	s_cbranch_execz .LBB0_507
	v_ashrrev_i32_e32 v147, 31, v146
	s_waitcnt lgkmcnt(0)
	v_add_f32_e32 v144, v142, v143
	v_lshl_add_u64 v[142:143], v[146:147], 2, s[62:63]
	global_atomic_add_f32 v[142:143], v144, off

; DI unsigned pack_bf16(float lo, float hi) { f32x2 v = {lo, hi}; bf16v2 b = __builtin_convertvector(v, bf16v2); return __builtin_bit_cast(unsigned, b); }
; DI float red16(float v) { v += __shfl_xor(v, 1); v += __shfl_xor(v, 2); v += __shfl_xor(v, 4); v += __shfl_xor(v, 8); return v; }
;   DI void run8(f32x4 (&acc)[8][4], int rb, int cb, int fr, int fq) const {
;     ...
;         for (int ps = 0; ps < 4; ++ps) {
;           const f32x4 a = *(const f32x4*)(scr + (ps * 4 + prow) * 68 + c4 * 4);
;           f32x4 v;
;           v.x = xv[mm][ps].x + a.x * sc; v.y = xv[mm][ps].y + a.y * sc; v.z = xv[mm][ps].z + a.z * sc; v.w = xv[mm][ps].w + a.w * sc;
;           const int grow = rb + m * 16 + ps * 4 + prow;
;           __builtin_nontemporal_store(v, (f32x4*)(op + (size_t)(m * 16 + ps * 4) * D));
;           if (xbp) {
;             u32x2 o; o.x = pack_bf16(v.x, v.y); o.y = pack_bf16(v.z, v.w);
;             *(u32x2*)(xbp + (size_t)grow * LDH + cb + c4 * 4) = o;
;             const float t = red16(v.x * v.x + v.y * v.y + v.z * v.z + v.w * v.w);
;             if (c4 == 0) atomicAdd(ssqp + grow, t);
;           }
.LBB0_508:
	s_waitcnt lgkmcnt(0)
	ds_read_b128 v[142:145], v0 offset:1088
	s_waitcnt vmcnt(15) lgkmcnt(0)
	v_pk_fma_f32 v[138:139], v[142:143], 0.5, v[138:139] op_sel_hi:[1,0,1]
	v_add_co_u32_e32 v142, vcc, 0x14000, v182
	v_pk_fma_f32 v[140:141], v[144:145], 0.5, v[140:141] op_sel_hi:[1,0,1]
	s_nop 0
	v_addc_co_u32_e32 v143, vcc, 0, v183, vcc
	s_and_b64 vcc, exec, s[10:11]
	global_store_dwordx4 v[142:143], v[138:141], off nt
	s_cbranch_vccnz .LBB0_512
	v_pk_mul_f32 v[142:143], v[138:139], v[138:139]
	v_pk_mul_f32 v[144:145], v[140:141], v[140:141]
	v_add_f32_e32 v142, v142, v143
	v_add_f32_e32 v142, v144, v142
	v_and_b32_e32 v144, 64, v219
	v_add_f32_e32 v142, v145, v142
	s_nop 0
	v_add_u32_e32 v145, 64, v144
	s_nop 0
	v_cvt_pk_bf16_f32 v144, v138, v139
	v_xor_b32_e32 v139, 8, v219
	s_nop 1
	v_mov_b32_dpp v143, v142 quad_perm:[1,0,3,2] row_mask:0xf bank_mask:0xf
	s_waitcnt lgkmcnt(0)
	v_add_f32_e32 v142, v142, v143
	s_nop 5
	v_mov_b32_dpp v143, v142 quad_perm:[2,3,0,1] row_mask:0xf bank_mask:0xf
	s_waitcnt lgkmcnt(0)
	v_add_f32_e32 v143, v142, v143
	s_nop 5
	v_mov_b32_dpp v146, v143 row_half_mirror row_mask:0xf bank_mask:0xf
	v_cmp_lt_i32_e32 vcc, v139, v145
	v_or_b32_e32 v142, 20, v178
	v_cvt_pk_bf16_f32 v145, v140, v141
	s_nop 0
	s_waitcnt lgkmcnt(0)
	v_add_f32_e32 v138, v143, v146
	s_nop 1
	v_mov_b32_dpp v139, v138 row_mirror row_mask:0xf bank_mask:0xf
	v_mad_i64_i32 v[140:141], s[0:1], v142, s66, v[180:181]
	global_store_dwordx2 v[140:141], v[144:145], off
	s_and_saveexec_b64 s[0:1], s[8:9]
	s_cbranch_execz .LBB0_511
	v_ashrrev_i32_e32 v143, 31, v142
	s_waitcnt lgkmcnt(0)
	v_add_f32_e32 v140, v138, v139
	v_lshl_add_u64 v[138:139], v[142:143], 2, s[62:63]
	global_atomic_add_f32 v[138:139], v140, off

; DI unsigned pack_bf16(float lo, float hi) { f32x2 v = {lo, hi}; bf16v2 b = __builtin_convertvector(v, bf16v2); return __builtin_bit_cast(unsigned, b); }
; DI float red16(float v) { v += __shfl_xor(v, 1); v += __shfl_xor(v, 2); v += __shfl_xor(v, 4); v += __shfl_xor(v, 8); return v; }
;   DI void run8(f32x4 (&acc)[8][4], int rb, int cb, int fr, int fq) const {
;     ...
;         for (int ps = 0; ps < 4; ++ps) {
;           const f32x4 a = *(const f32x4*)(scr + (ps * 4 + prow) * 68 + c4 * 4);
;           f32x4 v;
;           v.x = xv[mm][ps].x + a.x * sc; v.y = xv[mm][ps].y + a.y * sc; v.z = xv[mm][ps].z + a.z * sc; v.w = xv[mm][ps].w + a.w * sc;
;           const int grow = rb + m * 16 + ps * 4 + prow;
;           __builtin_nontemporal_store(v, (f32x4*)(op + (size_t)(m * 16 + ps * 4) * D));
;           if (xbp) {
;             u32x2 o; o.x = pack_bf16(v.x, v.y); o.y = pack_bf16(v.z, v.w);
;             *(u32x2*)(xbp + (size_t)grow * LDH + cb + c4 * 4) = o;
;             const float t = red16(v.x * v.x + v.y * v.y + v.z * v.z + v.w * v.w);
;             if (c4 == 0) atomicAdd(ssqp + grow, t);
;           }
.LBB0_512:
	s_waitcnt lgkmcnt(0)
	ds_read_b128 v[138:141], v0 offset:2176
	s_waitcnt vmcnt(15) lgkmcnt(0)
	v_pk_fma_f32 v[134:135], v[138:139], 0.5, v[134:135] op_sel_hi:[1,0,1]
	v_add_co_u32_e32 v138, vcc, 0x18000, v182
	v_pk_fma_f32 v[136:137], v[140:141], 0.5, v[136:137] op_sel_hi:[1,0,1]
	s_nop 0
	v_addc_co_u32_e32 v139, vcc, 0, v183, vcc
	s_and_b64 vcc, exec, s[10:11]
	global_store_dwordx4 v[138:139], v[134:137], off nt
	s_cbranch_vccnz .LBB0_516
	v_pk_mul_f32 v[138:139], v[134:135], v[134:135]
	v_pk_mul_f32 v[140:141], v[136:137], v[136:137]
	v_add_f32_e32 v138, v138, v139
	v_add_f32_e32 v138, v140, v138
	v_and_b32_e32 v140, 64, v219
	v_add_f32_e32 v138, v141, v138
	s_nop 0
	v_add_u32_e32 v141, 64, v140
	s_nop 0
	v_cvt_pk_bf16_f32 v140, v134, v135
	v_xor_b32_e32 v135, 8, v219
	s_nop 1
	v_mov_b32_dpp v139, v138 quad_perm:[1,0,3,2] row_mask:0xf bank_mask:0xf
	s_waitcnt lgkmcnt(0)
	v_add_f32_e32 v138, v138, v139
	s_nop 5
	v_mov_b32_dpp v139, v138 quad_perm:[2,3,0,1] row_mask:0xf bank_mask:0xf
	s_waitcnt lgkmcnt(0)
	v_add_f32_e32 v139, v138, v139
	s_nop 5
	v_mov_b32_dpp v142, v139 row_half_mirror row_mask:0xf bank_mask:0xf
	v_cmp_lt_i32_e32 vcc, v135, v141
	v_or_b32_e32 v138, 24, v178
	v_cvt_pk_bf16_f32 v141, v136, v137
	s_nop 0
	s_waitcnt lgkmcnt(0)
	v_add_f32_e32 v134, v139, v142
	s_nop 1
	v_mov_b32_dpp v135, v134 row_mirror row_mask:0xf bank_mask:0xf
	v_mad_i64_i32 v[136:137], s[0:1], v138, s66, v[180:181]
	global_store_dwordx2 v[136:137], v[140:141], off
	s_and_saveexec_b64 s[0:1], s[8:9]
	s_cbranch_execz .LBB0_515
	v_ashrrev_i32_e32 v139, 31, v138
	s_waitcnt lgkmcnt(0)
	v_add_f32_e32 v136, v134, v135
	v_lshl_add_u64 v[134:135], v[138:139], 2, s[62:63]
	global_atomic_add_f32 v[134:135], v136, off

; DI unsigned pack_bf16(float lo, float hi) { f32x2 v = {lo, hi}; bf16v2 b = __builtin_convertvector(v, bf16v2); return __builtin_bit_cast(unsigned, b); }
; DI float red16(float v) { v += __shfl_xor(v, 1); v += __shfl_xor(v, 2); v += __shfl_xor(v, 4); v += __shfl_xor(v, 8); return v; }
;   DI void run8(f32x4 (&acc)[8][4], int rb, int cb, int fr, int fq) const {
;     ...
;         for (int ps = 0; ps < 4; ++ps) {
;           const f32x4 a = *(const f32x4*)(scr + (ps * 4 + prow) * 68 + c4 * 4);
;           f32x4 v;
;           v.x = xv[mm][ps].x + a.x * sc; v.y = xv[mm][ps].y + a.y * sc; v.z = xv[mm][ps].z + a.z * sc; v.w = xv[mm][ps].w + a.w * sc;
;           const int grow = rb + m * 16 + ps * 4 + prow;
;           __builtin_nontemporal_store(v, (f32x4*)(op + (size_t)(m * 16 + ps * 4) * D));
;           if (xbp) {
;             u32x2 o; o.x = pack_bf16(v.x, v.y); o.y = pack_bf16(v.z, v.w);
;             *(u32x2*)(xbp + (size_t)grow * LDH + cb + c4 * 4) = o;
;             const float t = red16(v.x * v.x + v.y * v.y + v.z * v.z + v.w * v.w);
;             if (c4 == 0) atomicAdd(ssqp + grow, t);
;           }
.LBB0_516:
	s_waitcnt lgkmcnt(0)
	ds_read_b128 v[134:137], v0 offset:3264
	s_waitcnt vmcnt(15) lgkmcnt(0)
	v_pk_fma_f32 v[130:131], v[134:135], 0.5, v[130:131] op_sel_hi:[1,0,1]
	v_add_co_u32_e32 v134, vcc, 0x1c000, v182
	v_pk_fma_f32 v[132:133], v[136:137], 0.5, v[132:133] op_sel_hi:[1,0,1]
	s_nop 0
	v_addc_co_u32_e32 v135, vcc, 0, v183, vcc
	s_and_b64 vcc, exec, s[10:11]
	global_store_dwordx4 v[134:135], v[130:133], off nt
	s_cbranch_vccnz .LBB0_520
	v_pk_mul_f32 v[134:135], v[130:131], v[130:131]
	v_pk_mul_f32 v[136:137], v[132:133], v[132:133]
	v_add_f32_e32 v134, v134, v135
	v_add_f32_e32 v134, v136, v134
	v_and_b32_e32 v136, 64, v219
	v_add_f32_e32 v134, v137, v134
	s_nop 0
	v_add_u32_e32 v137, 64, v136
	s_nop 0
	v_cvt_pk_bf16_f32 v136, v130, v131
	v_xor_b32_e32 v131, 8, v219
	s_nop 1
	v_mov_b32_dpp v135, v134 quad_perm:[1,0,3,2] row_mask:0xf bank_mask:0xf
	s_waitcnt lgkmcnt(0)
	v_add_f32_e32 v134, v134, v135
	s_nop 5
	v_mov_b32_dpp v135, v134 quad_perm:[2,3,0,1] row_mask:0xf bank_mask:0xf
	s_waitcnt lgkmcnt(0)
	v_add_f32_e32 v135, v134, v135
	s_nop 5
	v_mov_b32_dpp v138, v135 row_half_mirror row_mask:0xf bank_mask:0xf
	v_cmp_lt_i32_e32 vcc, v131, v137
	v_or_b32_e32 v134, 28, v178
	v_cvt_pk_bf16_f32 v137, v132, v133
	s_nop 0
	s_waitcnt lgkmcnt(0)
	v_add_f32_e32 v130, v135, v138
	s_nop 1
	v_mov_b32_dpp v131, v130 row_mirror row_mask:0xf bank_mask:0xf
	v_mad_i64_i32 v[132:133], s[0:1], v134, s66, v[180:181]
	global_store_dwordx2 v[132:133], v[136:137], off
	s_and_saveexec_b64 s[0:1], s[8:9]
	s_cbranch_execz .LBB0_519
	v_ashrrev_i32_e32 v135, 31, v134
	s_waitcnt lgkmcnt(0)
	v_add_f32_e32 v132, v130, v131
	v_lshl_add_u64 v[130:131], v[134:135], 2, s[62:63]
	global_atomic_add_f32 v[130:131], v132, off

; DI unsigned pack_bf16(float lo, float hi) { f32x2 v = {lo, hi}; bf16v2 b = __builtin_convertvector(v, bf16v2); return __builtin_bit_cast(unsigned, b); }
; DI float red16(float v) { v += __shfl_xor(v, 1); v += __shfl_xor(v, 2); v += __shfl_xor(v, 4); v += __shfl_xor(v, 8); return v; }
;   DI void run8(f32x4 (&acc)[8][4], int rb, int cb, int fr, int fq) const {
;     ...
;       for (int mm = 0; mm < 4; ++mm) {
;         const int m = mh * 4 + mm;
; #pragma unroll
;         for (int n = 0; n < 4; ++n)
; #pragma unroll
;           for (int j = 0; j < 4; ++j) scr[(fq * 4 + j) * 68 + n * 16 + fr] = acc[m][n][j];
;         __builtin_amdgcn_sched_barrier(0);
; #pragma unroll
;         for (int ps = 0; ps < 4; ++ps) {
;           const f32x4 a = *(const f32x4*)(scr + (ps * 4 + prow) * 68 + c4 * 4);
;           f32x4 v;
;           v.x = xv[mm][ps].x + a.x * sc; v.y = xv[mm][ps].y + a.y * sc; v.z = xv[mm][ps].z + a.z * sc; v.w = xv[mm][ps].w + a.w * sc;
;           const int grow = rb + m * 16 + ps * 4 + prow;
;           __builtin_nontemporal_store(v, (f32x4*)(op + (size_t)(m * 16 + ps * 4) * D));
;           if (xbp) {
;             u32x2 o; o.x = pack_bf16(v.x, v.y); o.y = pack_bf16(v.z, v.w);
;             *(u32x2*)(xbp + (size_t)grow * LDH + cb + c4 * 4) = o;
;             const float t = red16(v.x * v.x + v.y * v.y + v.z * v.z + v.w * v.w);
;             if (c4 == 0) atomicAdd(ssqp + grow, t);
;           }
.LBB0_520:
	ds_write2_b32 v186, v114, v118 offset1:16
	ds_write2_b32 v186, v115, v119 offset0:68 offset1:84
	ds_write2_b32 v186, v116, v120 offset0:136 offset1:152
	ds_write2_b32 v186, v117, v121 offset0:204 offset1:220
	ds_write2_b32 v186, v106, v110 offset0:32 offset1:48
	ds_write2_b32 v186, v107, v111 offset0:100 offset1:116
	ds_write2_b32 v186, v108, v112 offset0:168 offset1:184
	ds_write2_b32 v186, v109, v113 offset0:236 offset1:252
	ds_read_b128 v[106:109], v0
	v_add_co_u32_e32 v110, vcc, 0x20000, v182
	s_waitcnt vmcnt(15) lgkmcnt(0)
	v_pk_fma_f32 v[106:107], v[106:107], 0.5, v[126:127] op_sel_hi:[1,0,1]
	v_addc_co_u32_e32 v111, vcc, 0, v183, vcc
	v_pk_fma_f32 v[108:109], v[108:109], 0.5, v[128:129] op_sel_hi:[1,0,1]
	s_and_b64 vcc, exec, s[10:11]
	global_store_dwordx4 v[110:111], v[106:109], off nt
	s_cbranch_vccnz .LBB0_524
	v_pk_mul_f32 v[110:111], v[106:107], v[106:107]
	v_pk_mul_f32 v[112:113], v[108:109], v[108:109]
	v_add_f32_e32 v110, v110, v111
	v_add_f32_e32 v110, v112, v110
	v_and_b32_e32 v112, 64, v219
	v_add_f32_e32 v110, v113, v110
	s_nop 0
	v_add_u32_e32 v113, 64, v112
	s_nop 0
	v_cvt_pk_bf16_f32 v112, v106, v107
	v_xor_b32_e32 v107, 8, v219
	s_nop 1
	v_mov_b32_dpp v111, v110 quad_perm:[1,0,3,2] row_mask:0xf bank_mask:0xf
	s_waitcnt lgkmcnt(0)
	v_add_f32_e32 v110, v110, v111
	s_nop 5
	v_mov_b32_dpp v111, v110 quad_perm:[2,3,0,1] row_mask:0xf bank_mask:0xf
	s_waitcnt lgkmcnt(0)
	v_add_f32_e32 v111, v110, v111
	s_nop 5
	v_mov_b32_dpp v114, v111 row_half_mirror row_mask:0xf bank_mask:0xf
	v_cmp_lt_i32_e32 vcc, v107, v113
	v_or_b32_e32 v110, 32, v178
	v_cvt_pk_bf16_f32 v113, v108, v109
	s_nop 0
	s_waitcnt lgkmcnt(0)
	v_add_f32_e32 v106, v111, v114
	s_nop 1
	v_mov_b32_dpp v107, v106 row_mirror row_mask:0xf bank_mask:0xf
	v_mad_i64_i32 v[108:109], s[0:1], v110, s66, v[180:181]
	global_store_dwordx2 v[108:109], v[112:113], off
	s_and_saveexec_b64 s[0:1], s[8:9]
	s_cbranch_execz .LBB0_523
	v_ashrrev_i32_e32 v111, 31, v110
	s_waitcnt lgkmcnt(0)
	v_add_f32_e32 v108, v106, v107
	v_lshl_add_u64 v[106:107], v[110:111], 2, s[62:63]
	global_atomic_add_f32 v[106:107], v108, off

; DI unsigned pack_bf16(float lo, float hi) { f32x2 v = {lo, hi}; bf16v2 b = __builtin_convertvector(v, bf16v2); return __builtin_bit_cast(unsigned, b); }
; DI float red16(float v) { v += __shfl_xor(v, 1); v += __shfl_xor(v, 2); v += __shfl_xor(v, 4); v += __shfl_xor(v, 8); return v; }
;   DI void run8(f32x4 (&acc)[8][4], int rb, int cb, int fr, int fq) const {
;     ...
;         for (int ps = 0; ps < 4; ++ps) {
;           const f32x4 a = *(const f32x4*)(scr + (ps * 4 + prow) * 68 + c4 * 4);
;           f32x4 v;
;           v.x = xv[mm][ps].x + a.x * sc; v.y = xv[mm][ps].y + a.y * sc; v.z = xv[mm][ps].z + a.z * sc; v.w = xv[mm][ps].w + a.w * sc;
;           const int grow = rb + m * 16 + ps * 4 + prow;
;           __builtin_nontemporal_store(v, (f32x4*)(op + (size_t)(m * 16 + ps * 4) * D));
;           if (xbp) {
;             u32x2 o; o.x = pack_bf16(v.x, v.y); o.y = pack_bf16(v.z, v.w);
;             *(u32x2*)(xbp + (size_t)grow * LDH + cb + c4 * 4) = o;
;             const float t = red16(v.x * v.x + v.y * v.y + v.z * v.z + v.w * v.w);
;             if (c4 == 0) atomicAdd(ssqp + grow, t);
;           }
.LBB0_524:
	s_waitcnt lgkmcnt(0)
	ds_read_b128 v[106:109], v0 offset:1088
	v_add_co_u32_e32 v110, vcc, 0x24000, v182
	s_waitcnt vmcnt(15) lgkmcnt(0)
	v_pk_fma_f32 v[106:107], v[106:107], 0.5, v[122:123] op_sel_hi:[1,0,1]
	v_addc_co_u32_e32 v111, vcc, 0, v183, vcc
	v_pk_fma_f32 v[108:109], v[108:109], 0.5, v[124:125] op_sel_hi:[1,0,1]
	s_and_b64 vcc, exec, s[10:11]
	global_store_dwordx4 v[110:111], v[106:109], off nt
	s_cbranch_vccnz .LBB0_528
	v_pk_mul_f32 v[110:111], v[106:107], v[106:107]
	v_pk_mul_f32 v[112:113], v[108:109], v[108:109]
	v_add_f32_e32 v110, v110, v111
	v_add_f32_e32 v110, v112, v110
	v_and_b32_e32 v112, 64, v219
	v_add_f32_e32 v110, v113, v110
	s_nop 0
	v_add_u32_e32 v113, 64, v112
	s_nop 0
	v_cvt_pk_bf16_f32 v112, v106, v107
	v_xor_b32_e32 v107, 8, v219
	s_nop 1
	v_mov_b32_dpp v111, v110 quad_perm:[1,0,3,2] row_mask:0xf bank_mask:0xf
	s_waitcnt lgkmcnt(0)
	v_add_f32_e32 v110, v110, v111
	s_nop 5
	v_mov_b32_dpp v111, v110 quad_perm:[2,3,0,1] row_mask:0xf bank_mask:0xf
	s_waitcnt lgkmcnt(0)
	v_add_f32_e32 v111, v110, v111
	s_nop 5
	v_mov_b32_dpp v114, v111 row_half_mirror row_mask:0xf bank_mask:0xf
	v_cmp_lt_i32_e32 vcc, v107, v113
	v_or_b32_e32 v110, 36, v178
	v_cvt_pk_bf16_f32 v113, v108, v109
	s_nop 0
	s_waitcnt lgkmcnt(0)
	v_add_f32_e32 v106, v111, v114
	s_nop 1
	v_mov_b32_dpp v107, v106 row_mirror row_mask:0xf bank_mask:0xf
	v_mad_i64_i32 v[108:109], s[0:1], v110, s66, v[180:181]
	global_store_dwordx2 v[108:109], v[112:113], off
	s_and_saveexec_b64 s[0:1], s[8:9]
	s_cbranch_execz .LBB0_527
	v_ashrrev_i32_e32 v111, 31, v110
	s_waitcnt lgkmcnt(0)
	v_add_f32_e32 v108, v106, v107
	v_lshl_add_u64 v[106:107], v[110:111], 2, s[62:63]
	global_atomic_add_f32 v[106:107], v108, off

; DI unsigned pack_bf16(float lo, float hi) { f32x2 v = {lo, hi}; bf16v2 b = __builtin_convertvector(v, bf16v2); return __builtin_bit_cast(unsigned, b); }
; DI float red16(float v) { v += __shfl_xor(v, 1); v += __shfl_xor(v, 2); v += __shfl_xor(v, 4); v += __shfl_xor(v, 8); return v; }
;   DI void run8(f32x4 (&acc)[8][4], int rb, int cb, int fr, int fq) const {
;     ...
;         for (int ps = 0; ps < 4; ++ps) {
;           const f32x4 a = *(const f32x4*)(scr + (ps * 4 + prow) * 68 + c4 * 4);
;           f32x4 v;
;           v.x = xv[mm][ps].x + a.x * sc; v.y = xv[mm][ps].y + a.y * sc; v.z = xv[mm][ps].z + a.z * sc; v.w = xv[mm][ps].w + a.w * sc;
;           const int grow = rb + m * 16 + ps * 4 + prow;
;           __builtin_nontemporal_store(v, (f32x4*)(op + (size_t)(m * 16 + ps * 4) * D));
;           if (xbp) {
;             u32x2 o; o.x = pack_bf16(v.x, v.y); o.y = pack_bf16(v.z, v.w);
;             *(u32x2*)(xbp + (size_t)grow * LDH + cb + c4 * 4) = o;
;             const float t = red16(v.x * v.x + v.y * v.y + v.z * v.z + v.w * v.w);
;             if (c4 == 0) atomicAdd(ssqp + grow, t);
;           }
.LBB0_528:
	s_waitcnt lgkmcnt(0)
	ds_read_b128 v[106:109], v0 offset:2176
	s_waitcnt vmcnt(15) lgkmcnt(0)
	v_pk_fma_f32 v[102:103], v[106:107], 0.5, v[102:103] op_sel_hi:[1,0,1]
	v_add_co_u32_e32 v106, vcc, 0x28000, v182
	v_pk_fma_f32 v[104:105], v[108:109], 0.5, v[104:105] op_sel_hi:[1,0,1]
	s_nop 0
	v_addc_co_u32_e32 v107, vcc, 0, v183, vcc
	s_and_b64 vcc, exec, s[10:11]
	global_store_dwordx4 v[106:107], v[102:105], off nt
	s_cbranch_vccnz .LBB0_532
	v_pk_mul_f32 v[106:107], v[102:103], v[102:103]
	v_pk_mul_f32 v[108:109], v[104:105], v[104:105]
	v_add_f32_e32 v106, v106, v107
	v_add_f32_e32 v106, v108, v106
	v_and_b32_e32 v108, 64, v219
	v_add_f32_e32 v106, v109, v106
	s_nop 0
	v_add_u32_e32 v109, 64, v108
	s_nop 0
	v_cvt_pk_bf16_f32 v108, v102, v103
	v_xor_b32_e32 v103, 8, v219
	s_nop 1
	v_mov_b32_dpp v107, v106 quad_perm:[1,0,3,2] row_mask:0xf bank_mask:0xf
	s_waitcnt lgkmcnt(0)
	v_add_f32_e32 v106, v106, v107
	s_nop 5
	v_mov_b32_dpp v107, v106 quad_perm:[2,3,0,1] row_mask:0xf bank_mask:0xf
	s_waitcnt lgkmcnt(0)
	v_add_f32_e32 v107, v106, v107
	s_nop 5
	v_mov_b32_dpp v110, v107 row_half_mirror row_mask:0xf bank_mask:0xf
	v_cmp_lt_i32_e32 vcc, v103, v109
	v_or_b32_e32 v106, 40, v178
	v_cvt_pk_bf16_f32 v109, v104, v105
	s_nop 0
	s_waitcnt lgkmcnt(0)
	v_add_f32_e32 v102, v107, v110
	s_nop 1
	v_mov_b32_dpp v103, v102 row_mirror row_mask:0xf bank_mask:0xf
	v_mad_i64_i32 v[104:105], s[0:1], v106, s66, v[180:181]
	global_store_dwordx2 v[104:105], v[108:109], off
	s_and_saveexec_b64 s[0:1], s[8:9]
	s_cbranch_execz .LBB0_531
	v_ashrrev_i32_e32 v107, 31, v106
	s_waitcnt lgkmcnt(0)
	v_add_f32_e32 v104, v102, v103
	v_lshl_add_u64 v[102:103], v[106:107], 2, s[62:63]
	global_atomic_add_f32 v[102:103], v104, off

; DI unsigned pack_bf16(float lo, float hi) { f32x2 v = {lo, hi}; bf16v2 b = __builtin_convertvector(v, bf16v2); return __builtin_bit_cast(unsigned, b); }
; DI float red16(float v) { v += __shfl_xor(v, 1); v += __shfl_xor(v, 2); v += __shfl_xor(v, 4); v += __shfl_xor(v, 8); return v; }
;   DI void run8(f32x4 (&acc)[8][4], int rb, int cb, int fr, int fq) const {
;     ...
;         for (int ps = 0; ps < 4; ++ps) {
;           const f32x4 a = *(const f32x4*)(scr + (ps * 4 + prow) * 68 + c4 * 4);
;           f32x4 v;
;           v.x = xv[mm][ps].x + a.x * sc; v.y = xv[mm][ps].y + a.y * sc; v.z = xv[mm][ps].z + a.z * sc; v.w = xv[mm][ps].w + a.w * sc;
;           const int grow = rb + m * 16 + ps * 4 + prow;
;           __builtin_nontemporal_store(v, (f32x4*)(op + (size_t)(m * 16 + ps * 4) * D));
;           if (xbp) {
;             u32x2 o; o.x = pack_bf16(v.x, v.y); o.y = pack_bf16(v.z, v.w);
;             *(u32x2*)(xbp + (size_t)grow * LDH + cb + c4 * 4) = o;
;             const float t = red16(v.x * v.x + v.y * v.y + v.z * v.z + v.w * v.w);
;             if (c4 == 0) atomicAdd(ssqp + grow, t);
;           }
.LBB0_532:
	s_waitcnt lgkmcnt(0)
	ds_read_b128 v[102:105], v0 offset:3264
	s_waitcnt vmcnt(15) lgkmcnt(0)
	v_pk_fma_f32 v[98:99], v[102:103], 0.5, v[98:99] op_sel_hi:[1,0,1]
	v_add_co_u32_e32 v102, vcc, 0x2c000, v182
	v_pk_fma_f32 v[100:101], v[104:105], 0.5, v[100:101] op_sel_hi:[1,0,1]
	s_nop 0
	v_addc_co_u32_e32 v103, vcc, 0, v183, vcc
	s_and_b64 vcc, exec, s[10:11]
	global_store_dwordx4 v[102:103], v[98:101], off nt
	s_cbranch_vccnz .LBB0_536
	v_pk_mul_f32 v[102:103], v[98:99], v[98:99]
	v_pk_mul_f32 v[104:105], v[100:101], v[100:101]
	v_add_f32_e32 v102, v102, v103
	v_add_f32_e32 v102, v104, v102
	v_and_b32_e32 v104, 64, v219
	v_add_f32_e32 v102, v105, v102
	s_nop 0
	v_add_u32_e32 v105, 64, v104
	s_nop 0
	v_cvt_pk_bf16_f32 v104, v98, v99
	v_xor_b32_e32 v99, 8, v219
	s_nop 1
	v_mov_b32_dpp v103, v102 quad_perm:[1,0,3,2] row_mask:0xf bank_mask:0xf
	s_waitcnt lgkmcnt(0)
	v_add_f32_e32 v102, v102, v103
	s_nop 5
	v_mov_b32_dpp v103, v102 quad_perm:[2,3,0,1] row_mask:0xf bank_mask:0xf
	s_waitcnt lgkmcnt(0)
	v_add_f32_e32 v103, v102, v103
	s_nop 5
	v_mov_b32_dpp v106, v103 row_half_mirror row_mask:0xf bank_mask:0xf
	v_cmp_lt_i32_e32 vcc, v99, v105
	v_or_b32_e32 v102, 44, v178
	v_cvt_pk_bf16_f32 v105, v100, v101
	s_nop 0
	s_waitcnt lgkmcnt(0)
	v_add_f32_e32 v98, v103, v106
	s_nop 1
	v_mov_b32_dpp v99, v98 row_mirror row_mask:0xf bank_mask:0xf
	v_mad_i64_i32 v[100:101], s[0:1], v102, s66, v[180:181]
	global_store_dwordx2 v[100:101], v[104:105], off
	s_and_saveexec_b64 s[0:1], s[8:9]
	s_cbranch_execz .LBB0_535
	v_ashrrev_i32_e32 v103, 31, v102
	s_waitcnt lgkmcnt(0)
	v_add_f32_e32 v100, v98, v99
	v_lshl_add_u64 v[98:99], v[102:103], 2, s[62:63]
	global_atomic_add_f32 v[98:99], v100, off

; DI unsigned pack_bf16(float lo, float hi) { f32x2 v = {lo, hi}; bf16v2 b = __builtin_convertvector(v, bf16v2); return __builtin_bit_cast(unsigned, b); }
; DI float red16(float v) { v += __shfl_xor(v, 1); v += __shfl_xor(v, 2); v += __shfl_xor(v, 4); v += __shfl_xor(v, 8); return v; }
;   DI void run8(f32x4 (&acc)[8][4], int rb, int cb, int fr, int fq) const {
;     ...
;       for (int mm = 0; mm < 4; ++mm) {
;         const int m = mh * 4 + mm;
; #pragma unroll
;         for (int n = 0; n < 4; ++n)
; #pragma unroll
;           for (int j = 0; j < 4; ++j) scr[(fq * 4 + j) * 68 + n * 16 + fr] = acc[m][n][j];
;         __builtin_amdgcn_sched_barrier(0);
; #pragma unroll
;         for (int ps = 0; ps < 4; ++ps) {
;           const f32x4 a = *(const f32x4*)(scr + (ps * 4 + prow) * 68 + c4 * 4);
;           f32x4 v;
;           v.x = xv[mm][ps].x + a.x * sc; v.y = xv[mm][ps].y + a.y * sc; v.z = xv[mm][ps].z + a.z * sc; v.w = xv[mm][ps].w + a.w * sc;
;           const int grow = rb + m * 16 + ps * 4 + prow;
;           __builtin_nontemporal_store(v, (f32x4*)(op + (size_t)(m * 16 + ps * 4) * D));
;           if (xbp) {
;             u32x2 o; o.x = pack_bf16(v.x, v.y); o.y = pack_bf16(v.z, v.w);
;             *(u32x2*)(xbp + (size_t)grow * LDH + cb + c4 * 4) = o;
;             const float t = red16(v.x * v.x + v.y * v.y + v.z * v.z + v.w * v.w);
;             if (c4 == 0) atomicAdd(ssqp + grow, t);
;           }
.LBB0_536:
	ds_write2_b32 v186, v82, v86 offset1:16
	ds_write2_b32 v186, v83, v87 offset0:68 offset1:84
	ds_write2_b32 v186, v84, v88 offset0:136 offset1:152
	ds_write2_b32 v186, v85, v89 offset0:204 offset1:220
	ds_write2_b32 v186, v74, v78 offset0:32 offset1:48
	ds_write2_b32 v186, v75, v79 offset0:100 offset1:116
	ds_write2_b32 v186, v76, v80 offset0:168 offset1:184
	ds_write2_b32 v186, v77, v81 offset0:236 offset1:252
	ds_read_b128 v[74:77], v0
	v_add_co_u32_e32 v78, vcc, 0x30000, v182
	s_waitcnt vmcnt(15) lgkmcnt(0)
	v_pk_fma_f32 v[74:75], v[74:75], 0.5, v[94:95] op_sel_hi:[1,0,1]
	v_addc_co_u32_e32 v79, vcc, 0, v183, vcc
	v_pk_fma_f32 v[76:77], v[76:77], 0.5, v[96:97] op_sel_hi:[1,0,1]
	s_and_b64 vcc, exec, s[10:11]
	global_store_dwordx4 v[78:79], v[74:77], off nt
	s_cbranch_vccnz .LBB0_540
	v_pk_mul_f32 v[78:79], v[74:75], v[74:75]
	v_pk_mul_f32 v[80:81], v[76:77], v[76:77]
	v_add_f32_e32 v78, v78, v79
	v_add_f32_e32 v78, v80, v78
	v_and_b32_e32 v80, 64, v219
	v_add_f32_e32 v78, v81, v78
	s_nop 0
	v_add_u32_e32 v81, 64, v80
	s_nop 0
	v_cvt_pk_bf16_f32 v80, v74, v75
	v_xor_b32_e32 v75, 8, v219
	s_nop 1
	v_mov_b32_dpp v79, v78 quad_perm:[1,0,3,2] row_mask:0xf bank_mask:0xf
	s_waitcnt lgkmcnt(0)
	v_add_f32_e32 v78, v78, v79
	s_nop 5
	v_mov_b32_dpp v79, v78 quad_perm:[2,3,0,1] row_mask:0xf bank_mask:0xf
	s_waitcnt lgkmcnt(0)
	v_add_f32_e32 v79, v78, v79
	s_nop 5
	v_mov_b32_dpp v82, v79 row_half_mirror row_mask:0xf bank_mask:0xf
	v_cmp_lt_i32_e32 vcc, v75, v81
	v_or_b32_e32 v78, 48, v178
	v_cvt_pk_bf16_f32 v81, v76, v77
	s_nop 0
	s_waitcnt lgkmcnt(0)
	v_add_f32_e32 v74, v79, v82
	s_nop 1
	v_mov_b32_dpp v75, v74 row_mirror row_mask:0xf bank_mask:0xf
	v_mad_i64_i32 v[76:77], s[0:1], v78, s66, v[180:181]
	global_store_dwordx2 v[76:77], v[80:81], off
	s_and_saveexec_b64 s[0:1], s[8:9]
	s_cbranch_execz .LBB0_539
	v_ashrrev_i32_e32 v79, 31, v78
	s_waitcnt lgkmcnt(0)
	v_add_f32_e32 v76, v74, v75
	v_lshl_add_u64 v[74:75], v[78:79], 2, s[62:63]
	global_atomic_add_f32 v[74:75], v76, off

; DI unsigned pack_bf16(float lo, float hi) { f32x2 v = {lo, hi}; bf16v2 b = __builtin_convertvector(v, bf16v2); return __builtin_bit_cast(unsigned, b); }
; DI float red16(float v) { v += __shfl_xor(v, 1); v += __shfl_xor(v, 2); v += __shfl_xor(v, 4); v += __shfl_xor(v, 8); return v; }
;   DI void run8(f32x4 (&acc)[8][4], int rb, int cb, int fr, int fq) const {
;     ...
;         for (int ps = 0; ps < 4; ++ps) {
;           const f32x4 a = *(const f32x4*)(scr + (ps * 4 + prow) * 68 + c4 * 4);
;           f32x4 v;
;           v.x = xv[mm][ps].x + a.x * sc; v.y = xv[mm][ps].y + a.y * sc; v.z = xv[mm][ps].z + a.z * sc; v.w = xv[mm][ps].w + a.w * sc;
;           const int grow = rb + m * 16 + ps * 4 + prow;
;           __builtin_nontemporal_store(v, (f32x4*)(op + (size_t)(m * 16 + ps * 4) * D));
;           if (xbp) {
;             u32x2 o; o.x = pack_bf16(v.x, v.y); o.y = pack_bf16(v.z, v.w);
;             *(u32x2*)(xbp + (size_t)grow * LDH + cb + c4 * 4) = o;
;             const float t = red16(v.x * v.x + v.y * v.y + v.z * v.z + v.w * v.w);
;             if (c4 == 0) atomicAdd(ssqp + grow, t);
;           }
.LBB0_540:
	s_waitcnt lgkmcnt(0)
	ds_read_b128 v[74:77], v0 offset:1088
	v_add_co_u32_e32 v78, vcc, 0x34000, v182
	s_waitcnt vmcnt(15) lgkmcnt(0)
	v_pk_fma_f32 v[74:75], v[74:75], 0.5, v[90:91] op_sel_hi:[1,0,1]
	v_addc_co_u32_e32 v79, vcc, 0, v183, vcc
	v_pk_fma_f32 v[76:77], v[76:77], 0.5, v[92:93] op_sel_hi:[1,0,1]
	s_and_b64 vcc, exec, s[10:11]
	global_store_dwordx4 v[78:79], v[74:77], off nt
	s_cbranch_vccnz .LBB0_544
	v_pk_mul_f32 v[78:79], v[74:75], v[74:75]
	v_pk_mul_f32 v[80:81], v[76:77], v[76:77]
	v_add_f32_e32 v78, v78, v79
	v_add_f32_e32 v78, v80, v78
	v_and_b32_e32 v80, 64, v219
	v_add_f32_e32 v78, v81, v78
	s_nop 0
	v_add_u32_e32 v81, 64, v80
	s_nop 0
	v_cvt_pk_bf16_f32 v80, v74, v75
	v_xor_b32_e32 v75, 8, v219
	s_nop 1
	v_mov_b32_dpp v79, v78 quad_perm:[1,0,3,2] row_mask:0xf bank_mask:0xf
	s_waitcnt lgkmcnt(0)
	v_add_f32_e32 v78, v78, v79
	s_nop 5
	v_mov_b32_dpp v79, v78 quad_perm:[2,3,0,1] row_mask:0xf bank_mask:0xf
	s_waitcnt lgkmcnt(0)
	v_add_f32_e32 v79, v78, v79
	s_nop 5
	v_mov_b32_dpp v82, v79 row_half_mirror row_mask:0xf bank_mask:0xf
	v_cmp_lt_i32_e32 vcc, v75, v81
	v_or_b32_e32 v78, 52, v178
	v_cvt_pk_bf16_f32 v81, v76, v77
	s_nop 0
	s_waitcnt lgkmcnt(0)
	v_add_f32_e32 v74, v79, v82
	s_nop 1
	v_mov_b32_dpp v75, v74 row_mirror row_mask:0xf bank_mask:0xf
	v_mad_i64_i32 v[76:77], s[0:1], v78, s66, v[180:181]
	global_store_dwordx2 v[76:77], v[80:81], off
	s_and_saveexec_b64 s[0:1], s[8:9]
	s_cbranch_execz .LBB0_543
	v_ashrrev_i32_e32 v79, 31, v78
	s_waitcnt lgkmcnt(0)
	v_add_f32_e32 v76, v74, v75
	v_lshl_add_u64 v[74:75], v[78:79], 2, s[62:63]
	global_atomic_add_f32 v[74:75], v76, off

; DI unsigned pack_bf16(float lo, float hi) { f32x2 v = {lo, hi}; bf16v2 b = __builtin_convertvector(v, bf16v2); return __builtin_bit_cast(unsigned, b); }
; DI float red16(float v) { v += __shfl_xor(v, 1); v += __shfl_xor(v, 2); v += __shfl_xor(v, 4); v += __shfl_xor(v, 8); return v; }
;   DI void run8(f32x4 (&acc)[8][4], int rb, int cb, int fr, int fq) const {
;     ...
;         for (int ps = 0; ps < 4; ++ps) {
;           const f32x4 a = *(const f32x4*)(scr + (ps * 4 + prow) * 68 + c4 * 4);
;           f32x4 v;
;           v.x = xv[mm][ps].x + a.x * sc; v.y = xv[mm][ps].y + a.y * sc; v.z = xv[mm][ps].z + a.z * sc; v.w = xv[mm][ps].w + a.w * sc;
;           const int grow = rb + m * 16 + ps * 4 + prow;
;           __builtin_nontemporal_store(v, (f32x4*)(op + (size_t)(m * 16 + ps * 4) * D));
;           if (xbp) {
;             u32x2 o; o.x = pack_bf16(v.x, v.y); o.y = pack_bf16(v.z, v.w);
;             *(u32x2*)(xbp + (size_t)grow * LDH + cb + c4 * 4) = o;
;             const float t = red16(v.x * v.x + v.y * v.y + v.z * v.z + v.w * v.w);
;             if (c4 == 0) atomicAdd(ssqp + grow, t);
;           }
.LBB0_544:
	s_waitcnt lgkmcnt(0)
	ds_read_b128 v[74:77], v0 offset:2176
	s_waitcnt vmcnt(15) lgkmcnt(0)
	v_pk_fma_f32 v[70:71], v[74:75], 0.5, v[70:71] op_sel_hi:[1,0,1]
	v_add_co_u32_e32 v74, vcc, 0x38000, v182
	v_pk_fma_f32 v[72:73], v[76:77], 0.5, v[72:73] op_sel_hi:[1,0,1]
	s_nop 0
	v_addc_co_u32_e32 v75, vcc, 0, v183, vcc
	s_and_b64 vcc, exec, s[10:11]
	global_store_dwordx4 v[74:75], v[70:73], off nt
	s_cbranch_vccnz .LBB0_548
	v_pk_mul_f32 v[74:75], v[70:71], v[70:71]
	v_pk_mul_f32 v[76:77], v[72:73], v[72:73]
	v_add_f32_e32 v74, v74, v75
	v_add_f32_e32 v74, v76, v74
	v_and_b32_e32 v76, 64, v219
	v_add_f32_e32 v74, v77, v74
	s_nop 0
	v_add_u32_e32 v77, 64, v76
	s_nop 0
	v_cvt_pk_bf16_f32 v76, v70, v71
	v_xor_b32_e32 v71, 8, v219
	s_nop 1
	v_mov_b32_dpp v75, v74 quad_perm:[1,0,3,2] row_mask:0xf bank_mask:0xf
	s_waitcnt lgkmcnt(0)
	v_add_f32_e32 v74, v74, v75
	s_nop 5
	v_mov_b32_dpp v75, v74 quad_perm:[2,3,0,1] row_mask:0xf bank_mask:0xf
	s_waitcnt lgkmcnt(0)
	v_add_f32_e32 v75, v74, v75
	s_nop 5
	v_mov_b32_dpp v78, v75 row_half_mirror row_mask:0xf bank_mask:0xf
	v_cmp_lt_i32_e32 vcc, v71, v77
	v_or_b32_e32 v74, 56, v178
	v_cvt_pk_bf16_f32 v77, v72, v73
	s_nop 0
	s_waitcnt lgkmcnt(0)
	v_add_f32_e32 v70, v75, v78
	s_nop 1
	v_mov_b32_dpp v71, v70 row_mirror row_mask:0xf bank_mask:0xf
	v_mad_i64_i32 v[72:73], s[0:1], v74, s66, v[180:181]
	global_store_dwordx2 v[72:73], v[76:77], off
	s_and_saveexec_b64 s[0:1], s[8:9]
	s_cbranch_execz .LBB0_547
	v_ashrrev_i32_e32 v75, 31, v74
	s_waitcnt lgkmcnt(0)
	v_add_f32_e32 v72, v70, v71
	v_lshl_add_u64 v[70:71], v[74:75], 2, s[62:63]
	global_atomic_add_f32 v[70:71], v72, off

; DI unsigned pack_bf16(float lo, float hi) { f32x2 v = {lo, hi}; bf16v2 b = __builtin_convertvector(v, bf16v2); return __builtin_bit_cast(unsigned, b); }
; DI float red16(float v) { v += __shfl_xor(v, 1); v += __shfl_xor(v, 2); v += __shfl_xor(v, 4); v += __shfl_xor(v, 8); return v; }
;   DI void run8(f32x4 (&acc)[8][4], int rb, int cb, int fr, int fq) const {
;     ...
;         for (int ps = 0; ps < 4; ++ps) {
;           const f32x4 a = *(const f32x4*)(scr + (ps * 4 + prow) * 68 + c4 * 4);
;           f32x4 v;
;           v.x = xv[mm][ps].x + a.x * sc; v.y = xv[mm][ps].y + a.y * sc; v.z = xv[mm][ps].z + a.z * sc; v.w = xv[mm][ps].w + a.w * sc;
;           const int grow = rb + m * 16 + ps * 4 + prow;
;           __builtin_nontemporal_store(v, (f32x4*)(op + (size_t)(m * 16 + ps * 4) * D));
;           if (xbp) {
;             u32x2 o; o.x = pack_bf16(v.x, v.y); o.y = pack_bf16(v.z, v.w);
;             *(u32x2*)(xbp + (size_t)grow * LDH + cb + c4 * 4) = o;
;             const float t = red16(v.x * v.x + v.y * v.y + v.z * v.z + v.w * v.w);
;             if (c4 == 0) atomicAdd(ssqp + grow, t);
;           }
.LBB0_548:
	s_waitcnt lgkmcnt(0)
	ds_read_b128 v[70:73], v0 offset:3264
	s_waitcnt vmcnt(15) lgkmcnt(0)
	v_pk_fma_f32 v[66:67], v[70:71], 0.5, v[66:67] op_sel_hi:[1,0,1]
	v_add_co_u32_e32 v70, vcc, 0x3c000, v182
	v_pk_fma_f32 v[68:69], v[72:73], 0.5, v[68:69] op_sel_hi:[1,0,1]
	s_nop 0
	v_addc_co_u32_e32 v71, vcc, 0, v183, vcc
	s_and_b64 vcc, exec, s[10:11]
	global_store_dwordx4 v[70:71], v[66:69], off nt
	s_cbranch_vccnz .LBB0_552
	v_pk_mul_f32 v[70:71], v[66:67], v[66:67]
	v_pk_mul_f32 v[72:73], v[68:69], v[68:69]
	v_add_f32_e32 v70, v70, v71
	v_add_f32_e32 v70, v72, v70
	v_and_b32_e32 v72, 64, v219
	v_add_f32_e32 v70, v73, v70
	s_nop 0
	v_add_u32_e32 v73, 64, v72
	s_nop 0
	v_cvt_pk_bf16_f32 v72, v66, v67
	v_xor_b32_e32 v67, 8, v219
	s_nop 1
	v_mov_b32_dpp v71, v70 quad_perm:[1,0,3,2] row_mask:0xf bank_mask:0xf
	s_waitcnt lgkmcnt(0)
	v_add_f32_e32 v70, v70, v71
	s_nop 5
	v_mov_b32_dpp v71, v70 quad_perm:[2,3,0,1] row_mask:0xf bank_mask:0xf
	s_waitcnt lgkmcnt(0)
	v_add_f32_e32 v71, v70, v71
	s_nop 5
	v_mov_b32_dpp v74, v71 row_half_mirror row_mask:0xf bank_mask:0xf
	v_cmp_lt_i32_e32 vcc, v67, v73
	v_or_b32_e32 v70, 60, v178
	v_cvt_pk_bf16_f32 v73, v68, v69
	s_nop 0
	s_waitcnt lgkmcnt(0)
	v_add_f32_e32 v66, v71, v74
	s_nop 1
	v_mov_b32_dpp v67, v66 row_mirror row_mask:0xf bank_mask:0xf
	v_mad_i64_i32 v[68:69], s[0:1], v70, s66, v[180:181]
	global_store_dwordx2 v[68:69], v[72:73], off
	s_and_saveexec_b64 s[0:1], s[8:9]
	s_cbranch_execz .LBB0_551
	v_ashrrev_i32_e32 v71, 31, v70
	s_waitcnt lgkmcnt(0)
	v_add_f32_e32 v68, v66, v67
	v_lshl_add_u64 v[66:67], v[70:71], 2, s[62:63]
	global_atomic_add_f32 v[66:67], v68, off

; DI unsigned pack_bf16(float lo, float hi) { f32x2 v = {lo, hi}; bf16v2 b = __builtin_convertvector(v, bf16v2); return __builtin_bit_cast(unsigned, b); }
; DI float red16(float v) { v += __shfl_xor(v, 1); v += __shfl_xor(v, 2); v += __shfl_xor(v, 4); v += __shfl_xor(v, 8); return v; }
;   DI void run8(f32x4 (&acc)[8][4], int rb, int cb, int fr, int fq) const {
;     ...
; #pragma unroll
;       for (int mm = 0; mm < 4; ++mm)
; #pragma unroll
;         for (int ps = 0; ps < 4; ++ps) xv[mm][ps] = __builtin_nontemporal_load((const f32x4*)(xp + (size_t)((mh * 4 + mm) * 16 + ps * 4) * D));
;       __builtin_amdgcn_sched_barrier(0);
; #pragma unroll
;       for (int mm = 0; mm < 4; ++mm) {
;         const int m = mh * 4 + mm;
; #pragma unroll
;         for (int n = 0; n < 4; ++n)
; #pragma unroll
;           for (int j = 0; j < 4; ++j) scr[(fq * 4 + j) * 68 + n * 16 + fr] = acc[m][n][j];
;         __builtin_amdgcn_sched_barrier(0);
; #pragma unroll
;         for (int ps = 0; ps < 4; ++ps) {
;           const f32x4 a = *(const f32x4*)(scr + (ps * 4 + prow) * 68 + c4 * 4);
;           f32x4 v;
;           v.x = xv[mm][ps].x + a.x * sc; v.y = xv[mm][ps].y + a.y * sc; v.z = xv[mm][ps].z + a.z * sc; v.w = xv[mm][ps].w + a.w * sc;
;           const int grow = rb + m * 16 + ps * 4 + prow;
;           __builtin_nontemporal_store(v, (f32x4*)(op + (size_t)(m * 16 + ps * 4) * D));
;           if (xbp) {
;             u32x2 o; o.x = pack_bf16(v.x, v.y); o.y = pack_bf16(v.z, v.w);
;             *(u32x2*)(xbp + (size_t)grow * LDH + cb + c4 * 4) = o;
;             const float t = red16(v.x * v.x + v.y * v.y + v.z * v.z + v.w * v.w);
;             if (c4 == 0) atomicAdd(ssqp + grow, t);
;           }
.LBB0_552:
	s_nop 0
	v_add_co_u32_e32 v66, vcc, 0x40000, v184
	s_waitcnt lgkmcnt(0)
	s_nop 0
	v_addc_co_u32_e32 v67, vcc, 0, v185, vcc
	v_add_co_u32_e32 v68, vcc, 0x44000, v184
	s_nop 1
	v_addc_co_u32_e32 v69, vcc, 0, v185, vcc
	global_load_dwordx4 v[126:129], v[66:67], off nt
	global_load_dwordx4 v[122:125], v[68:69], off nt
	v_add_co_u32_e32 v66, vcc, 0x48000, v184
	s_nop 1
	v_addc_co_u32_e32 v67, vcc, 0, v185, vcc
	v_add_co_u32_e32 v68, vcc, 0x4c000, v184
	s_nop 1
	v_addc_co_u32_e32 v69, vcc, 0, v185, vcc
	global_load_dwordx4 v[118:121], v[66:67], off nt
	global_load_dwordx4 v[114:117], v[68:69], off nt
	v_add_co_u32_e32 v66, vcc, 0x50000, v184
	s_nop 1
	v_addc_co_u32_e32 v67, vcc, 0, v185, vcc
	v_add_co_u32_e32 v68, vcc, 0x54000, v184
	s_nop 1
	v_addc_co_u32_e32 v69, vcc, 0, v185, vcc
	global_load_dwordx4 v[110:113], v[66:67], off nt
	global_load_dwordx4 v[106:109], v[68:69], off nt
	v_add_co_u32_e32 v66, vcc, 0x58000, v184
	s_nop 1
	v_addc_co_u32_e32 v67, vcc, 0, v185, vcc
	v_add_co_u32_e32 v68, vcc, 0x5c000, v184
	s_nop 1
	v_addc_co_u32_e32 v69, vcc, 0, v185, vcc
	global_load_dwordx4 v[102:105], v[66:67], off nt
	global_load_dwordx4 v[98:101], v[68:69], off nt
	v_add_co_u32_e32 v66, vcc, 0x60000, v184
	s_nop 1
	v_addc_co_u32_e32 v67, vcc, 0, v185, vcc
	v_add_co_u32_e32 v68, vcc, 0x64000, v184
	s_nop 1
	v_addc_co_u32_e32 v69, vcc, 0, v185, vcc
	global_load_dwordx4 v[94:97], v[66:67], off nt
	global_load_dwordx4 v[90:93], v[68:69], off nt
	v_add_co_u32_e32 v66, vcc, 0x68000, v184
	s_nop 1
	v_addc_co_u32_e32 v67, vcc, 0, v185, vcc
	v_add_co_u32_e32 v68, vcc, 0x6c000, v184
	s_nop 1
	v_addc_co_u32_e32 v69, vcc, 0, v185, vcc
	global_load_dwordx4 v[86:89], v[66:67], off nt
	global_load_dwordx4 v[82:85], v[68:69], off nt
	v_add_co_u32_e32 v66, vcc, s68, v184
	s_nop 1
	v_addc_co_u32_e32 v67, vcc, 0, v185, vcc
	v_add_co_u32_e32 v68, vcc, 0x74000, v184
	s_nop 1
	v_addc_co_u32_e32 v69, vcc, 0, v185, vcc
	global_load_dwordx4 v[78:81], v[66:67], off nt
	global_load_dwordx4 v[74:77], v[68:69], off nt
	v_add_co_u32_e32 v66, vcc, 0x78000, v184
	s_nop 1
	v_addc_co_u32_e32 v67, vcc, 0, v185, vcc
	v_add_co_u32_e32 v68, vcc, 0x7c000, v184
	s_nop 1
	v_addc_co_u32_e32 v69, vcc, 0, v185, vcc
	global_load_dwordx4 v[70:73], v[66:67], off nt
	s_nop 0
	global_load_dwordx4 v[66:69], v[68:69], off nt
	ds_write2_b32 v186, v58, v62 offset1:16
	ds_write2_b32 v186, v59, v63 offset0:68 offset1:84
	ds_write2_b32 v186, v60, v64 offset0:136 offset1:152
	ds_write2_b32 v186, v61, v65 offset0:204 offset1:220
	ds_write2_b32 v186, v50, v54 offset0:32 offset1:48
	ds_write2_b32 v186, v51, v55 offset0:100 offset1:116
	ds_write2_b32 v186, v52, v56 offset0:168 offset1:184
	ds_write2_b32 v186, v53, v57 offset0:236 offset1:252
	ds_read_b128 v[50:53], v0
	v_add_co_u32_e32 v54, vcc, 0x40000, v182
	s_waitcnt vmcnt(15) lgkmcnt(0)
	v_pk_fma_f32 v[50:51], v[50:51], 0.5, v[126:127] op_sel_hi:[1,0,1]
	v_addc_co_u32_e32 v55, vcc, 0, v183, vcc
	v_pk_fma_f32 v[52:53], v[52:53], 0.5, v[128:129] op_sel_hi:[1,0,1]
	s_and_b64 vcc, exec, s[10:11]
	global_store_dwordx4 v[54:55], v[50:53], off nt
	s_cbranch_vccnz .LBB0_556
	v_pk_mul_f32 v[54:55], v[50:51], v[50:51]
	v_pk_mul_f32 v[56:57], v[52:53], v[52:53]
	v_add_f32_e32 v54, v54, v55
	v_add_f32_e32 v54, v56, v54
	v_and_b32_e32 v56, 64, v219
	v_add_f32_e32 v54, v57, v54
	s_nop 0
	v_add_u32_e32 v57, 64, v56
	s_nop 0
	v_cvt_pk_bf16_f32 v56, v50, v51
	v_xor_b32_e32 v51, 8, v219
	s_nop 1
	v_mov_b32_dpp v55, v54 quad_perm:[1,0,3,2] row_mask:0xf bank_mask:0xf
	s_waitcnt lgkmcnt(0)
	v_add_f32_e32 v54, v54, v55
	s_nop 5
	v_mov_b32_dpp v55, v54 quad_perm:[2,3,0,1] row_mask:0xf bank_mask:0xf
	s_waitcnt lgkmcnt(0)
	v_add_f32_e32 v55, v54, v55
	s_nop 5
	v_mov_b32_dpp v58, v55 row_half_mirror row_mask:0xf bank_mask:0xf
	v_cmp_lt_i32_e32 vcc, v51, v57
	v_or_b32_e32 v54, 64, v178
	v_cvt_pk_bf16_f32 v57, v52, v53
	s_nop 0
	s_waitcnt lgkmcnt(0)
	v_add_f32_e32 v50, v55, v58
	s_nop 1
	v_mov_b32_dpp v51, v50 row_mirror row_mask:0xf bank_mask:0xf
	v_mad_i64_i32 v[52:53], s[0:1], v54, s66, v[180:181]
	global_store_dwordx2 v[52:53], v[56:57], off
	s_and_saveexec_b64 s[0:1], s[8:9]
	s_cbranch_execz .LBB0_555
	v_ashrrev_i32_e32 v55, 31, v54
	s_waitcnt lgkmcnt(0)
	v_add_f32_e32 v52, v50, v51
	v_lshl_add_u64 v[50:51], v[54:55], 2, s[62:63]
	global_atomic_add_f32 v[50:51], v52, off

; DI unsigned pack_bf16(float lo, float hi) { f32x2 v = {lo, hi}; bf16v2 b = __builtin_convertvector(v, bf16v2); return __builtin_bit_cast(unsigned, b); }
; DI float red16(float v) { v += __shfl_xor(v, 1); v += __shfl_xor(v, 2); v += __shfl_xor(v, 4); v += __shfl_xor(v, 8); return v; }
;   DI void run8(f32x4 (&acc)[8][4], int rb, int cb, int fr, int fq) const {
;     ...
;         for (int ps = 0; ps < 4; ++ps) {
;           const f32x4 a = *(const f32x4*)(scr + (ps * 4 + prow) * 68 + c4 * 4);
;           f32x4 v;
;           v.x = xv[mm][ps].x + a.x * sc; v.y = xv[mm][ps].y + a.y * sc; v.z = xv[mm][ps].z + a.z * sc; v.w = xv[mm][ps].w + a.w * sc;
;           const int grow = rb + m * 16 + ps * 4 + prow;
;           __builtin_nontemporal_store(v, (f32x4*)(op + (size_t)(m * 16 + ps * 4) * D));
;           if (xbp) {
;             u32x2 o; o.x = pack_bf16(v.x, v.y); o.y = pack_bf16(v.z, v.w);
;             *(u32x2*)(xbp + (size_t)grow * LDH + cb + c4 * 4) = o;
;             const float t = red16(v.x * v.x + v.y * v.y + v.z * v.z + v.w * v.w);
;             if (c4 == 0) atomicAdd(ssqp + grow, t);
;           }
.LBB0_556:
	s_waitcnt lgkmcnt(0)
	ds_read_b128 v[50:53], v0 offset:1088
	v_add_co_u32_e32 v54, vcc, 0x44000, v182
	s_waitcnt vmcnt(15) lgkmcnt(0)
	v_pk_fma_f32 v[50:51], v[50:51], 0.5, v[122:123] op_sel_hi:[1,0,1]
	v_addc_co_u32_e32 v55, vcc, 0, v183, vcc
	v_pk_fma_f32 v[52:53], v[52:53], 0.5, v[124:125] op_sel_hi:[1,0,1]
	s_and_b64 vcc, exec, s[10:11]
	global_store_dwordx4 v[54:55], v[50:53], off nt
	s_cbranch_vccnz .LBB0_560
	v_pk_mul_f32 v[54:55], v[50:51], v[50:51]
	v_pk_mul_f32 v[56:57], v[52:53], v[52:53]
	v_add_f32_e32 v54, v54, v55
	v_add_f32_e32 v54, v56, v54
	v_and_b32_e32 v56, 64, v219
	v_add_f32_e32 v54, v57, v54
	s_nop 0
	v_add_u32_e32 v57, 64, v56
	s_nop 0
	v_cvt_pk_bf16_f32 v56, v50, v51
	v_xor_b32_e32 v51, 8, v219
	s_nop 1
	v_mov_b32_dpp v55, v54 quad_perm:[1,0,3,2] row_mask:0xf bank_mask:0xf
	s_waitcnt lgkmcnt(0)
	v_add_f32_e32 v54, v54, v55
	s_nop 5
	v_mov_b32_dpp v55, v54 quad_perm:[2,3,0,1] row_mask:0xf bank_mask:0xf
	s_waitcnt lgkmcnt(0)
	v_add_f32_e32 v55, v54, v55
	s_nop 5
	v_mov_b32_dpp v58, v55 row_half_mirror row_mask:0xf bank_mask:0xf
	v_cmp_lt_i32_e32 vcc, v51, v57
	v_or_b32_e32 v54, 0x44, v178
	v_cvt_pk_bf16_f32 v57, v52, v53
	s_nop 0
	s_waitcnt lgkmcnt(0)
	v_add_f32_e32 v50, v55, v58
	s_nop 1
	v_mov_b32_dpp v51, v50 row_mirror row_mask:0xf bank_mask:0xf
	v_mad_i64_i32 v[52:53], s[0:1], v54, s66, v[180:181]
	global_store_dwordx2 v[52:53], v[56:57], off
	s_and_saveexec_b64 s[0:1], s[8:9]
	s_cbranch_execz .LBB0_559
	v_ashrrev_i32_e32 v55, 31, v54
	s_waitcnt lgkmcnt(0)
	v_add_f32_e32 v52, v50, v51
	v_lshl_add_u64 v[50:51], v[54:55], 2, s[62:63]
	global_atomic_add_f32 v[50:51], v52, off

; DI unsigned pack_bf16(float lo, float hi) { f32x2 v = {lo, hi}; bf16v2 b = __builtin_convertvector(v, bf16v2); return __builtin_bit_cast(unsigned, b); }
; DI float red16(float v) { v += __shfl_xor(v, 1); v += __shfl_xor(v, 2); v += __shfl_xor(v, 4); v += __shfl_xor(v, 8); return v; }
;   DI void run8(f32x4 (&acc)[8][4], int rb, int cb, int fr, int fq) const {
;     ...
;         for (int ps = 0; ps < 4; ++ps) {
;           const f32x4 a = *(const f32x4*)(scr + (ps * 4 + prow) * 68 + c4 * 4);
;           f32x4 v;
;           v.x = xv[mm][ps].x + a.x * sc; v.y = xv[mm][ps].y + a.y * sc; v.z = xv[mm][ps].z + a.z * sc; v.w = xv[mm][ps].w + a.w * sc;
;           const int grow = rb + m * 16 + ps * 4 + prow;
;           __builtin_nontemporal_store(v, (f32x4*)(op + (size_t)(m * 16 + ps * 4) * D));
;           if (xbp) {
;             u32x2 o; o.x = pack_bf16(v.x, v.y); o.y = pack_bf16(v.z, v.w);
;             *(u32x2*)(xbp + (size_t)grow * LDH + cb + c4 * 4) = o;
;             const float t = red16(v.x * v.x + v.y * v.y + v.z * v.z + v.w * v.w);
;             if (c4 == 0) atomicAdd(ssqp + grow, t);
;           }
.LBB0_560:
	s_waitcnt lgkmcnt(0)
	ds_read_b128 v[50:53], v0 offset:2176
	v_add_co_u32_e32 v54, vcc, 0x48000, v182
	s_waitcnt vmcnt(15) lgkmcnt(0)
	v_pk_fma_f32 v[50:51], v[50:51], 0.5, v[118:119] op_sel_hi:[1,0,1]
	v_addc_co_u32_e32 v55, vcc, 0, v183, vcc
	v_pk_fma_f32 v[52:53], v[52:53], 0.5, v[120:121] op_sel_hi:[1,0,1]
	s_and_b64 vcc, exec, s[10:11]
	global_store_dwordx4 v[54:55], v[50:53], off nt
	s_cbranch_vccnz .LBB0_564
	v_pk_mul_f32 v[54:55], v[50:51], v[50:51]
	v_pk_mul_f32 v[56:57], v[52:53], v[52:53]
	v_add_f32_e32 v54, v54, v55
	v_add_f32_e32 v54, v56, v54
	v_and_b32_e32 v56, 64, v219
	v_add_f32_e32 v54, v57, v54
	s_nop 0
	v_add_u32_e32 v57, 64, v56
	s_nop 0
	v_cvt_pk_bf16_f32 v56, v50, v51
	v_xor_b32_e32 v51, 8, v219
	s_nop 1
	v_mov_b32_dpp v55, v54 quad_perm:[1,0,3,2] row_mask:0xf bank_mask:0xf
	s_waitcnt lgkmcnt(0)
	v_add_f32_e32 v54, v54, v55
	s_nop 5
	v_mov_b32_dpp v55, v54 quad_perm:[2,3,0,1] row_mask:0xf bank_mask:0xf
	s_waitcnt lgkmcnt(0)
	v_add_f32_e32 v55, v54, v55
	s_nop 5
	v_mov_b32_dpp v58, v55 row_half_mirror row_mask:0xf bank_mask:0xf
	v_cmp_lt_i32_e32 vcc, v51, v57
	v_or_b32_e32 v54, 0x48, v178
	v_cvt_pk_bf16_f32 v57, v52, v53
	s_nop 0
	s_waitcnt lgkmcnt(0)
	v_add_f32_e32 v50, v55, v58
	s_nop 1
	v_mov_b32_dpp v51, v50 row_mirror row_mask:0xf bank_mask:0xf
	v_mad_i64_i32 v[52:53], s[0:1], v54, s66, v[180:181]
	global_store_dwordx2 v[52:53], v[56:57], off
	s_and_saveexec_b64 s[0:1], s[8:9]
	s_cbranch_execz .LBB0_563
	v_ashrrev_i32_e32 v55, 31, v54
	s_waitcnt lgkmcnt(0)
	v_add_f32_e32 v52, v50, v51
	v_lshl_add_u64 v[50:51], v[54:55], 2, s[62:63]
	global_atomic_add_f32 v[50:51], v52, off

; DI unsigned pack_bf16(float lo, float hi) { f32x2 v = {lo, hi}; bf16v2 b = __builtin_convertvector(v, bf16v2); return __builtin_bit_cast(unsigned, b); }
; DI float red16(float v) { v += __shfl_xor(v, 1); v += __shfl_xor(v, 2); v += __shfl_xor(v, 4); v += __shfl_xor(v, 8); return v; }
;   DI void run8(f32x4 (&acc)[8][4], int rb, int cb, int fr, int fq) const {
;     ...
;         for (int ps = 0; ps < 4; ++ps) {
;           const f32x4 a = *(const f32x4*)(scr + (ps * 4 + prow) * 68 + c4 * 4);
;           f32x4 v;
;           v.x = xv[mm][ps].x + a.x * sc; v.y = xv[mm][ps].y + a.y * sc; v.z = xv[mm][ps].z + a.z * sc; v.w = xv[mm][ps].w + a.w * sc;
;           const int grow = rb + m * 16 + ps * 4 + prow;
;           __builtin_nontemporal_store(v, (f32x4*)(op + (size_t)(m * 16 + ps * 4) * D));
;           if (xbp) {
;             u32x2 o; o.x = pack_bf16(v.x, v.y); o.y = pack_bf16(v.z, v.w);
;             *(u32x2*)(xbp + (size_t)grow * LDH + cb + c4 * 4) = o;
;             const float t = red16(v.x * v.x + v.y * v.y + v.z * v.z + v.w * v.w);
;             if (c4 == 0) atomicAdd(ssqp + grow, t);
;           }
.LBB0_564:
	s_waitcnt lgkmcnt(0)
	ds_read_b128 v[50:53], v0 offset:3264
	v_add_co_u32_e32 v54, vcc, 0x4c000, v182
	s_waitcnt vmcnt(15) lgkmcnt(0)
	v_pk_fma_f32 v[50:51], v[50:51], 0.5, v[114:115] op_sel_hi:[1,0,1]
	v_addc_co_u32_e32 v55, vcc, 0, v183, vcc
	v_pk_fma_f32 v[52:53], v[52:53], 0.5, v[116:117] op_sel_hi:[1,0,1]
	s_and_b64 vcc, exec, s[10:11]
	global_store_dwordx4 v[54:55], v[50:53], off nt
	s_cbranch_vccnz .LBB0_568
	v_pk_mul_f32 v[54:55], v[50:51], v[50:51]
	v_pk_mul_f32 v[56:57], v[52:53], v[52:53]
	v_add_f32_e32 v54, v54, v55
	v_add_f32_e32 v54, v56, v54
	v_and_b32_e32 v56, 64, v219
	v_add_f32_e32 v54, v57, v54
	s_nop 0
	v_add_u32_e32 v57, 64, v56
	s_nop 0
	v_cvt_pk_bf16_f32 v56, v50, v51
	v_xor_b32_e32 v51, 8, v219
	s_nop 1
	v_mov_b32_dpp v55, v54 quad_perm:[1,0,3,2] row_mask:0xf bank_mask:0xf
	s_waitcnt lgkmcnt(0)
	v_add_f32_e32 v54, v54, v55
	s_nop 5
	v_mov_b32_dpp v55, v54 quad_perm:[2,3,0,1] row_mask:0xf bank_mask:0xf
	s_waitcnt lgkmcnt(0)
	v_add_f32_e32 v55, v54, v55
	s_nop 5
	v_mov_b32_dpp v58, v55 row_half_mirror row_mask:0xf bank_mask:0xf
	v_cmp_lt_i32_e32 vcc, v51, v57
	v_or_b32_e32 v54, 0x4c, v178
	v_cvt_pk_bf16_f32 v57, v52, v53
	s_nop 0
	s_waitcnt lgkmcnt(0)
	v_add_f32_e32 v50, v55, v58
	s_nop 1
	v_mov_b32_dpp v51, v50 row_mirror row_mask:0xf bank_mask:0xf
	v_mad_i64_i32 v[52:53], s[0:1], v54, s66, v[180:181]
	global_store_dwordx2 v[52:53], v[56:57], off
	s_and_saveexec_b64 s[0:1], s[8:9]
	s_cbranch_execz .LBB0_567
	v_ashrrev_i32_e32 v55, 31, v54
	s_waitcnt lgkmcnt(0)
	v_add_f32_e32 v52, v50, v51
	v_lshl_add_u64 v[50:51], v[54:55], 2, s[62:63]
	global_atomic_add_f32 v[50:51], v52, off

; DI unsigned pack_bf16(float lo, float hi) { f32x2 v = {lo, hi}; bf16v2 b = __builtin_convertvector(v, bf16v2); return __builtin_bit_cast(unsigned, b); }
; DI float red16(float v) { v += __shfl_xor(v, 1); v += __shfl_xor(v, 2); v += __shfl_xor(v, 4); v += __shfl_xor(v, 8); return v; }
;   DI void run8(f32x4 (&acc)[8][4], int rb, int cb, int fr, int fq) const {
;     ...
;       for (int mm = 0; mm < 4; ++mm) {
;         const int m = mh * 4 + mm;
; #pragma unroll
;         for (int n = 0; n < 4; ++n)
; #pragma unroll
;           for (int j = 0; j < 4; ++j) scr[(fq * 4 + j) * 68 + n * 16 + fr] = acc[m][n][j];
;         __builtin_amdgcn_sched_barrier(0);
; #pragma unroll
;         for (int ps = 0; ps < 4; ++ps) {
;           const f32x4 a = *(const f32x4*)(scr + (ps * 4 + prow) * 68 + c4 * 4);
;           f32x4 v;
;           v.x = xv[mm][ps].x + a.x * sc; v.y = xv[mm][ps].y + a.y * sc; v.z = xv[mm][ps].z + a.z * sc; v.w = xv[mm][ps].w + a.w * sc;
;           const int grow = rb + m * 16 + ps * 4 + prow;
;           __builtin_nontemporal_store(v, (f32x4*)(op + (size_t)(m * 16 + ps * 4) * D));
;           if (xbp) {
;             u32x2 o; o.x = pack_bf16(v.x, v.y); o.y = pack_bf16(v.z, v.w);
;             *(u32x2*)(xbp + (size_t)grow * LDH + cb + c4 * 4) = o;
;             const float t = red16(v.x * v.x + v.y * v.y + v.z * v.z + v.w * v.w);
;             if (c4 == 0) atomicAdd(ssqp + grow, t);
;           }
.LBB0_568:
	ds_write2_b32 v186, v42, v46 offset1:16
	ds_write2_b32 v186, v43, v47 offset0:68 offset1:84
	ds_write2_b32 v186, v44, v48 offset0:136 offset1:152
	ds_write2_b32 v186, v45, v49 offset0:204 offset1:220
	ds_write2_b32 v186, v34, v38 offset0:32 offset1:48
	ds_write2_b32 v186, v35, v39 offset0:100 offset1:116
	ds_write2_b32 v186, v36, v40 offset0:168 offset1:184
	ds_write2_b32 v186, v37, v41 offset0:236 offset1:252
	ds_read_b128 v[34:37], v0
	v_add_co_u32_e32 v38, vcc, 0x50000, v182
	s_waitcnt vmcnt(15) lgkmcnt(0)
	v_pk_fma_f32 v[34:35], v[34:35], 0.5, v[110:111] op_sel_hi:[1,0,1]
	v_addc_co_u32_e32 v39, vcc, 0, v183, vcc
	v_pk_fma_f32 v[36:37], v[36:37], 0.5, v[112:113] op_sel_hi:[1,0,1]
	s_and_b64 vcc, exec, s[10:11]
	global_store_dwordx4 v[38:39], v[34:37], off nt
	s_cbranch_vccnz .LBB0_572
	v_pk_mul_f32 v[38:39], v[34:35], v[34:35]
	v_pk_mul_f32 v[40:41], v[36:37], v[36:37]
	v_add_f32_e32 v38, v38, v39
	v_add_f32_e32 v38, v40, v38
	v_and_b32_e32 v40, 64, v219
	v_add_f32_e32 v38, v41, v38
	s_nop 0
	v_add_u32_e32 v41, 64, v40
	s_nop 0
	v_cvt_pk_bf16_f32 v40, v34, v35
	v_xor_b32_e32 v35, 8, v219
	s_nop 1
	v_mov_b32_dpp v39, v38 quad_perm:[1,0,3,2] row_mask:0xf bank_mask:0xf
	s_waitcnt lgkmcnt(0)
	v_add_f32_e32 v38, v38, v39
	s_nop 5
	v_mov_b32_dpp v39, v38 quad_perm:[2,3,0,1] row_mask:0xf bank_mask:0xf
	s_waitcnt lgkmcnt(0)
	v_add_f32_e32 v39, v38, v39
	s_nop 5
	v_mov_b32_dpp v42, v39 row_half_mirror row_mask:0xf bank_mask:0xf
	v_cmp_lt_i32_e32 vcc, v35, v41
	v_or_b32_e32 v38, 0x50, v178
	v_cvt_pk_bf16_f32 v41, v36, v37
	s_nop 0
	s_waitcnt lgkmcnt(0)
	v_add_f32_e32 v34, v39, v42
	s_nop 1
	v_mov_b32_dpp v35, v34 row_mirror row_mask:0xf bank_mask:0xf
	v_mad_i64_i32 v[36:37], s[0:1], v38, s66, v[180:181]
	global_store_dwordx2 v[36:37], v[40:41], off
	s_and_saveexec_b64 s[0:1], s[8:9]
	s_cbranch_execz .LBB0_571
	v_ashrrev_i32_e32 v39, 31, v38
	s_waitcnt lgkmcnt(0)
	v_add_f32_e32 v36, v34, v35
	v_lshl_add_u64 v[34:35], v[38:39], 2, s[62:63]
	global_atomic_add_f32 v[34:35], v36, off

; DI unsigned pack_bf16(float lo, float hi) { f32x2 v = {lo, hi}; bf16v2 b = __builtin_convertvector(v, bf16v2); return __builtin_bit_cast(unsigned, b); }
; DI float red16(float v) { v += __shfl_xor(v, 1); v += __shfl_xor(v, 2); v += __shfl_xor(v, 4); v += __shfl_xor(v, 8); return v; }
;   DI void run8(f32x4 (&acc)[8][4], int rb, int cb, int fr, int fq) const {
;     ...
;         for (int ps = 0; ps < 4; ++ps) {
;           const f32x4 a = *(const f32x4*)(scr + (ps * 4 + prow) * 68 + c4 * 4);
;           f32x4 v;
;           v.x = xv[mm][ps].x + a.x * sc; v.y = xv[mm][ps].y + a.y * sc; v.z = xv[mm][ps].z + a.z * sc; v.w = xv[mm][ps].w + a.w * sc;
;           const int grow = rb + m * 16 + ps * 4 + prow;
;           __builtin_nontemporal_store(v, (f32x4*)(op + (size_t)(m * 16 + ps * 4) * D));
;           if (xbp) {
;             u32x2 o; o.x = pack_bf16(v.x, v.y); o.y = pack_bf16(v.z, v.w);
;             *(u32x2*)(xbp + (size_t)grow * LDH + cb + c4 * 4) = o;
;             const float t = red16(v.x * v.x + v.y * v.y + v.z * v.z + v.w * v.w);
;             if (c4 == 0) atomicAdd(ssqp + grow, t);
;           }
.LBB0_572:
	s_waitcnt lgkmcnt(0)
	ds_read_b128 v[34:37], v0 offset:1088
	v_add_co_u32_e32 v38, vcc, 0x54000, v182
	s_waitcnt vmcnt(15) lgkmcnt(0)
	v_pk_fma_f32 v[34:35], v[34:35], 0.5, v[106:107] op_sel_hi:[1,0,1]
	v_addc_co_u32_e32 v39, vcc, 0, v183, vcc
	v_pk_fma_f32 v[36:37], v[36:37], 0.5, v[108:109] op_sel_hi:[1,0,1]
	s_and_b64 vcc, exec, s[10:11]
	global_store_dwordx4 v[38:39], v[34:37], off nt
	s_cbranch_vccnz .LBB0_576
	v_pk_mul_f32 v[38:39], v[34:35], v[34:35]
	v_pk_mul_f32 v[40:41], v[36:37], v[36:37]
	v_add_f32_e32 v38, v38, v39
	v_add_f32_e32 v38, v40, v38
	v_and_b32_e32 v40, 64, v219
	v_add_f32_e32 v38, v41, v38
	s_nop 0
	v_add_u32_e32 v41, 64, v40
	s_nop 0
	v_cvt_pk_bf16_f32 v40, v34, v35
	v_xor_b32_e32 v35, 8, v219
	s_nop 1
	v_mov_b32_dpp v39, v38 quad_perm:[1,0,3,2] row_mask:0xf bank_mask:0xf
	s_waitcnt lgkmcnt(0)
	v_add_f32_e32 v38, v38, v39
	s_nop 5
	v_mov_b32_dpp v39, v38 quad_perm:[2,3,0,1] row_mask:0xf bank_mask:0xf
	s_waitcnt lgkmcnt(0)
	v_add_f32_e32 v39, v38, v39
	s_nop 5
	v_mov_b32_dpp v42, v39 row_half_mirror row_mask:0xf bank_mask:0xf
	v_cmp_lt_i32_e32 vcc, v35, v41
	v_or_b32_e32 v38, 0x54, v178
	v_cvt_pk_bf16_f32 v41, v36, v37
	s_nop 0
	s_waitcnt lgkmcnt(0)
	v_add_f32_e32 v34, v39, v42
	s_nop 1
	v_mov_b32_dpp v35, v34 row_mirror row_mask:0xf bank_mask:0xf
	v_mad_i64_i32 v[36:37], s[0:1], v38, s66, v[180:181]
	global_store_dwordx2 v[36:37], v[40:41], off
	s_and_saveexec_b64 s[0:1], s[8:9]
	s_cbranch_execz .LBB0_575
	v_ashrrev_i32_e32 v39, 31, v38
	s_waitcnt lgkmcnt(0)
	v_add_f32_e32 v36, v34, v35
	v_lshl_add_u64 v[34:35], v[38:39], 2, s[62:63]
	global_atomic_add_f32 v[34:35], v36, off

; DI unsigned pack_bf16(float lo, float hi) { f32x2 v = {lo, hi}; bf16v2 b = __builtin_convertvector(v, bf16v2); return __builtin_bit_cast(unsigned, b); }
; DI float red16(float v) { v += __shfl_xor(v, 1); v += __shfl_xor(v, 2); v += __shfl_xor(v, 4); v += __shfl_xor(v, 8); return v; }
;   DI void run8(f32x4 (&acc)[8][4], int rb, int cb, int fr, int fq) const {
;     ...
;         for (int ps = 0; ps < 4; ++ps) {
;           const f32x4 a = *(const f32x4*)(scr + (ps * 4 + prow) * 68 + c4 * 4);
;           f32x4 v;
;           v.x = xv[mm][ps].x + a.x * sc; v.y = xv[mm][ps].y + a.y * sc; v.z = xv[mm][ps].z + a.z * sc; v.w = xv[mm][ps].w + a.w * sc;
;           const int grow = rb + m * 16 + ps * 4 + prow;
;           __builtin_nontemporal_store(v, (f32x4*)(op + (size_t)(m * 16 + ps * 4) * D));
;           if (xbp) {
;             u32x2 o; o.x = pack_bf16(v.x, v.y); o.y = pack_bf16(v.z, v.w);
;             *(u32x2*)(xbp + (size_t)grow * LDH + cb + c4 * 4) = o;
;             const float t = red16(v.x * v.x + v.y * v.y + v.z * v.z + v.w * v.w);
;             if (c4 == 0) atomicAdd(ssqp + grow, t);
;           }
.LBB0_576:
	s_waitcnt lgkmcnt(0)
	ds_read_b128 v[34:37], v0 offset:2176
	v_add_co_u32_e32 v38, vcc, 0x58000, v182
	s_waitcnt vmcnt(15) lgkmcnt(0)
	v_pk_fma_f32 v[34:35], v[34:35], 0.5, v[102:103] op_sel_hi:[1,0,1]
	v_addc_co_u32_e32 v39, vcc, 0, v183, vcc
	v_pk_fma_f32 v[36:37], v[36:37], 0.5, v[104:105] op_sel_hi:[1,0,1]
	s_and_b64 vcc, exec, s[10:11]
	global_store_dwordx4 v[38:39], v[34:37], off nt
	s_cbranch_vccnz .LBB0_580
	v_pk_mul_f32 v[38:39], v[34:35], v[34:35]
	v_pk_mul_f32 v[40:41], v[36:37], v[36:37]
	v_add_f32_e32 v38, v38, v39
	v_add_f32_e32 v38, v40, v38
	v_and_b32_e32 v40, 64, v219
	v_add_f32_e32 v38, v41, v38
	s_nop 0
	v_add_u32_e32 v41, 64, v40
	s_nop 0
	v_cvt_pk_bf16_f32 v40, v34, v35
	v_xor_b32_e32 v35, 8, v219
	s_nop 1
	v_mov_b32_dpp v39, v38 quad_perm:[1,0,3,2] row_mask:0xf bank_mask:0xf
	s_waitcnt lgkmcnt(0)
	v_add_f32_e32 v38, v38, v39
	s_nop 5
	v_mov_b32_dpp v39, v38 quad_perm:[2,3,0,1] row_mask:0xf bank_mask:0xf
	s_waitcnt lgkmcnt(0)
	v_add_f32_e32 v39, v38, v39
	s_nop 5
	v_mov_b32_dpp v42, v39 row_half_mirror row_mask:0xf bank_mask:0xf
	v_cmp_lt_i32_e32 vcc, v35, v41
	v_or_b32_e32 v38, 0x58, v178
	v_cvt_pk_bf16_f32 v41, v36, v37
	s_nop 0
	s_waitcnt lgkmcnt(0)
	v_add_f32_e32 v34, v39, v42
	s_nop 1
	v_mov_b32_dpp v35, v34 row_mirror row_mask:0xf bank_mask:0xf
	v_mad_i64_i32 v[36:37], s[0:1], v38, s66, v[180:181]
	global_store_dwordx2 v[36:37], v[40:41], off
	s_and_saveexec_b64 s[0:1], s[8:9]
	s_cbranch_execz .LBB0_579
	v_ashrrev_i32_e32 v39, 31, v38
	s_waitcnt lgkmcnt(0)
	v_add_f32_e32 v36, v34, v35
	v_lshl_add_u64 v[34:35], v[38:39], 2, s[62:63]
	global_atomic_add_f32 v[34:35], v36, off

; DI unsigned pack_bf16(float lo, float hi) { f32x2 v = {lo, hi}; bf16v2 b = __builtin_convertvector(v, bf16v2); return __builtin_bit_cast(unsigned, b); }
; DI float red16(float v) { v += __shfl_xor(v, 1); v += __shfl_xor(v, 2); v += __shfl_xor(v, 4); v += __shfl_xor(v, 8); return v; }
;   DI void run8(f32x4 (&acc)[8][4], int rb, int cb, int fr, int fq) const {
;     ...
;         for (int ps = 0; ps < 4; ++ps) {
;           const f32x4 a = *(const f32x4*)(scr + (ps * 4 + prow) * 68 + c4 * 4);
;           f32x4 v;
;           v.x = xv[mm][ps].x + a.x * sc; v.y = xv[mm][ps].y + a.y * sc; v.z = xv[mm][ps].z + a.z * sc; v.w = xv[mm][ps].w + a.w * sc;
;           const int grow = rb + m * 16 + ps * 4 + prow;
;           __builtin_nontemporal_store(v, (f32x4*)(op + (size_t)(m * 16 + ps * 4) * D));
;           if (xbp) {
;             u32x2 o; o.x = pack_bf16(v.x, v.y); o.y = pack_bf16(v.z, v.w);
;             *(u32x2*)(xbp + (size_t)grow * LDH + cb + c4 * 4) = o;
;             const float t = red16(v.x * v.x + v.y * v.y + v.z * v.z + v.w * v.w);
;             if (c4 == 0) atomicAdd(ssqp + grow, t);
;           }
.LBB0_580:
	s_waitcnt lgkmcnt(0)
	ds_read_b128 v[34:37], v0 offset:3264
	v_add_co_u32_e32 v38, vcc, 0x5c000, v182
	s_waitcnt vmcnt(15) lgkmcnt(0)
	v_pk_fma_f32 v[34:35], v[34:35], 0.5, v[98:99] op_sel_hi:[1,0,1]
	v_addc_co_u32_e32 v39, vcc, 0, v183, vcc
	v_pk_fma_f32 v[36:37], v[36:37], 0.5, v[100:101] op_sel_hi:[1,0,1]
	s_and_b64 vcc, exec, s[10:11]
	global_store_dwordx4 v[38:39], v[34:37], off nt
	s_cbranch_vccnz .LBB0_584
	v_pk_mul_f32 v[38:39], v[34:35], v[34:35]
	v_pk_mul_f32 v[40:41], v[36:37], v[36:37]
	v_add_f32_e32 v38, v38, v39
	v_add_f32_e32 v38, v40, v38
	v_and_b32_e32 v40, 64, v219
	v_add_f32_e32 v38, v41, v38
	s_nop 0
	v_add_u32_e32 v41, 64, v40
	s_nop 0
	v_cvt_pk_bf16_f32 v40, v34, v35
	v_xor_b32_e32 v35, 8, v219
	s_nop 1
	v_mov_b32_dpp v39, v38 quad_perm:[1,0,3,2] row_mask:0xf bank_mask:0xf
	s_waitcnt lgkmcnt(0)
	v_add_f32_e32 v38, v38, v39
	s_nop 5
	v_mov_b32_dpp v39, v38 quad_perm:[2,3,0,1] row_mask:0xf bank_mask:0xf
	s_waitcnt lgkmcnt(0)
	v_add_f32_e32 v39, v38, v39
	s_nop 5
	v_mov_b32_dpp v42, v39 row_half_mirror row_mask:0xf bank_mask:0xf
	v_cmp_lt_i32_e32 vcc, v35, v41
	v_or_b32_e32 v38, 0x5c, v178
	v_cvt_pk_bf16_f32 v41, v36, v37
	s_nop 0
	s_waitcnt lgkmcnt(0)
	v_add_f32_e32 v34, v39, v42
	s_nop 1
	v_mov_b32_dpp v35, v34 row_mirror row_mask:0xf bank_mask:0xf
	v_mad_i64_i32 v[36:37], s[0:1], v38, s66, v[180:181]
	global_store_dwordx2 v[36:37], v[40:41], off
	s_and_saveexec_b64 s[0:1], s[8:9]
	s_cbranch_execz .LBB0_583
	v_ashrrev_i32_e32 v39, 31, v38
	s_waitcnt lgkmcnt(0)
	v_add_f32_e32 v36, v34, v35
	v_lshl_add_u64 v[34:35], v[38:39], 2, s[62:63]
	global_atomic_add_f32 v[34:35], v36, off

; DI unsigned pack_bf16(float lo, float hi) { f32x2 v = {lo, hi}; bf16v2 b = __builtin_convertvector(v, bf16v2); return __builtin_bit_cast(unsigned, b); }
; DI float red16(float v) { v += __shfl_xor(v, 1); v += __shfl_xor(v, 2); v += __shfl_xor(v, 4); v += __shfl_xor(v, 8); return v; }
;   DI void run8(f32x4 (&acc)[8][4], int rb, int cb, int fr, int fq) const {
;     ...
;         for (int n = 0; n < 4; ++n)
; #pragma unroll
;           for (int j = 0; j < 4; ++j) scr[(fq * 4 + j) * 68 + n * 16 + fr] = acc[m][n][j];
;         __builtin_amdgcn_sched_barrier(0);
; #pragma unroll
;         for (int ps = 0; ps < 4; ++ps) {
;           const f32x4 a = *(const f32x4*)(scr + (ps * 4 + prow) * 68 + c4 * 4);
;           f32x4 v;
;           v.x = xv[mm][ps].x + a.x * sc; v.y = xv[mm][ps].y + a.y * sc; v.z = xv[mm][ps].z + a.z * sc; v.w = xv[mm][ps].w + a.w * sc;
;           const int grow = rb + m * 16 + ps * 4 + prow;
;           __builtin_nontemporal_store(v, (f32x4*)(op + (size_t)(m * 16 + ps * 4) * D));
;           if (xbp) {
;             u32x2 o; o.x = pack_bf16(v.x, v.y); o.y = pack_bf16(v.z, v.w);
;             *(u32x2*)(xbp + (size_t)grow * LDH + cb + c4 * 4) = o;
;             const float t = red16(v.x * v.x + v.y * v.y + v.z * v.z + v.w * v.w);
;             if (c4 == 0) atomicAdd(ssqp + grow, t);
;           }
.LBB0_584:
	ds_write2_b32 v186, v26, v30 offset1:16
	ds_write2_b32 v186, v27, v31 offset0:68 offset1:84
	ds_write2_b32 v186, v28, v32 offset0:136 offset1:152
	ds_write2_b32 v186, v29, v33 offset0:204 offset1:220
	ds_write2_b32 v186, v18, v22 offset0:32 offset1:48
	ds_write2_b32 v186, v19, v23 offset0:100 offset1:116
	ds_write2_b32 v186, v20, v24 offset0:168 offset1:184
	ds_write2_b32 v186, v21, v25 offset0:236 offset1:252
	ds_read_b128 v[18:21], v0
	v_add_co_u32_e32 v22, vcc, 0x60000, v182
	s_waitcnt vmcnt(15) lgkmcnt(0)
	v_pk_fma_f32 v[18:19], v[18:19], 0.5, v[94:95] op_sel_hi:[1,0,1]
	v_addc_co_u32_e32 v23, vcc, 0, v183, vcc
	v_pk_fma_f32 v[20:21], v[20:21], 0.5, v[96:97] op_sel_hi:[1,0,1]
	s_and_b64 vcc, exec, s[10:11]
	global_store_dwordx4 v[22:23], v[18:21], off nt
	s_cbranch_vccnz .LBB0_588
	v_pk_mul_f32 v[22:23], v[18:19], v[18:19]
	v_pk_mul_f32 v[24:25], v[20:21], v[20:21]
	v_add_f32_e32 v22, v22, v23
	v_add_f32_e32 v22, v24, v22
	v_and_b32_e32 v24, 64, v219
	v_add_f32_e32 v22, v25, v22
	s_nop 0
	v_add_u32_e32 v25, 64, v24
	s_nop 0
	v_cvt_pk_bf16_f32 v24, v18, v19
	v_xor_b32_e32 v19, 8, v219
	s_nop 1
	v_mov_b32_dpp v23, v22 quad_perm:[1,0,3,2] row_mask:0xf bank_mask:0xf
	s_waitcnt lgkmcnt(0)
	v_add_f32_e32 v22, v22, v23
	s_nop 5
	v_mov_b32_dpp v23, v22 quad_perm:[2,3,0,1] row_mask:0xf bank_mask:0xf
	s_waitcnt lgkmcnt(0)
	v_add_f32_e32 v23, v22, v23
	s_nop 5
	v_mov_b32_dpp v26, v23 row_half_mirror row_mask:0xf bank_mask:0xf
	v_cmp_lt_i32_e32 vcc, v19, v25
	v_or_b32_e32 v22, 0x60, v178
	v_cvt_pk_bf16_f32 v25, v20, v21
	s_nop 0
	s_waitcnt lgkmcnt(0)
	v_add_f32_e32 v18, v23, v26
	s_nop 1
	v_mov_b32_dpp v19, v18 row_mirror row_mask:0xf bank_mask:0xf
	v_mad_i64_i32 v[20:21], s[0:1], v22, s66, v[180:181]
	global_store_dwordx2 v[20:21], v[24:25], off
	s_and_saveexec_b64 s[0:1], s[8:9]
	s_cbranch_execz .LBB0_587
	v_ashrrev_i32_e32 v23, 31, v22
	s_waitcnt lgkmcnt(0)
	v_add_f32_e32 v20, v18, v19
	v_lshl_add_u64 v[18:19], v[22:23], 2, s[62:63]
	global_atomic_add_f32 v[18:19], v20, off

; DI unsigned pack_bf16(float lo, float hi) { f32x2 v = {lo, hi}; bf16v2 b = __builtin_convertvector(v, bf16v2); return __builtin_bit_cast(unsigned, b); }
; DI float red16(float v) { v += __shfl_xor(v, 1); v += __shfl_xor(v, 2); v += __shfl_xor(v, 4); v += __shfl_xor(v, 8); return v; }
;   DI void run8(f32x4 (&acc)[8][4], int rb, int cb, int fr, int fq) const {
;     ...
;         for (int ps = 0; ps < 4; ++ps) {
;           const f32x4 a = *(const f32x4*)(scr + (ps * 4 + prow) * 68 + c4 * 4);
;           f32x4 v;
;           v.x = xv[mm][ps].x + a.x * sc; v.y = xv[mm][ps].y + a.y * sc; v.z = xv[mm][ps].z + a.z * sc; v.w = xv[mm][ps].w + a.w * sc;
;           const int grow = rb + m * 16 + ps * 4 + prow;
;           __builtin_nontemporal_store(v, (f32x4*)(op + (size_t)(m * 16 + ps * 4) * D));
;           if (xbp) {
;             u32x2 o; o.x = pack_bf16(v.x, v.y); o.y = pack_bf16(v.z, v.w);
;             *(u32x2*)(xbp + (size_t)grow * LDH + cb + c4 * 4) = o;
;             const float t = red16(v.x * v.x + v.y * v.y + v.z * v.z + v.w * v.w);
;             if (c4 == 0) atomicAdd(ssqp + grow, t);
;           }
.LBB0_588:
	s_waitcnt lgkmcnt(0)
	ds_read_b128 v[18:21], v0 offset:1088
	v_add_co_u32_e32 v22, vcc, 0x64000, v182
	s_waitcnt vmcnt(15) lgkmcnt(0)
	v_pk_fma_f32 v[18:19], v[18:19], 0.5, v[90:91] op_sel_hi:[1,0,1]
	v_addc_co_u32_e32 v23, vcc, 0, v183, vcc
	v_pk_fma_f32 v[20:21], v[20:21], 0.5, v[92:93] op_sel_hi:[1,0,1]
	s_and_b64 vcc, exec, s[10:11]
	global_store_dwordx4 v[22:23], v[18:21], off nt
	s_cbranch_vccnz .LBB0_592
	v_pk_mul_f32 v[22:23], v[18:19], v[18:19]
	v_pk_mul_f32 v[24:25], v[20:21], v[20:21]
	v_add_f32_e32 v22, v22, v23
	v_add_f32_e32 v22, v24, v22
	v_and_b32_e32 v24, 64, v219
	v_add_f32_e32 v22, v25, v22
	s_nop 0
	v_add_u32_e32 v25, 64, v24
	s_nop 0
	v_cvt_pk_bf16_f32 v24, v18, v19
	v_xor_b32_e32 v19, 8, v219
	s_nop 1
	v_mov_b32_dpp v23, v22 quad_perm:[1,0,3,2] row_mask:0xf bank_mask:0xf
	s_waitcnt lgkmcnt(0)
	v_add_f32_e32 v22, v22, v23
	s_nop 5
	v_mov_b32_dpp v23, v22 quad_perm:[2,3,0,1] row_mask:0xf bank_mask:0xf
	s_waitcnt lgkmcnt(0)
	v_add_f32_e32 v23, v22, v23
	s_nop 5
	v_mov_b32_dpp v26, v23 row_half_mirror row_mask:0xf bank_mask:0xf
	v_cmp_lt_i32_e32 vcc, v19, v25
	v_or_b32_e32 v22, 0x64, v178
	v_cvt_pk_bf16_f32 v25, v20, v21
	s_nop 0
	s_waitcnt lgkmcnt(0)
	v_add_f32_e32 v18, v23, v26
	s_nop 1
	v_mov_b32_dpp v19, v18 row_mirror row_mask:0xf bank_mask:0xf
	v_mad_i64_i32 v[20:21], s[0:1], v22, s66, v[180:181]
	global_store_dwordx2 v[20:21], v[24:25], off
	s_and_saveexec_b64 s[0:1], s[8:9]
	s_cbranch_execz .LBB0_591
	v_ashrrev_i32_e32 v23, 31, v22
	s_waitcnt lgkmcnt(0)
	v_add_f32_e32 v20, v18, v19
	v_lshl_add_u64 v[18:19], v[22:23], 2, s[62:63]
	global_atomic_add_f32 v[18:19], v20, off

; DI unsigned pack_bf16(float lo, float hi) { f32x2 v = {lo, hi}; bf16v2 b = __builtin_convertvector(v, bf16v2); return __builtin_bit_cast(unsigned, b); }
; DI float red16(float v) { v += __shfl_xor(v, 1); v += __shfl_xor(v, 2); v += __shfl_xor(v, 4); v += __shfl_xor(v, 8); return v; }
;   DI void run8(f32x4 (&acc)[8][4], int rb, int cb, int fr, int fq) const {
;     ...
;         for (int ps = 0; ps < 4; ++ps) {
;           const f32x4 a = *(const f32x4*)(scr + (ps * 4 + prow) * 68 + c4 * 4);
;           f32x4 v;
;           v.x = xv[mm][ps].x + a.x * sc; v.y = xv[mm][ps].y + a.y * sc; v.z = xv[mm][ps].z + a.z * sc; v.w = xv[mm][ps].w + a.w * sc;
;           const int grow = rb + m * 16 + ps * 4 + prow;
;           __builtin_nontemporal_store(v, (f32x4*)(op + (size_t)(m * 16 + ps * 4) * D));
;           if (xbp) {
;             u32x2 o; o.x = pack_bf16(v.x, v.y); o.y = pack_bf16(v.z, v.w);
;             *(u32x2*)(xbp + (size_t)grow * LDH + cb + c4 * 4) = o;
;             const float t = red16(v.x * v.x + v.y * v.y + v.z * v.z + v.w * v.w);
;             if (c4 == 0) atomicAdd(ssqp + grow, t);
;           }
.LBB0_592:
	s_waitcnt lgkmcnt(0)
	ds_read_b128 v[18:21], v0 offset:2176
	v_add_co_u32_e32 v22, vcc, 0x68000, v182
	s_waitcnt vmcnt(15) lgkmcnt(0)
	v_pk_fma_f32 v[18:19], v[18:19], 0.5, v[86:87] op_sel_hi:[1,0,1]
	v_addc_co_u32_e32 v23, vcc, 0, v183, vcc
	v_pk_fma_f32 v[20:21], v[20:21], 0.5, v[88:89] op_sel_hi:[1,0,1]
	s_and_b64 vcc, exec, s[10:11]
	global_store_dwordx4 v[22:23], v[18:21], off nt
	s_cbranch_vccnz .LBB0_596
	v_pk_mul_f32 v[22:23], v[18:19], v[18:19]
	v_pk_mul_f32 v[24:25], v[20:21], v[20:21]
	v_add_f32_e32 v22, v22, v23
	v_add_f32_e32 v22, v24, v22
	v_and_b32_e32 v24, 64, v219
	v_add_f32_e32 v22, v25, v22
	s_nop 0
	v_add_u32_e32 v25, 64, v24
	s_nop 0
	v_cvt_pk_bf16_f32 v24, v18, v19
	v_xor_b32_e32 v19, 8, v219
	s_nop 1
	v_mov_b32_dpp v23, v22 quad_perm:[1,0,3,2] row_mask:0xf bank_mask:0xf
	s_waitcnt lgkmcnt(0)
	v_add_f32_e32 v22, v22, v23
	s_nop 5
	v_mov_b32_dpp v23, v22 quad_perm:[2,3,0,1] row_mask:0xf bank_mask:0xf
	s_waitcnt lgkmcnt(0)
	v_add_f32_e32 v23, v22, v23
	s_nop 5
	v_mov_b32_dpp v26, v23 row_half_mirror row_mask:0xf bank_mask:0xf
	v_cmp_lt_i32_e32 vcc, v19, v25
	v_or_b32_e32 v22, 0x68, v178
	v_cvt_pk_bf16_f32 v25, v20, v21
	s_nop 0
	s_waitcnt lgkmcnt(0)
	v_add_f32_e32 v18, v23, v26
	s_nop 1
	v_mov_b32_dpp v19, v18 row_mirror row_mask:0xf bank_mask:0xf
	v_mad_i64_i32 v[20:21], s[0:1], v22, s66, v[180:181]
	global_store_dwordx2 v[20:21], v[24:25], off
	s_and_saveexec_b64 s[0:1], s[8:9]
	s_cbranch_execz .LBB0_595
	v_ashrrev_i32_e32 v23, 31, v22
	s_waitcnt lgkmcnt(0)
	v_add_f32_e32 v20, v18, v19
	v_lshl_add_u64 v[18:19], v[22:23], 2, s[62:63]
	global_atomic_add_f32 v[18:19], v20, off

; DI unsigned pack_bf16(float lo, float hi) { f32x2 v = {lo, hi}; bf16v2 b = __builtin_convertvector(v, bf16v2); return __builtin_bit_cast(unsigned, b); }
; DI float red16(float v) { v += __shfl_xor(v, 1); v += __shfl_xor(v, 2); v += __shfl_xor(v, 4); v += __shfl_xor(v, 8); return v; }
;   DI void run8(f32x4 (&acc)[8][4], int rb, int cb, int fr, int fq) const {
;     ...
;         for (int ps = 0; ps < 4; ++ps) {
;           const f32x4 a = *(const f32x4*)(scr + (ps * 4 + prow) * 68 + c4 * 4);
;           f32x4 v;
;           v.x = xv[mm][ps].x + a.x * sc; v.y = xv[mm][ps].y + a.y * sc; v.z = xv[mm][ps].z + a.z * sc; v.w = xv[mm][ps].w + a.w * sc;
;           const int grow = rb + m * 16 + ps * 4 + prow;
;           __builtin_nontemporal_store(v, (f32x4*)(op + (size_t)(m * 16 + ps * 4) * D));
;           if (xbp) {
;             u32x2 o; o.x = pack_bf16(v.x, v.y); o.y = pack_bf16(v.z, v.w);
;             *(u32x2*)(xbp + (size_t)grow * LDH + cb + c4 * 4) = o;
;             const float t = red16(v.x * v.x + v.y * v.y + v.z * v.z + v.w * v.w);
;             if (c4 == 0) atomicAdd(ssqp + grow, t);
;           }
.LBB0_596:
	s_waitcnt lgkmcnt(0)
	ds_read_b128 v[18:21], v0 offset:3264
	v_add_co_u32_e32 v22, vcc, 0x6c000, v182
	s_waitcnt vmcnt(15) lgkmcnt(0)
	v_pk_fma_f32 v[18:19], v[18:19], 0.5, v[82:83] op_sel_hi:[1,0,1]
	v_addc_co_u32_e32 v23, vcc, 0, v183, vcc
	v_pk_fma_f32 v[20:21], v[20:21], 0.5, v[84:85] op_sel_hi:[1,0,1]
	s_and_b64 vcc, exec, s[10:11]
	global_store_dwordx4 v[22:23], v[18:21], off nt
	s_cbranch_vccnz .LBB0_600
	v_pk_mul_f32 v[22:23], v[18:19], v[18:19]
	v_pk_mul_f32 v[24:25], v[20:21], v[20:21]
	v_add_f32_e32 v22, v22, v23
	v_add_f32_e32 v22, v24, v22
	v_and_b32_e32 v24, 64, v219
	v_add_f32_e32 v22, v25, v22
	s_nop 0
	v_add_u32_e32 v25, 64, v24
	s_nop 0
	v_cvt_pk_bf16_f32 v24, v18, v19
	v_xor_b32_e32 v19, 8, v219
	s_nop 1
	v_mov_b32_dpp v23, v22 quad_perm:[1,0,3,2] row_mask:0xf bank_mask:0xf
	s_waitcnt lgkmcnt(0)
	v_add_f32_e32 v22, v22, v23
	s_nop 5
	v_mov_b32_dpp v23, v22 quad_perm:[2,3,0,1] row_mask:0xf bank_mask:0xf
	s_waitcnt lgkmcnt(0)
	v_add_f32_e32 v23, v22, v23
	s_nop 5
	v_mov_b32_dpp v26, v23 row_half_mirror row_mask:0xf bank_mask:0xf
	v_cmp_lt_i32_e32 vcc, v19, v25
	v_or_b32_e32 v22, 0x6c, v178
	v_cvt_pk_bf16_f32 v25, v20, v21
	s_nop 0
	s_waitcnt lgkmcnt(0)
	v_add_f32_e32 v18, v23, v26
	s_nop 1
	v_mov_b32_dpp v19, v18 row_mirror row_mask:0xf bank_mask:0xf
	v_mad_i64_i32 v[20:21], s[0:1], v22, s66, v[180:181]
	global_store_dwordx2 v[20:21], v[24:25], off
	s_and_saveexec_b64 s[0:1], s[8:9]
	s_cbranch_execz .LBB0_599
	v_ashrrev_i32_e32 v23, 31, v22
	s_waitcnt lgkmcnt(0)
	v_add_f32_e32 v20, v18, v19
	v_lshl_add_u64 v[18:19], v[22:23], 2, s[62:63]
	global_atomic_add_f32 v[18:19], v20, off

; DI unsigned pack_bf16(float lo, float hi) { f32x2 v = {lo, hi}; bf16v2 b = __builtin_convertvector(v, bf16v2); return __builtin_bit_cast(unsigned, b); }
; DI float red16(float v) { v += __shfl_xor(v, 1); v += __shfl_xor(v, 2); v += __shfl_xor(v, 4); v += __shfl_xor(v, 8); return v; }
;   DI void run8(f32x4 (&acc)[8][4], int rb, int cb, int fr, int fq) const {
;     ...
;         for (int n = 0; n < 4; ++n)
; #pragma unroll
;           for (int j = 0; j < 4; ++j) scr[(fq * 4 + j) * 68 + n * 16 + fr] = acc[m][n][j];
;         __builtin_amdgcn_sched_barrier(0);
; #pragma unroll
;         for (int ps = 0; ps < 4; ++ps) {
;           const f32x4 a = *(const f32x4*)(scr + (ps * 4 + prow) * 68 + c4 * 4);
;           f32x4 v;
;           v.x = xv[mm][ps].x + a.x * sc; v.y = xv[mm][ps].y + a.y * sc; v.z = xv[mm][ps].z + a.z * sc; v.w = xv[mm][ps].w + a.w * sc;
;           const int grow = rb + m * 16 + ps * 4 + prow;
;           __builtin_nontemporal_store(v, (f32x4*)(op + (size_t)(m * 16 + ps * 4) * D));
;           if (xbp) {
;             u32x2 o; o.x = pack_bf16(v.x, v.y); o.y = pack_bf16(v.z, v.w);
;             *(u32x2*)(xbp + (size_t)grow * LDH + cb + c4 * 4) = o;
;             const float t = red16(v.x * v.x + v.y * v.y + v.z * v.z + v.w * v.w);
;             if (c4 == 0) atomicAdd(ssqp + grow, t);
;           }
.LBB0_600:
	ds_write2_b32 v186, v10, v14 offset1:16
	ds_write2_b32 v186, v11, v15 offset0:68 offset1:84
	ds_write2_b32 v186, v12, v16 offset0:136 offset1:152
	ds_write2_b32 v186, v13, v17 offset0:204 offset1:220
	ds_write2_b32 v186, v2, v6 offset0:32 offset1:48
	ds_write2_b32 v186, v3, v7 offset0:100 offset1:116
	ds_write2_b32 v186, v4, v8 offset0:168 offset1:184
	ds_write2_b32 v186, v5, v9 offset0:236 offset1:252
	ds_read_b128 v[2:5], v0
	v_add_co_u32_e32 v6, vcc, 0x70000, v182
	s_waitcnt vmcnt(15) lgkmcnt(0)
	v_pk_fma_f32 v[2:3], v[2:3], 0.5, v[78:79] op_sel_hi:[1,0,1]
	v_addc_co_u32_e32 v7, vcc, 0, v183, vcc
	v_pk_fma_f32 v[4:5], v[4:5], 0.5, v[80:81] op_sel_hi:[1,0,1]
	s_and_b64 vcc, exec, s[10:11]
	global_store_dwordx4 v[6:7], v[2:5], off nt
	s_cbranch_vccnz .LBB0_604
	v_pk_mul_f32 v[6:7], v[2:3], v[2:3]
	v_pk_mul_f32 v[8:9], v[4:5], v[4:5]
	v_add_f32_e32 v6, v6, v7
	v_add_f32_e32 v6, v8, v6
	v_and_b32_e32 v8, 64, v219
	v_add_f32_e32 v6, v9, v6
	s_nop 0
	v_add_u32_e32 v9, 64, v8
	s_nop 0
	v_cvt_pk_bf16_f32 v8, v2, v3
	v_xor_b32_e32 v3, 8, v219
	s_nop 1
	v_mov_b32_dpp v7, v6 quad_perm:[1,0,3,2] row_mask:0xf bank_mask:0xf
	s_waitcnt lgkmcnt(0)
	v_add_f32_e32 v6, v6, v7
	s_nop 5
	v_mov_b32_dpp v7, v6 quad_perm:[2,3,0,1] row_mask:0xf bank_mask:0xf
	s_waitcnt lgkmcnt(0)
	v_add_f32_e32 v7, v6, v7
	s_nop 5
	v_mov_b32_dpp v10, v7 row_half_mirror row_mask:0xf bank_mask:0xf
	v_cmp_lt_i32_e32 vcc, v3, v9
	v_or_b32_e32 v6, 0x70, v178
	v_cvt_pk_bf16_f32 v9, v4, v5
	s_nop 0
	s_waitcnt lgkmcnt(0)
	v_add_f32_e32 v2, v7, v10
	s_nop 1
	v_mov_b32_dpp v3, v2 row_mirror row_mask:0xf bank_mask:0xf
	v_mad_i64_i32 v[4:5], s[0:1], v6, s66, v[180:181]
	global_store_dwordx2 v[4:5], v[8:9], off
	s_and_saveexec_b64 s[0:1], s[8:9]
	s_cbranch_execz .LBB0_603
	v_ashrrev_i32_e32 v7, 31, v6
	s_waitcnt lgkmcnt(0)
	v_add_f32_e32 v4, v2, v3
	v_lshl_add_u64 v[2:3], v[6:7], 2, s[62:63]
	global_atomic_add_f32 v[2:3], v4, off

; DI unsigned pack_bf16(float lo, float hi) { f32x2 v = {lo, hi}; bf16v2 b = __builtin_convertvector(v, bf16v2); return __builtin_bit_cast(unsigned, b); }
; DI float red16(float v) { v += __shfl_xor(v, 1); v += __shfl_xor(v, 2); v += __shfl_xor(v, 4); v += __shfl_xor(v, 8); return v; }
;   DI void run8(f32x4 (&acc)[8][4], int rb, int cb, int fr, int fq) const {
;     ...
;         for (int ps = 0; ps < 4; ++ps) {
;           const f32x4 a = *(const f32x4*)(scr + (ps * 4 + prow) * 68 + c4 * 4);
;           f32x4 v;
;           v.x = xv[mm][ps].x + a.x * sc; v.y = xv[mm][ps].y + a.y * sc; v.z = xv[mm][ps].z + a.z * sc; v.w = xv[mm][ps].w + a.w * sc;
;           const int grow = rb + m * 16 + ps * 4 + prow;
;           __builtin_nontemporal_store(v, (f32x4*)(op + (size_t)(m * 16 + ps * 4) * D));
;           if (xbp) {
;             u32x2 o; o.x = pack_bf16(v.x, v.y); o.y = pack_bf16(v.z, v.w);
;             *(u32x2*)(xbp + (size_t)grow * LDH + cb + c4 * 4) = o;
;             const float t = red16(v.x * v.x + v.y * v.y + v.z * v.z + v.w * v.w);
;             if (c4 == 0) atomicAdd(ssqp + grow, t);
;           }
.LBB0_604:
	s_waitcnt lgkmcnt(0)
	ds_read_b128 v[2:5], v0 offset:1088
	v_add_co_u32_e32 v6, vcc, 0x74000, v182
	s_waitcnt vmcnt(15) lgkmcnt(0)
	v_pk_fma_f32 v[2:3], v[2:3], 0.5, v[74:75] op_sel_hi:[1,0,1]
	v_addc_co_u32_e32 v7, vcc, 0, v183, vcc
	v_pk_fma_f32 v[4:5], v[4:5], 0.5, v[76:77] op_sel_hi:[1,0,1]
	s_and_b64 vcc, exec, s[10:11]
	global_store_dwordx4 v[6:7], v[2:5], off nt
	s_cbranch_vccnz .LBB0_608
	v_pk_mul_f32 v[6:7], v[2:3], v[2:3]
	v_pk_mul_f32 v[8:9], v[4:5], v[4:5]
	v_add_f32_e32 v6, v6, v7
	v_add_f32_e32 v6, v8, v6
	v_and_b32_e32 v8, 64, v219
	v_add_f32_e32 v6, v9, v6
	s_nop 0
	v_add_u32_e32 v9, 64, v8
	s_nop 0
	v_cvt_pk_bf16_f32 v8, v2, v3
	v_xor_b32_e32 v3, 8, v219
	s_nop 1
	v_mov_b32_dpp v7, v6 quad_perm:[1,0,3,2] row_mask:0xf bank_mask:0xf
	s_waitcnt lgkmcnt(0)
	v_add_f32_e32 v6, v6, v7
	s_nop 5
	v_mov_b32_dpp v7, v6 quad_perm:[2,3,0,1] row_mask:0xf bank_mask:0xf
	s_waitcnt lgkmcnt(0)
	v_add_f32_e32 v7, v6, v7
	s_nop 5
	v_mov_b32_dpp v10, v7 row_half_mirror row_mask:0xf bank_mask:0xf
	v_cmp_lt_i32_e32 vcc, v3, v9
	v_or_b32_e32 v6, 0x74, v178
	v_cvt_pk_bf16_f32 v9, v4, v5
	s_nop 0
	s_waitcnt lgkmcnt(0)
	v_add_f32_e32 v2, v7, v10
	s_nop 1
	v_mov_b32_dpp v3, v2 row_mirror row_mask:0xf bank_mask:0xf
	v_mad_i64_i32 v[4:5], s[0:1], v6, s66, v[180:181]
	global_store_dwordx2 v[4:5], v[8:9], off
	s_and_saveexec_b64 s[0:1], s[8:9]
	s_cbranch_execz .LBB0_607
	v_ashrrev_i32_e32 v7, 31, v6
	s_waitcnt lgkmcnt(0)
	v_add_f32_e32 v4, v2, v3
	v_lshl_add_u64 v[2:3], v[6:7], 2, s[62:63]
	global_atomic_add_f32 v[2:3], v4, off

; DI unsigned pack_bf16(float lo, float hi) { f32x2 v = {lo, hi}; bf16v2 b = __builtin_convertvector(v, bf16v2); return __builtin_bit_cast(unsigned, b); }
; DI float red16(float v) { v += __shfl_xor(v, 1); v += __shfl_xor(v, 2); v += __shfl_xor(v, 4); v += __shfl_xor(v, 8); return v; }
;   DI void run8(f32x4 (&acc)[8][4], int rb, int cb, int fr, int fq) const {
;     ...
;         for (int ps = 0; ps < 4; ++ps) {
;           const f32x4 a = *(const f32x4*)(scr + (ps * 4 + prow) * 68 + c4 * 4);
;           f32x4 v;
;           v.x = xv[mm][ps].x + a.x * sc; v.y = xv[mm][ps].y + a.y * sc; v.z = xv[mm][ps].z + a.z * sc; v.w = xv[mm][ps].w + a.w * sc;
;           const int grow = rb + m * 16 + ps * 4 + prow;
;           __builtin_nontemporal_store(v, (f32x4*)(op + (size_t)(m * 16 + ps * 4) * D));
;           if (xbp) {
;             u32x2 o; o.x = pack_bf16(v.x, v.y); o.y = pack_bf16(v.z, v.w);
;             *(u32x2*)(xbp + (size_t)grow * LDH + cb + c4 * 4) = o;
;             const float t = red16(v.x * v.x + v.y * v.y + v.z * v.z + v.w * v.w);
;             if (c4 == 0) atomicAdd(ssqp + grow, t);
;           }
.LBB0_608:
	s_waitcnt lgkmcnt(0)
	ds_read_b128 v[2:5], v0 offset:2176
	v_add_co_u32_e32 v6, vcc, 0x78000, v182
	s_waitcnt vmcnt(15) lgkmcnt(0)
	v_pk_fma_f32 v[2:3], v[2:3], 0.5, v[70:71] op_sel_hi:[1,0,1]
	v_addc_co_u32_e32 v7, vcc, 0, v183, vcc
	v_pk_fma_f32 v[4:5], v[4:5], 0.5, v[72:73] op_sel_hi:[1,0,1]
	s_and_b64 vcc, exec, s[10:11]
	global_store_dwordx4 v[6:7], v[2:5], off nt
	s_cbranch_vccnz .LBB0_612
	v_pk_mul_f32 v[6:7], v[2:3], v[2:3]
	v_pk_mul_f32 v[8:9], v[4:5], v[4:5]
	v_add_f32_e32 v6, v6, v7
	v_add_f32_e32 v6, v8, v6
	v_and_b32_e32 v8, 64, v219
	v_add_f32_e32 v6, v9, v6
	s_nop 0
	v_add_u32_e32 v9, 64, v8
	s_nop 0
	v_cvt_pk_bf16_f32 v8, v2, v3
	v_xor_b32_e32 v3, 8, v219
	s_nop 1
	v_mov_b32_dpp v7, v6 quad_perm:[1,0,3,2] row_mask:0xf bank_mask:0xf
	s_waitcnt lgkmcnt(0)
	v_add_f32_e32 v6, v6, v7
	s_nop 5
	v_mov_b32_dpp v7, v6 quad_perm:[2,3,0,1] row_mask:0xf bank_mask:0xf
	s_waitcnt lgkmcnt(0)
	v_add_f32_e32 v7, v6, v7
	s_nop 5
	v_mov_b32_dpp v10, v7 row_half_mirror row_mask:0xf bank_mask:0xf
	v_cmp_lt_i32_e32 vcc, v3, v9
	v_or_b32_e32 v6, 0x78, v178
	v_cvt_pk_bf16_f32 v9, v4, v5
	s_nop 0
	s_waitcnt lgkmcnt(0)
	v_add_f32_e32 v2, v7, v10
	s_nop 1
	v_mov_b32_dpp v3, v2 row_mirror row_mask:0xf bank_mask:0xf
	v_mad_i64_i32 v[4:5], s[0:1], v6, s66, v[180:181]
	global_store_dwordx2 v[4:5], v[8:9], off
	s_and_saveexec_b64 s[0:1], s[8:9]
	s_cbranch_execz .LBB0_611
	v_ashrrev_i32_e32 v7, 31, v6
	s_waitcnt lgkmcnt(0)
	v_add_f32_e32 v4, v2, v3
	v_lshl_add_u64 v[2:3], v[6:7], 2, s[62:63]
	global_atomic_add_f32 v[2:3], v4, off

; DI unsigned pack_bf16(float lo, float hi) { f32x2 v = {lo, hi}; bf16v2 b = __builtin_convertvector(v, bf16v2); return __builtin_bit_cast(unsigned, b); }
; DI float red16(float v) { v += __shfl_xor(v, 1); v += __shfl_xor(v, 2); v += __shfl_xor(v, 4); v += __shfl_xor(v, 8); return v; }
;   DI void run8(f32x4 (&acc)[8][4], int rb, int cb, int fr, int fq) const {
;     ...
;         for (int ps = 0; ps < 4; ++ps) {
;           const f32x4 a = *(const f32x4*)(scr + (ps * 4 + prow) * 68 + c4 * 4);
;           f32x4 v;
;           v.x = xv[mm][ps].x + a.x * sc; v.y = xv[mm][ps].y + a.y * sc; v.z = xv[mm][ps].z + a.z * sc; v.w = xv[mm][ps].w + a.w * sc;
;           const int grow = rb + m * 16 + ps * 4 + prow;
;           __builtin_nontemporal_store(v, (f32x4*)(op + (size_t)(m * 16 + ps * 4) * D));
;           if (xbp) {
;             u32x2 o; o.x = pack_bf16(v.x, v.y); o.y = pack_bf16(v.z, v.w);
;             *(u32x2*)(xbp + (size_t)grow * LDH + cb + c4 * 4) = o;
;             const float t = red16(v.x * v.x + v.y * v.y + v.z * v.z + v.w * v.w);
;             if (c4 == 0) atomicAdd(ssqp + grow, t);
;           }
;         }
.LBB0_612:
	s_waitcnt lgkmcnt(0)
	ds_read_b128 v[2:5], v0 offset:3264
	v_add_co_u32_e32 v6, vcc, 0x7c000, v182
	s_waitcnt vmcnt(15) lgkmcnt(0)
	v_pk_fma_f32 v[2:3], v[2:3], 0.5, v[66:67] op_sel_hi:[1,0,1]
	v_addc_co_u32_e32 v7, vcc, 0, v183, vcc
	v_pk_fma_f32 v[4:5], v[4:5], 0.5, v[68:69] op_sel_hi:[1,0,1]
	s_and_b64 vcc, exec, s[10:11]
	global_store_dwordx4 v[6:7], v[2:5], off nt
	s_cbranch_vccnz .LBB0_477
	v_cvt_pk_bf16_f32 v8, v2, v3
	v_pk_mul_f32 v[2:3], v[2:3], v[2:3]
	v_cvt_pk_bf16_f32 v9, v4, v5
	v_add_f32_e32 v0, v2, v3
	v_and_b32_e32 v3, 64, v219
	s_nop 0
	v_add_u32_e32 v3, 64, v3
	v_pk_mul_f32 v[4:5], v[4:5], v[4:5]
	s_nop 0
	v_add_f32_e32 v0, v4, v0
	v_add_f32_e32 v0, v5, v0
	s_nop 1
	v_mov_b32_dpp v2, v0 quad_perm:[1,0,3,2] row_mask:0xf bank_mask:0xf
	v_or_b32_e32 v6, 0x7c, v178
	v_mad_i64_i32 v[10:11], s[0:1], v6, s66, v[180:181]
	global_store_dwordx2 v[10:11], v[8:9], off
	s_waitcnt lgkmcnt(0)
	v_add_f32_e32 v0, v0, v2
	s_nop 5
	v_mov_b32_dpp v2, v0 quad_perm:[2,3,0,1] row_mask:0xf bank_mask:0xf
	s_waitcnt lgkmcnt(0)
	v_add_f32_e32 v0, v0, v2
	s_nop 5
	v_mov_b32_dpp v2, v0 row_half_mirror row_mask:0xf bank_mask:0xf
	s_waitcnt lgkmcnt(0)
	v_add_f32_e32 v0, v0, v2
	v_xor_b32_e32 v2, 8, v219
	v_cmp_lt_i32_e32 vcc, v2, v3
	s_nop 3
	v_mov_b32_dpp v2, v0 row_mirror row_mask:0xf bank_mask:0xf
	s_and_saveexec_b64 s[0:1], s[8:9]
	s_cbranch_execz .LBB0_476
	v_ashrrev_i32_e32 v7, 31, v6
	s_waitcnt lgkmcnt(0)
	v_add_f32_e32 v0, v0, v2
	v_lshl_add_u64 v[2:3], v[6:7], 2, s[62:63]
	global_atomic_add_f32 v[2:3], v0, off
	s_branch .LBB0_476

; #define MFMA16(a, b, c) __builtin_amdgcn_mfma_f32_16x16x32_bf16((a), (b), (c), 0, 0, 0)
; template <class Epi>
; DI void gemm8_tile(const bf16_t* __restrict__ Ab, int lda, const bf16_t* __restrict__ Bb, int ldb, int K, int brow, int bcol, const Epi epi,
;                    bool staged, bool has_next, const bf16_t* __restrict__ Abn, const bf16_t* __restrict__ Bbn) {
;     ...
;       for (int m = 0; m < 8; ++m)
; #pragma unroll
;         for (int n = 0; n < 4; ++n) acc[m][n] = MFMA16(At[m], Bf[n], acc[m][n]);
;       __builtin_amdgcn_sched_barrier(0);
;     }
;     asm volatile("s_waitcnt vmcnt(0)" ::: "memory");
;     __syncthreads();
;   DI void run8(f32x4 (&acc)[8][4], int rb, int cb, int fr, int fq) const {
;     const int lane = fq * 16 + fr, wid = (int)(threadIdx.x >> 6);
;     const float sc = scale; bf16_t* const xbp = xb; float* const ssqp = ssq;
;     float* scr = (float*)(smem + G8_STAGE_B + wid * 4352);
;     const int prow = lane >> 4, c4 = lane & 15;
;     const float* xp = xin + (size_t)(rb + prow) * D + cb + c4 * 4;
;     float* op = xout + (size_t)(rb + prow) * D + cb + c4 * 4;
.LBB0_1317:
	v_lshrrev_b32_e32 v194, 4, v206
	s_waitcnt lgkmcnt(0)
	v_mfma_f32_16x16x32_bf16 v[200:203], v[58:61], v[2:5], v[126:129]
	v_mfma_f32_16x16x32_bf16 v[206:209], v[58:61], v[138:141], v[122:125]
	v_mfma_f32_16x16x32_bf16 v[212:215], v[58:61], v[182:185], v[118:121]
	v_mfma_f32_16x16x32_bf16 v[222:225], v[58:61], v[186:189], v[114:117]
	v_mfma_f32_16x16x32_bf16 v[150:153], v[50:53], v[2:5], v[110:113]
	v_mfma_f32_16x16x32_bf16 v[154:157], v[50:53], v[138:141], v[106:109]
	v_mfma_f32_16x16x32_bf16 v[142:145], v[50:53], v[182:185], v[102:105]
	v_mfma_f32_16x16x32_bf16 v[146:149], v[50:53], v[186:189], v[98:101]
	v_mfma_f32_16x16x32_bf16 v[118:121], v[42:45], v[2:5], v[94:97]
	v_mfma_f32_16x16x32_bf16 v[122:125], v[42:45], v[138:141], v[90:93]
	v_mfma_f32_16x16x32_bf16 v[110:113], v[42:45], v[182:185], v[86:89]
	v_mfma_f32_16x16x32_bf16 v[114:117], v[42:45], v[186:189], v[82:85]
	v_mfma_f32_16x16x32_bf16 v[86:89], v[34:37], v[2:5], v[78:81]
	v_mfma_f32_16x16x32_bf16 v[90:93], v[34:37], v[138:141], v[74:77]
	v_mfma_f32_16x16x32_bf16 v[78:81], v[34:37], v[182:185], v[70:73]
	v_mfma_f32_16x16x32_bf16 v[82:85], v[34:37], v[186:189], v[66:69]
	v_mfma_f32_16x16x32_bf16 v[58:61], v[26:29], v[2:5], v[62:65]
	v_mfma_f32_16x16x32_bf16 v[62:65], v[26:29], v[138:141], v[158:161]
	v_mfma_f32_16x16x32_bf16 v[50:53], v[26:29], v[182:185], v[54:57]
	v_mfma_f32_16x16x32_bf16 v[54:57], v[26:29], v[186:189], v[162:165]
	v_mfma_f32_16x16x32_bf16 v[42:45], v[18:21], v[2:5], v[46:49]
	v_mfma_f32_16x16x32_bf16 v[46:49], v[18:21], v[138:141], v[166:169]
	v_mfma_f32_16x16x32_bf16 v[34:37], v[18:21], v[182:185], v[38:41]
	v_mfma_f32_16x16x32_bf16 v[38:41], v[18:21], v[186:189], v[170:173]
	v_mfma_f32_16x16x32_bf16 v[26:29], v[10:13], v[2:5], v[30:33]
	v_mfma_f32_16x16x32_bf16 v[30:33], v[10:13], v[138:141], v[174:177]
	v_mfma_f32_16x16x32_bf16 v[18:21], v[10:13], v[182:185], v[22:25]
	v_mfma_f32_16x16x32_bf16 v[22:25], v[10:13], v[186:189], v[178:181]
	v_mfma_f32_16x16x32_bf16 v[10:13], v[190:193], v[2:5], v[14:17]
	v_mfma_f32_16x16x32_bf16 v[14:17], v[190:193], v[138:141], v[130:133]
	v_mfma_f32_16x16x32_bf16 v[2:5], v[190:193], v[182:185], v[6:9]
	v_mfma_f32_16x16x32_bf16 v[6:9], v[190:193], v[186:189], v[134:137]
	v_add_u32_e32 v0, s31, v205
	v_or_b32_e32 v178, v0, v194
	v_ashrrev_i32_e32 v179, 31, v178
	v_readlane_b32 s8, v254, 0
	v_lshl_or_b32 v182, v204, 6, s70
	v_lshlrev_b64 v[66:67], 12, v[178:179]
	v_readlane_b32 s10, v254, 2
	v_readlane_b32 s11, v254, 3
	v_ashrrev_i32_e32 v183, 31, v182
	v_lshlrev_b32_e32 v0, 2, v199
	v_lshl_add_u64 v[66:67], s[10:11], 0, v[66:67]
	v_lshl_add_u64 v[66:67], v[182:183], 2, v[66:67]
	v_lshl_add_u64 v[180:181], v[66:67], 0, v[0:1]
	s_movk_i32 s0, 0x4000
	v_add_co_u32_e32 v66, vcc, s0, v180
	s_mov_b32 s0, 0x8000
	s_nop 0
	v_addc_co_u32_e32 v67, vcc, 0, v181, vcc
	s_waitcnt vmcnt(0)
	s_waitcnt vmcnt(0)
	s_barrier
; DI unsigned pack_bf16(float lo, float hi) { f32x2 v = {lo, hi}; bf16v2 b = __builtin_convertvector(v, bf16v2); return __builtin_bit_cast(unsigned, b); }
; DI float red16(float v) { v += __shfl_xor(v, 1); v += __shfl_xor(v, 2); v += __shfl_xor(v, 4); v += __shfl_xor(v, 8); return v; }
;   DI void run8(f32x4 (&acc)[8][4], int rb, int cb, int fr, int fq) const {
;     ...
;     for (int mh = 0; mh < 2; ++mh) {
;       f32x4 xv[4][4];
; #pragma unroll
;       for (int mm = 0; mm < 4; ++mm)
; #pragma unroll
;         for (int ps = 0; ps < 4; ++ps) xv[mm][ps] = __builtin_nontemporal_load((const f32x4*)(xp + (size_t)((mh * 4 + mm) * 16 + ps * 4) * D));
;       __builtin_amdgcn_sched_barrier(0);
; #pragma unroll
;       for (int mm = 0; mm < 4; ++mm) {
;         const int m = mh * 4 + mm;
; #pragma unroll
;         for (int n = 0; n < 4; ++n)
; #pragma unroll
;           for (int j = 0; j < 4; ++j) scr[(fq * 4 + j) * 68 + n * 16 + fr] = acc[m][n][j];
;         __builtin_amdgcn_sched_barrier(0);
; #pragma unroll
;         for (int ps = 0; ps < 4; ++ps) {
;           const f32x4 a = *(const f32x4*)(scr + (ps * 4 + prow) * 68 + c4 * 4);
;           f32x4 v;
;           v.x = xv[mm][ps].x + a.x * sc; v.y = xv[mm][ps].y + a.y * sc; v.z = xv[mm][ps].z + a.z * sc; v.w = xv[mm][ps].w + a.w * sc;
;           const int grow = rb + m * 16 + ps * 4 + prow;
;           __builtin_nontemporal_store(v, (f32x4*)(op + (size_t)(m * 16 + ps * 4) * D));
;           if (xbp) {
;             u32x2 o; o.x = pack_bf16(v.x, v.y); o.y = pack_bf16(v.z, v.w);
;             *(u32x2*)(xbp + (size_t)grow * LDH + cb + c4 * 4) = o;
;             const float t = red16(v.x * v.x + v.y * v.y + v.z * v.z + v.w * v.w);
;             if (c4 == 0) atomicAdd(ssqp + grow, t);
;           }
	global_load_dwordx4 v[174:177], v[180:181], off nt
	global_load_dwordx4 v[170:173], v[66:67], off nt
	v_add_co_u32_e32 v66, vcc, s0, v180
	s_mov_b32 s0, 0xc000
	s_nop 0
	v_addc_co_u32_e32 v67, vcc, 0, v181, vcc
	v_add_co_u32_e32 v68, vcc, s0, v180
	s_mov_b32 s0, 0x14000
	s_nop 0
	v_addc_co_u32_e32 v69, vcc, 0, v181, vcc
	global_load_dwordx4 v[166:169], v[66:67], off nt
	global_load_dwordx4 v[162:165], v[68:69], off nt
	v_add_co_u32_e32 v66, vcc, s92, v180
	v_readlane_b32 s9, v254, 1
	s_nop 0
	v_addc_co_u32_e32 v67, vcc, 0, v181, vcc
	v_add_co_u32_e32 v68, vcc, s0, v180
	s_mov_b32 s0, 0x18000
	s_nop 0
	v_addc_co_u32_e32 v69, vcc, 0, v181, vcc
	global_load_dwordx4 v[158:161], v[66:67], off nt
	global_load_dwordx4 v[138:141], v[68:69], off nt
	v_add_co_u32_e32 v66, vcc, s0, v180
	s_mov_b32 s0, 0x1c000
	s_nop 0
	v_addc_co_u32_e32 v67, vcc, 0, v181, vcc
	v_add_co_u32_e32 v68, vcc, s0, v180
	s_mov_b32 s0, 0x20000
	s_nop 0
	v_addc_co_u32_e32 v69, vcc, 0, v181, vcc
	global_load_dwordx4 v[134:137], v[66:67], off nt
	global_load_dwordx4 v[130:133], v[68:69], off nt
	v_add_co_u32_e32 v66, vcc, s0, v180
	s_mov_b32 s0, 0x24000
	s_nop 0
	v_addc_co_u32_e32 v67, vcc, 0, v181, vcc
	v_add_co_u32_e32 v68, vcc, s0, v180
	s_mov_b32 s0, 0x28000
	s_nop 0
	v_addc_co_u32_e32 v69, vcc, 0, v181, vcc
	global_load_dwordx4 v[126:129], v[66:67], off nt
	global_load_dwordx4 v[106:109], v[68:69], off nt
	v_add_co_u32_e32 v66, vcc, s0, v180
	s_mov_b32 s0, 0x2c000
	s_nop 0
	v_addc_co_u32_e32 v67, vcc, 0, v181, vcc
	v_add_co_u32_e32 v68, vcc, s0, v180
	s_mov_b32 s0, 0x30000
	s_nop 0
	v_addc_co_u32_e32 v69, vcc, 0, v181, vcc
	global_load_dwordx4 v[102:105], v[66:67], off nt
	global_load_dwordx4 v[98:101], v[68:69], off nt
	v_add_co_u32_e32 v66, vcc, s0, v180
	s_mov_b32 s0, 0x34000
	s_nop 0
	v_addc_co_u32_e32 v67, vcc, 0, v181, vcc
	v_add_co_u32_e32 v68, vcc, s0, v180
	s_mov_b32 s0, 0x38000
	s_nop 0
	v_addc_co_u32_e32 v69, vcc, 0, v181, vcc
	global_load_dwordx4 v[94:97], v[66:67], off nt
	global_load_dwordx4 v[74:77], v[68:69], off nt
	v_add_co_u32_e32 v66, vcc, s0, v180
	s_mov_b32 s0, 0x3c000
	s_nop 0
	v_addc_co_u32_e32 v67, vcc, 0, v181, vcc
	v_add_co_u32_e32 v68, vcc, s0, v180
	v_lshl_add_u32 v184, v198, 2, v218
	s_nop 0
	v_addc_co_u32_e32 v69, vcc, 0, v181, vcc
	global_load_dwordx4 v[70:73], v[66:67], off nt
	s_nop 0
	global_load_dwordx4 v[66:69], v[68:69], off nt
	v_lshl_add_u64 v[182:183], v[182:183], 1, s[50:51]
	v_lshlrev_b32_e32 v0, 1, v199
	v_mad_u32_u24 v185, v198, 12, v184
	v_lshl_add_u64 v[182:183], v[182:183], 0, v[0:1]
	v_cmp_eq_u32_e64 s[8:9], 0, v198
	v_mad_u32_u24 v184, v194, s88, v184
	ds_write2_b32 v184, v200, v206 offset1:16
	ds_write2_b32 v184, v201, v207 offset0:68 offset1:84
	ds_write2_b32 v184, v202, v208 offset0:136 offset1:152
	ds_write2_b32 v184, v203, v209 offset0:204 offset1:220
	ds_write2_b32 v184, v212, v222 offset0:32 offset1:48
	ds_write2_b32 v184, v213, v223 offset0:100 offset1:116
	ds_write2_b32 v184, v214, v224 offset0:168 offset1:184
	ds_write2_b32 v184, v215, v225 offset0:236 offset1:252
	s_movk_i32 s0, 0x110
	v_mad_u32_u24 v0, v194, s0, v185
	ds_read_b128 v[186:189], v0
	v_cndmask_b32_e64 v0, 0, 1, s[76:77]
	v_cmp_ne_u32_e64 s[10:11], 1, v0
	s_andn2_b64 vcc, exec, s[76:77]
	s_waitcnt vmcnt(15) lgkmcnt(0)
	v_pk_add_f32 v[176:177], v[176:177], v[188:189]
	v_pk_add_f32 v[174:175], v[174:175], v[186:187]
	global_store_dwordx4 v[180:181], v[174:177], off nt
	s_cbranch_vccnz .LBB0_1321
	v_cvt_pk_bf16_f32 v186, v174, v175
	v_pk_mul_f32 v[174:175], v[174:175], v[174:175]
	v_cvt_pk_bf16_f32 v187, v176, v177
	v_add_f32_e32 v0, v174, v175
	v_and_b32_e32 v175, 64, v219
	s_nop 0
	v_add_u32_e32 v175, 64, v175
	v_pk_mul_f32 v[176:177], v[176:177], v[176:177]
	s_nop 0
	v_add_f32_e32 v0, v176, v0
	v_add_f32_e32 v0, v177, v0
	s_nop 1
	v_mov_b32_dpp v174, v0 quad_perm:[1,0,3,2] row_mask:0xf bank_mask:0xf
	v_mad_i64_i32 v[188:189], s[0:1], v178, s66, v[182:183]
	global_store_dwordx2 v[188:189], v[186:187], off
	s_waitcnt lgkmcnt(0)
	v_add_f32_e32 v0, v0, v174
	s_nop 5
	v_mov_b32_dpp v174, v0 quad_perm:[2,3,0,1] row_mask:0xf bank_mask:0xf
	s_waitcnt lgkmcnt(0)
	v_add_f32_e32 v0, v0, v174
	s_nop 5
	v_mov_b32_dpp v174, v0 row_half_mirror row_mask:0xf bank_mask:0xf
	s_waitcnt lgkmcnt(0)
	v_add_f32_e32 v0, v0, v174
	v_xor_b32_e32 v174, 8, v219
	v_cmp_lt_i32_e32 vcc, v174, v175
	s_nop 3
	v_mov_b32_dpp v174, v0 row_mirror row_mask:0xf bank_mask:0xf
	s_and_saveexec_b64 s[0:1], s[8:9]
	s_cbranch_execz .LBB0_1320
	s_waitcnt lgkmcnt(0)
	v_add_f32_e32 v0, v0, v174
	v_lshl_add_u64 v[174:175], v[178:179], 2, s[60:61]
	global_atomic_add_f32 v[174:175], v0, off

; DI unsigned pack_bf16(float lo, float hi) { f32x2 v = {lo, hi}; bf16v2 b = __builtin_convertvector(v, bf16v2); return __builtin_bit_cast(unsigned, b); }
; DI float red16(float v) { v += __shfl_xor(v, 1); v += __shfl_xor(v, 2); v += __shfl_xor(v, 4); v += __shfl_xor(v, 8); return v; }
;   DI void run8(f32x4 (&acc)[8][4], int rb, int cb, int fr, int fq) const {
;     ...
;         for (int ps = 0; ps < 4; ++ps) {
;           const f32x4 a = *(const f32x4*)(scr + (ps * 4 + prow) * 68 + c4 * 4);
;           f32x4 v;
;           v.x = xv[mm][ps].x + a.x * sc; v.y = xv[mm][ps].y + a.y * sc; v.z = xv[mm][ps].z + a.z * sc; v.w = xv[mm][ps].w + a.w * sc;
;           const int grow = rb + m * 16 + ps * 4 + prow;
;           __builtin_nontemporal_store(v, (f32x4*)(op + (size_t)(m * 16 + ps * 4) * D));
;           if (xbp) {
;             u32x2 o; o.x = pack_bf16(v.x, v.y); o.y = pack_bf16(v.z, v.w);
;             *(u32x2*)(xbp + (size_t)grow * LDH + cb + c4 * 4) = o;
;             const float t = red16(v.x * v.x + v.y * v.y + v.z * v.z + v.w * v.w);
;             if (c4 == 0) atomicAdd(ssqp + grow, t);
;           }
.LBB0_1321:
	v_mul_u32_u24_e32 v0, 0x110, v194
	v_add_u32_e32 v0, v185, v0
	s_waitcnt lgkmcnt(0)
	ds_read_b128 v[174:177], v0 offset:1088
	s_mov_b64 s[0:1], 0x4000
	v_lshl_add_u64 v[186:187], v[180:181], 0, s[0:1]
	s_and_b64 vcc, exec, s[10:11]
	s_waitcnt vmcnt(15) lgkmcnt(0)
	v_pk_add_f32 v[172:173], v[172:173], v[176:177]
	v_pk_add_f32 v[170:171], v[170:171], v[174:175]
	global_store_dwordx4 v[186:187], v[170:173], off nt
	s_cbranch_vccnz .LBB0_1325
	v_pk_mul_f32 v[176:177], v[170:171], v[170:171]
	v_pk_mul_f32 v[174:175], v[172:173], v[172:173]
	v_add_f32_e32 v176, v176, v177
	v_add_f32_e32 v174, v174, v176
	v_and_b32_e32 v176, 64, v219
	v_add_f32_e32 v174, v175, v174
	s_nop 0
	v_add_u32_e32 v177, 64, v176
	s_nop 0
	v_cvt_pk_bf16_f32 v176, v170, v171
	v_xor_b32_e32 v171, 8, v219
	s_nop 1
	v_mov_b32_dpp v175, v174 quad_perm:[1,0,3,2] row_mask:0xf bank_mask:0xf
	s_waitcnt lgkmcnt(0)
	v_add_f32_e32 v174, v174, v175
	s_nop 5
	v_mov_b32_dpp v175, v174 quad_perm:[2,3,0,1] row_mask:0xf bank_mask:0xf
	s_waitcnt lgkmcnt(0)
	v_add_f32_e32 v175, v174, v175
	s_nop 5
	v_mov_b32_dpp v179, v175 row_half_mirror row_mask:0xf bank_mask:0xf
	v_cmp_lt_i32_e32 vcc, v171, v177
	v_or_b32_e32 v174, 4, v178
	v_cvt_pk_bf16_f32 v177, v172, v173
	s_nop 0
	s_waitcnt lgkmcnt(0)
	v_add_f32_e32 v170, v175, v179
	s_nop 1
	v_mov_b32_dpp v171, v170 row_mirror row_mask:0xf bank_mask:0xf
	v_mad_i64_i32 v[172:173], s[0:1], v174, s66, v[182:183]
	global_store_dwordx2 v[172:173], v[176:177], off
	s_and_saveexec_b64 s[0:1], s[8:9]
	s_cbranch_execz .LBB0_1324
	v_ashrrev_i32_e32 v175, 31, v174
	s_waitcnt lgkmcnt(0)
	v_add_f32_e32 v172, v170, v171
	v_lshl_add_u64 v[170:171], v[174:175], 2, s[60:61]
	global_atomic_add_f32 v[170:171], v172, off

; DI unsigned pack_bf16(float lo, float hi) { f32x2 v = {lo, hi}; bf16v2 b = __builtin_convertvector(v, bf16v2); return __builtin_bit_cast(unsigned, b); }
; DI float red16(float v) { v += __shfl_xor(v, 1); v += __shfl_xor(v, 2); v += __shfl_xor(v, 4); v += __shfl_xor(v, 8); return v; }
;   DI void run8(f32x4 (&acc)[8][4], int rb, int cb, int fr, int fq) const {
;     ...
;         for (int ps = 0; ps < 4; ++ps) {
;           const f32x4 a = *(const f32x4*)(scr + (ps * 4 + prow) * 68 + c4 * 4);
;           f32x4 v;
;           v.x = xv[mm][ps].x + a.x * sc; v.y = xv[mm][ps].y + a.y * sc; v.z = xv[mm][ps].z + a.z * sc; v.w = xv[mm][ps].w + a.w * sc;
;           const int grow = rb + m * 16 + ps * 4 + prow;
;           __builtin_nontemporal_store(v, (f32x4*)(op + (size_t)(m * 16 + ps * 4) * D));
;           if (xbp) {
;             u32x2 o; o.x = pack_bf16(v.x, v.y); o.y = pack_bf16(v.z, v.w);
;             *(u32x2*)(xbp + (size_t)grow * LDH + cb + c4 * 4) = o;
;             const float t = red16(v.x * v.x + v.y * v.y + v.z * v.z + v.w * v.w);
;             if (c4 == 0) atomicAdd(ssqp + grow, t);
;           }
.LBB0_1325:
	s_waitcnt lgkmcnt(0)
	ds_read_b128 v[170:173], v0 offset:2176
	v_lshl_add_u64 v[174:175], v[180:181], 0, s[82:83]
	s_and_b64 vcc, exec, s[10:11]
	s_waitcnt vmcnt(15) lgkmcnt(0)
	v_pk_add_f32 v[168:169], v[168:169], v[172:173]
	v_pk_add_f32 v[166:167], v[166:167], v[170:171]
	global_store_dwordx4 v[174:175], v[166:169], off nt
	s_cbranch_vccnz .LBB0_1329
	v_pk_mul_f32 v[172:173], v[166:167], v[166:167]
	v_pk_mul_f32 v[170:171], v[168:169], v[168:169]
	v_add_f32_e32 v172, v172, v173
	v_add_f32_e32 v170, v170, v172
	v_and_b32_e32 v172, 64, v219
	v_add_f32_e32 v170, v171, v170
	s_nop 0
	v_add_u32_e32 v173, 64, v172
	s_nop 0
	v_cvt_pk_bf16_f32 v172, v166, v167
	v_xor_b32_e32 v167, 8, v219
	s_nop 1
	v_mov_b32_dpp v171, v170 quad_perm:[1,0,3,2] row_mask:0xf bank_mask:0xf
	s_waitcnt lgkmcnt(0)
	v_add_f32_e32 v170, v170, v171
	s_nop 5
	v_mov_b32_dpp v171, v170 quad_perm:[2,3,0,1] row_mask:0xf bank_mask:0xf
	s_waitcnt lgkmcnt(0)
	v_add_f32_e32 v171, v170, v171
	s_nop 5
	v_mov_b32_dpp v174, v171 row_half_mirror row_mask:0xf bank_mask:0xf
	v_cmp_lt_i32_e32 vcc, v167, v173
	v_or_b32_e32 v170, 8, v178
	v_cvt_pk_bf16_f32 v173, v168, v169
	s_nop 0
	s_waitcnt lgkmcnt(0)
	v_add_f32_e32 v166, v171, v174
	s_nop 1
	v_mov_b32_dpp v167, v166 row_mirror row_mask:0xf bank_mask:0xf
	v_mad_i64_i32 v[168:169], s[0:1], v170, s66, v[182:183]
	global_store_dwordx2 v[168:169], v[172:173], off
	s_and_saveexec_b64 s[0:1], s[8:9]
	s_cbranch_execz .LBB0_1328
	v_ashrrev_i32_e32 v171, 31, v170
	s_waitcnt lgkmcnt(0)
	v_add_f32_e32 v168, v166, v167
	v_lshl_add_u64 v[166:167], v[170:171], 2, s[60:61]
	global_atomic_add_f32 v[166:167], v168, off

; DI unsigned pack_bf16(float lo, float hi) { f32x2 v = {lo, hi}; bf16v2 b = __builtin_convertvector(v, bf16v2); return __builtin_bit_cast(unsigned, b); }
; DI float red16(float v) { v += __shfl_xor(v, 1); v += __shfl_xor(v, 2); v += __shfl_xor(v, 4); v += __shfl_xor(v, 8); return v; }
;   DI void run8(f32x4 (&acc)[8][4], int rb, int cb, int fr, int fq) const {
;     ...
;         for (int ps = 0; ps < 4; ++ps) {
;           const f32x4 a = *(const f32x4*)(scr + (ps * 4 + prow) * 68 + c4 * 4);
;           f32x4 v;
;           v.x = xv[mm][ps].x + a.x * sc; v.y = xv[mm][ps].y + a.y * sc; v.z = xv[mm][ps].z + a.z * sc; v.w = xv[mm][ps].w + a.w * sc;
;           const int grow = rb + m * 16 + ps * 4 + prow;
;           __builtin_nontemporal_store(v, (f32x4*)(op + (size_t)(m * 16 + ps * 4) * D));
;           if (xbp) {
;             u32x2 o; o.x = pack_bf16(v.x, v.y); o.y = pack_bf16(v.z, v.w);
;             *(u32x2*)(xbp + (size_t)grow * LDH + cb + c4 * 4) = o;
;             const float t = red16(v.x * v.x + v.y * v.y + v.z * v.z + v.w * v.w);
;             if (c4 == 0) atomicAdd(ssqp + grow, t);
;           }
.LBB0_1329:
	s_waitcnt lgkmcnt(0)
	ds_read_b128 v[166:169], v0 offset:3264
	s_mov_b64 s[0:1], 0xc000
	v_lshl_add_u64 v[170:171], v[180:181], 0, s[0:1]
	s_and_b64 vcc, exec, s[10:11]
	s_waitcnt vmcnt(15) lgkmcnt(0)
	v_pk_add_f32 v[164:165], v[164:165], v[168:169]
	v_pk_add_f32 v[162:163], v[162:163], v[166:167]
	global_store_dwordx4 v[170:171], v[162:165], off nt
	s_cbranch_vccnz .LBB0_1333
	v_pk_mul_f32 v[168:169], v[162:163], v[162:163]
	v_pk_mul_f32 v[166:167], v[164:165], v[164:165]
	v_add_f32_e32 v168, v168, v169
	v_add_f32_e32 v166, v166, v168
	v_and_b32_e32 v168, 64, v219
	v_add_f32_e32 v166, v167, v166
	s_nop 0
	v_add_u32_e32 v169, 64, v168
	s_nop 0
	v_cvt_pk_bf16_f32 v168, v162, v163
	v_xor_b32_e32 v163, 8, v219
	s_nop 1
	v_mov_b32_dpp v167, v166 quad_perm:[1,0,3,2] row_mask:0xf bank_mask:0xf
	s_waitcnt lgkmcnt(0)
	v_add_f32_e32 v166, v166, v167
	s_nop 5
	v_mov_b32_dpp v167, v166 quad_perm:[2,3,0,1] row_mask:0xf bank_mask:0xf
	s_waitcnt lgkmcnt(0)
	v_add_f32_e32 v167, v166, v167
	s_nop 5
	v_mov_b32_dpp v170, v167 row_half_mirror row_mask:0xf bank_mask:0xf
	v_cmp_lt_i32_e32 vcc, v163, v169
	v_or_b32_e32 v166, 12, v178
	v_cvt_pk_bf16_f32 v169, v164, v165
	s_nop 0
	s_waitcnt lgkmcnt(0)
	v_add_f32_e32 v162, v167, v170
	s_nop 1
	v_mov_b32_dpp v163, v162 row_mirror row_mask:0xf bank_mask:0xf
	v_mad_i64_i32 v[164:165], s[0:1], v166, s66, v[182:183]
	global_store_dwordx2 v[164:165], v[168:169], off
	s_and_saveexec_b64 s[0:1], s[8:9]
	s_cbranch_execz .LBB0_1332
	v_ashrrev_i32_e32 v167, 31, v166
	s_waitcnt lgkmcnt(0)
	v_add_f32_e32 v164, v162, v163
	v_lshl_add_u64 v[162:163], v[166:167], 2, s[60:61]
	global_atomic_add_f32 v[162:163], v164, off

; DI unsigned pack_bf16(float lo, float hi) { f32x2 v = {lo, hi}; bf16v2 b = __builtin_convertvector(v, bf16v2); return __builtin_bit_cast(unsigned, b); }
; DI float red16(float v) { v += __shfl_xor(v, 1); v += __shfl_xor(v, 2); v += __shfl_xor(v, 4); v += __shfl_xor(v, 8); return v; }
;   DI void run8(f32x4 (&acc)[8][4], int rb, int cb, int fr, int fq) const {
;     ...
;         for (int n = 0; n < 4; ++n)
; #pragma unroll
;           for (int j = 0; j < 4; ++j) scr[(fq * 4 + j) * 68 + n * 16 + fr] = acc[m][n][j];
;         __builtin_amdgcn_sched_barrier(0);
; #pragma unroll
;         for (int ps = 0; ps < 4; ++ps) {
;           const f32x4 a = *(const f32x4*)(scr + (ps * 4 + prow) * 68 + c4 * 4);
;           f32x4 v;
;           v.x = xv[mm][ps].x + a.x * sc; v.y = xv[mm][ps].y + a.y * sc; v.z = xv[mm][ps].z + a.z * sc; v.w = xv[mm][ps].w + a.w * sc;
;           const int grow = rb + m * 16 + ps * 4 + prow;
;           __builtin_nontemporal_store(v, (f32x4*)(op + (size_t)(m * 16 + ps * 4) * D));
;           if (xbp) {
;             u32x2 o; o.x = pack_bf16(v.x, v.y); o.y = pack_bf16(v.z, v.w);
;             *(u32x2*)(xbp + (size_t)grow * LDH + cb + c4 * 4) = o;
;             const float t = red16(v.x * v.x + v.y * v.y + v.z * v.z + v.w * v.w);
;             if (c4 == 0) atomicAdd(ssqp + grow, t);
;           }
.LBB0_1333:
	s_mov_b64 s[0:1], 0x10000
	v_lshl_add_u64 v[164:165], v[180:181], 0, s[0:1]
	s_mov_b64 s[0:1], 0x14000
	s_waitcnt lgkmcnt(0)
	v_lshl_add_u64 v[162:163], v[180:181], 0, s[0:1]
	ds_write2_b32 v184, v150, v154 offset1:16
	ds_write2_b32 v184, v151, v155 offset0:68 offset1:84
	ds_write2_b32 v184, v152, v156 offset0:136 offset1:152
	ds_write2_b32 v184, v153, v157 offset0:204 offset1:220
	ds_write2_b32 v184, v142, v146 offset0:32 offset1:48
	ds_write2_b32 v184, v143, v147 offset0:100 offset1:116
	ds_write2_b32 v184, v144, v148 offset0:168 offset1:184
	ds_write2_b32 v184, v145, v149 offset0:236 offset1:252
	ds_read_b128 v[142:145], v0
	s_and_b64 vcc, exec, s[10:11]
	s_waitcnt vmcnt(15) lgkmcnt(0)
	v_pk_add_f32 v[144:145], v[160:161], v[144:145]
	v_pk_add_f32 v[142:143], v[158:159], v[142:143]
	global_store_dwordx4 v[164:165], v[142:145], off nt
	s_cbranch_vccnz .LBB0_1444
	v_cvt_pk_bf16_f32 v148, v142, v143
	v_pk_mul_f32 v[142:143], v[142:143], v[142:143]
	v_cvt_pk_bf16_f32 v149, v144, v145
	v_pk_mul_f32 v[144:145], v[144:145], v[144:145]
	v_add_f32_e32 v142, v142, v143
	v_add_f32_e32 v142, v144, v142
	v_and_b32_e32 v144, 64, v219
	v_add_f32_e32 v143, v145, v142
	v_xor_b32_e32 v142, 1, v219
	v_add_u32_e32 v145, 64, v144
	v_cmp_lt_i32_e32 vcc, v142, v145
	v_or_b32_e32 v146, 16, v178
	v_mad_i64_i32 v[150:151], s[0:1], v146, s66, v[182:183]
	v_cndmask_b32_e32 v142, v219, v142, vcc
	v_lshlrev_b32_e32 v142, 2, v142
	v_mov_b32_dpp v144, v143 quad_perm:[1,0,3,2] row_mask:0xf bank_mask:0xf
	global_store_dwordx2 v[150:151], v[148:149], off
	s_waitcnt lgkmcnt(0)
	v_add_f32_e32 v144, v143, v144
	v_xor_b32_e32 v143, 2, v219
	v_cmp_lt_i32_e32 vcc, v143, v145
	s_nop 1
	v_cndmask_b32_e32 v143, v219, v143, vcc
	v_lshlrev_b32_e32 v143, 2, v143
	v_mov_b32_dpp v147, v144 quad_perm:[2,3,0,1] row_mask:0xf bank_mask:0xf
	s_waitcnt lgkmcnt(0)
	v_add_f32_e32 v147, v144, v147
	v_xor_b32_e32 v144, 4, v219
	v_cmp_lt_i32_e32 vcc, v144, v145
	s_nop 1
	v_cndmask_b32_e32 v144, v219, v144, vcc
	v_lshlrev_b32_e32 v144, 2, v144
	v_mov_b32_dpp v148, v147 row_half_mirror row_mask:0xf bank_mask:0xf
	s_waitcnt lgkmcnt(0)
	v_add_f32_e32 v148, v147, v148
	v_xor_b32_e32 v147, 8, v219
	v_cmp_lt_i32_e32 vcc, v147, v145
	s_nop 1
	v_cndmask_b32_e32 v145, v219, v147, vcc
	v_lshlrev_b32_e32 v145, 2, v145
	v_mov_b32_dpp v149, v148 row_mirror row_mask:0xf bank_mask:0xf
	s_and_saveexec_b64 s[0:1], s[8:9]
	s_cbranch_execz .LBB0_1336
	v_ashrrev_i32_e32 v147, 31, v146
	s_waitcnt lgkmcnt(0)
	v_add_f32_e32 v148, v148, v149
	v_lshl_add_u64 v[146:147], v[146:147], 2, s[60:61]
	global_atomic_add_f32 v[146:147], v148, off

; DI unsigned pack_bf16(float lo, float hi) { f32x2 v = {lo, hi}; bf16v2 b = __builtin_convertvector(v, bf16v2); return __builtin_bit_cast(unsigned, b); }
; DI float red16(float v) { v += __shfl_xor(v, 1); v += __shfl_xor(v, 2); v += __shfl_xor(v, 4); v += __shfl_xor(v, 8); return v; }
;   DI void run8(f32x4 (&acc)[8][4], int rb, int cb, int fr, int fq) const {
;     ...
;         for (int ps = 0; ps < 4; ++ps) {
;           const f32x4 a = *(const f32x4*)(scr + (ps * 4 + prow) * 68 + c4 * 4);
;           f32x4 v;
;           v.x = xv[mm][ps].x + a.x * sc; v.y = xv[mm][ps].y + a.y * sc; v.z = xv[mm][ps].z + a.z * sc; v.w = xv[mm][ps].w + a.w * sc;
;           const int grow = rb + m * 16 + ps * 4 + prow;
;           __builtin_nontemporal_store(v, (f32x4*)(op + (size_t)(m * 16 + ps * 4) * D));
;           if (xbp) {
;             u32x2 o; o.x = pack_bf16(v.x, v.y); o.y = pack_bf16(v.z, v.w);
;             *(u32x2*)(xbp + (size_t)grow * LDH + cb + c4 * 4) = o;
;             const float t = red16(v.x * v.x + v.y * v.y + v.z * v.z + v.w * v.w);
;             if (c4 == 0) atomicAdd(ssqp + grow, t);
;           }
.LBB0_1340:
	s_waitcnt vmcnt(15)
	ds_read_b128 v[140:143], v0 offset:2176
	s_mov_b64 s[0:1], 0x18000
	s_waitcnt lgkmcnt(1)
	v_lshl_add_u64 v[144:145], v[180:181], 0, s[0:1]
	s_mov_b64 s[0:1], 0x1c000
	v_lshl_add_u64 v[138:139], v[180:181], 0, s[0:1]
	s_waitcnt vmcnt(14) lgkmcnt(0)
	v_pk_add_f32 v[136:137], v[136:137], v[142:143]
	v_pk_add_f32 v[134:135], v[134:135], v[140:141]
	s_and_b64 vcc, exec, s[10:11]
	global_store_dwordx4 v[144:145], v[134:137], off nt
	s_cbranch_vccnz .LBB0_1445
	v_pk_mul_f32 v[142:143], v[134:135], v[134:135]
	v_pk_mul_f32 v[140:141], v[136:137], v[136:137]
	v_add_f32_e32 v142, v142, v143
	v_add_f32_e32 v140, v140, v142
	v_add_f32_e32 v140, v141, v140
	v_and_b32_e32 v141, 64, v219
	v_xor_b32_e32 v143, 1, v219
	v_add_u32_e32 v142, 64, v141
	s_nop 0
	v_xor_b32_e32 v145, 2, v219
	v_xor_b32_e32 v144, 4, v219
	s_nop 1
	v_mov_b32_dpp v141, v140 quad_perm:[1,0,3,2] row_mask:0xf bank_mask:0xf
	s_nop 0
	v_cvt_pk_bf16_f32 v148, v134, v135
	v_cvt_pk_bf16_f32 v149, v136, v137
	s_waitcnt lgkmcnt(0)
	v_add_f32_e32 v140, v140, v141
	s_nop 1
	v_mov_b32_dpp v141, v140 quad_perm:[2,3,0,1] row_mask:0xf bank_mask:0xf
	s_nop 0
	s_waitcnt lgkmcnt(0)
	v_add_f32_e32 v141, v140, v141
	s_nop 1
	v_mov_b32_dpp v146, v141 row_half_mirror row_mask:0xf bank_mask:0xf
	v_or_b32_e32 v140, 24, v178
	v_mad_i64_i32 v[136:137], s[0:1], v140, s66, v[182:183]
	global_store_dwordx2 v[136:137], v[148:149], off
	s_waitcnt lgkmcnt(0)
	v_add_f32_e32 v134, v141, v146
	v_xor_b32_e32 v146, 8, v219
	v_cmp_lt_i32_e32 vcc, v146, v142
	s_nop 3
	v_mov_b32_dpp v135, v134 row_mirror row_mask:0xf bank_mask:0xf
	s_and_saveexec_b64 s[0:1], s[8:9]
	s_cbranch_execz .LBB0_1343
	v_ashrrev_i32_e32 v141, 31, v140
	s_waitcnt lgkmcnt(0)
	v_add_f32_e32 v136, v134, v135
	v_lshl_add_u64 v[134:135], v[140:141], 2, s[60:61]
	global_atomic_add_f32 v[134:135], v136, off

; DI unsigned pack_bf16(float lo, float hi) { f32x2 v = {lo, hi}; bf16v2 b = __builtin_convertvector(v, bf16v2); return __builtin_bit_cast(unsigned, b); }
; DI float red16(float v) { v += __shfl_xor(v, 1); v += __shfl_xor(v, 2); v += __shfl_xor(v, 4); v += __shfl_xor(v, 8); return v; }
;   DI void run8(f32x4 (&acc)[8][4], int rb, int cb, int fr, int fq) const {
;     ...
;         for (int n = 0; n < 4; ++n)
; #pragma unroll
;           for (int j = 0; j < 4; ++j) scr[(fq * 4 + j) * 68 + n * 16 + fr] = acc[m][n][j];
;         __builtin_amdgcn_sched_barrier(0);
; #pragma unroll
;         for (int ps = 0; ps < 4; ++ps) {
;           const f32x4 a = *(const f32x4*)(scr + (ps * 4 + prow) * 68 + c4 * 4);
;           f32x4 v;
;           v.x = xv[mm][ps].x + a.x * sc; v.y = xv[mm][ps].y + a.y * sc; v.z = xv[mm][ps].z + a.z * sc; v.w = xv[mm][ps].w + a.w * sc;
;           const int grow = rb + m * 16 + ps * 4 + prow;
;           __builtin_nontemporal_store(v, (f32x4*)(op + (size_t)(m * 16 + ps * 4) * D));
;           if (xbp) {
;             u32x2 o; o.x = pack_bf16(v.x, v.y); o.y = pack_bf16(v.z, v.w);
;             *(u32x2*)(xbp + (size_t)grow * LDH + cb + c4 * 4) = o;
;             const float t = red16(v.x * v.x + v.y * v.y + v.z * v.z + v.w * v.w);
;             if (c4 == 0) atomicAdd(ssqp + grow, t);
;           }
.LBB0_1349:
	s_mov_b64 s[0:1], 0x20000
	s_waitcnt vmcnt(14)
	v_lshl_add_u64 v[132:133], v[180:181], 0, s[0:1]
	s_mov_b64 s[0:1], 0x24000
	v_lshl_add_u64 v[130:131], v[180:181], 0, s[0:1]
	ds_write2_b32 v184, v118, v122 offset1:16
	ds_write2_b32 v184, v119, v123 offset0:68 offset1:84
	ds_write2_b32 v184, v120, v124 offset0:136 offset1:152
	ds_write2_b32 v184, v121, v125 offset0:204 offset1:220
	ds_write2_b32 v184, v110, v114 offset0:32 offset1:48
	ds_write2_b32 v184, v111, v115 offset0:100 offset1:116
	ds_write2_b32 v184, v112, v116 offset0:168 offset1:184
	ds_write2_b32 v184, v113, v117 offset0:236 offset1:252
	ds_read_b128 v[110:113], v0
	s_and_b64 vcc, exec, s[10:11]
	s_waitcnt vmcnt(13) lgkmcnt(0)
	v_pk_add_f32 v[112:113], v[128:129], v[112:113]
	v_pk_add_f32 v[110:111], v[126:127], v[110:111]
	global_store_dwordx4 v[132:133], v[110:113], off nt
	s_cbranch_vccnz .LBB0_1446
	v_pk_mul_f32 v[116:117], v[110:111], v[110:111]
	v_pk_mul_f32 v[114:115], v[112:113], v[112:113]
	v_add_f32_e32 v116, v116, v117
	v_add_f32_e32 v114, v114, v116
	v_and_b32_e32 v116, 64, v219
	v_add_f32_e32 v114, v115, v114
	v_xor_b32_e32 v115, 1, v219
	v_add_u32_e32 v119, 64, v116
	v_cmp_lt_i32_e32 vcc, v115, v119
	v_cvt_pk_bf16_f32 v120, v110, v111
	v_xor_b32_e32 v111, 8, v219
	v_cndmask_b32_e32 v115, v219, v115, vcc
	v_lshlrev_b32_e32 v116, 2, v115
	v_mov_b32_dpp v115, v114 quad_perm:[1,0,3,2] row_mask:0xf bank_mask:0xf
	s_waitcnt lgkmcnt(0)
	v_add_f32_e32 v114, v114, v115
	v_xor_b32_e32 v115, 2, v219
	v_cmp_lt_i32_e32 vcc, v115, v119
	s_nop 1
	v_cndmask_b32_e32 v115, v219, v115, vcc
	v_lshlrev_b32_e32 v117, 2, v115
	v_mov_b32_dpp v115, v114 quad_perm:[2,3,0,1] row_mask:0xf bank_mask:0xf
	s_waitcnt lgkmcnt(0)
	v_add_f32_e32 v115, v114, v115
	v_xor_b32_e32 v114, 4, v219
	v_cmp_lt_i32_e32 vcc, v114, v119
	s_nop 1
	v_cndmask_b32_e32 v114, v219, v114, vcc
	v_lshlrev_b32_e32 v118, 2, v114
	v_mov_b32_dpp v121, v115 row_half_mirror row_mask:0xf bank_mask:0xf
	v_cmp_lt_i32_e32 vcc, v111, v119
	v_or_b32_e32 v114, 32, v178
	s_waitcnt lgkmcnt(0)
	v_add_f32_e32 v110, v115, v121
	v_cndmask_b32_e32 v111, v219, v111, vcc
	v_lshlrev_b32_e32 v111, 2, v111
	v_mov_b32_dpp v119, v110 row_mirror row_mask:0xf bank_mask:0xf
	v_cvt_pk_bf16_f32 v121, v112, v113
	v_mad_i64_i32 v[112:113], s[0:1], v114, s66, v[182:183]
	global_store_dwordx2 v[112:113], v[120:121], off
	s_and_saveexec_b64 s[0:1], s[8:9]
	s_cbranch_execz .LBB0_1352
	v_ashrrev_i32_e32 v115, 31, v114
	s_waitcnt lgkmcnt(0)
	v_add_f32_e32 v110, v110, v119
	v_lshl_add_u64 v[112:113], v[114:115], 2, s[60:61]
	global_atomic_add_f32 v[112:113], v110, off

; DI unsigned pack_bf16(float lo, float hi) { f32x2 v = {lo, hi}; bf16v2 b = __builtin_convertvector(v, bf16v2); return __builtin_bit_cast(unsigned, b); }
; DI float red16(float v) { v += __shfl_xor(v, 1); v += __shfl_xor(v, 2); v += __shfl_xor(v, 4); v += __shfl_xor(v, 8); return v; }
;   DI void run8(f32x4 (&acc)[8][4], int rb, int cb, int fr, int fq) const {
;     ...
;         for (int ps = 0; ps < 4; ++ps) {
;           const f32x4 a = *(const f32x4*)(scr + (ps * 4 + prow) * 68 + c4 * 4);
;           f32x4 v;
;           v.x = xv[mm][ps].x + a.x * sc; v.y = xv[mm][ps].y + a.y * sc; v.z = xv[mm][ps].z + a.z * sc; v.w = xv[mm][ps].w + a.w * sc;
;           const int grow = rb + m * 16 + ps * 4 + prow;
;           __builtin_nontemporal_store(v, (f32x4*)(op + (size_t)(m * 16 + ps * 4) * D));
;           if (xbp) {
;             u32x2 o; o.x = pack_bf16(v.x, v.y); o.y = pack_bf16(v.z, v.w);
;             *(u32x2*)(xbp + (size_t)grow * LDH + cb + c4 * 4) = o;
;             const float t = red16(v.x * v.x + v.y * v.y + v.z * v.z + v.w * v.w);
;             if (c4 == 0) atomicAdd(ssqp + grow, t);
;           }
.LBB0_1356:
	s_waitcnt vmcnt(13)
	ds_read_b128 v[108:111], v0 offset:2176
	s_mov_b64 s[0:1], 0x28000
	s_waitcnt lgkmcnt(1)
	v_lshl_add_u64 v[112:113], v[180:181], 0, s[0:1]
	s_mov_b64 s[0:1], 0x2c000
	v_lshl_add_u64 v[106:107], v[180:181], 0, s[0:1]
	s_waitcnt vmcnt(12) lgkmcnt(0)
	v_pk_add_f32 v[104:105], v[104:105], v[110:111]
	v_pk_add_f32 v[102:103], v[102:103], v[108:109]
	s_and_b64 vcc, exec, s[10:11]
	global_store_dwordx4 v[112:113], v[102:105], off nt
	s_cbranch_vccnz .LBB0_1447
	v_or_b32_e32 v108, 40, v178
	v_cvt_pk_bf16_f32 v110, v102, v103
	v_pk_mul_f32 v[102:103], v[102:103], v[102:103]
	v_cvt_pk_bf16_f32 v111, v104, v105
	v_mad_i64_i32 v[112:113], s[0:1], v108, s66, v[182:183]
	v_add_f32_e32 v102, v102, v103
	v_and_b32_e32 v103, 64, v219
	global_store_dwordx2 v[112:113], v[110:111], off
	v_xor_b32_e32 v111, 1, v219
	v_add_u32_e32 v110, 64, v103
	v_pk_mul_f32 v[104:105], v[104:105], v[104:105]
	s_nop 0
	v_add_f32_e32 v102, v104, v102
	v_add_f32_e32 v102, v105, v102
	s_nop 1
	v_mov_b32_dpp v103, v102 quad_perm:[1,0,3,2] row_mask:0xf bank_mask:0xf
	v_xor_b32_e32 v113, 2, v219
	s_nop 0
	v_xor_b32_e32 v112, 4, v219
	v_xor_b32_e32 v114, 8, v219
	s_waitcnt lgkmcnt(0)
	v_add_f32_e32 v102, v102, v103
	s_nop 1
	v_mov_b32_dpp v103, v102 quad_perm:[2,3,0,1] row_mask:0xf bank_mask:0xf
	s_nop 0
	s_waitcnt lgkmcnt(0)
	v_add_f32_e32 v102, v102, v103
	s_nop 1
	v_mov_b32_dpp v103, v102 row_half_mirror row_mask:0xf bank_mask:0xf
	v_cmp_lt_i32_e32 vcc, v114, v110
	s_waitcnt lgkmcnt(0)
	v_add_f32_e32 v102, v102, v103
	s_nop 1
	v_mov_b32_dpp v103, v102 row_mirror row_mask:0xf bank_mask:0xf
	s_and_saveexec_b64 s[0:1], s[8:9]
	s_cbranch_execz .LBB0_1359
	v_ashrrev_i32_e32 v109, 31, v108
	s_waitcnt lgkmcnt(0)
	v_add_f32_e32 v104, v102, v103
	v_lshl_add_u64 v[102:103], v[108:109], 2, s[60:61]
	global_atomic_add_f32 v[102:103], v104, off

; DI unsigned pack_bf16(float lo, float hi) { f32x2 v = {lo, hi}; bf16v2 b = __builtin_convertvector(v, bf16v2); return __builtin_bit_cast(unsigned, b); }
; DI float red16(float v) { v += __shfl_xor(v, 1); v += __shfl_xor(v, 2); v += __shfl_xor(v, 4); v += __shfl_xor(v, 8); return v; }
;   DI void run8(f32x4 (&acc)[8][4], int rb, int cb, int fr, int fq) const {
;     ...
;         for (int n = 0; n < 4; ++n)
; #pragma unroll
;           for (int j = 0; j < 4; ++j) scr[(fq * 4 + j) * 68 + n * 16 + fr] = acc[m][n][j];
;         __builtin_amdgcn_sched_barrier(0);
; #pragma unroll
;         for (int ps = 0; ps < 4; ++ps) {
;           const f32x4 a = *(const f32x4*)(scr + (ps * 4 + prow) * 68 + c4 * 4);
;           f32x4 v;
;           v.x = xv[mm][ps].x + a.x * sc; v.y = xv[mm][ps].y + a.y * sc; v.z = xv[mm][ps].z + a.z * sc; v.w = xv[mm][ps].w + a.w * sc;
;           const int grow = rb + m * 16 + ps * 4 + prow;
;           __builtin_nontemporal_store(v, (f32x4*)(op + (size_t)(m * 16 + ps * 4) * D));
;           if (xbp) {
;             u32x2 o; o.x = pack_bf16(v.x, v.y); o.y = pack_bf16(v.z, v.w);
;             *(u32x2*)(xbp + (size_t)grow * LDH + cb + c4 * 4) = o;
;             const float t = red16(v.x * v.x + v.y * v.y + v.z * v.z + v.w * v.w);
;             if (c4 == 0) atomicAdd(ssqp + grow, t);
;           }
.LBB0_1365:
	s_mov_b64 s[0:1], 0x30000
	s_waitcnt vmcnt(12)
	v_lshl_add_u64 v[100:101], v[180:181], 0, s[0:1]
	s_mov_b64 s[0:1], 0x34000
	v_lshl_add_u64 v[98:99], v[180:181], 0, s[0:1]
	ds_write2_b32 v184, v86, v90 offset1:16
	ds_write2_b32 v184, v87, v91 offset0:68 offset1:84
	ds_write2_b32 v184, v88, v92 offset0:136 offset1:152
	ds_write2_b32 v184, v89, v93 offset0:204 offset1:220
	ds_write2_b32 v184, v78, v82 offset0:32 offset1:48
	ds_write2_b32 v184, v79, v83 offset0:100 offset1:116
	ds_write2_b32 v184, v80, v84 offset0:168 offset1:184
	ds_write2_b32 v184, v81, v85 offset0:236 offset1:252
	ds_read_b128 v[78:81], v0
	s_and_b64 vcc, exec, s[10:11]
	s_waitcnt vmcnt(11) lgkmcnt(0)
	v_pk_add_f32 v[80:81], v[96:97], v[80:81]
	v_pk_add_f32 v[78:79], v[94:95], v[78:79]
	global_store_dwordx4 v[100:101], v[78:81], off nt
	s_cbranch_vccnz .LBB0_1448
	v_pk_mul_f32 v[84:85], v[78:79], v[78:79]
	v_pk_mul_f32 v[82:83], v[80:81], v[80:81]
	v_add_f32_e32 v84, v84, v85
	v_add_f32_e32 v82, v82, v84
	v_and_b32_e32 v84, 64, v219
	v_add_f32_e32 v82, v83, v82
	v_xor_b32_e32 v83, 1, v219
	v_add_u32_e32 v87, 64, v84
	v_cmp_lt_i32_e32 vcc, v83, v87
	v_cvt_pk_bf16_f32 v88, v78, v79
	v_xor_b32_e32 v79, 8, v219
	v_cndmask_b32_e32 v83, v219, v83, vcc
	v_lshlrev_b32_e32 v84, 2, v83
	v_mov_b32_dpp v83, v82 quad_perm:[1,0,3,2] row_mask:0xf bank_mask:0xf
	s_waitcnt lgkmcnt(0)
	v_add_f32_e32 v82, v82, v83
	v_xor_b32_e32 v83, 2, v219
	v_cmp_lt_i32_e32 vcc, v83, v87
	s_nop 1
	v_cndmask_b32_e32 v83, v219, v83, vcc
	v_lshlrev_b32_e32 v85, 2, v83
	v_mov_b32_dpp v83, v82 quad_perm:[2,3,0,1] row_mask:0xf bank_mask:0xf
	s_waitcnt lgkmcnt(0)
	v_add_f32_e32 v83, v82, v83
	v_xor_b32_e32 v82, 4, v219
	v_cmp_lt_i32_e32 vcc, v82, v87
	s_nop 1
	v_cndmask_b32_e32 v82, v219, v82, vcc
	v_lshlrev_b32_e32 v86, 2, v82
	v_mov_b32_dpp v89, v83 row_half_mirror row_mask:0xf bank_mask:0xf
	v_cmp_lt_i32_e32 vcc, v79, v87
	v_or_b32_e32 v82, 48, v178
	s_waitcnt lgkmcnt(0)
	v_add_f32_e32 v78, v83, v89
	v_cndmask_b32_e32 v79, v219, v79, vcc
	v_lshlrev_b32_e32 v79, 2, v79
	v_mov_b32_dpp v87, v78 row_mirror row_mask:0xf bank_mask:0xf
	v_cvt_pk_bf16_f32 v89, v80, v81
	v_mad_i64_i32 v[80:81], s[0:1], v82, s66, v[182:183]
	global_store_dwordx2 v[80:81], v[88:89], off
	s_and_saveexec_b64 s[0:1], s[8:9]
	s_cbranch_execz .LBB0_1368
	v_ashrrev_i32_e32 v83, 31, v82
	s_waitcnt lgkmcnt(0)
	v_add_f32_e32 v78, v78, v87
	v_lshl_add_u64 v[80:81], v[82:83], 2, s[60:61]
	global_atomic_add_f32 v[80:81], v78, off

; DI unsigned pack_bf16(float lo, float hi) { f32x2 v = {lo, hi}; bf16v2 b = __builtin_convertvector(v, bf16v2); return __builtin_bit_cast(unsigned, b); }
; DI float red16(float v) { v += __shfl_xor(v, 1); v += __shfl_xor(v, 2); v += __shfl_xor(v, 4); v += __shfl_xor(v, 8); return v; }
;   DI void run8(f32x4 (&acc)[8][4], int rb, int cb, int fr, int fq) const {
;     ...
;         for (int ps = 0; ps < 4; ++ps) {
;           const f32x4 a = *(const f32x4*)(scr + (ps * 4 + prow) * 68 + c4 * 4);
;           f32x4 v;
;           v.x = xv[mm][ps].x + a.x * sc; v.y = xv[mm][ps].y + a.y * sc; v.z = xv[mm][ps].z + a.z * sc; v.w = xv[mm][ps].w + a.w * sc;
;           const int grow = rb + m * 16 + ps * 4 + prow;
;           __builtin_nontemporal_store(v, (f32x4*)(op + (size_t)(m * 16 + ps * 4) * D));
;           if (xbp) {
;             u32x2 o; o.x = pack_bf16(v.x, v.y); o.y = pack_bf16(v.z, v.w);
;             *(u32x2*)(xbp + (size_t)grow * LDH + cb + c4 * 4) = o;
;             const float t = red16(v.x * v.x + v.y * v.y + v.z * v.z + v.w * v.w);
;             if (c4 == 0) atomicAdd(ssqp + grow, t);
;           }
.LBB0_1372:
	s_waitcnt vmcnt(11)
	ds_read_b128 v[76:79], v0 offset:2176
	s_mov_b64 s[0:1], 0x38000
	s_waitcnt lgkmcnt(1)
	v_lshl_add_u64 v[80:81], v[180:181], 0, s[0:1]
	s_mov_b64 s[0:1], 0x3c000
	v_lshl_add_u64 v[74:75], v[180:181], 0, s[0:1]
	s_waitcnt vmcnt(10) lgkmcnt(0)
	v_pk_add_f32 v[72:73], v[72:73], v[78:79]
	v_pk_add_f32 v[70:71], v[70:71], v[76:77]
	s_and_b64 vcc, exec, s[10:11]
	global_store_dwordx4 v[80:81], v[70:73], off nt
	s_cbranch_vccnz .LBB0_1449
	v_or_b32_e32 v76, 56, v178
	v_cvt_pk_bf16_f32 v78, v70, v71
	v_pk_mul_f32 v[70:71], v[70:71], v[70:71]
	v_cvt_pk_bf16_f32 v79, v72, v73
	v_mad_i64_i32 v[80:81], s[0:1], v76, s66, v[182:183]
	v_add_f32_e32 v70, v70, v71
	v_and_b32_e32 v71, 64, v219
	global_store_dwordx2 v[80:81], v[78:79], off
	v_xor_b32_e32 v79, 1, v219
	v_add_u32_e32 v78, 64, v71
	v_pk_mul_f32 v[72:73], v[72:73], v[72:73]
	s_nop 0
	v_add_f32_e32 v70, v72, v70
	v_add_f32_e32 v70, v73, v70
	s_nop 1
	v_mov_b32_dpp v71, v70 quad_perm:[1,0,3,2] row_mask:0xf bank_mask:0xf
	v_xor_b32_e32 v81, 2, v219
	s_nop 0
	v_xor_b32_e32 v80, 4, v219
	v_xor_b32_e32 v82, 8, v219
	s_waitcnt lgkmcnt(0)
	v_add_f32_e32 v70, v70, v71
	s_nop 1
	v_mov_b32_dpp v71, v70 quad_perm:[2,3,0,1] row_mask:0xf bank_mask:0xf
	s_nop 0
	s_waitcnt lgkmcnt(0)
	v_add_f32_e32 v70, v70, v71
	s_nop 1
	v_mov_b32_dpp v71, v70 row_half_mirror row_mask:0xf bank_mask:0xf
	v_cmp_lt_i32_e32 vcc, v82, v78
	s_waitcnt lgkmcnt(0)
	v_add_f32_e32 v70, v70, v71
	s_nop 1
	v_mov_b32_dpp v71, v70 row_mirror row_mask:0xf bank_mask:0xf
	s_and_saveexec_b64 s[0:1], s[8:9]
	s_cbranch_execz .LBB0_1375
	v_ashrrev_i32_e32 v77, 31, v76
	s_waitcnt lgkmcnt(0)
	v_add_f32_e32 v72, v70, v71
	v_lshl_add_u64 v[70:71], v[76:77], 2, s[60:61]
	global_atomic_add_f32 v[70:71], v72, off

; DI unsigned pack_bf16(float lo, float hi) { f32x2 v = {lo, hi}; bf16v2 b = __builtin_convertvector(v, bf16v2); return __builtin_bit_cast(unsigned, b); }
; DI float red16(float v) { v += __shfl_xor(v, 1); v += __shfl_xor(v, 2); v += __shfl_xor(v, 4); v += __shfl_xor(v, 8); return v; }
;   DI void run8(f32x4 (&acc)[8][4], int rb, int cb, int fr, int fq) const {
;     ...
;     for (int mh = 0; mh < 2; ++mh) {
;       f32x4 xv[4][4];
; #pragma unroll
;       for (int mm = 0; mm < 4; ++mm)
; #pragma unroll
;         for (int ps = 0; ps < 4; ++ps) xv[mm][ps] = __builtin_nontemporal_load((const f32x4*)(xp + (size_t)((mh * 4 + mm) * 16 + ps * 4) * D));
;       __builtin_amdgcn_sched_barrier(0);
; #pragma unroll
;       for (int mm = 0; mm < 4; ++mm) {
;         const int m = mh * 4 + mm;
; #pragma unroll
;         for (int n = 0; n < 4; ++n)
; #pragma unroll
;           for (int j = 0; j < 4; ++j) scr[(fq * 4 + j) * 68 + n * 16 + fr] = acc[m][n][j];
;         __builtin_amdgcn_sched_barrier(0);
; #pragma unroll
;         for (int ps = 0; ps < 4; ++ps) {
;           const f32x4 a = *(const f32x4*)(scr + (ps * 4 + prow) * 68 + c4 * 4);
;           f32x4 v;
;           v.x = xv[mm][ps].x + a.x * sc; v.y = xv[mm][ps].y + a.y * sc; v.z = xv[mm][ps].z + a.z * sc; v.w = xv[mm][ps].w + a.w * sc;
;           const int grow = rb + m * 16 + ps * 4 + prow;
;           __builtin_nontemporal_store(v, (f32x4*)(op + (size_t)(m * 16 + ps * 4) * D));
;           if (xbp) {
;             u32x2 o; o.x = pack_bf16(v.x, v.y); o.y = pack_bf16(v.z, v.w);
;             *(u32x2*)(xbp + (size_t)grow * LDH + cb + c4 * 4) = o;
;             const float t = red16(v.x * v.x + v.y * v.y + v.z * v.z + v.w * v.w);
;             if (c4 == 0) atomicAdd(ssqp + grow, t);
;           }
.LBB0_1381:
	v_add_co_u32_e32 v132, vcc, 0x40000, v180
	s_mov_b64 s[0:1], 0x44000
	s_nop 0
	v_addc_co_u32_e32 v133, vcc, 0, v181, vcc
	s_waitcnt vmcnt(10)
	v_add_co_u32_e32 v66, vcc, 0x44000, v180
	v_lshl_add_u64 v[126:127], v[180:181], 0, s[0:1]
	s_nop 0
	v_addc_co_u32_e32 v67, vcc, 0, v181, vcc
	global_load_dwordx4 v[128:131], v[132:133], off nt
	global_load_dwordx4 v[122:125], v[66:67], off nt
	v_add_co_u32_e32 v66, vcc, 0x48000, v180
	s_nop 1
	v_addc_co_u32_e32 v67, vcc, 0, v181, vcc
	v_add_co_u32_e32 v68, vcc, 0x4c000, v180
	s_nop 1
	v_addc_co_u32_e32 v69, vcc, 0, v181, vcc
	global_load_dwordx4 v[118:121], v[66:67], off nt
	global_load_dwordx4 v[114:117], v[68:69], off nt
	v_add_co_u32_e32 v66, vcc, 0x50000, v180
	s_nop 1
	v_addc_co_u32_e32 v67, vcc, 0, v181, vcc
	v_add_co_u32_e32 v68, vcc, 0x54000, v180
	s_nop 1
	v_addc_co_u32_e32 v69, vcc, 0, v181, vcc
	global_load_dwordx4 v[110:113], v[66:67], off nt
	global_load_dwordx4 v[106:109], v[68:69], off nt
	v_add_co_u32_e32 v66, vcc, 0x58000, v180
	s_nop 1
	v_addc_co_u32_e32 v67, vcc, 0, v181, vcc
	v_add_co_u32_e32 v68, vcc, 0x5c000, v180
	s_nop 1
	v_addc_co_u32_e32 v69, vcc, 0, v181, vcc
	global_load_dwordx4 v[102:105], v[66:67], off nt
	global_load_dwordx4 v[98:101], v[68:69], off nt
	v_add_co_u32_e32 v66, vcc, 0x60000, v180
	s_nop 1
	v_addc_co_u32_e32 v67, vcc, 0, v181, vcc
	v_add_co_u32_e32 v68, vcc, 0x64000, v180
	s_nop 1
	v_addc_co_u32_e32 v69, vcc, 0, v181, vcc
	global_load_dwordx4 v[94:97], v[66:67], off nt
	global_load_dwordx4 v[90:93], v[68:69], off nt
	v_add_co_u32_e32 v66, vcc, 0x68000, v180
	s_nop 1
	v_addc_co_u32_e32 v67, vcc, 0, v181, vcc
	v_add_co_u32_e32 v68, vcc, 0x6c000, v180
	s_nop 1
	v_addc_co_u32_e32 v69, vcc, 0, v181, vcc
	global_load_dwordx4 v[86:89], v[66:67], off nt
	global_load_dwordx4 v[82:85], v[68:69], off nt
	v_add_co_u32_e32 v66, vcc, s68, v180
	s_nop 1
	v_addc_co_u32_e32 v67, vcc, 0, v181, vcc
	v_add_co_u32_e32 v68, vcc, 0x74000, v180
	s_nop 1
	v_addc_co_u32_e32 v69, vcc, 0, v181, vcc
	global_load_dwordx4 v[78:81], v[66:67], off nt
	global_load_dwordx4 v[74:77], v[68:69], off nt
	v_add_co_u32_e32 v66, vcc, 0x78000, v180
	s_nop 1
	v_addc_co_u32_e32 v67, vcc, 0, v181, vcc
	v_add_co_u32_e32 v68, vcc, 0x7c000, v180
	s_nop 1
	v_addc_co_u32_e32 v69, vcc, 0, v181, vcc
	s_waitcnt lgkmcnt(0)
	global_load_dwordx4 v[70:73], v[66:67], off nt
	s_nop 0
	global_load_dwordx4 v[66:69], v[68:69], off nt
	ds_write2_b32 v184, v58, v62 offset1:16
	ds_write2_b32 v184, v59, v63 offset0:68 offset1:84
	ds_write2_b32 v184, v60, v64 offset0:136 offset1:152
	ds_write2_b32 v184, v61, v65 offset0:204 offset1:220
	ds_write2_b32 v184, v50, v54 offset0:32 offset1:48
	ds_write2_b32 v184, v51, v55 offset0:100 offset1:116
	ds_write2_b32 v184, v52, v56 offset0:168 offset1:184
	ds_write2_b32 v184, v53, v57 offset0:236 offset1:252
	ds_read_b128 v[50:53], v0
	s_and_b64 vcc, exec, s[10:11]
	s_waitcnt vmcnt(15) lgkmcnt(0)
	v_pk_add_f32 v[52:53], v[130:131], v[52:53]
	v_pk_add_f32 v[50:51], v[128:129], v[50:51]
	global_store_dwordx4 v[132:133], v[50:53], off nt
	s_cbranch_vccnz .LBB0_1450
	v_pk_mul_f32 v[56:57], v[50:51], v[50:51]
	v_pk_mul_f32 v[54:55], v[52:53], v[52:53]
	v_add_f32_e32 v56, v56, v57
	v_add_f32_e32 v54, v54, v56
	v_and_b32_e32 v56, 64, v219
	v_add_f32_e32 v54, v55, v54
	v_xor_b32_e32 v55, 1, v219
	v_add_u32_e32 v59, 64, v56
	v_cmp_lt_i32_e32 vcc, v55, v59
	v_cvt_pk_bf16_f32 v60, v50, v51
	v_xor_b32_e32 v51, 8, v219
	v_cndmask_b32_e32 v55, v219, v55, vcc
	v_lshlrev_b32_e32 v56, 2, v55
	v_mov_b32_dpp v55, v54 quad_perm:[1,0,3,2] row_mask:0xf bank_mask:0xf
	s_waitcnt lgkmcnt(0)
	v_add_f32_e32 v54, v54, v55
	v_xor_b32_e32 v55, 2, v219
	v_cmp_lt_i32_e32 vcc, v55, v59
	s_nop 1
	v_cndmask_b32_e32 v55, v219, v55, vcc
	v_lshlrev_b32_e32 v57, 2, v55
	v_mov_b32_dpp v55, v54 quad_perm:[2,3,0,1] row_mask:0xf bank_mask:0xf
	s_waitcnt lgkmcnt(0)
	v_add_f32_e32 v55, v54, v55
	v_xor_b32_e32 v54, 4, v219
	v_cmp_lt_i32_e32 vcc, v54, v59
	s_nop 1
	v_cndmask_b32_e32 v54, v219, v54, vcc
	v_lshlrev_b32_e32 v58, 2, v54
	v_mov_b32_dpp v61, v55 row_half_mirror row_mask:0xf bank_mask:0xf
	v_cmp_lt_i32_e32 vcc, v51, v59
	v_or_b32_e32 v54, 64, v178
	s_waitcnt lgkmcnt(0)
	v_add_f32_e32 v50, v55, v61
	v_cndmask_b32_e32 v51, v219, v51, vcc
	v_lshlrev_b32_e32 v51, 2, v51
	v_mov_b32_dpp v59, v50 row_mirror row_mask:0xf bank_mask:0xf
	v_cvt_pk_bf16_f32 v61, v52, v53
	v_mad_i64_i32 v[52:53], s[0:1], v54, s66, v[182:183]
	global_store_dwordx2 v[52:53], v[60:61], off
	s_and_saveexec_b64 s[0:1], s[8:9]
	s_cbranch_execz .LBB0_1384
	v_ashrrev_i32_e32 v55, 31, v54
	s_waitcnt lgkmcnt(0)
	v_add_f32_e32 v50, v50, v59
	v_lshl_add_u64 v[52:53], v[54:55], 2, s[60:61]
	global_atomic_add_f32 v[52:53], v50, off

; DI unsigned pack_bf16(float lo, float hi) { f32x2 v = {lo, hi}; bf16v2 b = __builtin_convertvector(v, bf16v2); return __builtin_bit_cast(unsigned, b); }
; DI float red16(float v) { v += __shfl_xor(v, 1); v += __shfl_xor(v, 2); v += __shfl_xor(v, 4); v += __shfl_xor(v, 8); return v; }
;   DI void run8(f32x4 (&acc)[8][4], int rb, int cb, int fr, int fq) const {
;     ...
;         for (int ps = 0; ps < 4; ++ps) {
;           const f32x4 a = *(const f32x4*)(scr + (ps * 4 + prow) * 68 + c4 * 4);
;           f32x4 v;
;           v.x = xv[mm][ps].x + a.x * sc; v.y = xv[mm][ps].y + a.y * sc; v.z = xv[mm][ps].z + a.z * sc; v.w = xv[mm][ps].w + a.w * sc;
;           const int grow = rb + m * 16 + ps * 4 + prow;
;           __builtin_nontemporal_store(v, (f32x4*)(op + (size_t)(m * 16 + ps * 4) * D));
;           if (xbp) {
;             u32x2 o; o.x = pack_bf16(v.x, v.y); o.y = pack_bf16(v.z, v.w);
;             *(u32x2*)(xbp + (size_t)grow * LDH + cb + c4 * 4) = o;
;             const float t = red16(v.x * v.x + v.y * v.y + v.z * v.z + v.w * v.w);
;             if (c4 == 0) atomicAdd(ssqp + grow, t);
;           }
.LBB0_1388:
	s_waitcnt lgkmcnt(0)
	ds_read_b128 v[50:53], v0 offset:2176
	s_mov_b64 s[0:1], 0x48000
	v_lshl_add_u64 v[56:57], v[180:181], 0, s[0:1]
	s_mov_b64 s[0:1], 0x4c000
	v_lshl_add_u64 v[54:55], v[180:181], 0, s[0:1]
	s_waitcnt vmcnt(14) lgkmcnt(0)
	v_pk_add_f32 v[52:53], v[120:121], v[52:53]
	v_pk_add_f32 v[50:51], v[118:119], v[50:51]
	s_and_b64 vcc, exec, s[10:11]
	global_store_dwordx4 v[56:57], v[50:53], off nt
	s_cbranch_vccnz .LBB0_1451
	v_or_b32_e32 v56, 0x48, v178
	v_cvt_pk_bf16_f32 v58, v50, v51
	v_pk_mul_f32 v[50:51], v[50:51], v[50:51]
	v_cvt_pk_bf16_f32 v59, v52, v53
	v_mad_i64_i32 v[60:61], s[0:1], v56, s66, v[182:183]
	v_add_f32_e32 v50, v50, v51
	v_and_b32_e32 v51, 64, v219
	global_store_dwordx2 v[60:61], v[58:59], off
	v_xor_b32_e32 v59, 1, v219
	v_add_u32_e32 v58, 64, v51
	v_pk_mul_f32 v[52:53], v[52:53], v[52:53]
	s_nop 0
	v_add_f32_e32 v50, v52, v50
	v_add_f32_e32 v50, v53, v50
	s_nop 1
	v_mov_b32_dpp v51, v50 quad_perm:[1,0,3,2] row_mask:0xf bank_mask:0xf
	v_xor_b32_e32 v61, 2, v219
	s_nop 0
	v_xor_b32_e32 v60, 4, v219
	v_xor_b32_e32 v62, 8, v219
	s_waitcnt lgkmcnt(0)
	v_add_f32_e32 v50, v50, v51
	s_nop 1
	v_mov_b32_dpp v51, v50 quad_perm:[2,3,0,1] row_mask:0xf bank_mask:0xf
	s_nop 0
	s_waitcnt lgkmcnt(0)
	v_add_f32_e32 v50, v50, v51
	s_nop 1
	v_mov_b32_dpp v51, v50 row_half_mirror row_mask:0xf bank_mask:0xf
	v_cmp_lt_i32_e32 vcc, v62, v58
	s_waitcnt lgkmcnt(0)
	v_add_f32_e32 v50, v50, v51
	s_nop 1
	v_mov_b32_dpp v51, v50 row_mirror row_mask:0xf bank_mask:0xf
	s_and_saveexec_b64 s[0:1], s[8:9]
	s_cbranch_execz .LBB0_1391
	v_ashrrev_i32_e32 v57, 31, v56
	s_waitcnt lgkmcnt(0)
	v_add_f32_e32 v52, v50, v51
	v_lshl_add_u64 v[50:51], v[56:57], 2, s[60:61]
	global_atomic_add_f32 v[50:51], v52, off

; DI unsigned pack_bf16(float lo, float hi) { f32x2 v = {lo, hi}; bf16v2 b = __builtin_convertvector(v, bf16v2); return __builtin_bit_cast(unsigned, b); }
; DI float red16(float v) { v += __shfl_xor(v, 1); v += __shfl_xor(v, 2); v += __shfl_xor(v, 4); v += __shfl_xor(v, 8); return v; }
;   DI void run8(f32x4 (&acc)[8][4], int rb, int cb, int fr, int fq) const {
;     ...
;         for (int n = 0; n < 4; ++n)
; #pragma unroll
;           for (int j = 0; j < 4; ++j) scr[(fq * 4 + j) * 68 + n * 16 + fr] = acc[m][n][j];
;         __builtin_amdgcn_sched_barrier(0);
; #pragma unroll
;         for (int ps = 0; ps < 4; ++ps) {
;           const f32x4 a = *(const f32x4*)(scr + (ps * 4 + prow) * 68 + c4 * 4);
;           f32x4 v;
;           v.x = xv[mm][ps].x + a.x * sc; v.y = xv[mm][ps].y + a.y * sc; v.z = xv[mm][ps].z + a.z * sc; v.w = xv[mm][ps].w + a.w * sc;
;           const int grow = rb + m * 16 + ps * 4 + prow;
;           __builtin_nontemporal_store(v, (f32x4*)(op + (size_t)(m * 16 + ps * 4) * D));
;           if (xbp) {
;             u32x2 o; o.x = pack_bf16(v.x, v.y); o.y = pack_bf16(v.z, v.w);
;             *(u32x2*)(xbp + (size_t)grow * LDH + cb + c4 * 4) = o;
;             const float t = red16(v.x * v.x + v.y * v.y + v.z * v.z + v.w * v.w);
;             if (c4 == 0) atomicAdd(ssqp + grow, t);
;           }
.LBB0_1397:
	s_mov_b64 s[0:1], 0x50000
	s_nop 0
	v_lshl_add_u64 v[52:53], v[180:181], 0, s[0:1]
	s_mov_b64 s[0:1], 0x54000
	s_waitcnt lgkmcnt(0)
	v_lshl_add_u64 v[50:51], v[180:181], 0, s[0:1]
	ds_write2_b32 v184, v42, v46 offset1:16
	ds_write2_b32 v184, v43, v47 offset0:68 offset1:84
	ds_write2_b32 v184, v44, v48 offset0:136 offset1:152
	ds_write2_b32 v184, v45, v49 offset0:204 offset1:220
	ds_write2_b32 v184, v34, v38 offset0:32 offset1:48
	ds_write2_b32 v184, v35, v39 offset0:100 offset1:116
	ds_write2_b32 v184, v36, v40 offset0:168 offset1:184
	ds_write2_b32 v184, v37, v41 offset0:236 offset1:252
	ds_read_b128 v[34:37], v0
	s_and_b64 vcc, exec, s[10:11]
	s_waitcnt vmcnt(13) lgkmcnt(0)
	v_pk_add_f32 v[36:37], v[112:113], v[36:37]
	v_pk_add_f32 v[34:35], v[110:111], v[34:35]
	global_store_dwordx4 v[52:53], v[34:37], off nt
	s_cbranch_vccnz .LBB0_1452
	v_pk_mul_f32 v[40:41], v[34:35], v[34:35]
	v_pk_mul_f32 v[38:39], v[36:37], v[36:37]
	v_add_f32_e32 v40, v40, v41
	v_add_f32_e32 v38, v38, v40
	v_and_b32_e32 v40, 64, v219
	v_add_f32_e32 v38, v39, v38
	v_xor_b32_e32 v39, 1, v219
	v_add_u32_e32 v43, 64, v40
	v_cmp_lt_i32_e32 vcc, v39, v43
	v_cvt_pk_bf16_f32 v44, v34, v35
	v_xor_b32_e32 v35, 8, v219
	v_cndmask_b32_e32 v39, v219, v39, vcc
	v_lshlrev_b32_e32 v40, 2, v39
	v_mov_b32_dpp v39, v38 quad_perm:[1,0,3,2] row_mask:0xf bank_mask:0xf
	s_waitcnt lgkmcnt(0)
	v_add_f32_e32 v38, v38, v39
	v_xor_b32_e32 v39, 2, v219
	v_cmp_lt_i32_e32 vcc, v39, v43
	s_nop 1
	v_cndmask_b32_e32 v39, v219, v39, vcc
	v_lshlrev_b32_e32 v41, 2, v39
	v_mov_b32_dpp v39, v38 quad_perm:[2,3,0,1] row_mask:0xf bank_mask:0xf
	s_waitcnt lgkmcnt(0)
	v_add_f32_e32 v39, v38, v39
	v_xor_b32_e32 v38, 4, v219
	v_cmp_lt_i32_e32 vcc, v38, v43
	s_nop 1
	v_cndmask_b32_e32 v38, v219, v38, vcc
	v_lshlrev_b32_e32 v42, 2, v38
	v_mov_b32_dpp v45, v39 row_half_mirror row_mask:0xf bank_mask:0xf
	v_cmp_lt_i32_e32 vcc, v35, v43
	v_or_b32_e32 v38, 0x50, v178
	s_waitcnt lgkmcnt(0)
	v_add_f32_e32 v34, v39, v45
	v_cndmask_b32_e32 v35, v219, v35, vcc
	v_lshlrev_b32_e32 v35, 2, v35
	v_mov_b32_dpp v43, v34 row_mirror row_mask:0xf bank_mask:0xf
	v_cvt_pk_bf16_f32 v45, v36, v37
	v_mad_i64_i32 v[36:37], s[0:1], v38, s66, v[182:183]
	global_store_dwordx2 v[36:37], v[44:45], off
	s_and_saveexec_b64 s[0:1], s[8:9]
	s_cbranch_execz .LBB0_1400
	v_ashrrev_i32_e32 v39, 31, v38
	s_waitcnt lgkmcnt(0)
	v_add_f32_e32 v34, v34, v43
	v_lshl_add_u64 v[36:37], v[38:39], 2, s[60:61]
	global_atomic_add_f32 v[36:37], v34, off

; DI unsigned pack_bf16(float lo, float hi) { f32x2 v = {lo, hi}; bf16v2 b = __builtin_convertvector(v, bf16v2); return __builtin_bit_cast(unsigned, b); }
; DI float red16(float v) { v += __shfl_xor(v, 1); v += __shfl_xor(v, 2); v += __shfl_xor(v, 4); v += __shfl_xor(v, 8); return v; }
;   DI void run8(f32x4 (&acc)[8][4], int rb, int cb, int fr, int fq) const {
;     ...
;         for (int ps = 0; ps < 4; ++ps) {
;           const f32x4 a = *(const f32x4*)(scr + (ps * 4 + prow) * 68 + c4 * 4);
;           f32x4 v;
;           v.x = xv[mm][ps].x + a.x * sc; v.y = xv[mm][ps].y + a.y * sc; v.z = xv[mm][ps].z + a.z * sc; v.w = xv[mm][ps].w + a.w * sc;
;           const int grow = rb + m * 16 + ps * 4 + prow;
;           __builtin_nontemporal_store(v, (f32x4*)(op + (size_t)(m * 16 + ps * 4) * D));
;           if (xbp) {
;             u32x2 o; o.x = pack_bf16(v.x, v.y); o.y = pack_bf16(v.z, v.w);
;             *(u32x2*)(xbp + (size_t)grow * LDH + cb + c4 * 4) = o;
;             const float t = red16(v.x * v.x + v.y * v.y + v.z * v.z + v.w * v.w);
;             if (c4 == 0) atomicAdd(ssqp + grow, t);
;           }
.LBB0_1404:
	s_waitcnt lgkmcnt(0)
	ds_read_b128 v[34:37], v0 offset:2176
	s_mov_b64 s[0:1], 0x58000
	v_lshl_add_u64 v[40:41], v[180:181], 0, s[0:1]
	s_mov_b64 s[0:1], 0x5c000
	v_lshl_add_u64 v[38:39], v[180:181], 0, s[0:1]
	s_waitcnt vmcnt(12) lgkmcnt(0)
	v_pk_add_f32 v[36:37], v[104:105], v[36:37]
	v_pk_add_f32 v[34:35], v[102:103], v[34:35]
	s_and_b64 vcc, exec, s[10:11]
	global_store_dwordx4 v[40:41], v[34:37], off nt
	s_cbranch_vccnz .LBB0_1453
	v_or_b32_e32 v40, 0x58, v178
	v_cvt_pk_bf16_f32 v42, v34, v35
	v_pk_mul_f32 v[34:35], v[34:35], v[34:35]
	v_cvt_pk_bf16_f32 v43, v36, v37
	v_mad_i64_i32 v[44:45], s[0:1], v40, s66, v[182:183]
	v_add_f32_e32 v34, v34, v35
	v_and_b32_e32 v35, 64, v219
	global_store_dwordx2 v[44:45], v[42:43], off
	v_xor_b32_e32 v43, 1, v219
	v_add_u32_e32 v42, 64, v35
	v_pk_mul_f32 v[36:37], v[36:37], v[36:37]
	s_nop 0
	v_add_f32_e32 v34, v36, v34
	v_add_f32_e32 v34, v37, v34
	s_nop 1
	v_mov_b32_dpp v35, v34 quad_perm:[1,0,3,2] row_mask:0xf bank_mask:0xf
	v_xor_b32_e32 v45, 2, v219
	s_nop 0
	v_xor_b32_e32 v44, 4, v219
	v_xor_b32_e32 v46, 8, v219
	s_waitcnt lgkmcnt(0)
	v_add_f32_e32 v34, v34, v35
	s_nop 1
	v_mov_b32_dpp v35, v34 quad_perm:[2,3,0,1] row_mask:0xf bank_mask:0xf
	s_nop 0
	s_waitcnt lgkmcnt(0)
	v_add_f32_e32 v34, v34, v35
	s_nop 1
	v_mov_b32_dpp v35, v34 row_half_mirror row_mask:0xf bank_mask:0xf
	v_cmp_lt_i32_e32 vcc, v46, v42
	s_waitcnt lgkmcnt(0)
	v_add_f32_e32 v34, v34, v35
	s_nop 1
	v_mov_b32_dpp v35, v34 row_mirror row_mask:0xf bank_mask:0xf
	s_and_saveexec_b64 s[0:1], s[8:9]
	s_cbranch_execz .LBB0_1407
	v_ashrrev_i32_e32 v41, 31, v40
	s_waitcnt lgkmcnt(0)
	v_add_f32_e32 v36, v34, v35
	v_lshl_add_u64 v[34:35], v[40:41], 2, s[60:61]
	global_atomic_add_f32 v[34:35], v36, off

; DI unsigned pack_bf16(float lo, float hi) { f32x2 v = {lo, hi}; bf16v2 b = __builtin_convertvector(v, bf16v2); return __builtin_bit_cast(unsigned, b); }
; DI float red16(float v) { v += __shfl_xor(v, 1); v += __shfl_xor(v, 2); v += __shfl_xor(v, 4); v += __shfl_xor(v, 8); return v; }
;   DI void run8(f32x4 (&acc)[8][4], int rb, int cb, int fr, int fq) const {
;     ...
;         for (int n = 0; n < 4; ++n)
; #pragma unroll
;           for (int j = 0; j < 4; ++j) scr[(fq * 4 + j) * 68 + n * 16 + fr] = acc[m][n][j];
;         __builtin_amdgcn_sched_barrier(0);
; #pragma unroll
;         for (int ps = 0; ps < 4; ++ps) {
;           const f32x4 a = *(const f32x4*)(scr + (ps * 4 + prow) * 68 + c4 * 4);
;           f32x4 v;
;           v.x = xv[mm][ps].x + a.x * sc; v.y = xv[mm][ps].y + a.y * sc; v.z = xv[mm][ps].z + a.z * sc; v.w = xv[mm][ps].w + a.w * sc;
;           const int grow = rb + m * 16 + ps * 4 + prow;
;           __builtin_nontemporal_store(v, (f32x4*)(op + (size_t)(m * 16 + ps * 4) * D));
;           if (xbp) {
;             u32x2 o; o.x = pack_bf16(v.x, v.y); o.y = pack_bf16(v.z, v.w);
;             *(u32x2*)(xbp + (size_t)grow * LDH + cb + c4 * 4) = o;
;             const float t = red16(v.x * v.x + v.y * v.y + v.z * v.z + v.w * v.w);
;             if (c4 == 0) atomicAdd(ssqp + grow, t);
;           }
.LBB0_1413:
	s_mov_b64 s[0:1], 0x60000
	s_nop 0
	v_lshl_add_u64 v[36:37], v[180:181], 0, s[0:1]
	s_mov_b64 s[0:1], 0x64000
	s_waitcnt lgkmcnt(0)
	v_lshl_add_u64 v[34:35], v[180:181], 0, s[0:1]
	ds_write2_b32 v184, v26, v30 offset1:16
	ds_write2_b32 v184, v27, v31 offset0:68 offset1:84
	ds_write2_b32 v184, v28, v32 offset0:136 offset1:152
	ds_write2_b32 v184, v29, v33 offset0:204 offset1:220
	ds_write2_b32 v184, v18, v22 offset0:32 offset1:48
	ds_write2_b32 v184, v19, v23 offset0:100 offset1:116
	ds_write2_b32 v184, v20, v24 offset0:168 offset1:184
	ds_write2_b32 v184, v21, v25 offset0:236 offset1:252
	ds_read_b128 v[18:21], v0
	s_and_b64 vcc, exec, s[10:11]
	s_waitcnt vmcnt(11) lgkmcnt(0)
	v_pk_add_f32 v[20:21], v[96:97], v[20:21]
	v_pk_add_f32 v[18:19], v[94:95], v[18:19]
	global_store_dwordx4 v[36:37], v[18:21], off nt
	s_cbranch_vccnz .LBB0_1454
	v_cvt_pk_bf16_f32 v24, v18, v19
	v_pk_mul_f32 v[18:19], v[18:19], v[18:19]
	v_cvt_pk_bf16_f32 v25, v20, v21
	v_pk_mul_f32 v[20:21], v[20:21], v[20:21]
	v_add_f32_e32 v18, v18, v19
	v_add_f32_e32 v18, v20, v18
	v_and_b32_e32 v20, 64, v219
	v_add_f32_e32 v19, v21, v18
	v_xor_b32_e32 v18, 1, v219
	v_add_u32_e32 v21, 64, v20
	v_cmp_lt_i32_e32 vcc, v18, v21
	v_or_b32_e32 v22, 0x60, v178
	v_mad_i64_i32 v[26:27], s[0:1], v22, s66, v[182:183]
	v_cndmask_b32_e32 v18, v219, v18, vcc
	v_lshlrev_b32_e32 v18, 2, v18
	v_mov_b32_dpp v20, v19 quad_perm:[1,0,3,2] row_mask:0xf bank_mask:0xf
	global_store_dwordx2 v[26:27], v[24:25], off
	s_waitcnt lgkmcnt(0)
	v_add_f32_e32 v20, v19, v20
	v_xor_b32_e32 v19, 2, v219
	v_cmp_lt_i32_e32 vcc, v19, v21
	s_nop 1
	v_cndmask_b32_e32 v19, v219, v19, vcc
	v_lshlrev_b32_e32 v19, 2, v19
	v_mov_b32_dpp v23, v20 quad_perm:[2,3,0,1] row_mask:0xf bank_mask:0xf
	s_waitcnt lgkmcnt(0)
	v_add_f32_e32 v23, v20, v23
	v_xor_b32_e32 v20, 4, v219
	v_cmp_lt_i32_e32 vcc, v20, v21
	s_nop 1
	v_cndmask_b32_e32 v20, v219, v20, vcc
	v_lshlrev_b32_e32 v20, 2, v20
	v_mov_b32_dpp v24, v23 row_half_mirror row_mask:0xf bank_mask:0xf
	s_waitcnt lgkmcnt(0)
	v_add_f32_e32 v24, v23, v24
	v_xor_b32_e32 v23, 8, v219
	v_cmp_lt_i32_e32 vcc, v23, v21
	s_nop 1
	v_cndmask_b32_e32 v21, v219, v23, vcc
	v_lshlrev_b32_e32 v21, 2, v21
	v_mov_b32_dpp v25, v24 row_mirror row_mask:0xf bank_mask:0xf
	s_and_saveexec_b64 s[0:1], s[8:9]
	s_cbranch_execz .LBB0_1416
	v_ashrrev_i32_e32 v23, 31, v22
	s_waitcnt lgkmcnt(0)
	v_add_f32_e32 v24, v24, v25
	v_lshl_add_u64 v[22:23], v[22:23], 2, s[60:61]
	global_atomic_add_f32 v[22:23], v24, off

; DI unsigned pack_bf16(float lo, float hi) { f32x2 v = {lo, hi}; bf16v2 b = __builtin_convertvector(v, bf16v2); return __builtin_bit_cast(unsigned, b); }
; DI float red16(float v) { v += __shfl_xor(v, 1); v += __shfl_xor(v, 2); v += __shfl_xor(v, 4); v += __shfl_xor(v, 8); return v; }
;   DI void run8(f32x4 (&acc)[8][4], int rb, int cb, int fr, int fq) const {
;     ...
;         for (int ps = 0; ps < 4; ++ps) {
;           const f32x4 a = *(const f32x4*)(scr + (ps * 4 + prow) * 68 + c4 * 4);
;           f32x4 v;
;           v.x = xv[mm][ps].x + a.x * sc; v.y = xv[mm][ps].y + a.y * sc; v.z = xv[mm][ps].z + a.z * sc; v.w = xv[mm][ps].w + a.w * sc;
;           const int grow = rb + m * 16 + ps * 4 + prow;
;           __builtin_nontemporal_store(v, (f32x4*)(op + (size_t)(m * 16 + ps * 4) * D));
;           if (xbp) {
;             u32x2 o; o.x = pack_bf16(v.x, v.y); o.y = pack_bf16(v.z, v.w);
;             *(u32x2*)(xbp + (size_t)grow * LDH + cb + c4 * 4) = o;
;             const float t = red16(v.x * v.x + v.y * v.y + v.z * v.z + v.w * v.w);
;             if (c4 == 0) atomicAdd(ssqp + grow, t);
;           }
.LBB0_1420:
	s_waitcnt lgkmcnt(0)
	ds_read_b128 v[18:21], v0 offset:2176
	s_mov_b64 s[0:1], 0x68000
	v_lshl_add_u64 v[24:25], v[180:181], 0, s[0:1]
	s_mov_b64 s[0:1], 0x6c000
	v_lshl_add_u64 v[22:23], v[180:181], 0, s[0:1]
	s_waitcnt vmcnt(10) lgkmcnt(0)
	v_pk_add_f32 v[20:21], v[88:89], v[20:21]
	v_pk_add_f32 v[18:19], v[86:87], v[18:19]
	s_and_b64 vcc, exec, s[10:11]
	global_store_dwordx4 v[24:25], v[18:21], off nt
	s_cbranch_vccnz .LBB0_1455
	v_pk_mul_f32 v[26:27], v[18:19], v[18:19]
	v_pk_mul_f32 v[24:25], v[20:21], v[20:21]
	v_add_f32_e32 v26, v26, v27
	v_add_f32_e32 v24, v24, v26
	v_add_f32_e32 v24, v25, v24
	v_and_b32_e32 v25, 64, v219
	v_xor_b32_e32 v27, 1, v219
	v_add_u32_e32 v26, 64, v25
	s_nop 0
	v_xor_b32_e32 v29, 2, v219
	v_xor_b32_e32 v28, 4, v219
	s_nop 1
	v_mov_b32_dpp v25, v24 quad_perm:[1,0,3,2] row_mask:0xf bank_mask:0xf
	s_nop 0
	v_cvt_pk_bf16_f32 v32, v18, v19
	v_cvt_pk_bf16_f32 v33, v20, v21
	s_waitcnt lgkmcnt(0)
	v_add_f32_e32 v24, v24, v25
	s_nop 1
	v_mov_b32_dpp v25, v24 quad_perm:[2,3,0,1] row_mask:0xf bank_mask:0xf
	s_nop 0
	s_waitcnt lgkmcnt(0)
	v_add_f32_e32 v25, v24, v25
	s_nop 1
	v_mov_b32_dpp v30, v25 row_half_mirror row_mask:0xf bank_mask:0xf
	v_or_b32_e32 v24, 0x68, v178
	v_mad_i64_i32 v[20:21], s[0:1], v24, s66, v[182:183]
	global_store_dwordx2 v[20:21], v[32:33], off
	s_waitcnt lgkmcnt(0)
	v_add_f32_e32 v18, v25, v30
	v_xor_b32_e32 v30, 8, v219
	v_cmp_lt_i32_e32 vcc, v30, v26
	s_nop 3
	v_mov_b32_dpp v19, v18 row_mirror row_mask:0xf bank_mask:0xf
	s_and_saveexec_b64 s[0:1], s[8:9]
	s_cbranch_execz .LBB0_1423
	v_ashrrev_i32_e32 v25, 31, v24
	s_waitcnt lgkmcnt(0)
	v_add_f32_e32 v20, v18, v19
	v_lshl_add_u64 v[18:19], v[24:25], 2, s[60:61]
	global_atomic_add_f32 v[18:19], v20, off

; DI unsigned pack_bf16(float lo, float hi) { f32x2 v = {lo, hi}; bf16v2 b = __builtin_convertvector(v, bf16v2); return __builtin_bit_cast(unsigned, b); }
; DI float red16(float v) { v += __shfl_xor(v, 1); v += __shfl_xor(v, 2); v += __shfl_xor(v, 4); v += __shfl_xor(v, 8); return v; }
;   DI void run8(f32x4 (&acc)[8][4], int rb, int cb, int fr, int fq) const {
;     ...
;         for (int n = 0; n < 4; ++n)
; #pragma unroll
;           for (int j = 0; j < 4; ++j) scr[(fq * 4 + j) * 68 + n * 16 + fr] = acc[m][n][j];
;         __builtin_amdgcn_sched_barrier(0);
; #pragma unroll
;         for (int ps = 0; ps < 4; ++ps) {
;           const f32x4 a = *(const f32x4*)(scr + (ps * 4 + prow) * 68 + c4 * 4);
;           f32x4 v;
;           v.x = xv[mm][ps].x + a.x * sc; v.y = xv[mm][ps].y + a.y * sc; v.z = xv[mm][ps].z + a.z * sc; v.w = xv[mm][ps].w + a.w * sc;
;           const int grow = rb + m * 16 + ps * 4 + prow;
;           __builtin_nontemporal_store(v, (f32x4*)(op + (size_t)(m * 16 + ps * 4) * D));
;           if (xbp) {
;             u32x2 o; o.x = pack_bf16(v.x, v.y); o.y = pack_bf16(v.z, v.w);
;             *(u32x2*)(xbp + (size_t)grow * LDH + cb + c4 * 4) = o;
;             const float t = red16(v.x * v.x + v.y * v.y + v.z * v.z + v.w * v.w);
;             if (c4 == 0) atomicAdd(ssqp + grow, t);
;           }
.LBB0_1429:
	s_mov_b64 s[0:1], 0x70000
	s_nop 0
	v_lshl_add_u64 v[20:21], v[180:181], 0, s[0:1]
	s_mov_b64 s[0:1], 0x74000
	s_waitcnt lgkmcnt(0)
	v_lshl_add_u64 v[18:19], v[180:181], 0, s[0:1]
	ds_write2_b32 v184, v10, v14 offset1:16
	ds_write2_b32 v184, v11, v15 offset0:68 offset1:84
	ds_write2_b32 v184, v12, v16 offset0:136 offset1:152
	ds_write2_b32 v184, v13, v17 offset0:204 offset1:220
	ds_write2_b32 v184, v2, v6 offset0:32 offset1:48
	ds_write2_b32 v184, v3, v7 offset0:100 offset1:116
	ds_write2_b32 v184, v4, v8 offset0:168 offset1:184
	ds_write2_b32 v184, v5, v9 offset0:236 offset1:252
	ds_read_b128 v[2:5], v0
	s_and_b64 vcc, exec, s[10:11]
	s_waitcnt vmcnt(9) lgkmcnt(0)
	v_pk_add_f32 v[4:5], v[80:81], v[4:5]
	v_pk_add_f32 v[2:3], v[78:79], v[2:3]
	global_store_dwordx4 v[20:21], v[2:5], off nt
	s_cbranch_vccnz .LBB0_1456
	v_pk_mul_f32 v[8:9], v[2:3], v[2:3]
	v_pk_mul_f32 v[6:7], v[4:5], v[4:5]
	v_add_f32_e32 v8, v8, v9
	v_add_f32_e32 v6, v6, v8
	v_and_b32_e32 v8, 64, v219
	v_add_f32_e32 v6, v7, v6
	v_xor_b32_e32 v7, 1, v219
	v_add_u32_e32 v11, 64, v8
	v_cmp_lt_i32_e32 vcc, v7, v11
	v_cvt_pk_bf16_f32 v12, v2, v3
	v_xor_b32_e32 v3, 8, v219
	v_cndmask_b32_e32 v7, v219, v7, vcc
	v_lshlrev_b32_e32 v8, 2, v7
	v_mov_b32_dpp v7, v6 quad_perm:[1,0,3,2] row_mask:0xf bank_mask:0xf
	s_waitcnt lgkmcnt(0)
	v_add_f32_e32 v6, v6, v7
	v_xor_b32_e32 v7, 2, v219
	v_cmp_lt_i32_e32 vcc, v7, v11
	s_nop 1
	v_cndmask_b32_e32 v7, v219, v7, vcc
	v_lshlrev_b32_e32 v9, 2, v7
	v_mov_b32_dpp v7, v6 quad_perm:[2,3,0,1] row_mask:0xf bank_mask:0xf
	s_waitcnt lgkmcnt(0)
	v_add_f32_e32 v7, v6, v7
	v_xor_b32_e32 v6, 4, v219
	v_cmp_lt_i32_e32 vcc, v6, v11
	s_nop 1
	v_cndmask_b32_e32 v6, v219, v6, vcc
	v_lshlrev_b32_e32 v10, 2, v6
	v_mov_b32_dpp v13, v7 row_half_mirror row_mask:0xf bank_mask:0xf
	v_cmp_lt_i32_e32 vcc, v3, v11
	v_or_b32_e32 v6, 0x70, v178
	s_waitcnt lgkmcnt(0)
	v_add_f32_e32 v2, v7, v13
	v_cndmask_b32_e32 v3, v219, v3, vcc
	v_lshlrev_b32_e32 v3, 2, v3
	v_mov_b32_dpp v11, v2 row_mirror row_mask:0xf bank_mask:0xf
	v_cvt_pk_bf16_f32 v13, v4, v5
	v_mad_i64_i32 v[4:5], s[0:1], v6, s66, v[182:183]
	global_store_dwordx2 v[4:5], v[12:13], off
	s_and_saveexec_b64 s[0:1], s[8:9]
	s_cbranch_execz .LBB0_1432
	v_ashrrev_i32_e32 v7, 31, v6
	s_waitcnt lgkmcnt(0)
	v_add_f32_e32 v2, v2, v11
	v_lshl_add_u64 v[4:5], v[6:7], 2, s[60:61]
	global_atomic_add_f32 v[4:5], v2, off

; DI unsigned pack_bf16(float lo, float hi) { f32x2 v = {lo, hi}; bf16v2 b = __builtin_convertvector(v, bf16v2); return __builtin_bit_cast(unsigned, b); }
; DI float red16(float v) { v += __shfl_xor(v, 1); v += __shfl_xor(v, 2); v += __shfl_xor(v, 4); v += __shfl_xor(v, 8); return v; }
;   DI void run8(f32x4 (&acc)[8][4], int rb, int cb, int fr, int fq) const {
;     ...
;         for (int ps = 0; ps < 4; ++ps) {
;           const f32x4 a = *(const f32x4*)(scr + (ps * 4 + prow) * 68 + c4 * 4);
;           f32x4 v;
;           v.x = xv[mm][ps].x + a.x * sc; v.y = xv[mm][ps].y + a.y * sc; v.z = xv[mm][ps].z + a.z * sc; v.w = xv[mm][ps].w + a.w * sc;
;           const int grow = rb + m * 16 + ps * 4 + prow;
;           __builtin_nontemporal_store(v, (f32x4*)(op + (size_t)(m * 16 + ps * 4) * D));
;           if (xbp) {
;             u32x2 o; o.x = pack_bf16(v.x, v.y); o.y = pack_bf16(v.z, v.w);
;             *(u32x2*)(xbp + (size_t)grow * LDH + cb + c4 * 4) = o;
;             const float t = red16(v.x * v.x + v.y * v.y + v.z * v.z + v.w * v.w);
;             if (c4 == 0) atomicAdd(ssqp + grow, t);
;           }
.LBB0_1436:
	s_waitcnt lgkmcnt(0)
	ds_read_b128 v[2:5], v0 offset:2176
	s_mov_b64 s[0:1], 0x78000
	v_lshl_add_u64 v[8:9], v[180:181], 0, s[0:1]
	s_mov_b64 s[0:1], 0x7c000
	v_lshl_add_u64 v[6:7], v[180:181], 0, s[0:1]
	s_waitcnt vmcnt(8) lgkmcnt(0)
	v_pk_add_f32 v[4:5], v[72:73], v[4:5]
	v_pk_add_f32 v[2:3], v[70:71], v[2:3]
	s_and_b64 vcc, exec, s[10:11]
	global_store_dwordx4 v[8:9], v[2:5], off nt
	s_cbranch_vccnz .LBB0_1457
	v_pk_mul_f32 v[10:11], v[2:3], v[2:3]
	v_pk_mul_f32 v[8:9], v[4:5], v[4:5]
	v_add_f32_e32 v10, v10, v11
	v_add_f32_e32 v8, v8, v10
	v_add_f32_e32 v8, v9, v8
	v_and_b32_e32 v9, 64, v219
	v_xor_b32_e32 v12, 1, v219
	v_add_u32_e32 v10, 64, v9
	s_nop 0
	v_xor_b32_e32 v14, 2, v219
	v_xor_b32_e32 v13, 4, v219
	s_nop 1
	v_mov_b32_dpp v9, v8 quad_perm:[1,0,3,2] row_mask:0xf bank_mask:0xf
	s_nop 0
	v_cvt_pk_bf16_f32 v16, v2, v3
	v_cvt_pk_bf16_f32 v17, v4, v5
	s_waitcnt lgkmcnt(0)
	v_add_f32_e32 v8, v8, v9
	s_nop 1
	v_mov_b32_dpp v9, v8 quad_perm:[2,3,0,1] row_mask:0xf bank_mask:0xf
	s_nop 0
	s_waitcnt lgkmcnt(0)
	v_add_f32_e32 v9, v8, v9
	s_nop 1
	v_mov_b32_dpp v11, v9 row_half_mirror row_mask:0xf bank_mask:0xf
	v_or_b32_e32 v8, 0x78, v178
	v_mad_i64_i32 v[4:5], s[0:1], v8, s66, v[182:183]
	global_store_dwordx2 v[4:5], v[16:17], off
	s_waitcnt lgkmcnt(0)
	v_add_f32_e32 v2, v9, v11
	v_xor_b32_e32 v11, 8, v219
	v_cmp_lt_i32_e32 vcc, v11, v10
	s_nop 3
	v_mov_b32_dpp v3, v2 row_mirror row_mask:0xf bank_mask:0xf
	s_and_saveexec_b64 s[0:1], s[8:9]
	s_cbranch_execz .LBB0_1439
	v_ashrrev_i32_e32 v9, 31, v8
	s_waitcnt lgkmcnt(0)
	v_add_f32_e32 v4, v2, v3
	v_lshl_add_u64 v[2:3], v[8:9], 2, s[60:61]
	global_atomic_add_f32 v[2:3], v4, off

; #define MFMA16(a, b, c) __builtin_amdgcn_mfma_f32_16x16x32_bf16((a), (b), (c), 0, 0, 0)
; template <class Epi>
; DI void gemm8_tile(const bf16_t* __restrict__ Ab, int lda, const bf16_t* __restrict__ Bb, int ldb, int K, int brow, int bcol, const Epi epi,
;                    bool staged, bool has_next, const bf16_t* __restrict__ Abn, const bf16_t* __restrict__ Bbn) {
;     ...
;       for (int m = 0; m < 8; ++m)
; #pragma unroll
;         for (int n = 0; n < 4; ++n) acc[m][n] = MFMA16(At[m], Bf[n], acc[m][n]);
;       __builtin_amdgcn_sched_barrier(0);
;     }
;     asm volatile("s_waitcnt vmcnt(0)" ::: "memory");
;     __syncthreads();
;   DI void run8(f32x4 (&acc)[8][4], int rb, int cb, int fr, int fq) const {
;     const int lane = fq * 16 + fr, wid = (int)(threadIdx.x >> 6);
;     const float sc = scale; bf16_t* const xbp = xb; float* const ssqp = ssq;
;     float* scr = (float*)(smem + G8_STAGE_B + wid * 4352);
;     const int prow = lane >> 4, c4 = lane & 15;
;     const float* xp = xin + (size_t)(rb + prow) * D + cb + c4 * 4;
;     float* op = xout + (size_t)(rb + prow) * D + cb + c4 * 4;
.LBB0_1515:
	v_lshrrev_b32_e32 v194, 4, v208
	s_waitcnt lgkmcnt(0)
	v_mfma_f32_16x16x32_bf16 v[196:199], v[58:61], v[2:5], v[126:129]
	v_mfma_f32_16x16x32_bf16 v[202:205], v[58:61], v[138:141], v[122:125]
	v_mfma_f32_16x16x32_bf16 v[212:215], v[58:61], v[182:185], v[118:121]
	v_mfma_f32_16x16x32_bf16 v[222:225], v[58:61], v[186:189], v[114:117]
	v_mfma_f32_16x16x32_bf16 v[150:153], v[50:53], v[2:5], v[110:113]
	v_mfma_f32_16x16x32_bf16 v[154:157], v[50:53], v[138:141], v[106:109]
	v_mfma_f32_16x16x32_bf16 v[142:145], v[50:53], v[182:185], v[102:105]
	v_mfma_f32_16x16x32_bf16 v[146:149], v[50:53], v[186:189], v[98:101]
	v_mfma_f32_16x16x32_bf16 v[118:121], v[42:45], v[2:5], v[94:97]
	v_mfma_f32_16x16x32_bf16 v[122:125], v[42:45], v[138:141], v[90:93]
	v_mfma_f32_16x16x32_bf16 v[110:113], v[42:45], v[182:185], v[86:89]
	v_mfma_f32_16x16x32_bf16 v[114:117], v[42:45], v[186:189], v[82:85]
	v_mfma_f32_16x16x32_bf16 v[86:89], v[34:37], v[2:5], v[78:81]
	v_mfma_f32_16x16x32_bf16 v[90:93], v[34:37], v[138:141], v[74:77]
	v_mfma_f32_16x16x32_bf16 v[78:81], v[34:37], v[182:185], v[70:73]
	v_mfma_f32_16x16x32_bf16 v[82:85], v[34:37], v[186:189], v[66:69]
	v_mfma_f32_16x16x32_bf16 v[58:61], v[26:29], v[2:5], v[62:65]
	v_mfma_f32_16x16x32_bf16 v[62:65], v[26:29], v[138:141], v[158:161]
	v_mfma_f32_16x16x32_bf16 v[50:53], v[26:29], v[182:185], v[54:57]
	v_mfma_f32_16x16x32_bf16 v[54:57], v[26:29], v[186:189], v[162:165]
	v_mfma_f32_16x16x32_bf16 v[42:45], v[18:21], v[2:5], v[46:49]
	v_mfma_f32_16x16x32_bf16 v[46:49], v[18:21], v[138:141], v[166:169]
	v_mfma_f32_16x16x32_bf16 v[34:37], v[18:21], v[182:185], v[38:41]
	v_mfma_f32_16x16x32_bf16 v[38:41], v[18:21], v[186:189], v[170:173]
	v_mfma_f32_16x16x32_bf16 v[26:29], v[10:13], v[2:5], v[30:33]
	v_mfma_f32_16x16x32_bf16 v[30:33], v[10:13], v[138:141], v[174:177]
	v_mfma_f32_16x16x32_bf16 v[18:21], v[10:13], v[182:185], v[22:25]
	v_mfma_f32_16x16x32_bf16 v[22:25], v[10:13], v[186:189], v[178:181]
	v_mfma_f32_16x16x32_bf16 v[10:13], v[190:193], v[2:5], v[14:17]
	v_mfma_f32_16x16x32_bf16 v[14:17], v[190:193], v[138:141], v[130:133]
	v_mfma_f32_16x16x32_bf16 v[2:5], v[190:193], v[182:185], v[6:9]
	v_mfma_f32_16x16x32_bf16 v[6:9], v[190:193], v[186:189], v[134:137]
	v_add_u32_e32 v0, s31, v207
	v_or_b32_e32 v178, v0, v194
	v_lshl_or_b32 v182, v206, 6, s8
	v_ashrrev_i32_e32 v179, 31, v178
	v_readlane_b32 s8, v254, 0
	v_lshlrev_b64 v[66:67], 12, v[178:179]
	v_readlane_b32 s10, v254, 2
	v_readlane_b32 s11, v254, 3
	v_ashrrev_i32_e32 v183, 31, v182
	v_lshlrev_b32_e32 v0, 2, v201
	v_lshl_add_u64 v[66:67], s[10:11], 0, v[66:67]
	v_lshl_add_u64 v[66:67], v[182:183], 2, v[66:67]
	v_lshl_add_u64 v[180:181], v[66:67], 0, v[0:1]
	s_movk_i32 s0, 0x4000
	v_add_co_u32_e32 v66, vcc, s0, v180
	s_mov_b32 s0, 0x8000
	s_nop 0
	v_addc_co_u32_e32 v67, vcc, 0, v181, vcc
	s_waitcnt vmcnt(0)
	s_waitcnt vmcnt(0)
	s_barrier
; DI unsigned pack_bf16(float lo, float hi) { f32x2 v = {lo, hi}; bf16v2 b = __builtin_convertvector(v, bf16v2); return __builtin_bit_cast(unsigned, b); }
; DI float red16(float v) { v += __shfl_xor(v, 1); v += __shfl_xor(v, 2); v += __shfl_xor(v, 4); v += __shfl_xor(v, 8); return v; }
;   DI void run8(f32x4 (&acc)[8][4], int rb, int cb, int fr, int fq) const {
;     ...
;     for (int mh = 0; mh < 2; ++mh) {
;       f32x4 xv[4][4];
; #pragma unroll
;       for (int mm = 0; mm < 4; ++mm)
; #pragma unroll
;         for (int ps = 0; ps < 4; ++ps) xv[mm][ps] = __builtin_nontemporal_load((const f32x4*)(xp + (size_t)((mh * 4 + mm) * 16 + ps * 4) * D));
;       __builtin_amdgcn_sched_barrier(0);
; #pragma unroll
;       for (int mm = 0; mm < 4; ++mm) {
;         const int m = mh * 4 + mm;
; #pragma unroll
;         for (int n = 0; n < 4; ++n)
; #pragma unroll
;           for (int j = 0; j < 4; ++j) scr[(fq * 4 + j) * 68 + n * 16 + fr] = acc[m][n][j];
;         __builtin_amdgcn_sched_barrier(0);
; #pragma unroll
;         for (int ps = 0; ps < 4; ++ps) {
;           const f32x4 a = *(const f32x4*)(scr + (ps * 4 + prow) * 68 + c4 * 4);
;           f32x4 v;
;           v.x = xv[mm][ps].x + a.x * sc; v.y = xv[mm][ps].y + a.y * sc; v.z = xv[mm][ps].z + a.z * sc; v.w = xv[mm][ps].w + a.w * sc;
;           const int grow = rb + m * 16 + ps * 4 + prow;
;           __builtin_nontemporal_store(v, (f32x4*)(op + (size_t)(m * 16 + ps * 4) * D));
;           if (xbp) {
;             u32x2 o; o.x = pack_bf16(v.x, v.y); o.y = pack_bf16(v.z, v.w);
;             *(u32x2*)(xbp + (size_t)grow * LDH + cb + c4 * 4) = o;
;             const float t = red16(v.x * v.x + v.y * v.y + v.z * v.z + v.w * v.w);
;             if (c4 == 0) atomicAdd(ssqp + grow, t);
;           }
	global_load_dwordx4 v[174:177], v[180:181], off nt
	global_load_dwordx4 v[170:173], v[66:67], off nt
	v_add_co_u32_e32 v66, vcc, s0, v180
	s_mov_b32 s0, 0xc000
	s_nop 0
	v_addc_co_u32_e32 v67, vcc, 0, v181, vcc
	v_add_co_u32_e32 v68, vcc, s0, v180
	s_mov_b32 s0, 0x14000
	s_nop 0
	v_addc_co_u32_e32 v69, vcc, 0, v181, vcc
	global_load_dwordx4 v[166:169], v[66:67], off nt
	global_load_dwordx4 v[162:165], v[68:69], off nt
	v_add_co_u32_e32 v66, vcc, s92, v180
	v_readlane_b32 s9, v254, 1
	s_nop 0
	v_addc_co_u32_e32 v67, vcc, 0, v181, vcc
	v_add_co_u32_e32 v68, vcc, s0, v180
	s_mov_b32 s0, 0x18000
	s_nop 0
	v_addc_co_u32_e32 v69, vcc, 0, v181, vcc
	global_load_dwordx4 v[158:161], v[66:67], off nt
	global_load_dwordx4 v[138:141], v[68:69], off nt
	v_add_co_u32_e32 v66, vcc, s0, v180
	s_mov_b32 s0, 0x1c000
	s_nop 0
	v_addc_co_u32_e32 v67, vcc, 0, v181, vcc
	v_add_co_u32_e32 v68, vcc, s0, v180
	s_mov_b32 s0, 0x20000
	s_nop 0
	v_addc_co_u32_e32 v69, vcc, 0, v181, vcc
	global_load_dwordx4 v[134:137], v[66:67], off nt
	global_load_dwordx4 v[130:133], v[68:69], off nt
	v_add_co_u32_e32 v66, vcc, s0, v180
	s_mov_b32 s0, 0x24000
	s_nop 0
	v_addc_co_u32_e32 v67, vcc, 0, v181, vcc
	v_add_co_u32_e32 v68, vcc, s0, v180
	s_mov_b32 s0, 0x28000
	s_nop 0
	v_addc_co_u32_e32 v69, vcc, 0, v181, vcc
	global_load_dwordx4 v[126:129], v[66:67], off nt
	global_load_dwordx4 v[106:109], v[68:69], off nt
	v_add_co_u32_e32 v66, vcc, s0, v180
	s_mov_b32 s0, 0x2c000
	s_nop 0
	v_addc_co_u32_e32 v67, vcc, 0, v181, vcc
	v_add_co_u32_e32 v68, vcc, s0, v180
	s_mov_b32 s0, 0x30000
	s_nop 0
	v_addc_co_u32_e32 v69, vcc, 0, v181, vcc
	global_load_dwordx4 v[102:105], v[66:67], off nt
	global_load_dwordx4 v[98:101], v[68:69], off nt
	v_add_co_u32_e32 v66, vcc, s0, v180
	s_mov_b32 s0, 0x34000
	s_nop 0
	v_addc_co_u32_e32 v67, vcc, 0, v181, vcc
	v_add_co_u32_e32 v68, vcc, s0, v180
	s_mov_b32 s0, 0x38000
	s_nop 0
	v_addc_co_u32_e32 v69, vcc, 0, v181, vcc
	global_load_dwordx4 v[94:97], v[66:67], off nt
	global_load_dwordx4 v[74:77], v[68:69], off nt
	v_add_co_u32_e32 v66, vcc, s0, v180
	s_mov_b32 s0, 0x3c000
	s_nop 0
	v_addc_co_u32_e32 v67, vcc, 0, v181, vcc
	v_add_co_u32_e32 v68, vcc, s0, v180
	v_lshl_add_u32 v184, v200, 2, v218
	s_nop 0
	v_addc_co_u32_e32 v69, vcc, 0, v181, vcc
	global_load_dwordx4 v[70:73], v[66:67], off nt
	s_nop 0
	global_load_dwordx4 v[66:69], v[68:69], off nt
	v_lshl_add_u64 v[182:183], v[182:183], 1, s[50:51]
	v_lshlrev_b32_e32 v0, 1, v201
	v_mad_u32_u24 v185, v200, 12, v184
	v_lshl_add_u64 v[182:183], v[182:183], 0, v[0:1]
	v_cmp_eq_u32_e64 s[8:9], 0, v200
	v_mad_u32_u24 v184, v194, s88, v184
	ds_write2_b32 v184, v196, v202 offset1:16
	ds_write2_b32 v184, v197, v203 offset0:68 offset1:84
	ds_write2_b32 v184, v198, v204 offset0:136 offset1:152
	ds_write2_b32 v184, v199, v205 offset0:204 offset1:220
	ds_write2_b32 v184, v212, v222 offset0:32 offset1:48
	ds_write2_b32 v184, v213, v223 offset0:100 offset1:116
	ds_write2_b32 v184, v214, v224 offset0:168 offset1:184
	ds_write2_b32 v184, v215, v225 offset0:236 offset1:252
	s_movk_i32 s0, 0x110
	v_mad_u32_u24 v0, v194, s0, v185
	ds_read_b128 v[186:189], v0
	v_cndmask_b32_e64 v0, 0, 1, s[76:77]
	v_cmp_ne_u32_e64 s[10:11], 1, v0
	s_andn2_b64 vcc, exec, s[76:77]
	s_waitcnt vmcnt(15) lgkmcnt(0)
	v_pk_add_f32 v[176:177], v[176:177], v[188:189]
	v_pk_add_f32 v[174:175], v[174:175], v[186:187]
	global_store_dwordx4 v[180:181], v[174:177], off nt
	s_cbranch_vccnz .LBB0_1519
	v_cvt_pk_bf16_f32 v186, v174, v175
	v_pk_mul_f32 v[174:175], v[174:175], v[174:175]
	v_cvt_pk_bf16_f32 v187, v176, v177
	v_add_f32_e32 v0, v174, v175
	v_and_b32_e32 v175, 64, v219
	s_nop 0
	v_add_u32_e32 v175, 64, v175
	v_pk_mul_f32 v[176:177], v[176:177], v[176:177]
	s_nop 0
	v_add_f32_e32 v0, v176, v0
	v_add_f32_e32 v0, v177, v0
	s_nop 1
	v_mov_b32_dpp v174, v0 quad_perm:[1,0,3,2] row_mask:0xf bank_mask:0xf
	v_mad_i64_i32 v[188:189], s[0:1], v178, s66, v[182:183]
	global_store_dwordx2 v[188:189], v[186:187], off
	s_waitcnt lgkmcnt(0)
	v_add_f32_e32 v0, v0, v174
	s_nop 5
	v_mov_b32_dpp v174, v0 quad_perm:[2,3,0,1] row_mask:0xf bank_mask:0xf
	s_waitcnt lgkmcnt(0)
	v_add_f32_e32 v0, v0, v174
	s_nop 5
	v_mov_b32_dpp v174, v0 row_half_mirror row_mask:0xf bank_mask:0xf
	s_waitcnt lgkmcnt(0)
	v_add_f32_e32 v0, v0, v174
	v_xor_b32_e32 v174, 8, v219
	v_cmp_lt_i32_e32 vcc, v174, v175
	s_nop 3
	v_mov_b32_dpp v174, v0 row_mirror row_mask:0xf bank_mask:0xf
	s_and_saveexec_b64 s[0:1], s[8:9]
	s_cbranch_execz .LBB0_1518
	s_waitcnt lgkmcnt(0)
	v_add_f32_e32 v0, v0, v174
	v_lshl_add_u64 v[174:175], v[178:179], 2, s[60:61]
	global_atomic_add_f32 v[174:175], v0, off

; #define MFMA16(a, b, c) __builtin_amdgcn_mfma_f32_16x16x32_bf16((a), (b), (c), 0, 0, 0)
; template <class Epi>
; DI void gemm8_tile(const bf16_t* __restrict__ Ab, int lda, const bf16_t* __restrict__ Bb, int ldb, int K, int brow, int bcol, const Epi epi,
;                    bool staged, bool has_next, const bf16_t* __restrict__ Abn, const bf16_t* __restrict__ Bbn) {
;     ...
;       for (int m = 0; m < 8; ++m)
; #pragma unroll
;         for (int n = 0; n < 4; ++n) acc[m][n] = MFMA16(At[m], Bf[n], acc[m][n]);
;       __builtin_amdgcn_sched_barrier(0);
;     }
;     asm volatile("s_waitcnt vmcnt(0)" ::: "memory");
;     __syncthreads();
;   DI void run8(f32x4 (&acc)[8][4], int rb, int cb, int fr, int fq) const {
;     const int lane = fq * 16 + fr, wid = (int)(threadIdx.x >> 6);
;     const float sc = scale; bf16_t* const xbp = xb; float* const ssqp = ssq;
;     float* scr = (float*)(smem + G8_STAGE_B + wid * 4352);
;     const int prow = lane >> 4, c4 = lane & 15;
;     const float* xp = xin + (size_t)(rb + prow) * D + cb + c4 * 4;
;     float* op = xout + (size_t)(rb + prow) * D + cb + c4 * 4;
.LBB0_1700:
	v_lshrrev_b32_e32 v194, 4, v206
	s_waitcnt lgkmcnt(0)
	v_mfma_f32_16x16x32_bf16 v[200:203], v[58:61], v[2:5], v[126:129]
	v_mfma_f32_16x16x32_bf16 v[206:209], v[58:61], v[178:181], v[122:125]
	v_mfma_f32_16x16x32_bf16 v[212:215], v[58:61], v[182:185], v[118:121]
	v_mfma_f32_16x16x32_bf16 v[222:225], v[58:61], v[186:189], v[114:117]
	v_mfma_f32_16x16x32_bf16 v[146:149], v[50:53], v[2:5], v[110:113]
	v_mfma_f32_16x16x32_bf16 v[150:153], v[50:53], v[178:181], v[106:109]
	v_mfma_f32_16x16x32_bf16 v[138:141], v[50:53], v[182:185], v[102:105]
	v_mfma_f32_16x16x32_bf16 v[142:145], v[50:53], v[186:189], v[98:101]
	v_mfma_f32_16x16x32_bf16 v[114:117], v[42:45], v[2:5], v[94:97]
	v_mfma_f32_16x16x32_bf16 v[118:121], v[42:45], v[178:181], v[90:93]
	v_mfma_f32_16x16x32_bf16 v[106:109], v[42:45], v[182:185], v[86:89]
	v_mfma_f32_16x16x32_bf16 v[110:113], v[42:45], v[186:189], v[82:85]
	v_mfma_f32_16x16x32_bf16 v[82:85], v[34:37], v[2:5], v[78:81]
	v_mfma_f32_16x16x32_bf16 v[86:89], v[34:37], v[178:181], v[74:77]
	v_mfma_f32_16x16x32_bf16 v[74:77], v[34:37], v[182:185], v[70:73]
	v_mfma_f32_16x16x32_bf16 v[78:81], v[34:37], v[186:189], v[66:69]
	v_mfma_f32_16x16x32_bf16 v[58:61], v[26:29], v[2:5], v[62:65]
	v_mfma_f32_16x16x32_bf16 v[62:65], v[26:29], v[178:181], v[154:157]
	v_mfma_f32_16x16x32_bf16 v[50:53], v[26:29], v[182:185], v[54:57]
	v_mfma_f32_16x16x32_bf16 v[54:57], v[26:29], v[186:189], v[158:161]
	v_mfma_f32_16x16x32_bf16 v[42:45], v[18:21], v[2:5], v[46:49]
	v_mfma_f32_16x16x32_bf16 v[46:49], v[18:21], v[178:181], v[162:165]
	v_mfma_f32_16x16x32_bf16 v[34:37], v[18:21], v[182:185], v[38:41]
	v_mfma_f32_16x16x32_bf16 v[38:41], v[18:21], v[186:189], v[166:169]
	v_mfma_f32_16x16x32_bf16 v[26:29], v[10:13], v[2:5], v[30:33]
	v_mfma_f32_16x16x32_bf16 v[30:33], v[10:13], v[178:181], v[170:173]
	v_mfma_f32_16x16x32_bf16 v[18:21], v[10:13], v[182:185], v[22:25]
	v_mfma_f32_16x16x32_bf16 v[22:25], v[10:13], v[186:189], v[174:177]
	v_mfma_f32_16x16x32_bf16 v[10:13], v[190:193], v[2:5], v[14:17]
	v_mfma_f32_16x16x32_bf16 v[14:17], v[190:193], v[178:181], v[130:133]
	v_mfma_f32_16x16x32_bf16 v[2:5], v[190:193], v[182:185], v[6:9]
	v_mfma_f32_16x16x32_bf16 v[6:9], v[190:193], v[186:189], v[134:137]
	v_add_u32_e32 v0, s3, v205
	v_or_b32_e32 v178, v0, v194
	v_ashrrev_i32_e32 v179, 31, v178
	v_readlane_b32 s4, v254, 0
	v_lshl_or_b32 v182, v204, 6, s31
	v_lshlrev_b64 v[66:67], 12, v[178:179]
	v_readlane_b32 s6, v254, 2
	v_readlane_b32 s7, v254, 3
	v_ashrrev_i32_e32 v183, 31, v182
	v_lshlrev_b32_e32 v0, 2, v199
	v_lshl_add_u64 v[66:67], s[6:7], 0, v[66:67]
	v_lshl_add_u64 v[66:67], v[182:183], 2, v[66:67]
	v_lshl_add_u64 v[180:181], v[66:67], 0, v[0:1]
	s_movk_i32 s0, 0x4000
	v_add_co_u32_e32 v66, vcc, s0, v180
	s_mov_b32 s0, 0x8000
	s_nop 0
	v_addc_co_u32_e32 v67, vcc, 0, v181, vcc
	s_waitcnt vmcnt(0)
	s_waitcnt vmcnt(0)
	s_barrier
; DI unsigned pack_bf16(float lo, float hi) { f32x2 v = {lo, hi}; bf16v2 b = __builtin_convertvector(v, bf16v2); return __builtin_bit_cast(unsigned, b); }
; DI float red16(float v) { v += __shfl_xor(v, 1); v += __shfl_xor(v, 2); v += __shfl_xor(v, 4); v += __shfl_xor(v, 8); return v; }
;   DI void run8(f32x4 (&acc)[8][4], int rb, int cb, int fr, int fq) const {
;     ...
;     for (int mh = 0; mh < 2; ++mh) {
;       f32x4 xv[4][4];
; #pragma unroll
;       for (int mm = 0; mm < 4; ++mm)
; #pragma unroll
;         for (int ps = 0; ps < 4; ++ps) xv[mm][ps] = __builtin_nontemporal_load((const f32x4*)(xp + (size_t)((mh * 4 + mm) * 16 + ps * 4) * D));
;       __builtin_amdgcn_sched_barrier(0);
; #pragma unroll
;       for (int mm = 0; mm < 4; ++mm) {
;         const int m = mh * 4 + mm;
; #pragma unroll
;         for (int n = 0; n < 4; ++n)
; #pragma unroll
;           for (int j = 0; j < 4; ++j) scr[(fq * 4 + j) * 68 + n * 16 + fr] = acc[m][n][j];
;         __builtin_amdgcn_sched_barrier(0);
; #pragma unroll
;         for (int ps = 0; ps < 4; ++ps) {
;           const f32x4 a = *(const f32x4*)(scr + (ps * 4 + prow) * 68 + c4 * 4);
;           f32x4 v;
;           v.x = xv[mm][ps].x + a.x * sc; v.y = xv[mm][ps].y + a.y * sc; v.z = xv[mm][ps].z + a.z * sc; v.w = xv[mm][ps].w + a.w * sc;
;           const int grow = rb + m * 16 + ps * 4 + prow;
;           __builtin_nontemporal_store(v, (f32x4*)(op + (size_t)(m * 16 + ps * 4) * D));
;           if (xbp) {
;             u32x2 o; o.x = pack_bf16(v.x, v.y); o.y = pack_bf16(v.z, v.w);
;             *(u32x2*)(xbp + (size_t)grow * LDH + cb + c4 * 4) = o;
;             const float t = red16(v.x * v.x + v.y * v.y + v.z * v.z + v.w * v.w);
;             if (c4 == 0) atomicAdd(ssqp + grow, t);
;           }
	global_load_dwordx4 v[174:177], v[180:181], off nt
	global_load_dwordx4 v[170:173], v[66:67], off nt
	v_add_co_u32_e32 v66, vcc, s0, v180
	s_mov_b32 s0, 0xc000
	s_nop 0
	v_addc_co_u32_e32 v67, vcc, 0, v181, vcc
	v_add_co_u32_e32 v68, vcc, s0, v180
	s_mov_b32 s0, 0x14000
	s_nop 0
	v_addc_co_u32_e32 v69, vcc, 0, v181, vcc
	global_load_dwordx4 v[166:169], v[66:67], off nt
	global_load_dwordx4 v[162:165], v[68:69], off nt
	v_add_co_u32_e32 v66, vcc, s92, v180
	v_readlane_b32 s5, v254, 1
	s_nop 0
	v_addc_co_u32_e32 v67, vcc, 0, v181, vcc
	v_add_co_u32_e32 v68, vcc, s0, v180
	s_mov_b32 s0, 0x18000
	s_nop 0
	v_addc_co_u32_e32 v69, vcc, 0, v181, vcc
	global_load_dwordx4 v[158:161], v[66:67], off nt
	global_load_dwordx4 v[154:157], v[68:69], off nt
	v_add_co_u32_e32 v66, vcc, s0, v180
	s_mov_b32 s0, 0x1c000
	s_nop 0
	v_addc_co_u32_e32 v67, vcc, 0, v181, vcc
	v_add_co_u32_e32 v68, vcc, s0, v180
	s_mov_b32 s0, 0x20000
	s_nop 0
	v_addc_co_u32_e32 v69, vcc, 0, v181, vcc
	global_load_dwordx4 v[134:137], v[66:67], off nt
	global_load_dwordx4 v[130:133], v[68:69], off nt
	v_add_co_u32_e32 v66, vcc, s0, v180
	s_mov_b32 s0, 0x24000
	s_nop 0
	v_addc_co_u32_e32 v67, vcc, 0, v181, vcc
	v_add_co_u32_e32 v68, vcc, s0, v180
	s_mov_b32 s0, 0x28000
	s_nop 0
	v_addc_co_u32_e32 v69, vcc, 0, v181, vcc
	global_load_dwordx4 v[126:129], v[66:67], off nt
	global_load_dwordx4 v[122:125], v[68:69], off nt
	v_add_co_u32_e32 v66, vcc, s0, v180
	s_mov_b32 s0, 0x2c000
	s_nop 0
	v_addc_co_u32_e32 v67, vcc, 0, v181, vcc
	v_add_co_u32_e32 v68, vcc, s0, v180
	s_mov_b32 s0, 0x30000
	s_nop 0
	v_addc_co_u32_e32 v69, vcc, 0, v181, vcc
	global_load_dwordx4 v[102:105], v[66:67], off nt
	global_load_dwordx4 v[98:101], v[68:69], off nt
	v_add_co_u32_e32 v66, vcc, s0, v180
	s_mov_b32 s0, 0x34000
	s_nop 0
	v_addc_co_u32_e32 v67, vcc, 0, v181, vcc
	v_add_co_u32_e32 v68, vcc, s0, v180
	s_mov_b32 s0, 0x38000
	s_nop 0
	v_addc_co_u32_e32 v69, vcc, 0, v181, vcc
	global_load_dwordx4 v[94:97], v[66:67], off nt
	global_load_dwordx4 v[90:93], v[68:69], off nt
	v_add_co_u32_e32 v66, vcc, s0, v180
	s_mov_b32 s0, 0x3c000
	s_nop 0
	v_addc_co_u32_e32 v67, vcc, 0, v181, vcc
	v_add_co_u32_e32 v68, vcc, s0, v180
	v_lshl_add_u32 v184, v198, 2, v218
	s_nop 0
	v_addc_co_u32_e32 v69, vcc, 0, v181, vcc
	global_load_dwordx4 v[70:73], v[66:67], off nt
	s_nop 0
	global_load_dwordx4 v[66:69], v[68:69], off nt
	v_lshl_add_u64 v[182:183], v[182:183], 1, s[12:13]
	v_lshlrev_b32_e32 v0, 1, v199
	v_mad_u32_u24 v185, v198, 12, v184
	v_lshl_add_u64 v[182:183], v[182:183], 0, v[0:1]
	v_cmp_eq_u32_e64 s[4:5], 0, v198
	v_mad_u32_u24 v184, v194, s88, v184
	ds_write2_b32 v184, v200, v206 offset1:16
	ds_write2_b32 v184, v201, v207 offset0:68 offset1:84
	ds_write2_b32 v184, v202, v208 offset0:136 offset1:152
	ds_write2_b32 v184, v203, v209 offset0:204 offset1:220
	ds_write2_b32 v184, v212, v222 offset0:32 offset1:48
	ds_write2_b32 v184, v213, v223 offset0:100 offset1:116
	ds_write2_b32 v184, v214, v224 offset0:168 offset1:184
	ds_write2_b32 v184, v215, v225 offset0:236 offset1:252
	s_movk_i32 s0, 0x110
	v_mad_u32_u24 v0, v194, s0, v185
	ds_read_b128 v[186:189], v0
	v_cndmask_b32_e64 v0, 0, 1, s[54:55]
	v_cmp_ne_u32_e64 s[6:7], 1, v0
	s_andn2_b64 vcc, exec, s[54:55]
	s_waitcnt vmcnt(15) lgkmcnt(0)
	v_pk_fma_f32 v[174:175], v[186:187], 0.5, v[174:175] op_sel_hi:[1,0,1]
	v_pk_fma_f32 v[176:177], v[188:189], 0.5, v[176:177] op_sel_hi:[1,0,1]
	global_store_dwordx4 v[180:181], v[174:177], off nt
	s_cbranch_vccnz .LBB0_1704
	v_cvt_pk_bf16_f32 v186, v174, v175
	v_pk_mul_f32 v[174:175], v[174:175], v[174:175]
	v_cvt_pk_bf16_f32 v187, v176, v177
	v_add_f32_e32 v0, v174, v175
	v_and_b32_e32 v175, 64, v219
	s_nop 0
	v_add_u32_e32 v175, 64, v175
	v_pk_mul_f32 v[176:177], v[176:177], v[176:177]
	s_nop 0
	v_add_f32_e32 v0, v176, v0
	v_add_f32_e32 v0, v177, v0
	s_nop 1
	v_mov_b32_dpp v174, v0 quad_perm:[1,0,3,2] row_mask:0xf bank_mask:0xf
	v_mad_i64_i32 v[188:189], s[0:1], v178, s66, v[182:183]
	global_store_dwordx2 v[188:189], v[186:187], off
	s_waitcnt lgkmcnt(0)
	v_add_f32_e32 v0, v0, v174
	s_nop 5
	v_mov_b32_dpp v174, v0 quad_perm:[2,3,0,1] row_mask:0xf bank_mask:0xf
	s_waitcnt lgkmcnt(0)
	v_add_f32_e32 v0, v0, v174
	s_nop 5
	v_mov_b32_dpp v174, v0 row_half_mirror row_mask:0xf bank_mask:0xf
	s_waitcnt lgkmcnt(0)
	v_add_f32_e32 v0, v0, v174
	v_xor_b32_e32 v174, 8, v219
	v_cmp_lt_i32_e32 vcc, v174, v175
	s_nop 3
	v_mov_b32_dpp v174, v0 row_mirror row_mask:0xf bank_mask:0xf
	s_and_saveexec_b64 s[0:1], s[4:5]
	s_cbranch_execz .LBB0_1703
	s_waitcnt lgkmcnt(0)
	v_add_f32_e32 v0, v0, v174
	v_lshl_add_u64 v[174:175], v[178:179], 2, s[38:39]
	global_atomic_add_f32 v[174:175], v0, off

; DI unsigned pack_bf16(float lo, float hi) { f32x2 v = {lo, hi}; bf16v2 b = __builtin_convertvector(v, bf16v2); return __builtin_bit_cast(unsigned, b); }
; DI float red16(float v) { v += __shfl_xor(v, 1); v += __shfl_xor(v, 2); v += __shfl_xor(v, 4); v += __shfl_xor(v, 8); return v; }
;   DI void run8(f32x4 (&acc)[8][4], int rb, int cb, int fr, int fq) const {
;     ...
;         for (int ps = 0; ps < 4; ++ps) {
;           const f32x4 a = *(const f32x4*)(scr + (ps * 4 + prow) * 68 + c4 * 4);
;           f32x4 v;
;           v.x = xv[mm][ps].x + a.x * sc; v.y = xv[mm][ps].y + a.y * sc; v.z = xv[mm][ps].z + a.z * sc; v.w = xv[mm][ps].w + a.w * sc;
;           const int grow = rb + m * 16 + ps * 4 + prow;
;           __builtin_nontemporal_store(v, (f32x4*)(op + (size_t)(m * 16 + ps * 4) * D));
;           if (xbp) {
;             u32x2 o; o.x = pack_bf16(v.x, v.y); o.y = pack_bf16(v.z, v.w);
;             *(u32x2*)(xbp + (size_t)grow * LDH + cb + c4 * 4) = o;
;             const float t = red16(v.x * v.x + v.y * v.y + v.z * v.z + v.w * v.w);
;             if (c4 == 0) atomicAdd(ssqp + grow, t);
;           }
.LBB0_1704:
	v_mul_u32_u24_e32 v0, 0x110, v194
	v_add_u32_e32 v0, v185, v0
	s_waitcnt lgkmcnt(0)
	ds_read_b128 v[174:177], v0 offset:1088
	s_mov_b64 s[0:1], 0x4000
	v_lshl_add_u64 v[186:187], v[180:181], 0, s[0:1]
	s_and_b64 vcc, exec, s[6:7]
	s_waitcnt vmcnt(15) lgkmcnt(0)
	v_pk_fma_f32 v[170:171], v[174:175], 0.5, v[170:171] op_sel_hi:[1,0,1]
	v_pk_fma_f32 v[172:173], v[176:177], 0.5, v[172:173] op_sel_hi:[1,0,1]
	global_store_dwordx4 v[186:187], v[170:173], off nt
	s_cbranch_vccnz .LBB0_1708
	v_pk_mul_f32 v[174:175], v[170:171], v[170:171]
	v_pk_mul_f32 v[176:177], v[172:173], v[172:173]
	v_add_f32_e32 v174, v174, v175
	v_add_f32_e32 v174, v176, v174
	v_and_b32_e32 v176, 64, v219
	s_nop 0
	v_add_u32_e32 v176, 64, v176
	s_nop 0
	v_add_f32_e32 v174, v177, v174
	v_or_b32_e32 v185, 4, v178
	s_nop 1
	v_mov_b32_dpp v175, v174 quad_perm:[1,0,3,2] row_mask:0xf bank_mask:0xf
	s_waitcnt lgkmcnt(0)
	v_add_f32_e32 v174, v174, v175
	s_nop 5
	v_mov_b32_dpp v175, v174 quad_perm:[2,3,0,1] row_mask:0xf bank_mask:0xf
	s_waitcnt lgkmcnt(0)
	v_add_f32_e32 v175, v174, v175
	s_nop 5
	v_mov_b32_dpp v177, v175 row_half_mirror row_mask:0xf bank_mask:0xf
	v_cvt_pk_bf16_f32 v174, v170, v171
	v_xor_b32_e32 v171, 8, v219
	v_cmp_lt_i32_e32 vcc, v171, v176
	s_waitcnt lgkmcnt(0)
	v_add_f32_e32 v170, v175, v177
	s_nop 1
	v_mov_b32_dpp v171, v170 row_mirror row_mask:0xf bank_mask:0xf
	v_cvt_pk_bf16_f32 v175, v172, v173
	v_mad_i64_i32 v[172:173], s[0:1], v185, s66, v[182:183]
	global_store_dwordx2 v[172:173], v[174:175], off
	s_and_saveexec_b64 s[0:1], s[4:5]
	s_cbranch_execz .LBB0_1707
	s_waitcnt lgkmcnt(0)
	v_add_f32_e32 v172, v170, v171
	v_lshl_add_u64 v[170:171], v[178:179], 2, s[38:39]
	global_atomic_add_f32 v[170:171], v172, off offset:16

; DI unsigned pack_bf16(float lo, float hi) { f32x2 v = {lo, hi}; bf16v2 b = __builtin_convertvector(v, bf16v2); return __builtin_bit_cast(unsigned, b); }
; DI float red16(float v) { v += __shfl_xor(v, 1); v += __shfl_xor(v, 2); v += __shfl_xor(v, 4); v += __shfl_xor(v, 8); return v; }
;   DI void run8(f32x4 (&acc)[8][4], int rb, int cb, int fr, int fq) const {
;     ...
;         for (int ps = 0; ps < 4; ++ps) {
;           const f32x4 a = *(const f32x4*)(scr + (ps * 4 + prow) * 68 + c4 * 4);
;           f32x4 v;
;           v.x = xv[mm][ps].x + a.x * sc; v.y = xv[mm][ps].y + a.y * sc; v.z = xv[mm][ps].z + a.z * sc; v.w = xv[mm][ps].w + a.w * sc;
;           const int grow = rb + m * 16 + ps * 4 + prow;
;           __builtin_nontemporal_store(v, (f32x4*)(op + (size_t)(m * 16 + ps * 4) * D));
;           if (xbp) {
;             u32x2 o; o.x = pack_bf16(v.x, v.y); o.y = pack_bf16(v.z, v.w);
;             *(u32x2*)(xbp + (size_t)grow * LDH + cb + c4 * 4) = o;
;             const float t = red16(v.x * v.x + v.y * v.y + v.z * v.z + v.w * v.w);
;             if (c4 == 0) atomicAdd(ssqp + grow, t);
;           }
.LBB0_1708:
	s_waitcnt lgkmcnt(0)
	ds_read_b128 v[170:173], v0 offset:2176
	v_lshl_add_u64 v[174:175], v[180:181], 0, s[82:83]
	s_and_b64 vcc, exec, s[6:7]
	s_waitcnt vmcnt(15) lgkmcnt(0)
	v_pk_fma_f32 v[166:167], v[170:171], 0.5, v[166:167] op_sel_hi:[1,0,1]
	v_pk_fma_f32 v[168:169], v[172:173], 0.5, v[168:169] op_sel_hi:[1,0,1]
	global_store_dwordx4 v[174:175], v[166:169], off nt
	s_cbranch_vccnz .LBB0_1712
	v_pk_mul_f32 v[170:171], v[166:167], v[166:167]
	v_pk_mul_f32 v[172:173], v[168:169], v[168:169]
	v_add_f32_e32 v170, v170, v171
	v_add_f32_e32 v170, v172, v170
	v_and_b32_e32 v172, 64, v219
	s_nop 0
	v_add_u32_e32 v172, 64, v172
	s_nop 0
	v_add_f32_e32 v170, v173, v170
	v_or_b32_e32 v174, 8, v178
	s_nop 1
	v_mov_b32_dpp v171, v170 quad_perm:[1,0,3,2] row_mask:0xf bank_mask:0xf
	s_waitcnt lgkmcnt(0)
	v_add_f32_e32 v170, v170, v171
	s_nop 5
	v_mov_b32_dpp v171, v170 quad_perm:[2,3,0,1] row_mask:0xf bank_mask:0xf
	s_waitcnt lgkmcnt(0)
	v_add_f32_e32 v171, v170, v171
	s_nop 5
	v_mov_b32_dpp v173, v171 row_half_mirror row_mask:0xf bank_mask:0xf
	v_cvt_pk_bf16_f32 v170, v166, v167
	v_xor_b32_e32 v167, 8, v219
	v_cmp_lt_i32_e32 vcc, v167, v172
	s_waitcnt lgkmcnt(0)
	v_add_f32_e32 v166, v171, v173
	s_nop 1
	v_mov_b32_dpp v167, v166 row_mirror row_mask:0xf bank_mask:0xf
	v_cvt_pk_bf16_f32 v171, v168, v169
	v_mad_i64_i32 v[168:169], s[0:1], v174, s66, v[182:183]
	global_store_dwordx2 v[168:169], v[170:171], off
	s_and_saveexec_b64 s[0:1], s[4:5]
	s_cbranch_execz .LBB0_1711
	s_waitcnt lgkmcnt(0)
	v_add_f32_e32 v168, v166, v167
	v_lshl_add_u64 v[166:167], v[178:179], 2, s[38:39]
	global_atomic_add_f32 v[166:167], v168, off offset:32

; DI unsigned pack_bf16(float lo, float hi) { f32x2 v = {lo, hi}; bf16v2 b = __builtin_convertvector(v, bf16v2); return __builtin_bit_cast(unsigned, b); }
; DI float red16(float v) { v += __shfl_xor(v, 1); v += __shfl_xor(v, 2); v += __shfl_xor(v, 4); v += __shfl_xor(v, 8); return v; }
;   DI void run8(f32x4 (&acc)[8][4], int rb, int cb, int fr, int fq) const {
;     ...
;         for (int ps = 0; ps < 4; ++ps) {
;           const f32x4 a = *(const f32x4*)(scr + (ps * 4 + prow) * 68 + c4 * 4);
;           f32x4 v;
;           v.x = xv[mm][ps].x + a.x * sc; v.y = xv[mm][ps].y + a.y * sc; v.z = xv[mm][ps].z + a.z * sc; v.w = xv[mm][ps].w + a.w * sc;
;           const int grow = rb + m * 16 + ps * 4 + prow;
;           __builtin_nontemporal_store(v, (f32x4*)(op + (size_t)(m * 16 + ps * 4) * D));
;           if (xbp) {
;             u32x2 o; o.x = pack_bf16(v.x, v.y); o.y = pack_bf16(v.z, v.w);
;             *(u32x2*)(xbp + (size_t)grow * LDH + cb + c4 * 4) = o;
;             const float t = red16(v.x * v.x + v.y * v.y + v.z * v.z + v.w * v.w);
;             if (c4 == 0) atomicAdd(ssqp + grow, t);
;           }
.LBB0_1712:
	s_waitcnt lgkmcnt(0)
	ds_read_b128 v[166:169], v0 offset:3264
	s_mov_b64 s[0:1], 0xc000
	v_lshl_add_u64 v[170:171], v[180:181], 0, s[0:1]
	s_and_b64 vcc, exec, s[6:7]
	s_waitcnt vmcnt(15) lgkmcnt(0)
	v_pk_fma_f32 v[162:163], v[166:167], 0.5, v[162:163] op_sel_hi:[1,0,1]
	v_pk_fma_f32 v[164:165], v[168:169], 0.5, v[164:165] op_sel_hi:[1,0,1]
	global_store_dwordx4 v[170:171], v[162:165], off nt
	s_cbranch_vccnz .LBB0_1716
	v_pk_mul_f32 v[166:167], v[162:163], v[162:163]
	v_pk_mul_f32 v[168:169], v[164:165], v[164:165]
	v_add_f32_e32 v166, v166, v167
	v_add_f32_e32 v166, v168, v166
	v_and_b32_e32 v168, 64, v219
	s_nop 0
	v_add_u32_e32 v168, 64, v168
	s_nop 0
	v_add_f32_e32 v166, v169, v166
	v_or_b32_e32 v170, 12, v178
	s_nop 1
	v_mov_b32_dpp v167, v166 quad_perm:[1,0,3,2] row_mask:0xf bank_mask:0xf
	s_waitcnt lgkmcnt(0)
	v_add_f32_e32 v166, v166, v167
	s_nop 5
	v_mov_b32_dpp v167, v166 quad_perm:[2,3,0,1] row_mask:0xf bank_mask:0xf
	s_waitcnt lgkmcnt(0)
	v_add_f32_e32 v167, v166, v167
	s_nop 5
	v_mov_b32_dpp v169, v167 row_half_mirror row_mask:0xf bank_mask:0xf
	v_cvt_pk_bf16_f32 v166, v162, v163
	v_xor_b32_e32 v163, 8, v219
	v_cmp_lt_i32_e32 vcc, v163, v168
	s_waitcnt lgkmcnt(0)
	v_add_f32_e32 v162, v167, v169
	s_nop 1
	v_mov_b32_dpp v163, v162 row_mirror row_mask:0xf bank_mask:0xf
	v_cvt_pk_bf16_f32 v167, v164, v165
	v_mad_i64_i32 v[164:165], s[0:1], v170, s66, v[182:183]
	global_store_dwordx2 v[164:165], v[166:167], off
	s_and_saveexec_b64 s[0:1], s[4:5]
	s_cbranch_execz .LBB0_1715
	s_waitcnt lgkmcnt(0)
	v_add_f32_e32 v164, v162, v163
	v_lshl_add_u64 v[162:163], v[178:179], 2, s[38:39]
	global_atomic_add_f32 v[162:163], v164, off offset:48

; DI unsigned pack_bf16(float lo, float hi) { f32x2 v = {lo, hi}; bf16v2 b = __builtin_convertvector(v, bf16v2); return __builtin_bit_cast(unsigned, b); }
; DI float red16(float v) { v += __shfl_xor(v, 1); v += __shfl_xor(v, 2); v += __shfl_xor(v, 4); v += __shfl_xor(v, 8); return v; }
;   DI void run8(f32x4 (&acc)[8][4], int rb, int cb, int fr, int fq) const {
;     ...
;         for (int n = 0; n < 4; ++n)
; #pragma unroll
;           for (int j = 0; j < 4; ++j) scr[(fq * 4 + j) * 68 + n * 16 + fr] = acc[m][n][j];
;         __builtin_amdgcn_sched_barrier(0);
; #pragma unroll
;         for (int ps = 0; ps < 4; ++ps) {
;           const f32x4 a = *(const f32x4*)(scr + (ps * 4 + prow) * 68 + c4 * 4);
;           f32x4 v;
;           v.x = xv[mm][ps].x + a.x * sc; v.y = xv[mm][ps].y + a.y * sc; v.z = xv[mm][ps].z + a.z * sc; v.w = xv[mm][ps].w + a.w * sc;
;           const int grow = rb + m * 16 + ps * 4 + prow;
;           __builtin_nontemporal_store(v, (f32x4*)(op + (size_t)(m * 16 + ps * 4) * D));
;           if (xbp) {
;             u32x2 o; o.x = pack_bf16(v.x, v.y); o.y = pack_bf16(v.z, v.w);
;             *(u32x2*)(xbp + (size_t)grow * LDH + cb + c4 * 4) = o;
;             const float t = red16(v.x * v.x + v.y * v.y + v.z * v.z + v.w * v.w);
;             if (c4 == 0) atomicAdd(ssqp + grow, t);
;           }
.LBB0_1716:
	s_mov_b64 s[0:1], 0x10000
	s_waitcnt lgkmcnt(0)
	v_lshl_add_u64 v[162:163], v[180:181], 0, s[0:1]
	ds_write2_b32 v184, v146, v150 offset1:16
	ds_write2_b32 v184, v147, v151 offset0:68 offset1:84
	ds_write2_b32 v184, v148, v152 offset0:136 offset1:152
	ds_write2_b32 v184, v149, v153 offset0:204 offset1:220
	ds_write2_b32 v184, v138, v142 offset0:32 offset1:48
	ds_write2_b32 v184, v139, v143 offset0:100 offset1:116
	ds_write2_b32 v184, v140, v144 offset0:168 offset1:184
	ds_write2_b32 v184, v141, v145 offset0:236 offset1:252
	ds_read_b128 v[138:141], v0
	s_and_b64 vcc, exec, s[6:7]
	s_waitcnt vmcnt(15) lgkmcnt(0)
	v_pk_fma_f32 v[138:139], v[138:139], 0.5, v[158:159] op_sel_hi:[1,0,1]
	v_pk_fma_f32 v[140:141], v[140:141], 0.5, v[160:161] op_sel_hi:[1,0,1]
	global_store_dwordx4 v[162:163], v[138:141], off nt
	s_cbranch_vccnz .LBB0_1720
	v_pk_mul_f32 v[142:143], v[138:139], v[138:139]
	v_pk_mul_f32 v[144:145], v[140:141], v[140:141]
	v_add_f32_e32 v142, v142, v143
	v_add_f32_e32 v142, v144, v142
	v_and_b32_e32 v144, 64, v219
	s_nop 0
	v_add_u32_e32 v144, 64, v144
	s_nop 0
	v_add_f32_e32 v142, v145, v142
	v_or_b32_e32 v146, 16, v178
	s_nop 1
	v_mov_b32_dpp v143, v142 quad_perm:[1,0,3,2] row_mask:0xf bank_mask:0xf
	s_waitcnt lgkmcnt(0)
	v_add_f32_e32 v142, v142, v143
	s_nop 5
	v_mov_b32_dpp v143, v142 quad_perm:[2,3,0,1] row_mask:0xf bank_mask:0xf
	s_waitcnt lgkmcnt(0)
	v_add_f32_e32 v143, v142, v143
	s_nop 5
	v_mov_b32_dpp v145, v143 row_half_mirror row_mask:0xf bank_mask:0xf
	v_cvt_pk_bf16_f32 v142, v138, v139
	v_xor_b32_e32 v139, 8, v219
	v_cmp_lt_i32_e32 vcc, v139, v144
	s_waitcnt lgkmcnt(0)
	v_add_f32_e32 v138, v143, v145
	s_nop 1
	v_mov_b32_dpp v139, v138 row_mirror row_mask:0xf bank_mask:0xf
	v_cvt_pk_bf16_f32 v143, v140, v141
	v_mad_i64_i32 v[140:141], s[0:1], v146, s66, v[182:183]
	global_store_dwordx2 v[140:141], v[142:143], off
	s_and_saveexec_b64 s[0:1], s[4:5]
	s_cbranch_execz .LBB0_1719
	s_waitcnt lgkmcnt(0)
	v_add_f32_e32 v140, v138, v139
	v_lshl_add_u64 v[138:139], v[178:179], 2, s[38:39]
	global_atomic_add_f32 v[138:139], v140, off offset:64

; DI unsigned pack_bf16(float lo, float hi) { f32x2 v = {lo, hi}; bf16v2 b = __builtin_convertvector(v, bf16v2); return __builtin_bit_cast(unsigned, b); }
; DI float red16(float v) { v += __shfl_xor(v, 1); v += __shfl_xor(v, 2); v += __shfl_xor(v, 4); v += __shfl_xor(v, 8); return v; }
;   DI void run8(f32x4 (&acc)[8][4], int rb, int cb, int fr, int fq) const {
;     ...
;         for (int ps = 0; ps < 4; ++ps) {
;           const f32x4 a = *(const f32x4*)(scr + (ps * 4 + prow) * 68 + c4 * 4);
;           f32x4 v;
;           v.x = xv[mm][ps].x + a.x * sc; v.y = xv[mm][ps].y + a.y * sc; v.z = xv[mm][ps].z + a.z * sc; v.w = xv[mm][ps].w + a.w * sc;
;           const int grow = rb + m * 16 + ps * 4 + prow;
;           __builtin_nontemporal_store(v, (f32x4*)(op + (size_t)(m * 16 + ps * 4) * D));
;           if (xbp) {
;             u32x2 o; o.x = pack_bf16(v.x, v.y); o.y = pack_bf16(v.z, v.w);
;             *(u32x2*)(xbp + (size_t)grow * LDH + cb + c4 * 4) = o;
;             const float t = red16(v.x * v.x + v.y * v.y + v.z * v.z + v.w * v.w);
;             if (c4 == 0) atomicAdd(ssqp + grow, t);
;           }
.LBB0_1720:
	s_waitcnt lgkmcnt(0)
	ds_read_b128 v[138:141], v0 offset:1088
	s_mov_b64 s[0:1], 0x14000
	v_lshl_add_u64 v[142:143], v[180:181], 0, s[0:1]
	s_and_b64 vcc, exec, s[6:7]
	s_waitcnt vmcnt(15) lgkmcnt(0)
	v_pk_fma_f32 v[138:139], v[138:139], 0.5, v[154:155] op_sel_hi:[1,0,1]
	v_pk_fma_f32 v[140:141], v[140:141], 0.5, v[156:157] op_sel_hi:[1,0,1]
	global_store_dwordx4 v[142:143], v[138:141], off nt
	s_cbranch_vccnz .LBB0_1724
	v_pk_mul_f32 v[142:143], v[138:139], v[138:139]
	v_pk_mul_f32 v[144:145], v[140:141], v[140:141]
	v_add_f32_e32 v142, v142, v143
	v_add_f32_e32 v142, v144, v142
	v_and_b32_e32 v144, 64, v219
	s_nop 0
	v_add_u32_e32 v144, 64, v144
	s_nop 0
	v_add_f32_e32 v142, v145, v142
	v_or_b32_e32 v146, 20, v178
	s_nop 1
	v_mov_b32_dpp v143, v142 quad_perm:[1,0,3,2] row_mask:0xf bank_mask:0xf
	s_waitcnt lgkmcnt(0)
	v_add_f32_e32 v142, v142, v143
	s_nop 5
	v_mov_b32_dpp v143, v142 quad_perm:[2,3,0,1] row_mask:0xf bank_mask:0xf
	s_waitcnt lgkmcnt(0)
	v_add_f32_e32 v143, v142, v143
	s_nop 5
	v_mov_b32_dpp v145, v143 row_half_mirror row_mask:0xf bank_mask:0xf
	v_cvt_pk_bf16_f32 v142, v138, v139
	v_xor_b32_e32 v139, 8, v219
	v_cmp_lt_i32_e32 vcc, v139, v144
	s_waitcnt lgkmcnt(0)
	v_add_f32_e32 v138, v143, v145
	s_nop 1
	v_mov_b32_dpp v139, v138 row_mirror row_mask:0xf bank_mask:0xf
	v_cvt_pk_bf16_f32 v143, v140, v141
	v_mad_i64_i32 v[140:141], s[0:1], v146, s66, v[182:183]
	global_store_dwordx2 v[140:141], v[142:143], off
	s_and_saveexec_b64 s[0:1], s[4:5]
	s_cbranch_execz .LBB0_1723
	s_waitcnt lgkmcnt(0)
	v_add_f32_e32 v140, v138, v139
	v_lshl_add_u64 v[138:139], v[178:179], 2, s[38:39]
	global_atomic_add_f32 v[138:139], v140, off offset:80

; DI unsigned pack_bf16(float lo, float hi) { f32x2 v = {lo, hi}; bf16v2 b = __builtin_convertvector(v, bf16v2); return __builtin_bit_cast(unsigned, b); }
; DI float red16(float v) { v += __shfl_xor(v, 1); v += __shfl_xor(v, 2); v += __shfl_xor(v, 4); v += __shfl_xor(v, 8); return v; }
;   DI void run8(f32x4 (&acc)[8][4], int rb, int cb, int fr, int fq) const {
;     ...
;         for (int ps = 0; ps < 4; ++ps) {
;           const f32x4 a = *(const f32x4*)(scr + (ps * 4 + prow) * 68 + c4 * 4);
;           f32x4 v;
;           v.x = xv[mm][ps].x + a.x * sc; v.y = xv[mm][ps].y + a.y * sc; v.z = xv[mm][ps].z + a.z * sc; v.w = xv[mm][ps].w + a.w * sc;
;           const int grow = rb + m * 16 + ps * 4 + prow;
;           __builtin_nontemporal_store(v, (f32x4*)(op + (size_t)(m * 16 + ps * 4) * D));
;           if (xbp) {
;             u32x2 o; o.x = pack_bf16(v.x, v.y); o.y = pack_bf16(v.z, v.w);
;             *(u32x2*)(xbp + (size_t)grow * LDH + cb + c4 * 4) = o;
;             const float t = red16(v.x * v.x + v.y * v.y + v.z * v.z + v.w * v.w);
;             if (c4 == 0) atomicAdd(ssqp + grow, t);
;           }
.LBB0_1724:
	s_waitcnt lgkmcnt(0)
	ds_read_b128 v[138:141], v0 offset:2176
	s_mov_b64 s[0:1], 0x18000
	v_lshl_add_u64 v[142:143], v[180:181], 0, s[0:1]
	s_and_b64 vcc, exec, s[6:7]
	s_waitcnt vmcnt(15) lgkmcnt(0)
	v_pk_fma_f32 v[134:135], v[138:139], 0.5, v[134:135] op_sel_hi:[1,0,1]
	v_pk_fma_f32 v[136:137], v[140:141], 0.5, v[136:137] op_sel_hi:[1,0,1]
	global_store_dwordx4 v[142:143], v[134:137], off nt
	s_cbranch_vccnz .LBB0_1728
	v_pk_mul_f32 v[138:139], v[134:135], v[134:135]
	v_pk_mul_f32 v[140:141], v[136:137], v[136:137]
	v_add_f32_e32 v138, v138, v139
	v_add_f32_e32 v138, v140, v138
	v_and_b32_e32 v140, 64, v219
	s_nop 0
	v_add_u32_e32 v140, 64, v140
	s_nop 0
	v_add_f32_e32 v138, v141, v138
	v_or_b32_e32 v142, 24, v178
	s_nop 1
	v_mov_b32_dpp v139, v138 quad_perm:[1,0,3,2] row_mask:0xf bank_mask:0xf
	s_waitcnt lgkmcnt(0)
	v_add_f32_e32 v138, v138, v139
	s_nop 5
	v_mov_b32_dpp v139, v138 quad_perm:[2,3,0,1] row_mask:0xf bank_mask:0xf
	s_waitcnt lgkmcnt(0)
	v_add_f32_e32 v139, v138, v139
	s_nop 5
	v_mov_b32_dpp v141, v139 row_half_mirror row_mask:0xf bank_mask:0xf
	v_cvt_pk_bf16_f32 v138, v134, v135
	v_xor_b32_e32 v135, 8, v219
	v_cmp_lt_i32_e32 vcc, v135, v140
	s_waitcnt lgkmcnt(0)
	v_add_f32_e32 v134, v139, v141
	s_nop 1
	v_mov_b32_dpp v135, v134 row_mirror row_mask:0xf bank_mask:0xf
	v_cvt_pk_bf16_f32 v139, v136, v137
	v_mad_i64_i32 v[136:137], s[0:1], v142, s66, v[182:183]
	global_store_dwordx2 v[136:137], v[138:139], off
	s_and_saveexec_b64 s[0:1], s[4:5]
	s_cbranch_execz .LBB0_1727
	s_waitcnt lgkmcnt(0)
	v_add_f32_e32 v136, v134, v135
	v_lshl_add_u64 v[134:135], v[178:179], 2, s[38:39]
	global_atomic_add_f32 v[134:135], v136, off offset:96

; DI unsigned pack_bf16(float lo, float hi) { f32x2 v = {lo, hi}; bf16v2 b = __builtin_convertvector(v, bf16v2); return __builtin_bit_cast(unsigned, b); }
; DI float red16(float v) { v += __shfl_xor(v, 1); v += __shfl_xor(v, 2); v += __shfl_xor(v, 4); v += __shfl_xor(v, 8); return v; }
;   DI void run8(f32x4 (&acc)[8][4], int rb, int cb, int fr, int fq) const {
;     ...
;         for (int ps = 0; ps < 4; ++ps) {
;           const f32x4 a = *(const f32x4*)(scr + (ps * 4 + prow) * 68 + c4 * 4);
;           f32x4 v;
;           v.x = xv[mm][ps].x + a.x * sc; v.y = xv[mm][ps].y + a.y * sc; v.z = xv[mm][ps].z + a.z * sc; v.w = xv[mm][ps].w + a.w * sc;
;           const int grow = rb + m * 16 + ps * 4 + prow;
;           __builtin_nontemporal_store(v, (f32x4*)(op + (size_t)(m * 16 + ps * 4) * D));
;           if (xbp) {
;             u32x2 o; o.x = pack_bf16(v.x, v.y); o.y = pack_bf16(v.z, v.w);
;             *(u32x2*)(xbp + (size_t)grow * LDH + cb + c4 * 4) = o;
;             const float t = red16(v.x * v.x + v.y * v.y + v.z * v.z + v.w * v.w);
;             if (c4 == 0) atomicAdd(ssqp + grow, t);
;           }
.LBB0_1728:
	s_waitcnt lgkmcnt(0)
	ds_read_b128 v[134:137], v0 offset:3264
	s_mov_b64 s[0:1], 0x1c000
	v_lshl_add_u64 v[138:139], v[180:181], 0, s[0:1]
	s_and_b64 vcc, exec, s[6:7]
	s_waitcnt vmcnt(15) lgkmcnt(0)
	v_pk_fma_f32 v[130:131], v[134:135], 0.5, v[130:131] op_sel_hi:[1,0,1]
	v_pk_fma_f32 v[132:133], v[136:137], 0.5, v[132:133] op_sel_hi:[1,0,1]
	global_store_dwordx4 v[138:139], v[130:133], off nt
	s_cbranch_vccnz .LBB0_1732
	v_pk_mul_f32 v[134:135], v[130:131], v[130:131]
	v_pk_mul_f32 v[136:137], v[132:133], v[132:133]
	v_add_f32_e32 v134, v134, v135
	v_add_f32_e32 v134, v136, v134
	v_and_b32_e32 v136, 64, v219
	s_nop 0
	v_add_u32_e32 v136, 64, v136
	s_nop 0
	v_add_f32_e32 v134, v137, v134
	v_or_b32_e32 v138, 28, v178
	s_nop 1
	v_mov_b32_dpp v135, v134 quad_perm:[1,0,3,2] row_mask:0xf bank_mask:0xf
	s_waitcnt lgkmcnt(0)
	v_add_f32_e32 v134, v134, v135
	s_nop 5
	v_mov_b32_dpp v135, v134 quad_perm:[2,3,0,1] row_mask:0xf bank_mask:0xf
	s_waitcnt lgkmcnt(0)
	v_add_f32_e32 v135, v134, v135
	s_nop 5
	v_mov_b32_dpp v137, v135 row_half_mirror row_mask:0xf bank_mask:0xf
	v_cvt_pk_bf16_f32 v134, v130, v131
	v_xor_b32_e32 v131, 8, v219
	v_cmp_lt_i32_e32 vcc, v131, v136
	s_waitcnt lgkmcnt(0)
	v_add_f32_e32 v130, v135, v137
	s_nop 1
	v_mov_b32_dpp v131, v130 row_mirror row_mask:0xf bank_mask:0xf
	v_cvt_pk_bf16_f32 v135, v132, v133
	v_mad_i64_i32 v[132:133], s[0:1], v138, s66, v[182:183]
	global_store_dwordx2 v[132:133], v[134:135], off
	s_and_saveexec_b64 s[0:1], s[4:5]
	s_cbranch_execz .LBB0_1731
	s_waitcnt lgkmcnt(0)
	v_add_f32_e32 v132, v130, v131
	v_lshl_add_u64 v[130:131], v[178:179], 2, s[38:39]
	global_atomic_add_f32 v[130:131], v132, off offset:112

; DI unsigned pack_bf16(float lo, float hi) { f32x2 v = {lo, hi}; bf16v2 b = __builtin_convertvector(v, bf16v2); return __builtin_bit_cast(unsigned, b); }
; DI float red16(float v) { v += __shfl_xor(v, 1); v += __shfl_xor(v, 2); v += __shfl_xor(v, 4); v += __shfl_xor(v, 8); return v; }
;   DI void run8(f32x4 (&acc)[8][4], int rb, int cb, int fr, int fq) const {
;     ...
;         for (int n = 0; n < 4; ++n)
; #pragma unroll
;           for (int j = 0; j < 4; ++j) scr[(fq * 4 + j) * 68 + n * 16 + fr] = acc[m][n][j];
;         __builtin_amdgcn_sched_barrier(0);
; #pragma unroll
;         for (int ps = 0; ps < 4; ++ps) {
;           const f32x4 a = *(const f32x4*)(scr + (ps * 4 + prow) * 68 + c4 * 4);
;           f32x4 v;
;           v.x = xv[mm][ps].x + a.x * sc; v.y = xv[mm][ps].y + a.y * sc; v.z = xv[mm][ps].z + a.z * sc; v.w = xv[mm][ps].w + a.w * sc;
;           const int grow = rb + m * 16 + ps * 4 + prow;
;           __builtin_nontemporal_store(v, (f32x4*)(op + (size_t)(m * 16 + ps * 4) * D));
;           if (xbp) {
;             u32x2 o; o.x = pack_bf16(v.x, v.y); o.y = pack_bf16(v.z, v.w);
;             *(u32x2*)(xbp + (size_t)grow * LDH + cb + c4 * 4) = o;
;             const float t = red16(v.x * v.x + v.y * v.y + v.z * v.z + v.w * v.w);
;             if (c4 == 0) atomicAdd(ssqp + grow, t);
;           }
.LBB0_1732:
	s_mov_b64 s[0:1], 0x20000
	s_waitcnt lgkmcnt(0)
	v_lshl_add_u64 v[130:131], v[180:181], 0, s[0:1]
	ds_write2_b32 v184, v114, v118 offset1:16
	ds_write2_b32 v184, v115, v119 offset0:68 offset1:84
	ds_write2_b32 v184, v116, v120 offset0:136 offset1:152
	ds_write2_b32 v184, v117, v121 offset0:204 offset1:220
	ds_write2_b32 v184, v106, v110 offset0:32 offset1:48
	ds_write2_b32 v184, v107, v111 offset0:100 offset1:116
	ds_write2_b32 v184, v108, v112 offset0:168 offset1:184
	ds_write2_b32 v184, v109, v113 offset0:236 offset1:252
	ds_read_b128 v[106:109], v0
	s_and_b64 vcc, exec, s[6:7]
	s_waitcnt vmcnt(15) lgkmcnt(0)
	v_pk_fma_f32 v[106:107], v[106:107], 0.5, v[126:127] op_sel_hi:[1,0,1]
	v_pk_fma_f32 v[108:109], v[108:109], 0.5, v[128:129] op_sel_hi:[1,0,1]
	global_store_dwordx4 v[130:131], v[106:109], off nt
	s_cbranch_vccnz .LBB0_1736
	v_pk_mul_f32 v[110:111], v[106:107], v[106:107]
	v_pk_mul_f32 v[112:113], v[108:109], v[108:109]
	v_add_f32_e32 v110, v110, v111
	v_add_f32_e32 v110, v112, v110
	v_and_b32_e32 v112, 64, v219
	s_nop 0
	v_add_u32_e32 v112, 64, v112
	s_nop 0
	v_add_f32_e32 v110, v113, v110
	v_or_b32_e32 v114, 32, v178
	s_nop 1
	v_mov_b32_dpp v111, v110 quad_perm:[1,0,3,2] row_mask:0xf bank_mask:0xf
	s_waitcnt lgkmcnt(0)
	v_add_f32_e32 v110, v110, v111
	s_nop 5
	v_mov_b32_dpp v111, v110 quad_perm:[2,3,0,1] row_mask:0xf bank_mask:0xf
	s_waitcnt lgkmcnt(0)
	v_add_f32_e32 v111, v110, v111
	s_nop 5
	v_mov_b32_dpp v113, v111 row_half_mirror row_mask:0xf bank_mask:0xf
	v_cvt_pk_bf16_f32 v110, v106, v107
	v_xor_b32_e32 v107, 8, v219
	v_cmp_lt_i32_e32 vcc, v107, v112
	s_waitcnt lgkmcnt(0)
	v_add_f32_e32 v106, v111, v113
	s_nop 1
	v_mov_b32_dpp v107, v106 row_mirror row_mask:0xf bank_mask:0xf
	v_cvt_pk_bf16_f32 v111, v108, v109
	v_mad_i64_i32 v[108:109], s[0:1], v114, s66, v[182:183]
	global_store_dwordx2 v[108:109], v[110:111], off
	s_and_saveexec_b64 s[0:1], s[4:5]
	s_cbranch_execz .LBB0_1735
	s_waitcnt lgkmcnt(0)
	v_add_f32_e32 v108, v106, v107
	v_lshl_add_u64 v[106:107], v[178:179], 2, s[38:39]
	global_atomic_add_f32 v[106:107], v108, off offset:128

; DI unsigned pack_bf16(float lo, float hi) { f32x2 v = {lo, hi}; bf16v2 b = __builtin_convertvector(v, bf16v2); return __builtin_bit_cast(unsigned, b); }
; DI float red16(float v) { v += __shfl_xor(v, 1); v += __shfl_xor(v, 2); v += __shfl_xor(v, 4); v += __shfl_xor(v, 8); return v; }
;   DI void run8(f32x4 (&acc)[8][4], int rb, int cb, int fr, int fq) const {
;     ...
;         for (int ps = 0; ps < 4; ++ps) {
;           const f32x4 a = *(const f32x4*)(scr + (ps * 4 + prow) * 68 + c4 * 4);
;           f32x4 v;
;           v.x = xv[mm][ps].x + a.x * sc; v.y = xv[mm][ps].y + a.y * sc; v.z = xv[mm][ps].z + a.z * sc; v.w = xv[mm][ps].w + a.w * sc;
;           const int grow = rb + m * 16 + ps * 4 + prow;
;           __builtin_nontemporal_store(v, (f32x4*)(op + (size_t)(m * 16 + ps * 4) * D));
;           if (xbp) {
;             u32x2 o; o.x = pack_bf16(v.x, v.y); o.y = pack_bf16(v.z, v.w);
;             *(u32x2*)(xbp + (size_t)grow * LDH + cb + c4 * 4) = o;
;             const float t = red16(v.x * v.x + v.y * v.y + v.z * v.z + v.w * v.w);
;             if (c4 == 0) atomicAdd(ssqp + grow, t);
;           }
.LBB0_1736:
	s_waitcnt lgkmcnt(0)
	ds_read_b128 v[106:109], v0 offset:1088
	s_mov_b64 s[0:1], 0x24000
	v_lshl_add_u64 v[110:111], v[180:181], 0, s[0:1]
	s_and_b64 vcc, exec, s[6:7]
	s_waitcnt vmcnt(15) lgkmcnt(0)
	v_pk_fma_f32 v[106:107], v[106:107], 0.5, v[122:123] op_sel_hi:[1,0,1]
	v_pk_fma_f32 v[108:109], v[108:109], 0.5, v[124:125] op_sel_hi:[1,0,1]
	global_store_dwordx4 v[110:111], v[106:109], off nt
	s_cbranch_vccnz .LBB0_1740
	v_pk_mul_f32 v[110:111], v[106:107], v[106:107]
	v_pk_mul_f32 v[112:113], v[108:109], v[108:109]
	v_add_f32_e32 v110, v110, v111
	v_add_f32_e32 v110, v112, v110
	v_and_b32_e32 v112, 64, v219
	s_nop 0
	v_add_u32_e32 v112, 64, v112
	s_nop 0
	v_add_f32_e32 v110, v113, v110
	v_or_b32_e32 v114, 36, v178
	s_nop 1
	v_mov_b32_dpp v111, v110 quad_perm:[1,0,3,2] row_mask:0xf bank_mask:0xf
	s_waitcnt lgkmcnt(0)
	v_add_f32_e32 v110, v110, v111
	s_nop 5
	v_mov_b32_dpp v111, v110 quad_perm:[2,3,0,1] row_mask:0xf bank_mask:0xf
	s_waitcnt lgkmcnt(0)
	v_add_f32_e32 v111, v110, v111
	s_nop 5
	v_mov_b32_dpp v113, v111 row_half_mirror row_mask:0xf bank_mask:0xf
	v_cvt_pk_bf16_f32 v110, v106, v107
	v_xor_b32_e32 v107, 8, v219
	v_cmp_lt_i32_e32 vcc, v107, v112
	s_waitcnt lgkmcnt(0)
	v_add_f32_e32 v106, v111, v113
	s_nop 1
	v_mov_b32_dpp v107, v106 row_mirror row_mask:0xf bank_mask:0xf
	v_cvt_pk_bf16_f32 v111, v108, v109
	v_mad_i64_i32 v[108:109], s[0:1], v114, s66, v[182:183]
	global_store_dwordx2 v[108:109], v[110:111], off
	s_and_saveexec_b64 s[0:1], s[4:5]
	s_cbranch_execz .LBB0_1739
	s_waitcnt lgkmcnt(0)
	v_add_f32_e32 v108, v106, v107
	v_lshl_add_u64 v[106:107], v[178:179], 2, s[38:39]
	global_atomic_add_f32 v[106:107], v108, off offset:144

; DI unsigned pack_bf16(float lo, float hi) { f32x2 v = {lo, hi}; bf16v2 b = __builtin_convertvector(v, bf16v2); return __builtin_bit_cast(unsigned, b); }
; DI float red16(float v) { v += __shfl_xor(v, 1); v += __shfl_xor(v, 2); v += __shfl_xor(v, 4); v += __shfl_xor(v, 8); return v; }
;   DI void run8(f32x4 (&acc)[8][4], int rb, int cb, int fr, int fq) const {
;     ...
;         for (int ps = 0; ps < 4; ++ps) {
;           const f32x4 a = *(const f32x4*)(scr + (ps * 4 + prow) * 68 + c4 * 4);
;           f32x4 v;
;           v.x = xv[mm][ps].x + a.x * sc; v.y = xv[mm][ps].y + a.y * sc; v.z = xv[mm][ps].z + a.z * sc; v.w = xv[mm][ps].w + a.w * sc;
;           const int grow = rb + m * 16 + ps * 4 + prow;
;           __builtin_nontemporal_store(v, (f32x4*)(op + (size_t)(m * 16 + ps * 4) * D));
;           if (xbp) {
;             u32x2 o; o.x = pack_bf16(v.x, v.y); o.y = pack_bf16(v.z, v.w);
;             *(u32x2*)(xbp + (size_t)grow * LDH + cb + c4 * 4) = o;
;             const float t = red16(v.x * v.x + v.y * v.y + v.z * v.z + v.w * v.w);
;             if (c4 == 0) atomicAdd(ssqp + grow, t);
;           }
.LBB0_1740:
	s_waitcnt lgkmcnt(0)
	ds_read_b128 v[106:109], v0 offset:2176
	s_mov_b64 s[0:1], 0x28000
	v_lshl_add_u64 v[110:111], v[180:181], 0, s[0:1]
	s_and_b64 vcc, exec, s[6:7]
	s_waitcnt vmcnt(15) lgkmcnt(0)
	v_pk_fma_f32 v[102:103], v[106:107], 0.5, v[102:103] op_sel_hi:[1,0,1]
	v_pk_fma_f32 v[104:105], v[108:109], 0.5, v[104:105] op_sel_hi:[1,0,1]
	global_store_dwordx4 v[110:111], v[102:105], off nt
	s_cbranch_vccnz .LBB0_1744
	v_pk_mul_f32 v[106:107], v[102:103], v[102:103]
	v_pk_mul_f32 v[108:109], v[104:105], v[104:105]
	v_add_f32_e32 v106, v106, v107
	v_add_f32_e32 v106, v108, v106
	v_and_b32_e32 v108, 64, v219
	s_nop 0
	v_add_u32_e32 v108, 64, v108
	s_nop 0
	v_add_f32_e32 v106, v109, v106
	v_or_b32_e32 v110, 40, v178
	s_nop 1
	v_mov_b32_dpp v107, v106 quad_perm:[1,0,3,2] row_mask:0xf bank_mask:0xf
	s_waitcnt lgkmcnt(0)
	v_add_f32_e32 v106, v106, v107
	s_nop 5
	v_mov_b32_dpp v107, v106 quad_perm:[2,3,0,1] row_mask:0xf bank_mask:0xf
	s_waitcnt lgkmcnt(0)
	v_add_f32_e32 v107, v106, v107
	s_nop 5
	v_mov_b32_dpp v109, v107 row_half_mirror row_mask:0xf bank_mask:0xf
	v_cvt_pk_bf16_f32 v106, v102, v103
	v_xor_b32_e32 v103, 8, v219
	v_cmp_lt_i32_e32 vcc, v103, v108
	s_waitcnt lgkmcnt(0)
	v_add_f32_e32 v102, v107, v109
	s_nop 1
	v_mov_b32_dpp v103, v102 row_mirror row_mask:0xf bank_mask:0xf
	v_cvt_pk_bf16_f32 v107, v104, v105
	v_mad_i64_i32 v[104:105], s[0:1], v110, s66, v[182:183]
	global_store_dwordx2 v[104:105], v[106:107], off
	s_and_saveexec_b64 s[0:1], s[4:5]
	s_cbranch_execz .LBB0_1743
	s_waitcnt lgkmcnt(0)
	v_add_f32_e32 v104, v102, v103
	v_lshl_add_u64 v[102:103], v[178:179], 2, s[38:39]
	global_atomic_add_f32 v[102:103], v104, off offset:160

; DI unsigned pack_bf16(float lo, float hi) { f32x2 v = {lo, hi}; bf16v2 b = __builtin_convertvector(v, bf16v2); return __builtin_bit_cast(unsigned, b); }
; DI float red16(float v) { v += __shfl_xor(v, 1); v += __shfl_xor(v, 2); v += __shfl_xor(v, 4); v += __shfl_xor(v, 8); return v; }
;   DI void run8(f32x4 (&acc)[8][4], int rb, int cb, int fr, int fq) const {
;     ...
;         for (int ps = 0; ps < 4; ++ps) {
;           const f32x4 a = *(const f32x4*)(scr + (ps * 4 + prow) * 68 + c4 * 4);
;           f32x4 v;
;           v.x = xv[mm][ps].x + a.x * sc; v.y = xv[mm][ps].y + a.y * sc; v.z = xv[mm][ps].z + a.z * sc; v.w = xv[mm][ps].w + a.w * sc;
;           const int grow = rb + m * 16 + ps * 4 + prow;
;           __builtin_nontemporal_store(v, (f32x4*)(op + (size_t)(m * 16 + ps * 4) * D));
;           if (xbp) {
;             u32x2 o; o.x = pack_bf16(v.x, v.y); o.y = pack_bf16(v.z, v.w);
;             *(u32x2*)(xbp + (size_t)grow * LDH + cb + c4 * 4) = o;
;             const float t = red16(v.x * v.x + v.y * v.y + v.z * v.z + v.w * v.w);
;             if (c4 == 0) atomicAdd(ssqp + grow, t);
;           }
.LBB0_1744:
	s_waitcnt lgkmcnt(0)
	ds_read_b128 v[102:105], v0 offset:3264
	s_mov_b64 s[0:1], 0x2c000
	v_lshl_add_u64 v[106:107], v[180:181], 0, s[0:1]
	s_and_b64 vcc, exec, s[6:7]
	s_waitcnt vmcnt(15) lgkmcnt(0)
	v_pk_fma_f32 v[98:99], v[102:103], 0.5, v[98:99] op_sel_hi:[1,0,1]
	v_pk_fma_f32 v[100:101], v[104:105], 0.5, v[100:101] op_sel_hi:[1,0,1]
	global_store_dwordx4 v[106:107], v[98:101], off nt
	s_cbranch_vccnz .LBB0_1748
	v_pk_mul_f32 v[102:103], v[98:99], v[98:99]
	v_pk_mul_f32 v[104:105], v[100:101], v[100:101]
	v_add_f32_e32 v102, v102, v103
	v_add_f32_e32 v102, v104, v102
	v_and_b32_e32 v104, 64, v219
	s_nop 0
	v_add_u32_e32 v104, 64, v104
	s_nop 0
	v_add_f32_e32 v102, v105, v102
	v_or_b32_e32 v106, 44, v178
	s_nop 1
	v_mov_b32_dpp v103, v102 quad_perm:[1,0,3,2] row_mask:0xf bank_mask:0xf
	s_waitcnt lgkmcnt(0)
	v_add_f32_e32 v102, v102, v103
	s_nop 5
	v_mov_b32_dpp v103, v102 quad_perm:[2,3,0,1] row_mask:0xf bank_mask:0xf
	s_waitcnt lgkmcnt(0)
	v_add_f32_e32 v103, v102, v103
	s_nop 5
	v_mov_b32_dpp v105, v103 row_half_mirror row_mask:0xf bank_mask:0xf
	v_cvt_pk_bf16_f32 v102, v98, v99
	v_xor_b32_e32 v99, 8, v219
	v_cmp_lt_i32_e32 vcc, v99, v104
	s_waitcnt lgkmcnt(0)
	v_add_f32_e32 v98, v103, v105
	s_nop 1
	v_mov_b32_dpp v99, v98 row_mirror row_mask:0xf bank_mask:0xf
	v_cvt_pk_bf16_f32 v103, v100, v101
	v_mad_i64_i32 v[100:101], s[0:1], v106, s66, v[182:183]
	global_store_dwordx2 v[100:101], v[102:103], off
	s_and_saveexec_b64 s[0:1], s[4:5]
	s_cbranch_execz .LBB0_1747
	s_waitcnt lgkmcnt(0)
	v_add_f32_e32 v100, v98, v99
	v_lshl_add_u64 v[98:99], v[178:179], 2, s[38:39]
	global_atomic_add_f32 v[98:99], v100, off offset:176

; DI unsigned pack_bf16(float lo, float hi) { f32x2 v = {lo, hi}; bf16v2 b = __builtin_convertvector(v, bf16v2); return __builtin_bit_cast(unsigned, b); }
; DI float red16(float v) { v += __shfl_xor(v, 1); v += __shfl_xor(v, 2); v += __shfl_xor(v, 4); v += __shfl_xor(v, 8); return v; }
;   DI void run8(f32x4 (&acc)[8][4], int rb, int cb, int fr, int fq) const {
;     ...
;         for (int n = 0; n < 4; ++n)
; #pragma unroll
;           for (int j = 0; j < 4; ++j) scr[(fq * 4 + j) * 68 + n * 16 + fr] = acc[m][n][j];
;         __builtin_amdgcn_sched_barrier(0);
; #pragma unroll
;         for (int ps = 0; ps < 4; ++ps) {
;           const f32x4 a = *(const f32x4*)(scr + (ps * 4 + prow) * 68 + c4 * 4);
;           f32x4 v;
;           v.x = xv[mm][ps].x + a.x * sc; v.y = xv[mm][ps].y + a.y * sc; v.z = xv[mm][ps].z + a.z * sc; v.w = xv[mm][ps].w + a.w * sc;
;           const int grow = rb + m * 16 + ps * 4 + prow;
;           __builtin_nontemporal_store(v, (f32x4*)(op + (size_t)(m * 16 + ps * 4) * D));
;           if (xbp) {
;             u32x2 o; o.x = pack_bf16(v.x, v.y); o.y = pack_bf16(v.z, v.w);
;             *(u32x2*)(xbp + (size_t)grow * LDH + cb + c4 * 4) = o;
;             const float t = red16(v.x * v.x + v.y * v.y + v.z * v.z + v.w * v.w);
;             if (c4 == 0) atomicAdd(ssqp + grow, t);
;           }
.LBB0_1748:
	s_mov_b64 s[0:1], 0x30000
	s_waitcnt lgkmcnt(0)
	v_lshl_add_u64 v[98:99], v[180:181], 0, s[0:1]
	ds_write2_b32 v184, v82, v86 offset1:16
	ds_write2_b32 v184, v83, v87 offset0:68 offset1:84
	ds_write2_b32 v184, v84, v88 offset0:136 offset1:152
	ds_write2_b32 v184, v85, v89 offset0:204 offset1:220
	ds_write2_b32 v184, v74, v78 offset0:32 offset1:48
	ds_write2_b32 v184, v75, v79 offset0:100 offset1:116
	ds_write2_b32 v184, v76, v80 offset0:168 offset1:184
	ds_write2_b32 v184, v77, v81 offset0:236 offset1:252
	ds_read_b128 v[74:77], v0
	s_and_b64 vcc, exec, s[6:7]
	s_waitcnt vmcnt(15) lgkmcnt(0)
	v_pk_fma_f32 v[74:75], v[74:75], 0.5, v[94:95] op_sel_hi:[1,0,1]
	v_pk_fma_f32 v[76:77], v[76:77], 0.5, v[96:97] op_sel_hi:[1,0,1]
	global_store_dwordx4 v[98:99], v[74:77], off nt
	s_cbranch_vccnz .LBB0_1752
	v_pk_mul_f32 v[78:79], v[74:75], v[74:75]
	v_pk_mul_f32 v[80:81], v[76:77], v[76:77]
	v_add_f32_e32 v78, v78, v79
	v_add_f32_e32 v78, v80, v78
	v_and_b32_e32 v80, 64, v219
	s_nop 0
	v_add_u32_e32 v80, 64, v80
	s_nop 0
	v_add_f32_e32 v78, v81, v78
	v_or_b32_e32 v82, 48, v178
	s_nop 1
	v_mov_b32_dpp v79, v78 quad_perm:[1,0,3,2] row_mask:0xf bank_mask:0xf
	s_waitcnt lgkmcnt(0)
	v_add_f32_e32 v78, v78, v79
	s_nop 5
	v_mov_b32_dpp v79, v78 quad_perm:[2,3,0,1] row_mask:0xf bank_mask:0xf
	s_waitcnt lgkmcnt(0)
	v_add_f32_e32 v79, v78, v79
	s_nop 5
	v_mov_b32_dpp v81, v79 row_half_mirror row_mask:0xf bank_mask:0xf
	v_cvt_pk_bf16_f32 v78, v74, v75
	v_xor_b32_e32 v75, 8, v219
	v_cmp_lt_i32_e32 vcc, v75, v80
	s_waitcnt lgkmcnt(0)
	v_add_f32_e32 v74, v79, v81
	s_nop 1
	v_mov_b32_dpp v75, v74 row_mirror row_mask:0xf bank_mask:0xf
	v_cvt_pk_bf16_f32 v79, v76, v77
	v_mad_i64_i32 v[76:77], s[0:1], v82, s66, v[182:183]
	global_store_dwordx2 v[76:77], v[78:79], off
	s_and_saveexec_b64 s[0:1], s[4:5]
	s_cbranch_execz .LBB0_1751
	s_waitcnt lgkmcnt(0)
	v_add_f32_e32 v76, v74, v75
	v_lshl_add_u64 v[74:75], v[178:179], 2, s[38:39]
	global_atomic_add_f32 v[74:75], v76, off offset:192

; DI unsigned pack_bf16(float lo, float hi) { f32x2 v = {lo, hi}; bf16v2 b = __builtin_convertvector(v, bf16v2); return __builtin_bit_cast(unsigned, b); }
; DI float red16(float v) { v += __shfl_xor(v, 1); v += __shfl_xor(v, 2); v += __shfl_xor(v, 4); v += __shfl_xor(v, 8); return v; }
;   DI void run8(f32x4 (&acc)[8][4], int rb, int cb, int fr, int fq) const {
;     ...
;         for (int ps = 0; ps < 4; ++ps) {
;           const f32x4 a = *(const f32x4*)(scr + (ps * 4 + prow) * 68 + c4 * 4);
;           f32x4 v;
;           v.x = xv[mm][ps].x + a.x * sc; v.y = xv[mm][ps].y + a.y * sc; v.z = xv[mm][ps].z + a.z * sc; v.w = xv[mm][ps].w + a.w * sc;
;           const int grow = rb + m * 16 + ps * 4 + prow;
;           __builtin_nontemporal_store(v, (f32x4*)(op + (size_t)(m * 16 + ps * 4) * D));
;           if (xbp) {
;             u32x2 o; o.x = pack_bf16(v.x, v.y); o.y = pack_bf16(v.z, v.w);
;             *(u32x2*)(xbp + (size_t)grow * LDH + cb + c4 * 4) = o;
;             const float t = red16(v.x * v.x + v.y * v.y + v.z * v.z + v.w * v.w);
;             if (c4 == 0) atomicAdd(ssqp + grow, t);
;           }
;         }
.LBB0_1752:
	s_waitcnt lgkmcnt(0)
	ds_read_b128 v[74:77], v0 offset:1088
	s_mov_b64 s[0:1], 0x34000
	v_lshl_add_u64 v[78:79], v[180:181], 0, s[0:1]
	s_and_b64 vcc, exec, s[6:7]
	s_waitcnt vmcnt(15) lgkmcnt(0)
	v_pk_fma_f32 v[74:75], v[74:75], 0.5, v[90:91] op_sel_hi:[1,0,1]
	v_pk_fma_f32 v[76:77], v[76:77], 0.5, v[92:93] op_sel_hi:[1,0,1]
	global_store_dwordx4 v[78:79], v[74:77], off nt
	s_cbranch_vccnz .LBB0_1756
	v_pk_mul_f32 v[78:79], v[74:75], v[74:75]
	v_pk_mul_f32 v[80:81], v[76:77], v[76:77]
	v_add_f32_e32 v78, v78, v79
	v_add_f32_e32 v78, v80, v78
	v_and_b32_e32 v80, 64, v219
	s_nop 0
	v_add_u32_e32 v80, 64, v80
	s_nop 0
	v_add_f32_e32 v78, v81, v78
	v_or_b32_e32 v82, 52, v178
	s_nop 1
	v_mov_b32_dpp v79, v78 quad_perm:[1,0,3,2] row_mask:0xf bank_mask:0xf
	s_waitcnt lgkmcnt(0)
	v_add_f32_e32 v78, v78, v79
	s_nop 5
	v_mov_b32_dpp v79, v78 quad_perm:[2,3,0,1] row_mask:0xf bank_mask:0xf
	s_waitcnt lgkmcnt(0)
	v_add_f32_e32 v79, v78, v79
	s_nop 5
	v_mov_b32_dpp v81, v79 row_half_mirror row_mask:0xf bank_mask:0xf
	v_cvt_pk_bf16_f32 v78, v74, v75
	v_xor_b32_e32 v75, 8, v219
	v_cmp_lt_i32_e32 vcc, v75, v80
	s_waitcnt lgkmcnt(0)
	v_add_f32_e32 v74, v79, v81
	s_nop 1
	v_mov_b32_dpp v75, v74 row_mirror row_mask:0xf bank_mask:0xf
	v_cvt_pk_bf16_f32 v79, v76, v77
	v_mad_i64_i32 v[76:77], s[0:1], v82, s66, v[182:183]
	global_store_dwordx2 v[76:77], v[78:79], off
	s_and_saveexec_b64 s[0:1], s[4:5]
	s_cbranch_execz .LBB0_1755
	s_waitcnt lgkmcnt(0)
	v_add_f32_e32 v76, v74, v75
	v_lshl_add_u64 v[74:75], v[178:179], 2, s[38:39]
	global_atomic_add_f32 v[74:75], v76, off offset:208

; DI unsigned pack_bf16(float lo, float hi) { f32x2 v = {lo, hi}; bf16v2 b = __builtin_convertvector(v, bf16v2); return __builtin_bit_cast(unsigned, b); }
; DI float red16(float v) { v += __shfl_xor(v, 1); v += __shfl_xor(v, 2); v += __shfl_xor(v, 4); v += __shfl_xor(v, 8); return v; }
;   DI void run8(f32x4 (&acc)[8][4], int rb, int cb, int fr, int fq) const {
;     ...
;         for (int ps = 0; ps < 4; ++ps) {
;           const f32x4 a = *(const f32x4*)(scr + (ps * 4 + prow) * 68 + c4 * 4);
;           f32x4 v;
;           v.x = xv[mm][ps].x + a.x * sc; v.y = xv[mm][ps].y + a.y * sc; v.z = xv[mm][ps].z + a.z * sc; v.w = xv[mm][ps].w + a.w * sc;
;           const int grow = rb + m * 16 + ps * 4 + prow;
;           __builtin_nontemporal_store(v, (f32x4*)(op + (size_t)(m * 16 + ps * 4) * D));
;           if (xbp) {
;             u32x2 o; o.x = pack_bf16(v.x, v.y); o.y = pack_bf16(v.z, v.w);
;             *(u32x2*)(xbp + (size_t)grow * LDH + cb + c4 * 4) = o;
;             const float t = red16(v.x * v.x + v.y * v.y + v.z * v.z + v.w * v.w);
;             if (c4 == 0) atomicAdd(ssqp + grow, t);
;           }
;         }
.LBB0_1756:
	s_waitcnt lgkmcnt(0)
	ds_read_b128 v[74:77], v0 offset:2176
	s_mov_b64 s[0:1], 0x38000
	v_lshl_add_u64 v[78:79], v[180:181], 0, s[0:1]
	s_and_b64 vcc, exec, s[6:7]
	s_waitcnt vmcnt(15) lgkmcnt(0)
	v_pk_fma_f32 v[70:71], v[74:75], 0.5, v[70:71] op_sel_hi:[1,0,1]
	v_pk_fma_f32 v[72:73], v[76:77], 0.5, v[72:73] op_sel_hi:[1,0,1]
	global_store_dwordx4 v[78:79], v[70:73], off nt
	s_cbranch_vccnz .LBB0_1760
	v_pk_mul_f32 v[74:75], v[70:71], v[70:71]
	v_pk_mul_f32 v[76:77], v[72:73], v[72:73]
	v_add_f32_e32 v74, v74, v75
	v_add_f32_e32 v74, v76, v74
	v_and_b32_e32 v76, 64, v219
	s_nop 0
	v_add_u32_e32 v76, 64, v76
	s_nop 0
	v_add_f32_e32 v74, v77, v74
	v_or_b32_e32 v78, 56, v178
	s_nop 1
	v_mov_b32_dpp v75, v74 quad_perm:[1,0,3,2] row_mask:0xf bank_mask:0xf
	s_waitcnt lgkmcnt(0)
	v_add_f32_e32 v74, v74, v75
	s_nop 5
	v_mov_b32_dpp v75, v74 quad_perm:[2,3,0,1] row_mask:0xf bank_mask:0xf
	s_waitcnt lgkmcnt(0)
	v_add_f32_e32 v75, v74, v75
	s_nop 5
	v_mov_b32_dpp v77, v75 row_half_mirror row_mask:0xf bank_mask:0xf
	v_cvt_pk_bf16_f32 v74, v70, v71
	v_xor_b32_e32 v71, 8, v219
	v_cmp_lt_i32_e32 vcc, v71, v76
	s_waitcnt lgkmcnt(0)
	v_add_f32_e32 v70, v75, v77
	s_nop 1
	v_mov_b32_dpp v71, v70 row_mirror row_mask:0xf bank_mask:0xf
	v_cvt_pk_bf16_f32 v75, v72, v73
	v_mad_i64_i32 v[72:73], s[0:1], v78, s66, v[182:183]
	global_store_dwordx2 v[72:73], v[74:75], off
	s_and_saveexec_b64 s[0:1], s[4:5]
	s_cbranch_execz .LBB0_1759
	s_waitcnt lgkmcnt(0)
	v_add_f32_e32 v72, v70, v71
	v_lshl_add_u64 v[70:71], v[178:179], 2, s[38:39]
	global_atomic_add_f32 v[70:71], v72, off offset:224

; DI unsigned pack_bf16(float lo, float hi) { f32x2 v = {lo, hi}; bf16v2 b = __builtin_convertvector(v, bf16v2); return __builtin_bit_cast(unsigned, b); }
; DI float red16(float v) { v += __shfl_xor(v, 1); v += __shfl_xor(v, 2); v += __shfl_xor(v, 4); v += __shfl_xor(v, 8); return v; }
;   DI void run8(f32x4 (&acc)[8][4], int rb, int cb, int fr, int fq) const {
;     ...
;         for (int ps = 0; ps < 4; ++ps) {
;           const f32x4 a = *(const f32x4*)(scr + (ps * 4 + prow) * 68 + c4 * 4);
;           f32x4 v;
;           v.x = xv[mm][ps].x + a.x * sc; v.y = xv[mm][ps].y + a.y * sc; v.z = xv[mm][ps].z + a.z * sc; v.w = xv[mm][ps].w + a.w * sc;
;           const int grow = rb + m * 16 + ps * 4 + prow;
;           __builtin_nontemporal_store(v, (f32x4*)(op + (size_t)(m * 16 + ps * 4) * D));
;           if (xbp) {
;             u32x2 o; o.x = pack_bf16(v.x, v.y); o.y = pack_bf16(v.z, v.w);
;             *(u32x2*)(xbp + (size_t)grow * LDH + cb + c4 * 4) = o;
;             const float t = red16(v.x * v.x + v.y * v.y + v.z * v.z + v.w * v.w);
;             if (c4 == 0) atomicAdd(ssqp + grow, t);
;           }
;         }
.LBB0_1760:
	s_waitcnt lgkmcnt(0)
	ds_read_b128 v[70:73], v0 offset:3264
	s_mov_b64 s[0:1], 0x3c000
	v_lshl_add_u64 v[74:75], v[180:181], 0, s[0:1]
	s_and_b64 vcc, exec, s[6:7]
	s_waitcnt vmcnt(15) lgkmcnt(0)
	v_pk_fma_f32 v[66:67], v[70:71], 0.5, v[66:67] op_sel_hi:[1,0,1]
	v_pk_fma_f32 v[68:69], v[72:73], 0.5, v[68:69] op_sel_hi:[1,0,1]
	global_store_dwordx4 v[74:75], v[66:69], off nt
	s_cbranch_vccnz .LBB0_1764
	v_pk_mul_f32 v[70:71], v[66:67], v[66:67]
	v_pk_mul_f32 v[72:73], v[68:69], v[68:69]
	v_add_f32_e32 v70, v70, v71
	v_add_f32_e32 v70, v72, v70
	v_and_b32_e32 v72, 64, v219
	s_nop 0
	v_add_u32_e32 v72, 64, v72
	s_nop 0
	v_add_f32_e32 v70, v73, v70
	v_or_b32_e32 v74, 60, v178
	s_nop 1
	v_mov_b32_dpp v71, v70 quad_perm:[1,0,3,2] row_mask:0xf bank_mask:0xf
	s_waitcnt lgkmcnt(0)
	v_add_f32_e32 v70, v70, v71
	s_nop 5
	v_mov_b32_dpp v71, v70 quad_perm:[2,3,0,1] row_mask:0xf bank_mask:0xf
	s_waitcnt lgkmcnt(0)
	v_add_f32_e32 v71, v70, v71
	s_nop 5
	v_mov_b32_dpp v73, v71 row_half_mirror row_mask:0xf bank_mask:0xf
	v_cvt_pk_bf16_f32 v70, v66, v67
	v_xor_b32_e32 v67, 8, v219
	v_cmp_lt_i32_e32 vcc, v67, v72
	s_waitcnt lgkmcnt(0)
	v_add_f32_e32 v66, v71, v73
	s_nop 1
	v_mov_b32_dpp v67, v66 row_mirror row_mask:0xf bank_mask:0xf
	v_cvt_pk_bf16_f32 v71, v68, v69
	v_mad_i64_i32 v[68:69], s[0:1], v74, s66, v[182:183]
	global_store_dwordx2 v[68:69], v[70:71], off
	s_and_saveexec_b64 s[0:1], s[4:5]
	s_cbranch_execz .LBB0_1763
	s_waitcnt lgkmcnt(0)
	v_add_f32_e32 v68, v66, v67
	v_lshl_add_u64 v[66:67], v[178:179], 2, s[38:39]
	global_atomic_add_f32 v[66:67], v68, off offset:240

; DI unsigned pack_bf16(float lo, float hi) { f32x2 v = {lo, hi}; bf16v2 b = __builtin_convertvector(v, bf16v2); return __builtin_bit_cast(unsigned, b); }
; DI float red16(float v) { v += __shfl_xor(v, 1); v += __shfl_xor(v, 2); v += __shfl_xor(v, 4); v += __shfl_xor(v, 8); return v; }
;   DI void run8(f32x4 (&acc)[8][4], int rb, int cb, int fr, int fq) const {
;     ...
;     for (int mh = 0; mh < 2; ++mh) {
;       f32x4 xv[4][4];
; #pragma unroll
;       for (int mm = 0; mm < 4; ++mm)
; #pragma unroll
;         for (int ps = 0; ps < 4; ++ps) xv[mm][ps] = __builtin_nontemporal_load((const f32x4*)(xp + (size_t)((mh * 4 + mm) * 16 + ps * 4) * D));
;       __builtin_amdgcn_sched_barrier(0);
; #pragma unroll
;       for (int mm = 0; mm < 4; ++mm) {
;         const int m = mh * 4 + mm;
; #pragma unroll
;         for (int n = 0; n < 4; ++n)
; #pragma unroll
;           for (int j = 0; j < 4; ++j) scr[(fq * 4 + j) * 68 + n * 16 + fr] = acc[m][n][j];
;         __builtin_amdgcn_sched_barrier(0);
; #pragma unroll
;         for (int ps = 0; ps < 4; ++ps) {
;           const f32x4 a = *(const f32x4*)(scr + (ps * 4 + prow) * 68 + c4 * 4);
;           f32x4 v;
;           v.x = xv[mm][ps].x + a.x * sc; v.y = xv[mm][ps].y + a.y * sc; v.z = xv[mm][ps].z + a.z * sc; v.w = xv[mm][ps].w + a.w * sc;
;           const int grow = rb + m * 16 + ps * 4 + prow;
;           __builtin_nontemporal_store(v, (f32x4*)(op + (size_t)(m * 16 + ps * 4) * D));
;           if (xbp) {
;             u32x2 o; o.x = pack_bf16(v.x, v.y); o.y = pack_bf16(v.z, v.w);
;             *(u32x2*)(xbp + (size_t)grow * LDH + cb + c4 * 4) = o;
;             const float t = red16(v.x * v.x + v.y * v.y + v.z * v.z + v.w * v.w);
;             if (c4 == 0) atomicAdd(ssqp + grow, t);
;           }
;         }
;         __builtin_amdgcn_sched_barrier(0);
;       }
.LBB0_1764:
	v_add_co_u32_e32 v130, vcc, 0x40000, v180
	s_nop 1
	v_addc_co_u32_e32 v131, vcc, 0, v181, vcc
	v_add_co_u32_e32 v66, vcc, 0x44000, v180
	s_waitcnt lgkmcnt(0)
	s_nop 0
	v_addc_co_u32_e32 v67, vcc, 0, v181, vcc
	global_load_dwordx4 v[126:129], v[130:131], off nt
	global_load_dwordx4 v[122:125], v[66:67], off nt
	v_add_co_u32_e32 v66, vcc, 0x48000, v180
	s_nop 1
	v_addc_co_u32_e32 v67, vcc, 0, v181, vcc
	v_add_co_u32_e32 v68, vcc, 0x4c000, v180
	s_nop 1
	v_addc_co_u32_e32 v69, vcc, 0, v181, vcc
	global_load_dwordx4 v[118:121], v[66:67], off nt
	global_load_dwordx4 v[114:117], v[68:69], off nt
	v_add_co_u32_e32 v66, vcc, 0x50000, v180
	s_nop 1
	v_addc_co_u32_e32 v67, vcc, 0, v181, vcc
	v_add_co_u32_e32 v68, vcc, 0x54000, v180
	s_nop 1
	v_addc_co_u32_e32 v69, vcc, 0, v181, vcc
	global_load_dwordx4 v[110:113], v[66:67], off nt
	global_load_dwordx4 v[106:109], v[68:69], off nt
	v_add_co_u32_e32 v66, vcc, 0x58000, v180
	s_nop 1
	v_addc_co_u32_e32 v67, vcc, 0, v181, vcc
	v_add_co_u32_e32 v68, vcc, 0x5c000, v180
	s_nop 1
	v_addc_co_u32_e32 v69, vcc, 0, v181, vcc
	global_load_dwordx4 v[102:105], v[66:67], off nt
	global_load_dwordx4 v[98:101], v[68:69], off nt
	v_add_co_u32_e32 v66, vcc, 0x60000, v180
	s_nop 1
	v_addc_co_u32_e32 v67, vcc, 0, v181, vcc
	v_add_co_u32_e32 v68, vcc, 0x64000, v180
	s_nop 1
	v_addc_co_u32_e32 v69, vcc, 0, v181, vcc
	global_load_dwordx4 v[94:97], v[66:67], off nt
	global_load_dwordx4 v[90:93], v[68:69], off nt
	v_add_co_u32_e32 v66, vcc, 0x68000, v180
	s_nop 1
	v_addc_co_u32_e32 v67, vcc, 0, v181, vcc
	v_add_co_u32_e32 v68, vcc, 0x6c000, v180
	s_nop 1
	v_addc_co_u32_e32 v69, vcc, 0, v181, vcc
	global_load_dwordx4 v[86:89], v[66:67], off nt
	global_load_dwordx4 v[82:85], v[68:69], off nt
	v_add_co_u32_e32 v66, vcc, s68, v180
	s_nop 1
	v_addc_co_u32_e32 v67, vcc, 0, v181, vcc
	v_add_co_u32_e32 v68, vcc, 0x74000, v180
	s_nop 1
	v_addc_co_u32_e32 v69, vcc, 0, v181, vcc
	global_load_dwordx4 v[78:81], v[66:67], off nt
	global_load_dwordx4 v[74:77], v[68:69], off nt
	v_add_co_u32_e32 v66, vcc, 0x78000, v180
	s_nop 1
	v_addc_co_u32_e32 v67, vcc, 0, v181, vcc
	v_add_co_u32_e32 v68, vcc, 0x7c000, v180
	s_nop 1
	v_addc_co_u32_e32 v69, vcc, 0, v181, vcc
	global_load_dwordx4 v[70:73], v[66:67], off nt
	s_nop 0
	global_load_dwordx4 v[66:69], v[68:69], off nt
	ds_write2_b32 v184, v58, v62 offset1:16
	ds_write2_b32 v184, v59, v63 offset0:68 offset1:84
	ds_write2_b32 v184, v60, v64 offset0:136 offset1:152
	ds_write2_b32 v184, v61, v65 offset0:204 offset1:220
	ds_write2_b32 v184, v50, v54 offset0:32 offset1:48
	ds_write2_b32 v184, v51, v55 offset0:100 offset1:116
	ds_write2_b32 v184, v52, v56 offset0:168 offset1:184
	ds_write2_b32 v184, v53, v57 offset0:236 offset1:252
	ds_read_b128 v[50:53], v0
	s_and_b64 vcc, exec, s[6:7]
	s_waitcnt vmcnt(15) lgkmcnt(0)
	v_pk_fma_f32 v[50:51], v[50:51], 0.5, v[126:127] op_sel_hi:[1,0,1]
	v_pk_fma_f32 v[52:53], v[52:53], 0.5, v[128:129] op_sel_hi:[1,0,1]
	global_store_dwordx4 v[130:131], v[50:53], off nt
	s_cbranch_vccnz .LBB0_1768
	v_pk_mul_f32 v[54:55], v[50:51], v[50:51]
	v_pk_mul_f32 v[56:57], v[52:53], v[52:53]
	v_add_f32_e32 v54, v54, v55
	v_add_f32_e32 v54, v56, v54
	v_and_b32_e32 v56, 64, v219
	s_nop 0
	v_add_u32_e32 v56, 64, v56
	s_nop 0
	v_add_f32_e32 v54, v57, v54
	v_or_b32_e32 v58, 64, v178
	s_nop 1
	v_mov_b32_dpp v55, v54 quad_perm:[1,0,3,2] row_mask:0xf bank_mask:0xf
	s_waitcnt lgkmcnt(0)
	v_add_f32_e32 v54, v54, v55
	s_nop 5
	v_mov_b32_dpp v55, v54 quad_perm:[2,3,0,1] row_mask:0xf bank_mask:0xf
	s_waitcnt lgkmcnt(0)
	v_add_f32_e32 v55, v54, v55
	s_nop 5
	v_mov_b32_dpp v57, v55 row_half_mirror row_mask:0xf bank_mask:0xf
	v_cvt_pk_bf16_f32 v54, v50, v51
	v_xor_b32_e32 v51, 8, v219
	v_cmp_lt_i32_e32 vcc, v51, v56
	s_waitcnt lgkmcnt(0)
	v_add_f32_e32 v50, v55, v57
	s_nop 1
	v_mov_b32_dpp v51, v50 row_mirror row_mask:0xf bank_mask:0xf
	v_cvt_pk_bf16_f32 v55, v52, v53
	v_mad_i64_i32 v[52:53], s[0:1], v58, s66, v[182:183]
	global_store_dwordx2 v[52:53], v[54:55], off
	s_and_saveexec_b64 s[0:1], s[4:5]
	s_cbranch_execz .LBB0_1767
	s_waitcnt lgkmcnt(0)
	v_add_f32_e32 v52, v50, v51
	v_lshl_add_u64 v[50:51], v[178:179], 2, s[38:39]
	global_atomic_add_f32 v[50:51], v52, off offset:256

; DI unsigned pack_bf16(float lo, float hi) { f32x2 v = {lo, hi}; bf16v2 b = __builtin_convertvector(v, bf16v2); return __builtin_bit_cast(unsigned, b); }
; DI float red16(float v) { v += __shfl_xor(v, 1); v += __shfl_xor(v, 2); v += __shfl_xor(v, 4); v += __shfl_xor(v, 8); return v; }
;   DI void run8(f32x4 (&acc)[8][4], int rb, int cb, int fr, int fq) const {
;     ...
;         for (int ps = 0; ps < 4; ++ps) {
;           const f32x4 a = *(const f32x4*)(scr + (ps * 4 + prow) * 68 + c4 * 4);
;           f32x4 v;
;           v.x = xv[mm][ps].x + a.x * sc; v.y = xv[mm][ps].y + a.y * sc; v.z = xv[mm][ps].z + a.z * sc; v.w = xv[mm][ps].w + a.w * sc;
;           const int grow = rb + m * 16 + ps * 4 + prow;
;           __builtin_nontemporal_store(v, (f32x4*)(op + (size_t)(m * 16 + ps * 4) * D));
;           if (xbp) {
;             u32x2 o; o.x = pack_bf16(v.x, v.y); o.y = pack_bf16(v.z, v.w);
;             *(u32x2*)(xbp + (size_t)grow * LDH + cb + c4 * 4) = o;
;             const float t = red16(v.x * v.x + v.y * v.y + v.z * v.z + v.w * v.w);
;             if (c4 == 0) atomicAdd(ssqp + grow, t);
;           }
;         }
.LBB0_1768:
	s_waitcnt lgkmcnt(0)
	ds_read_b128 v[50:53], v0 offset:1088
	s_mov_b64 s[0:1], 0x44000
	v_lshl_add_u64 v[54:55], v[180:181], 0, s[0:1]
	s_and_b64 vcc, exec, s[6:7]
	s_waitcnt vmcnt(15) lgkmcnt(0)
	v_pk_fma_f32 v[50:51], v[50:51], 0.5, v[122:123] op_sel_hi:[1,0,1]
	v_pk_fma_f32 v[52:53], v[52:53], 0.5, v[124:125] op_sel_hi:[1,0,1]
	global_store_dwordx4 v[54:55], v[50:53], off nt
	s_cbranch_vccnz .LBB0_1772
	v_pk_mul_f32 v[54:55], v[50:51], v[50:51]
	v_pk_mul_f32 v[56:57], v[52:53], v[52:53]
	v_add_f32_e32 v54, v54, v55
	v_add_f32_e32 v54, v56, v54
	v_and_b32_e32 v56, 64, v219
	s_nop 0
	v_add_u32_e32 v56, 64, v56
	s_nop 0
	v_add_f32_e32 v54, v57, v54
	v_or_b32_e32 v58, 0x44, v178
	s_nop 1
	v_mov_b32_dpp v55, v54 quad_perm:[1,0,3,2] row_mask:0xf bank_mask:0xf
	s_waitcnt lgkmcnt(0)
	v_add_f32_e32 v54, v54, v55
	s_nop 5
	v_mov_b32_dpp v55, v54 quad_perm:[2,3,0,1] row_mask:0xf bank_mask:0xf
	s_waitcnt lgkmcnt(0)
	v_add_f32_e32 v55, v54, v55
	s_nop 5
	v_mov_b32_dpp v57, v55 row_half_mirror row_mask:0xf bank_mask:0xf
	v_cvt_pk_bf16_f32 v54, v50, v51
	v_xor_b32_e32 v51, 8, v219
	v_cmp_lt_i32_e32 vcc, v51, v56
	s_waitcnt lgkmcnt(0)
	v_add_f32_e32 v50, v55, v57
	s_nop 1
	v_mov_b32_dpp v51, v50 row_mirror row_mask:0xf bank_mask:0xf
	v_cvt_pk_bf16_f32 v55, v52, v53
	v_mad_i64_i32 v[52:53], s[0:1], v58, s66, v[182:183]
	global_store_dwordx2 v[52:53], v[54:55], off
	s_and_saveexec_b64 s[0:1], s[4:5]
	s_cbranch_execz .LBB0_1771
	s_waitcnt lgkmcnt(0)
	v_add_f32_e32 v52, v50, v51
	v_lshl_add_u64 v[50:51], v[178:179], 2, s[38:39]
	global_atomic_add_f32 v[50:51], v52, off offset:272

; DI unsigned pack_bf16(float lo, float hi) { f32x2 v = {lo, hi}; bf16v2 b = __builtin_convertvector(v, bf16v2); return __builtin_bit_cast(unsigned, b); }
; DI float red16(float v) { v += __shfl_xor(v, 1); v += __shfl_xor(v, 2); v += __shfl_xor(v, 4); v += __shfl_xor(v, 8); return v; }
;   DI void run8(f32x4 (&acc)[8][4], int rb, int cb, int fr, int fq) const {
;     ...
;         for (int ps = 0; ps < 4; ++ps) {
;           const f32x4 a = *(const f32x4*)(scr + (ps * 4 + prow) * 68 + c4 * 4);
;           f32x4 v;
;           v.x = xv[mm][ps].x + a.x * sc; v.y = xv[mm][ps].y + a.y * sc; v.z = xv[mm][ps].z + a.z * sc; v.w = xv[mm][ps].w + a.w * sc;
;           const int grow = rb + m * 16 + ps * 4 + prow;
;           __builtin_nontemporal_store(v, (f32x4*)(op + (size_t)(m * 16 + ps * 4) * D));
;           if (xbp) {
;             u32x2 o; o.x = pack_bf16(v.x, v.y); o.y = pack_bf16(v.z, v.w);
;             *(u32x2*)(xbp + (size_t)grow * LDH + cb + c4 * 4) = o;
;             const float t = red16(v.x * v.x + v.y * v.y + v.z * v.z + v.w * v.w);
;             if (c4 == 0) atomicAdd(ssqp + grow, t);
;           }
;         }
.LBB0_1772:
	s_waitcnt lgkmcnt(0)
	ds_read_b128 v[50:53], v0 offset:2176
	s_mov_b64 s[0:1], 0x48000
	v_lshl_add_u64 v[54:55], v[180:181], 0, s[0:1]
	s_and_b64 vcc, exec, s[6:7]
	s_waitcnt vmcnt(15) lgkmcnt(0)
	v_pk_fma_f32 v[50:51], v[50:51], 0.5, v[118:119] op_sel_hi:[1,0,1]
	v_pk_fma_f32 v[52:53], v[52:53], 0.5, v[120:121] op_sel_hi:[1,0,1]
	global_store_dwordx4 v[54:55], v[50:53], off nt
	s_cbranch_vccnz .LBB0_1776
	v_pk_mul_f32 v[54:55], v[50:51], v[50:51]
	v_pk_mul_f32 v[56:57], v[52:53], v[52:53]
	v_add_f32_e32 v54, v54, v55
	v_add_f32_e32 v54, v56, v54
	v_and_b32_e32 v56, 64, v219
	s_nop 0
	v_add_u32_e32 v56, 64, v56
	s_nop 0
	v_add_f32_e32 v54, v57, v54
	v_or_b32_e32 v58, 0x48, v178
	s_nop 1
	v_mov_b32_dpp v55, v54 quad_perm:[1,0,3,2] row_mask:0xf bank_mask:0xf
	s_waitcnt lgkmcnt(0)
	v_add_f32_e32 v54, v54, v55
	s_nop 5
	v_mov_b32_dpp v55, v54 quad_perm:[2,3,0,1] row_mask:0xf bank_mask:0xf
	s_waitcnt lgkmcnt(0)
	v_add_f32_e32 v55, v54, v55
	s_nop 5
	v_mov_b32_dpp v57, v55 row_half_mirror row_mask:0xf bank_mask:0xf
	v_cvt_pk_bf16_f32 v54, v50, v51
	v_xor_b32_e32 v51, 8, v219
	v_cmp_lt_i32_e32 vcc, v51, v56
	s_waitcnt lgkmcnt(0)
	v_add_f32_e32 v50, v55, v57
	s_nop 1
	v_mov_b32_dpp v51, v50 row_mirror row_mask:0xf bank_mask:0xf
	v_cvt_pk_bf16_f32 v55, v52, v53
	v_mad_i64_i32 v[52:53], s[0:1], v58, s66, v[182:183]
	global_store_dwordx2 v[52:53], v[54:55], off
	s_and_saveexec_b64 s[0:1], s[4:5]
	s_cbranch_execz .LBB0_1775
	s_waitcnt lgkmcnt(0)
	v_add_f32_e32 v52, v50, v51
	v_lshl_add_u64 v[50:51], v[178:179], 2, s[38:39]
	global_atomic_add_f32 v[50:51], v52, off offset:288

; DI unsigned pack_bf16(float lo, float hi) { f32x2 v = {lo, hi}; bf16v2 b = __builtin_convertvector(v, bf16v2); return __builtin_bit_cast(unsigned, b); }
; DI float red16(float v) { v += __shfl_xor(v, 1); v += __shfl_xor(v, 2); v += __shfl_xor(v, 4); v += __shfl_xor(v, 8); return v; }
;   DI void run8(f32x4 (&acc)[8][4], int rb, int cb, int fr, int fq) const {
;     ...
;         for (int ps = 0; ps < 4; ++ps) {
;           const f32x4 a = *(const f32x4*)(scr + (ps * 4 + prow) * 68 + c4 * 4);
;           f32x4 v;
;           v.x = xv[mm][ps].x + a.x * sc; v.y = xv[mm][ps].y + a.y * sc; v.z = xv[mm][ps].z + a.z * sc; v.w = xv[mm][ps].w + a.w * sc;
;           const int grow = rb + m * 16 + ps * 4 + prow;
;           __builtin_nontemporal_store(v, (f32x4*)(op + (size_t)(m * 16 + ps * 4) * D));
;           if (xbp) {
;             u32x2 o; o.x = pack_bf16(v.x, v.y); o.y = pack_bf16(v.z, v.w);
;             *(u32x2*)(xbp + (size_t)grow * LDH + cb + c4 * 4) = o;
;             const float t = red16(v.x * v.x + v.y * v.y + v.z * v.z + v.w * v.w);
;             if (c4 == 0) atomicAdd(ssqp + grow, t);
;           }
;         }
.LBB0_1776:
	s_waitcnt lgkmcnt(0)
	ds_read_b128 v[50:53], v0 offset:3264
	s_mov_b64 s[0:1], 0x4c000
	v_lshl_add_u64 v[54:55], v[180:181], 0, s[0:1]
	s_and_b64 vcc, exec, s[6:7]
	s_waitcnt vmcnt(15) lgkmcnt(0)
	v_pk_fma_f32 v[50:51], v[50:51], 0.5, v[114:115] op_sel_hi:[1,0,1]
	v_pk_fma_f32 v[52:53], v[52:53], 0.5, v[116:117] op_sel_hi:[1,0,1]
	global_store_dwordx4 v[54:55], v[50:53], off nt
	s_cbranch_vccnz .LBB0_1780
	v_pk_mul_f32 v[54:55], v[50:51], v[50:51]
	v_pk_mul_f32 v[56:57], v[52:53], v[52:53]
	v_add_f32_e32 v54, v54, v55
	v_add_f32_e32 v54, v56, v54
	v_and_b32_e32 v56, 64, v219
	s_nop 0
	v_add_u32_e32 v56, 64, v56
	s_nop 0
	v_add_f32_e32 v54, v57, v54
	v_or_b32_e32 v58, 0x4c, v178
	s_nop 1
	v_mov_b32_dpp v55, v54 quad_perm:[1,0,3,2] row_mask:0xf bank_mask:0xf
	s_waitcnt lgkmcnt(0)
	v_add_f32_e32 v54, v54, v55
	s_nop 5
	v_mov_b32_dpp v55, v54 quad_perm:[2,3,0,1] row_mask:0xf bank_mask:0xf
	s_waitcnt lgkmcnt(0)
	v_add_f32_e32 v55, v54, v55
	s_nop 5
	v_mov_b32_dpp v57, v55 row_half_mirror row_mask:0xf bank_mask:0xf
	v_cvt_pk_bf16_f32 v54, v50, v51
	v_xor_b32_e32 v51, 8, v219
	v_cmp_lt_i32_e32 vcc, v51, v56
	s_waitcnt lgkmcnt(0)
	v_add_f32_e32 v50, v55, v57
	s_nop 1
	v_mov_b32_dpp v51, v50 row_mirror row_mask:0xf bank_mask:0xf
	v_cvt_pk_bf16_f32 v55, v52, v53
	v_mad_i64_i32 v[52:53], s[0:1], v58, s66, v[182:183]
	global_store_dwordx2 v[52:53], v[54:55], off
	s_and_saveexec_b64 s[0:1], s[4:5]
	s_cbranch_execz .LBB0_1779
	s_waitcnt lgkmcnt(0)
	v_add_f32_e32 v52, v50, v51
	v_lshl_add_u64 v[50:51], v[178:179], 2, s[38:39]
	global_atomic_add_f32 v[50:51], v52, off offset:304

; DI unsigned pack_bf16(float lo, float hi) { f32x2 v = {lo, hi}; bf16v2 b = __builtin_convertvector(v, bf16v2); return __builtin_bit_cast(unsigned, b); }
; DI float red16(float v) { v += __shfl_xor(v, 1); v += __shfl_xor(v, 2); v += __shfl_xor(v, 4); v += __shfl_xor(v, 8); return v; }
;   DI void run8(f32x4 (&acc)[8][4], int rb, int cb, int fr, int fq) const {
;     ...
;       for (int mm = 0; mm < 4; ++mm) {
;         const int m = mh * 4 + mm;
; #pragma unroll
;         for (int n = 0; n < 4; ++n)
; #pragma unroll
;           for (int j = 0; j < 4; ++j) scr[(fq * 4 + j) * 68 + n * 16 + fr] = acc[m][n][j];
;         __builtin_amdgcn_sched_barrier(0);
; #pragma unroll
;         for (int ps = 0; ps < 4; ++ps) {
;           const f32x4 a = *(const f32x4*)(scr + (ps * 4 + prow) * 68 + c4 * 4);
;           f32x4 v;
;           v.x = xv[mm][ps].x + a.x * sc; v.y = xv[mm][ps].y + a.y * sc; v.z = xv[mm][ps].z + a.z * sc; v.w = xv[mm][ps].w + a.w * sc;
;           const int grow = rb + m * 16 + ps * 4 + prow;
;           __builtin_nontemporal_store(v, (f32x4*)(op + (size_t)(m * 16 + ps * 4) * D));
;           if (xbp) {
;             u32x2 o; o.x = pack_bf16(v.x, v.y); o.y = pack_bf16(v.z, v.w);
;             *(u32x2*)(xbp + (size_t)grow * LDH + cb + c4 * 4) = o;
;             const float t = red16(v.x * v.x + v.y * v.y + v.z * v.z + v.w * v.w);
;             if (c4 == 0) atomicAdd(ssqp + grow, t);
;           }
;         }
.LBB0_1780:
	s_mov_b64 s[0:1], 0x50000
	s_waitcnt lgkmcnt(0)
	v_lshl_add_u64 v[50:51], v[180:181], 0, s[0:1]
	ds_write2_b32 v184, v42, v46 offset1:16
	ds_write2_b32 v184, v43, v47 offset0:68 offset1:84
	ds_write2_b32 v184, v44, v48 offset0:136 offset1:152
	ds_write2_b32 v184, v45, v49 offset0:204 offset1:220
	ds_write2_b32 v184, v34, v38 offset0:32 offset1:48
	ds_write2_b32 v184, v35, v39 offset0:100 offset1:116
	ds_write2_b32 v184, v36, v40 offset0:168 offset1:184
	ds_write2_b32 v184, v37, v41 offset0:236 offset1:252
	ds_read_b128 v[34:37], v0
	s_and_b64 vcc, exec, s[6:7]
	s_waitcnt vmcnt(15) lgkmcnt(0)
	v_pk_fma_f32 v[34:35], v[34:35], 0.5, v[110:111] op_sel_hi:[1,0,1]
	v_pk_fma_f32 v[36:37], v[36:37], 0.5, v[112:113] op_sel_hi:[1,0,1]
	global_store_dwordx4 v[50:51], v[34:37], off nt
	s_cbranch_vccnz .LBB0_1784
	v_pk_mul_f32 v[38:39], v[34:35], v[34:35]
	v_pk_mul_f32 v[40:41], v[36:37], v[36:37]
	v_add_f32_e32 v38, v38, v39
	v_add_f32_e32 v38, v40, v38
	v_and_b32_e32 v40, 64, v219
	s_nop 0
	v_add_u32_e32 v40, 64, v40
	s_nop 0
	v_add_f32_e32 v38, v41, v38
	v_or_b32_e32 v42, 0x50, v178
	s_nop 1
	v_mov_b32_dpp v39, v38 quad_perm:[1,0,3,2] row_mask:0xf bank_mask:0xf
	s_waitcnt lgkmcnt(0)
	v_add_f32_e32 v38, v38, v39
	s_nop 5
	v_mov_b32_dpp v39, v38 quad_perm:[2,3,0,1] row_mask:0xf bank_mask:0xf
	s_waitcnt lgkmcnt(0)
	v_add_f32_e32 v39, v38, v39
	s_nop 5
	v_mov_b32_dpp v41, v39 row_half_mirror row_mask:0xf bank_mask:0xf
	v_cvt_pk_bf16_f32 v38, v34, v35
	v_xor_b32_e32 v35, 8, v219
	v_cmp_lt_i32_e32 vcc, v35, v40
	s_waitcnt lgkmcnt(0)
	v_add_f32_e32 v34, v39, v41
	s_nop 1
	v_mov_b32_dpp v35, v34 row_mirror row_mask:0xf bank_mask:0xf
	v_cvt_pk_bf16_f32 v39, v36, v37
	v_mad_i64_i32 v[36:37], s[0:1], v42, s66, v[182:183]
	global_store_dwordx2 v[36:37], v[38:39], off
	s_and_saveexec_b64 s[0:1], s[4:5]
	s_cbranch_execz .LBB0_1783
	s_waitcnt lgkmcnt(0)
	v_add_f32_e32 v36, v34, v35
	v_lshl_add_u64 v[34:35], v[178:179], 2, s[38:39]
	global_atomic_add_f32 v[34:35], v36, off offset:320

; DI unsigned pack_bf16(float lo, float hi) { f32x2 v = {lo, hi}; bf16v2 b = __builtin_convertvector(v, bf16v2); return __builtin_bit_cast(unsigned, b); }
; DI float red16(float v) { v += __shfl_xor(v, 1); v += __shfl_xor(v, 2); v += __shfl_xor(v, 4); v += __shfl_xor(v, 8); return v; }
;   DI void run8(f32x4 (&acc)[8][4], int rb, int cb, int fr, int fq) const {
;     ...
;         for (int ps = 0; ps < 4; ++ps) {
;           const f32x4 a = *(const f32x4*)(scr + (ps * 4 + prow) * 68 + c4 * 4);
;           f32x4 v;
;           v.x = xv[mm][ps].x + a.x * sc; v.y = xv[mm][ps].y + a.y * sc; v.z = xv[mm][ps].z + a.z * sc; v.w = xv[mm][ps].w + a.w * sc;
;           const int grow = rb + m * 16 + ps * 4 + prow;
;           __builtin_nontemporal_store(v, (f32x4*)(op + (size_t)(m * 16 + ps * 4) * D));
;           if (xbp) {
;             u32x2 o; o.x = pack_bf16(v.x, v.y); o.y = pack_bf16(v.z, v.w);
;             *(u32x2*)(xbp + (size_t)grow * LDH + cb + c4 * 4) = o;
;             const float t = red16(v.x * v.x + v.y * v.y + v.z * v.z + v.w * v.w);
;             if (c4 == 0) atomicAdd(ssqp + grow, t);
;           }
;         }
.LBB0_1784:
	s_waitcnt lgkmcnt(0)
	ds_read_b128 v[34:37], v0 offset:1088
	s_mov_b64 s[0:1], 0x54000
	v_lshl_add_u64 v[38:39], v[180:181], 0, s[0:1]
	s_and_b64 vcc, exec, s[6:7]
	s_waitcnt vmcnt(15) lgkmcnt(0)
	v_pk_fma_f32 v[34:35], v[34:35], 0.5, v[106:107] op_sel_hi:[1,0,1]
	v_pk_fma_f32 v[36:37], v[36:37], 0.5, v[108:109] op_sel_hi:[1,0,1]
	global_store_dwordx4 v[38:39], v[34:37], off nt
	s_cbranch_vccnz .LBB0_1788
	v_pk_mul_f32 v[38:39], v[34:35], v[34:35]
	v_pk_mul_f32 v[40:41], v[36:37], v[36:37]
	v_add_f32_e32 v38, v38, v39
	v_add_f32_e32 v38, v40, v38
	v_and_b32_e32 v40, 64, v219
	s_nop 0
	v_add_u32_e32 v40, 64, v40
	s_nop 0
	v_add_f32_e32 v38, v41, v38
	v_or_b32_e32 v42, 0x54, v178
	s_nop 1
	v_mov_b32_dpp v39, v38 quad_perm:[1,0,3,2] row_mask:0xf bank_mask:0xf
	s_waitcnt lgkmcnt(0)
	v_add_f32_e32 v38, v38, v39
	s_nop 5
	v_mov_b32_dpp v39, v38 quad_perm:[2,3,0,1] row_mask:0xf bank_mask:0xf
	s_waitcnt lgkmcnt(0)
	v_add_f32_e32 v39, v38, v39
	s_nop 5
	v_mov_b32_dpp v41, v39 row_half_mirror row_mask:0xf bank_mask:0xf
	v_cvt_pk_bf16_f32 v38, v34, v35
	v_xor_b32_e32 v35, 8, v219
	v_cmp_lt_i32_e32 vcc, v35, v40
	s_waitcnt lgkmcnt(0)
	v_add_f32_e32 v34, v39, v41
	s_nop 1
	v_mov_b32_dpp v35, v34 row_mirror row_mask:0xf bank_mask:0xf
	v_cvt_pk_bf16_f32 v39, v36, v37
	v_mad_i64_i32 v[36:37], s[0:1], v42, s66, v[182:183]
	global_store_dwordx2 v[36:37], v[38:39], off
	s_and_saveexec_b64 s[0:1], s[4:5]
	s_cbranch_execz .LBB0_1787
	s_waitcnt lgkmcnt(0)
	v_add_f32_e32 v36, v34, v35
	v_lshl_add_u64 v[34:35], v[178:179], 2, s[38:39]
	global_atomic_add_f32 v[34:35], v36, off offset:336

; DI unsigned pack_bf16(float lo, float hi) { f32x2 v = {lo, hi}; bf16v2 b = __builtin_convertvector(v, bf16v2); return __builtin_bit_cast(unsigned, b); }
; DI float red16(float v) { v += __shfl_xor(v, 1); v += __shfl_xor(v, 2); v += __shfl_xor(v, 4); v += __shfl_xor(v, 8); return v; }
;   DI void run8(f32x4 (&acc)[8][4], int rb, int cb, int fr, int fq) const {
;     ...
;         for (int ps = 0; ps < 4; ++ps) {
;           const f32x4 a = *(const f32x4*)(scr + (ps * 4 + prow) * 68 + c4 * 4);
;           f32x4 v;
;           v.x = xv[mm][ps].x + a.x * sc; v.y = xv[mm][ps].y + a.y * sc; v.z = xv[mm][ps].z + a.z * sc; v.w = xv[mm][ps].w + a.w * sc;
;           const int grow = rb + m * 16 + ps * 4 + prow;
;           __builtin_nontemporal_store(v, (f32x4*)(op + (size_t)(m * 16 + ps * 4) * D));
;           if (xbp) {
;             u32x2 o; o.x = pack_bf16(v.x, v.y); o.y = pack_bf16(v.z, v.w);
;             *(u32x2*)(xbp + (size_t)grow * LDH + cb + c4 * 4) = o;
;             const float t = red16(v.x * v.x + v.y * v.y + v.z * v.z + v.w * v.w);
;             if (c4 == 0) atomicAdd(ssqp + grow, t);
;           }
;         }
.LBB0_1788:
	s_waitcnt lgkmcnt(0)
	ds_read_b128 v[34:37], v0 offset:2176
	s_mov_b64 s[0:1], 0x58000
	v_lshl_add_u64 v[38:39], v[180:181], 0, s[0:1]
	s_and_b64 vcc, exec, s[6:7]
	s_waitcnt vmcnt(15) lgkmcnt(0)
	v_pk_fma_f32 v[34:35], v[34:35], 0.5, v[102:103] op_sel_hi:[1,0,1]
	v_pk_fma_f32 v[36:37], v[36:37], 0.5, v[104:105] op_sel_hi:[1,0,1]
	global_store_dwordx4 v[38:39], v[34:37], off nt
	s_cbranch_vccnz .LBB0_1792
	v_pk_mul_f32 v[38:39], v[34:35], v[34:35]
	v_pk_mul_f32 v[40:41], v[36:37], v[36:37]
	v_add_f32_e32 v38, v38, v39
	v_add_f32_e32 v38, v40, v38
	v_and_b32_e32 v40, 64, v219
	s_nop 0
	v_add_u32_e32 v40, 64, v40
	s_nop 0
	v_add_f32_e32 v38, v41, v38
	v_or_b32_e32 v42, 0x58, v178
	s_nop 1
	v_mov_b32_dpp v39, v38 quad_perm:[1,0,3,2] row_mask:0xf bank_mask:0xf
	s_waitcnt lgkmcnt(0)
	v_add_f32_e32 v38, v38, v39
	s_nop 5
	v_mov_b32_dpp v39, v38 quad_perm:[2,3,0,1] row_mask:0xf bank_mask:0xf
	s_waitcnt lgkmcnt(0)
	v_add_f32_e32 v39, v38, v39
	s_nop 5
	v_mov_b32_dpp v41, v39 row_half_mirror row_mask:0xf bank_mask:0xf
	v_cvt_pk_bf16_f32 v38, v34, v35
	v_xor_b32_e32 v35, 8, v219
	v_cmp_lt_i32_e32 vcc, v35, v40
	s_waitcnt lgkmcnt(0)
	v_add_f32_e32 v34, v39, v41
	s_nop 1
	v_mov_b32_dpp v35, v34 row_mirror row_mask:0xf bank_mask:0xf
	v_cvt_pk_bf16_f32 v39, v36, v37
	v_mad_i64_i32 v[36:37], s[0:1], v42, s66, v[182:183]
	global_store_dwordx2 v[36:37], v[38:39], off
	s_and_saveexec_b64 s[0:1], s[4:5]
	s_cbranch_execz .LBB0_1791
	s_waitcnt lgkmcnt(0)
	v_add_f32_e32 v36, v34, v35
	v_lshl_add_u64 v[34:35], v[178:179], 2, s[38:39]
	global_atomic_add_f32 v[34:35], v36, off offset:352

; DI unsigned pack_bf16(float lo, float hi) { f32x2 v = {lo, hi}; bf16v2 b = __builtin_convertvector(v, bf16v2); return __builtin_bit_cast(unsigned, b); }
; DI float red16(float v) { v += __shfl_xor(v, 1); v += __shfl_xor(v, 2); v += __shfl_xor(v, 4); v += __shfl_xor(v, 8); return v; }
;   DI void run8(f32x4 (&acc)[8][4], int rb, int cb, int fr, int fq) const {
;     ...
;         for (int ps = 0; ps < 4; ++ps) {
;           const f32x4 a = *(const f32x4*)(scr + (ps * 4 + prow) * 68 + c4 * 4);
;           f32x4 v;
;           v.x = xv[mm][ps].x + a.x * sc; v.y = xv[mm][ps].y + a.y * sc; v.z = xv[mm][ps].z + a.z * sc; v.w = xv[mm][ps].w + a.w * sc;
;           const int grow = rb + m * 16 + ps * 4 + prow;
;           __builtin_nontemporal_store(v, (f32x4*)(op + (size_t)(m * 16 + ps * 4) * D));
;           if (xbp) {
;             u32x2 o; o.x = pack_bf16(v.x, v.y); o.y = pack_bf16(v.z, v.w);
;             *(u32x2*)(xbp + (size_t)grow * LDH + cb + c4 * 4) = o;
;             const float t = red16(v.x * v.x + v.y * v.y + v.z * v.z + v.w * v.w);
;             if (c4 == 0) atomicAdd(ssqp + grow, t);
;           }
;         }
.LBB0_1792:
	s_waitcnt lgkmcnt(0)
	ds_read_b128 v[34:37], v0 offset:3264
	s_mov_b64 s[0:1], 0x5c000
	v_lshl_add_u64 v[38:39], v[180:181], 0, s[0:1]
	s_and_b64 vcc, exec, s[6:7]
	s_waitcnt vmcnt(15) lgkmcnt(0)
	v_pk_fma_f32 v[34:35], v[34:35], 0.5, v[98:99] op_sel_hi:[1,0,1]
	v_pk_fma_f32 v[36:37], v[36:37], 0.5, v[100:101] op_sel_hi:[1,0,1]
	global_store_dwordx4 v[38:39], v[34:37], off nt
	s_cbranch_vccnz .LBB0_1796
	v_pk_mul_f32 v[38:39], v[34:35], v[34:35]
	v_pk_mul_f32 v[40:41], v[36:37], v[36:37]
	v_add_f32_e32 v38, v38, v39
	v_add_f32_e32 v38, v40, v38
	v_and_b32_e32 v40, 64, v219
	s_nop 0
	v_add_u32_e32 v40, 64, v40
	s_nop 0
	v_add_f32_e32 v38, v41, v38
	v_or_b32_e32 v42, 0x5c, v178
	s_nop 1
	v_mov_b32_dpp v39, v38 quad_perm:[1,0,3,2] row_mask:0xf bank_mask:0xf
	s_waitcnt lgkmcnt(0)
	v_add_f32_e32 v38, v38, v39
	s_nop 5
	v_mov_b32_dpp v39, v38 quad_perm:[2,3,0,1] row_mask:0xf bank_mask:0xf
	s_waitcnt lgkmcnt(0)
	v_add_f32_e32 v39, v38, v39
	s_nop 5
	v_mov_b32_dpp v41, v39 row_half_mirror row_mask:0xf bank_mask:0xf
	v_cvt_pk_bf16_f32 v38, v34, v35
	v_xor_b32_e32 v35, 8, v219
	v_cmp_lt_i32_e32 vcc, v35, v40
	s_waitcnt lgkmcnt(0)
	v_add_f32_e32 v34, v39, v41
	s_nop 1
	v_mov_b32_dpp v35, v34 row_mirror row_mask:0xf bank_mask:0xf
	v_cvt_pk_bf16_f32 v39, v36, v37
	v_mad_i64_i32 v[36:37], s[0:1], v42, s66, v[182:183]
	global_store_dwordx2 v[36:37], v[38:39], off
	s_and_saveexec_b64 s[0:1], s[4:5]
	s_cbranch_execz .LBB0_1795
	s_waitcnt lgkmcnt(0)
	v_add_f32_e32 v36, v34, v35
	v_lshl_add_u64 v[34:35], v[178:179], 2, s[38:39]
	global_atomic_add_f32 v[34:35], v36, off offset:368

; DI unsigned pack_bf16(float lo, float hi) { f32x2 v = {lo, hi}; bf16v2 b = __builtin_convertvector(v, bf16v2); return __builtin_bit_cast(unsigned, b); }
; DI float red16(float v) { v += __shfl_xor(v, 1); v += __shfl_xor(v, 2); v += __shfl_xor(v, 4); v += __shfl_xor(v, 8); return v; }
;   DI void run8(f32x4 (&acc)[8][4], int rb, int cb, int fr, int fq) const {
;     ...
;       for (int mm = 0; mm < 4; ++mm) {
;         const int m = mh * 4 + mm;
; #pragma unroll
;         for (int n = 0; n < 4; ++n)
; #pragma unroll
;           for (int j = 0; j < 4; ++j) scr[(fq * 4 + j) * 68 + n * 16 + fr] = acc[m][n][j];
;         __builtin_amdgcn_sched_barrier(0);
; #pragma unroll
;         for (int ps = 0; ps < 4; ++ps) {
;           const f32x4 a = *(const f32x4*)(scr + (ps * 4 + prow) * 68 + c4 * 4);
;           f32x4 v;
;           v.x = xv[mm][ps].x + a.x * sc; v.y = xv[mm][ps].y + a.y * sc; v.z = xv[mm][ps].z + a.z * sc; v.w = xv[mm][ps].w + a.w * sc;
;           const int grow = rb + m * 16 + ps * 4 + prow;
;           __builtin_nontemporal_store(v, (f32x4*)(op + (size_t)(m * 16 + ps * 4) * D));
;           if (xbp) {
;             u32x2 o; o.x = pack_bf16(v.x, v.y); o.y = pack_bf16(v.z, v.w);
;             *(u32x2*)(xbp + (size_t)grow * LDH + cb + c4 * 4) = o;
;             const float t = red16(v.x * v.x + v.y * v.y + v.z * v.z + v.w * v.w);
;             if (c4 == 0) atomicAdd(ssqp + grow, t);
;           }
;         }
.LBB0_1796:
	s_mov_b64 s[0:1], 0x60000
	s_waitcnt lgkmcnt(0)
	v_lshl_add_u64 v[34:35], v[180:181], 0, s[0:1]
	ds_write2_b32 v184, v26, v30 offset1:16
	ds_write2_b32 v184, v27, v31 offset0:68 offset1:84
	ds_write2_b32 v184, v28, v32 offset0:136 offset1:152
	ds_write2_b32 v184, v29, v33 offset0:204 offset1:220
	ds_write2_b32 v184, v18, v22 offset0:32 offset1:48
	ds_write2_b32 v184, v19, v23 offset0:100 offset1:116
	ds_write2_b32 v184, v20, v24 offset0:168 offset1:184
	ds_write2_b32 v184, v21, v25 offset0:236 offset1:252
	ds_read_b128 v[18:21], v0
	s_and_b64 vcc, exec, s[6:7]
	s_waitcnt vmcnt(15) lgkmcnt(0)
	v_pk_fma_f32 v[18:19], v[18:19], 0.5, v[94:95] op_sel_hi:[1,0,1]
	v_pk_fma_f32 v[20:21], v[20:21], 0.5, v[96:97] op_sel_hi:[1,0,1]
	global_store_dwordx4 v[34:35], v[18:21], off nt
	s_cbranch_vccnz .LBB0_1800
	v_pk_mul_f32 v[22:23], v[18:19], v[18:19]
	v_pk_mul_f32 v[24:25], v[20:21], v[20:21]
	v_add_f32_e32 v22, v22, v23
	v_add_f32_e32 v22, v24, v22
	v_and_b32_e32 v24, 64, v219
	s_nop 0
	v_add_u32_e32 v24, 64, v24
	s_nop 0
	v_add_f32_e32 v22, v25, v22
	v_or_b32_e32 v26, 0x60, v178
	s_nop 1
	v_mov_b32_dpp v23, v22 quad_perm:[1,0,3,2] row_mask:0xf bank_mask:0xf
	s_waitcnt lgkmcnt(0)
	v_add_f32_e32 v22, v22, v23
	s_nop 5
	v_mov_b32_dpp v23, v22 quad_perm:[2,3,0,1] row_mask:0xf bank_mask:0xf
	s_waitcnt lgkmcnt(0)
	v_add_f32_e32 v23, v22, v23
	s_nop 5
	v_mov_b32_dpp v25, v23 row_half_mirror row_mask:0xf bank_mask:0xf
	v_cvt_pk_bf16_f32 v22, v18, v19
	v_xor_b32_e32 v19, 8, v219
	v_cmp_lt_i32_e32 vcc, v19, v24
	s_waitcnt lgkmcnt(0)
	v_add_f32_e32 v18, v23, v25
	s_nop 1
	v_mov_b32_dpp v19, v18 row_mirror row_mask:0xf bank_mask:0xf
	v_cvt_pk_bf16_f32 v23, v20, v21
	v_mad_i64_i32 v[20:21], s[0:1], v26, s66, v[182:183]
	global_store_dwordx2 v[20:21], v[22:23], off
	s_and_saveexec_b64 s[0:1], s[4:5]
	s_cbranch_execz .LBB0_1799
	s_waitcnt lgkmcnt(0)
	v_add_f32_e32 v20, v18, v19
	v_lshl_add_u64 v[18:19], v[178:179], 2, s[38:39]
	global_atomic_add_f32 v[18:19], v20, off offset:384

; DI unsigned pack_bf16(float lo, float hi) { f32x2 v = {lo, hi}; bf16v2 b = __builtin_convertvector(v, bf16v2); return __builtin_bit_cast(unsigned, b); }
; DI float red16(float v) { v += __shfl_xor(v, 1); v += __shfl_xor(v, 2); v += __shfl_xor(v, 4); v += __shfl_xor(v, 8); return v; }
;   DI void run8(f32x4 (&acc)[8][4], int rb, int cb, int fr, int fq) const {
;     ...
;         for (int ps = 0; ps < 4; ++ps) {
;           const f32x4 a = *(const f32x4*)(scr + (ps * 4 + prow) * 68 + c4 * 4);
;           f32x4 v;
;           v.x = xv[mm][ps].x + a.x * sc; v.y = xv[mm][ps].y + a.y * sc; v.z = xv[mm][ps].z + a.z * sc; v.w = xv[mm][ps].w + a.w * sc;
;           const int grow = rb + m * 16 + ps * 4 + prow;
;           __builtin_nontemporal_store(v, (f32x4*)(op + (size_t)(m * 16 + ps * 4) * D));
;           if (xbp) {
;             u32x2 o; o.x = pack_bf16(v.x, v.y); o.y = pack_bf16(v.z, v.w);
;             *(u32x2*)(xbp + (size_t)grow * LDH + cb + c4 * 4) = o;
;             const float t = red16(v.x * v.x + v.y * v.y + v.z * v.z + v.w * v.w);
;             if (c4 == 0) atomicAdd(ssqp + grow, t);
;           }
;         }
.LBB0_1800:
	s_waitcnt lgkmcnt(0)
	ds_read_b128 v[18:21], v0 offset:1088
	s_mov_b64 s[0:1], 0x64000
	v_lshl_add_u64 v[22:23], v[180:181], 0, s[0:1]
	s_and_b64 vcc, exec, s[6:7]
	s_waitcnt vmcnt(15) lgkmcnt(0)
	v_pk_fma_f32 v[18:19], v[18:19], 0.5, v[90:91] op_sel_hi:[1,0,1]
	v_pk_fma_f32 v[20:21], v[20:21], 0.5, v[92:93] op_sel_hi:[1,0,1]
	global_store_dwordx4 v[22:23], v[18:21], off nt
	s_cbranch_vccnz .LBB0_1804
	v_pk_mul_f32 v[22:23], v[18:19], v[18:19]
	v_pk_mul_f32 v[24:25], v[20:21], v[20:21]
	v_add_f32_e32 v22, v22, v23
	v_add_f32_e32 v22, v24, v22
	v_and_b32_e32 v24, 64, v219
	s_nop 0
	v_add_u32_e32 v24, 64, v24
	s_nop 0
	v_add_f32_e32 v22, v25, v22
	v_or_b32_e32 v26, 0x64, v178
	s_nop 1
	v_mov_b32_dpp v23, v22 quad_perm:[1,0,3,2] row_mask:0xf bank_mask:0xf
	s_waitcnt lgkmcnt(0)
	v_add_f32_e32 v22, v22, v23
	s_nop 5
	v_mov_b32_dpp v23, v22 quad_perm:[2,3,0,1] row_mask:0xf bank_mask:0xf
	s_waitcnt lgkmcnt(0)
	v_add_f32_e32 v23, v22, v23
	s_nop 5
	v_mov_b32_dpp v25, v23 row_half_mirror row_mask:0xf bank_mask:0xf
	v_cvt_pk_bf16_f32 v22, v18, v19
	v_xor_b32_e32 v19, 8, v219
	v_cmp_lt_i32_e32 vcc, v19, v24
	s_waitcnt lgkmcnt(0)
	v_add_f32_e32 v18, v23, v25
	s_nop 1
	v_mov_b32_dpp v19, v18 row_mirror row_mask:0xf bank_mask:0xf
	v_cvt_pk_bf16_f32 v23, v20, v21
	v_mad_i64_i32 v[20:21], s[0:1], v26, s66, v[182:183]
	global_store_dwordx2 v[20:21], v[22:23], off
	s_and_saveexec_b64 s[0:1], s[4:5]
	s_cbranch_execz .LBB0_1803
	s_waitcnt lgkmcnt(0)
	v_add_f32_e32 v20, v18, v19
	v_lshl_add_u64 v[18:19], v[178:179], 2, s[38:39]
	global_atomic_add_f32 v[18:19], v20, off offset:400

; DI unsigned pack_bf16(float lo, float hi) { f32x2 v = {lo, hi}; bf16v2 b = __builtin_convertvector(v, bf16v2); return __builtin_bit_cast(unsigned, b); }
; DI float red16(float v) { v += __shfl_xor(v, 1); v += __shfl_xor(v, 2); v += __shfl_xor(v, 4); v += __shfl_xor(v, 8); return v; }
;   DI void run8(f32x4 (&acc)[8][4], int rb, int cb, int fr, int fq) const {
;     ...
;         for (int ps = 0; ps < 4; ++ps) {
;           const f32x4 a = *(const f32x4*)(scr + (ps * 4 + prow) * 68 + c4 * 4);
;           f32x4 v;
;           v.x = xv[mm][ps].x + a.x * sc; v.y = xv[mm][ps].y + a.y * sc; v.z = xv[mm][ps].z + a.z * sc; v.w = xv[mm][ps].w + a.w * sc;
;           const int grow = rb + m * 16 + ps * 4 + prow;
;           __builtin_nontemporal_store(v, (f32x4*)(op + (size_t)(m * 16 + ps * 4) * D));
;           if (xbp) {
;             u32x2 o; o.x = pack_bf16(v.x, v.y); o.y = pack_bf16(v.z, v.w);
;             *(u32x2*)(xbp + (size_t)grow * LDH + cb + c4 * 4) = o;
;             const float t = red16(v.x * v.x + v.y * v.y + v.z * v.z + v.w * v.w);
;             if (c4 == 0) atomicAdd(ssqp + grow, t);
;           }
;         }
.LBB0_1804:
	s_waitcnt lgkmcnt(0)
	ds_read_b128 v[18:21], v0 offset:2176
	s_mov_b64 s[0:1], 0x68000
	v_lshl_add_u64 v[22:23], v[180:181], 0, s[0:1]
	s_and_b64 vcc, exec, s[6:7]
	s_waitcnt vmcnt(15) lgkmcnt(0)
	v_pk_fma_f32 v[18:19], v[18:19], 0.5, v[86:87] op_sel_hi:[1,0,1]
	v_pk_fma_f32 v[20:21], v[20:21], 0.5, v[88:89] op_sel_hi:[1,0,1]
	global_store_dwordx4 v[22:23], v[18:21], off nt
	s_cbranch_vccnz .LBB0_1808
	v_pk_mul_f32 v[22:23], v[18:19], v[18:19]
	v_pk_mul_f32 v[24:25], v[20:21], v[20:21]
	v_add_f32_e32 v22, v22, v23
	v_add_f32_e32 v22, v24, v22
	v_and_b32_e32 v24, 64, v219
	s_nop 0
	v_add_u32_e32 v24, 64, v24
	s_nop 0
	v_add_f32_e32 v22, v25, v22
	v_or_b32_e32 v26, 0x68, v178
	s_nop 1
	v_mov_b32_dpp v23, v22 quad_perm:[1,0,3,2] row_mask:0xf bank_mask:0xf
	s_waitcnt lgkmcnt(0)
	v_add_f32_e32 v22, v22, v23
	s_nop 5
	v_mov_b32_dpp v23, v22 quad_perm:[2,3,0,1] row_mask:0xf bank_mask:0xf
	s_waitcnt lgkmcnt(0)
	v_add_f32_e32 v23, v22, v23
	s_nop 5
	v_mov_b32_dpp v25, v23 row_half_mirror row_mask:0xf bank_mask:0xf
	v_cvt_pk_bf16_f32 v22, v18, v19
	v_xor_b32_e32 v19, 8, v219
	v_cmp_lt_i32_e32 vcc, v19, v24
	s_waitcnt lgkmcnt(0)
	v_add_f32_e32 v18, v23, v25
	s_nop 1
	v_mov_b32_dpp v19, v18 row_mirror row_mask:0xf bank_mask:0xf
	v_cvt_pk_bf16_f32 v23, v20, v21
	v_mad_i64_i32 v[20:21], s[0:1], v26, s66, v[182:183]
	global_store_dwordx2 v[20:21], v[22:23], off
	s_and_saveexec_b64 s[0:1], s[4:5]
	s_cbranch_execz .LBB0_1807
	s_waitcnt lgkmcnt(0)
	v_add_f32_e32 v20, v18, v19
	v_lshl_add_u64 v[18:19], v[178:179], 2, s[38:39]
	global_atomic_add_f32 v[18:19], v20, off offset:416

; DI unsigned pack_bf16(float lo, float hi) { f32x2 v = {lo, hi}; bf16v2 b = __builtin_convertvector(v, bf16v2); return __builtin_bit_cast(unsigned, b); }
; DI float red16(float v) { v += __shfl_xor(v, 1); v += __shfl_xor(v, 2); v += __shfl_xor(v, 4); v += __shfl_xor(v, 8); return v; }
;   DI void run8(f32x4 (&acc)[8][4], int rb, int cb, int fr, int fq) const {
;     ...
;         for (int ps = 0; ps < 4; ++ps) {
;           const f32x4 a = *(const f32x4*)(scr + (ps * 4 + prow) * 68 + c4 * 4);
;           f32x4 v;
;           v.x = xv[mm][ps].x + a.x * sc; v.y = xv[mm][ps].y + a.y * sc; v.z = xv[mm][ps].z + a.z * sc; v.w = xv[mm][ps].w + a.w * sc;
;           const int grow = rb + m * 16 + ps * 4 + prow;
;           __builtin_nontemporal_store(v, (f32x4*)(op + (size_t)(m * 16 + ps * 4) * D));
;           if (xbp) {
;             u32x2 o; o.x = pack_bf16(v.x, v.y); o.y = pack_bf16(v.z, v.w);
;             *(u32x2*)(xbp + (size_t)grow * LDH + cb + c4 * 4) = o;
;             const float t = red16(v.x * v.x + v.y * v.y + v.z * v.z + v.w * v.w);
;             if (c4 == 0) atomicAdd(ssqp + grow, t);
;           }
;         }
.LBB0_1808:
	s_waitcnt lgkmcnt(0)
	ds_read_b128 v[18:21], v0 offset:3264
	s_mov_b64 s[0:1], 0x6c000
	v_lshl_add_u64 v[22:23], v[180:181], 0, s[0:1]
	s_and_b64 vcc, exec, s[6:7]
	s_waitcnt vmcnt(15) lgkmcnt(0)
	v_pk_fma_f32 v[18:19], v[18:19], 0.5, v[82:83] op_sel_hi:[1,0,1]
	v_pk_fma_f32 v[20:21], v[20:21], 0.5, v[84:85] op_sel_hi:[1,0,1]
	global_store_dwordx4 v[22:23], v[18:21], off nt
	s_cbranch_vccnz .LBB0_1812
	v_pk_mul_f32 v[22:23], v[18:19], v[18:19]
	v_pk_mul_f32 v[24:25], v[20:21], v[20:21]
	v_add_f32_e32 v22, v22, v23
	v_add_f32_e32 v22, v24, v22
	v_and_b32_e32 v24, 64, v219
	s_nop 0
	v_add_u32_e32 v24, 64, v24
	s_nop 0
	v_add_f32_e32 v22, v25, v22
	v_or_b32_e32 v26, 0x6c, v178
	s_nop 1
	v_mov_b32_dpp v23, v22 quad_perm:[1,0,3,2] row_mask:0xf bank_mask:0xf
	s_waitcnt lgkmcnt(0)
	v_add_f32_e32 v22, v22, v23
	s_nop 5
	v_mov_b32_dpp v23, v22 quad_perm:[2,3,0,1] row_mask:0xf bank_mask:0xf
	s_waitcnt lgkmcnt(0)
	v_add_f32_e32 v23, v22, v23
	s_nop 5
	v_mov_b32_dpp v25, v23 row_half_mirror row_mask:0xf bank_mask:0xf
	v_cvt_pk_bf16_f32 v22, v18, v19
	v_xor_b32_e32 v19, 8, v219
	v_cmp_lt_i32_e32 vcc, v19, v24
	s_waitcnt lgkmcnt(0)
	v_add_f32_e32 v18, v23, v25
	s_nop 1
	v_mov_b32_dpp v19, v18 row_mirror row_mask:0xf bank_mask:0xf
	v_cvt_pk_bf16_f32 v23, v20, v21
	v_mad_i64_i32 v[20:21], s[0:1], v26, s66, v[182:183]
	global_store_dwordx2 v[20:21], v[22:23], off
	s_and_saveexec_b64 s[0:1], s[4:5]
	s_cbranch_execz .LBB0_1811
	s_waitcnt lgkmcnt(0)
	v_add_f32_e32 v20, v18, v19
	v_lshl_add_u64 v[18:19], v[178:179], 2, s[38:39]
	global_atomic_add_f32 v[18:19], v20, off offset:432

; DI unsigned pack_bf16(float lo, float hi) { f32x2 v = {lo, hi}; bf16v2 b = __builtin_convertvector(v, bf16v2); return __builtin_bit_cast(unsigned, b); }
; DI float red16(float v) { v += __shfl_xor(v, 1); v += __shfl_xor(v, 2); v += __shfl_xor(v, 4); v += __shfl_xor(v, 8); return v; }
;   DI void run8(f32x4 (&acc)[8][4], int rb, int cb, int fr, int fq) const {
;     ...
;       for (int mm = 0; mm < 4; ++mm) {
;         const int m = mh * 4 + mm;
; #pragma unroll
;         for (int n = 0; n < 4; ++n)
; #pragma unroll
;           for (int j = 0; j < 4; ++j) scr[(fq * 4 + j) * 68 + n * 16 + fr] = acc[m][n][j];
;         __builtin_amdgcn_sched_barrier(0);
; #pragma unroll
;         for (int ps = 0; ps < 4; ++ps) {
;           const f32x4 a = *(const f32x4*)(scr + (ps * 4 + prow) * 68 + c4 * 4);
;           f32x4 v;
;           v.x = xv[mm][ps].x + a.x * sc; v.y = xv[mm][ps].y + a.y * sc; v.z = xv[mm][ps].z + a.z * sc; v.w = xv[mm][ps].w + a.w * sc;
;           const int grow = rb + m * 16 + ps * 4 + prow;
;           __builtin_nontemporal_store(v, (f32x4*)(op + (size_t)(m * 16 + ps * 4) * D));
;           if (xbp) {
;             u32x2 o; o.x = pack_bf16(v.x, v.y); o.y = pack_bf16(v.z, v.w);
;             *(u32x2*)(xbp + (size_t)grow * LDH + cb + c4 * 4) = o;
;             const float t = red16(v.x * v.x + v.y * v.y + v.z * v.z + v.w * v.w);
;             if (c4 == 0) atomicAdd(ssqp + grow, t);
;           }
;         }
.LBB0_1812:
	s_mov_b64 s[0:1], 0x70000
	s_waitcnt lgkmcnt(0)
	v_lshl_add_u64 v[18:19], v[180:181], 0, s[0:1]
	ds_write2_b32 v184, v10, v14 offset1:16
	ds_write2_b32 v184, v11, v15 offset0:68 offset1:84
	ds_write2_b32 v184, v12, v16 offset0:136 offset1:152
	ds_write2_b32 v184, v13, v17 offset0:204 offset1:220
	ds_write2_b32 v184, v2, v6 offset0:32 offset1:48
	ds_write2_b32 v184, v3, v7 offset0:100 offset1:116
	ds_write2_b32 v184, v4, v8 offset0:168 offset1:184
	ds_write2_b32 v184, v5, v9 offset0:236 offset1:252
	ds_read_b128 v[2:5], v0
	s_and_b64 vcc, exec, s[6:7]
	s_waitcnt vmcnt(15) lgkmcnt(0)
	v_pk_fma_f32 v[2:3], v[2:3], 0.5, v[78:79] op_sel_hi:[1,0,1]
	v_pk_fma_f32 v[4:5], v[4:5], 0.5, v[80:81] op_sel_hi:[1,0,1]
	global_store_dwordx4 v[18:19], v[2:5], off nt
	s_cbranch_vccnz .LBB0_1816
	v_pk_mul_f32 v[6:7], v[2:3], v[2:3]
	v_pk_mul_f32 v[8:9], v[4:5], v[4:5]
	v_add_f32_e32 v6, v6, v7
	v_add_f32_e32 v6, v8, v6
	v_and_b32_e32 v8, 64, v219
	s_nop 0
	v_add_u32_e32 v8, 64, v8
	s_nop 0
	v_add_f32_e32 v6, v9, v6
	v_or_b32_e32 v10, 0x70, v178
	s_nop 1
	v_mov_b32_dpp v7, v6 quad_perm:[1,0,3,2] row_mask:0xf bank_mask:0xf
	s_waitcnt lgkmcnt(0)
	v_add_f32_e32 v6, v6, v7
	s_nop 5
	v_mov_b32_dpp v7, v6 quad_perm:[2,3,0,1] row_mask:0xf bank_mask:0xf
	s_waitcnt lgkmcnt(0)
	v_add_f32_e32 v7, v6, v7
	s_nop 5
	v_mov_b32_dpp v9, v7 row_half_mirror row_mask:0xf bank_mask:0xf
	v_cvt_pk_bf16_f32 v6, v2, v3
	v_xor_b32_e32 v3, 8, v219
	v_cmp_lt_i32_e32 vcc, v3, v8
	s_waitcnt lgkmcnt(0)
	v_add_f32_e32 v2, v7, v9
	s_nop 1
	v_mov_b32_dpp v3, v2 row_mirror row_mask:0xf bank_mask:0xf
	v_cvt_pk_bf16_f32 v7, v4, v5
	v_mad_i64_i32 v[4:5], s[0:1], v10, s66, v[182:183]
	global_store_dwordx2 v[4:5], v[6:7], off
	s_and_saveexec_b64 s[0:1], s[4:5]
	s_cbranch_execz .LBB0_1815
	s_waitcnt lgkmcnt(0)
	v_add_f32_e32 v4, v2, v3
	v_lshl_add_u64 v[2:3], v[178:179], 2, s[38:39]
	global_atomic_add_f32 v[2:3], v4, off offset:448

; DI unsigned pack_bf16(float lo, float hi) { f32x2 v = {lo, hi}; bf16v2 b = __builtin_convertvector(v, bf16v2); return __builtin_bit_cast(unsigned, b); }
; DI float red16(float v) { v += __shfl_xor(v, 1); v += __shfl_xor(v, 2); v += __shfl_xor(v, 4); v += __shfl_xor(v, 8); return v; }
;   DI void run8(f32x4 (&acc)[8][4], int rb, int cb, int fr, int fq) const {
;     ...
;         for (int ps = 0; ps < 4; ++ps) {
;           const f32x4 a = *(const f32x4*)(scr + (ps * 4 + prow) * 68 + c4 * 4);
;           f32x4 v;
;           v.x = xv[mm][ps].x + a.x * sc; v.y = xv[mm][ps].y + a.y * sc; v.z = xv[mm][ps].z + a.z * sc; v.w = xv[mm][ps].w + a.w * sc;
;           const int grow = rb + m * 16 + ps * 4 + prow;
;           __builtin_nontemporal_store(v, (f32x4*)(op + (size_t)(m * 16 + ps * 4) * D));
;           if (xbp) {
;             u32x2 o; o.x = pack_bf16(v.x, v.y); o.y = pack_bf16(v.z, v.w);
;             *(u32x2*)(xbp + (size_t)grow * LDH + cb + c4 * 4) = o;
;             const float t = red16(v.x * v.x + v.y * v.y + v.z * v.z + v.w * v.w);
;             if (c4 == 0) atomicAdd(ssqp + grow, t);
;           }
;         }
.LBB0_1816:
	s_waitcnt lgkmcnt(0)
	ds_read_b128 v[2:5], v0 offset:1088
	s_mov_b64 s[0:1], 0x74000
	v_lshl_add_u64 v[6:7], v[180:181], 0, s[0:1]
	s_and_b64 vcc, exec, s[6:7]
	s_waitcnt vmcnt(15) lgkmcnt(0)
	v_pk_fma_f32 v[2:3], v[2:3], 0.5, v[74:75] op_sel_hi:[1,0,1]
	v_pk_fma_f32 v[4:5], v[4:5], 0.5, v[76:77] op_sel_hi:[1,0,1]
	global_store_dwordx4 v[6:7], v[2:5], off nt
	s_cbranch_vccnz .LBB0_1820
	v_pk_mul_f32 v[6:7], v[2:3], v[2:3]
	v_pk_mul_f32 v[8:9], v[4:5], v[4:5]
	v_add_f32_e32 v6, v6, v7
	v_add_f32_e32 v6, v8, v6
	v_and_b32_e32 v8, 64, v219
	s_nop 0
	v_add_u32_e32 v8, 64, v8
	s_nop 0
	v_add_f32_e32 v6, v9, v6
	v_or_b32_e32 v10, 0x74, v178
	s_nop 1
	v_mov_b32_dpp v7, v6 quad_perm:[1,0,3,2] row_mask:0xf bank_mask:0xf
	s_waitcnt lgkmcnt(0)
	v_add_f32_e32 v6, v6, v7
	s_nop 5
	v_mov_b32_dpp v7, v6 quad_perm:[2,3,0,1] row_mask:0xf bank_mask:0xf
	s_waitcnt lgkmcnt(0)
	v_add_f32_e32 v7, v6, v7
	s_nop 5
	v_mov_b32_dpp v9, v7 row_half_mirror row_mask:0xf bank_mask:0xf
	v_cvt_pk_bf16_f32 v6, v2, v3
	v_xor_b32_e32 v3, 8, v219
	v_cmp_lt_i32_e32 vcc, v3, v8
	s_waitcnt lgkmcnt(0)
	v_add_f32_e32 v2, v7, v9
	s_nop 1
	v_mov_b32_dpp v3, v2 row_mirror row_mask:0xf bank_mask:0xf
	v_cvt_pk_bf16_f32 v7, v4, v5
	v_mad_i64_i32 v[4:5], s[0:1], v10, s66, v[182:183]
	global_store_dwordx2 v[4:5], v[6:7], off
	s_and_saveexec_b64 s[0:1], s[4:5]
	s_cbranch_execz .LBB0_1819
	s_waitcnt lgkmcnt(0)
	v_add_f32_e32 v4, v2, v3
	v_lshl_add_u64 v[2:3], v[178:179], 2, s[38:39]
	global_atomic_add_f32 v[2:3], v4, off offset:464

; DI unsigned pack_bf16(float lo, float hi) { f32x2 v = {lo, hi}; bf16v2 b = __builtin_convertvector(v, bf16v2); return __builtin_bit_cast(unsigned, b); }
; DI float red16(float v) { v += __shfl_xor(v, 1); v += __shfl_xor(v, 2); v += __shfl_xor(v, 4); v += __shfl_xor(v, 8); return v; }
;   DI void run8(f32x4 (&acc)[8][4], int rb, int cb, int fr, int fq) const {
;     ...
;         for (int ps = 0; ps < 4; ++ps) {
;           const f32x4 a = *(const f32x4*)(scr + (ps * 4 + prow) * 68 + c4 * 4);
;           f32x4 v;
;           v.x = xv[mm][ps].x + a.x * sc; v.y = xv[mm][ps].y + a.y * sc; v.z = xv[mm][ps].z + a.z * sc; v.w = xv[mm][ps].w + a.w * sc;
;           const int grow = rb + m * 16 + ps * 4 + prow;
;           __builtin_nontemporal_store(v, (f32x4*)(op + (size_t)(m * 16 + ps * 4) * D));
;           if (xbp) {
;             u32x2 o; o.x = pack_bf16(v.x, v.y); o.y = pack_bf16(v.z, v.w);
;             *(u32x2*)(xbp + (size_t)grow * LDH + cb + c4 * 4) = o;
;             const float t = red16(v.x * v.x + v.y * v.y + v.z * v.z + v.w * v.w);
;             if (c4 == 0) atomicAdd(ssqp + grow, t);
;           }
;         }
.LBB0_1820:
	s_waitcnt lgkmcnt(0)
	ds_read_b128 v[2:5], v0 offset:2176
	s_mov_b64 s[0:1], 0x78000
	v_lshl_add_u64 v[6:7], v[180:181], 0, s[0:1]
	s_and_b64 vcc, exec, s[6:7]
	s_waitcnt vmcnt(15) lgkmcnt(0)
	v_pk_fma_f32 v[2:3], v[2:3], 0.5, v[70:71] op_sel_hi:[1,0,1]
	v_pk_fma_f32 v[4:5], v[4:5], 0.5, v[72:73] op_sel_hi:[1,0,1]
	global_store_dwordx4 v[6:7], v[2:5], off nt
	s_cbranch_vccnz .LBB0_1824
	v_pk_mul_f32 v[6:7], v[2:3], v[2:3]
	v_pk_mul_f32 v[8:9], v[4:5], v[4:5]
	v_add_f32_e32 v6, v6, v7
	v_add_f32_e32 v6, v8, v6
	v_and_b32_e32 v8, 64, v219
	s_nop 0
	v_add_u32_e32 v8, 64, v8
	s_nop 0
	v_add_f32_e32 v6, v9, v6
	v_or_b32_e32 v10, 0x78, v178
	s_nop 1
	v_mov_b32_dpp v7, v6 quad_perm:[1,0,3,2] row_mask:0xf bank_mask:0xf
	s_waitcnt lgkmcnt(0)
	v_add_f32_e32 v6, v6, v7
	s_nop 5
	v_mov_b32_dpp v7, v6 quad_perm:[2,3,0,1] row_mask:0xf bank_mask:0xf
	s_waitcnt lgkmcnt(0)
	v_add_f32_e32 v7, v6, v7
	s_nop 5
	v_mov_b32_dpp v9, v7 row_half_mirror row_mask:0xf bank_mask:0xf
	v_cvt_pk_bf16_f32 v6, v2, v3
	v_xor_b32_e32 v3, 8, v219
	v_cmp_lt_i32_e32 vcc, v3, v8
	s_waitcnt lgkmcnt(0)
	v_add_f32_e32 v2, v7, v9
	s_nop 1
	v_mov_b32_dpp v3, v2 row_mirror row_mask:0xf bank_mask:0xf
	v_cvt_pk_bf16_f32 v7, v4, v5
	v_mad_i64_i32 v[4:5], s[0:1], v10, s66, v[182:183]
	global_store_dwordx2 v[4:5], v[6:7], off
	s_and_saveexec_b64 s[0:1], s[4:5]
	s_cbranch_execz .LBB0_1823
	s_waitcnt lgkmcnt(0)
	v_add_f32_e32 v4, v2, v3
	v_lshl_add_u64 v[2:3], v[178:179], 2, s[38:39]
	global_atomic_add_f32 v[2:3], v4, off offset:480

; DI unsigned pack_bf16(float lo, float hi) { f32x2 v = {lo, hi}; bf16v2 b = __builtin_convertvector(v, bf16v2); return __builtin_bit_cast(unsigned, b); }
; DI float red16(float v) { v += __shfl_xor(v, 1); v += __shfl_xor(v, 2); v += __shfl_xor(v, 4); v += __shfl_xor(v, 8); return v; }
;   DI void run8(f32x4 (&acc)[8][4], int rb, int cb, int fr, int fq) const {
;     ...
;         for (int ps = 0; ps < 4; ++ps) {
;           const f32x4 a = *(const f32x4*)(scr + (ps * 4 + prow) * 68 + c4 * 4);
;           f32x4 v;
;           v.x = xv[mm][ps].x + a.x * sc; v.y = xv[mm][ps].y + a.y * sc; v.z = xv[mm][ps].z + a.z * sc; v.w = xv[mm][ps].w + a.w * sc;
;           const int grow = rb + m * 16 + ps * 4 + prow;
;           __builtin_nontemporal_store(v, (f32x4*)(op + (size_t)(m * 16 + ps * 4) * D));
;           if (xbp) {
;             u32x2 o; o.x = pack_bf16(v.x, v.y); o.y = pack_bf16(v.z, v.w);
;             *(u32x2*)(xbp + (size_t)grow * LDH + cb + c4 * 4) = o;
;             const float t = red16(v.x * v.x + v.y * v.y + v.z * v.z + v.w * v.w);
;             if (c4 == 0) atomicAdd(ssqp + grow, t);
;           }
;         }
.LBB0_1824:
	s_waitcnt lgkmcnt(0)
	ds_read_b128 v[2:5], v0 offset:3264
	s_mov_b64 s[0:1], 0x7c000
	v_lshl_add_u64 v[6:7], v[180:181], 0, s[0:1]
	s_and_b64 vcc, exec, s[6:7]
	s_waitcnt vmcnt(15) lgkmcnt(0)
	v_pk_fma_f32 v[2:3], v[2:3], 0.5, v[66:67] op_sel_hi:[1,0,1]
	v_pk_fma_f32 v[4:5], v[4:5], 0.5, v[68:69] op_sel_hi:[1,0,1]
	global_store_dwordx4 v[6:7], v[2:5], off nt
	s_cbranch_vccnz .LBB0_1689
	v_pk_mul_f32 v[6:7], v[2:3], v[2:3]
	v_pk_mul_f32 v[8:9], v[4:5], v[4:5]
	v_add_f32_e32 v0, v6, v7
	v_and_b32_e32 v7, 64, v219
	s_nop 0
	v_add_u32_e32 v7, 64, v7
	s_nop 0
	v_add_f32_e32 v0, v8, v0
	v_add_f32_e32 v0, v9, v0
	s_nop 1
	v_mov_b32_dpp v6, v0 quad_perm:[1,0,3,2] row_mask:0xf bank_mask:0xf
	v_or_b32_e32 v9, 0x7c, v178
	s_waitcnt lgkmcnt(0)
	v_add_f32_e32 v0, v0, v6
	s_nop 5
	v_mov_b32_dpp v6, v0 quad_perm:[2,3,0,1] row_mask:0xf bank_mask:0xf
	s_waitcnt lgkmcnt(0)
	v_add_f32_e32 v0, v0, v6
	s_nop 5
	v_mov_b32_dpp v8, v0 row_half_mirror row_mask:0xf bank_mask:0xf
	v_cvt_pk_bf16_f32 v6, v2, v3
	v_xor_b32_e32 v2, 8, v219
	v_cmp_lt_i32_e32 vcc, v2, v7
	v_cvt_pk_bf16_f32 v7, v4, v5
	s_waitcnt lgkmcnt(0)
	v_add_f32_e32 v0, v0, v8
	s_nop 1
	v_mov_b32_dpp v2, v0 row_mirror row_mask:0xf bank_mask:0xf
	v_mad_i64_i32 v[4:5], s[0:1], v9, s66, v[182:183]
	global_store_dwordx2 v[4:5], v[6:7], off
	s_and_saveexec_b64 s[0:1], s[4:5]
	s_cbranch_execz .LBB0_1688
	s_waitcnt lgkmcnt(0)
	v_add_f32_e32 v0, v0, v2
	v_lshl_add_u64 v[2:3], v[178:179], 2, s[38:39]
	global_atomic_add_f32 v[2:3], v0, off offset:496
	s_branch .LBB0_1688
